# K-loop loader critical path: hoist the 6-DMA slots' address VALU/SALU (v_lshl_add_u64 + s_add/addc) into the preceding 2-DMA slot's loader part with fresh VGPR pairs, 16 of 28 K-loops; bit-identical
# speedup vs baseline: 1.0013x; 1.0013x over previous
; #define PG8_STAGE(bufoff, gbase, voff) do { _Pragma("unroll") for (int _i = 0; _i < 2; ++_i) \
;         __builtin_amdgcn_global_load_lds((const unsigned*)((const char*)(gbase) + (voff)[_i]), (PG8_LAS unsigned*)(lds + (bufoff) + ldsw + _i * 8192), 16, 0, 0); } while (0)
; #define PG8_LDA(dst, b, h) do { _Pragma("unroll") for (int m = 0; m < 4; ++m) _Pragma("unroll") for (int k = 0; k < 2; ++k) dst[m][k] = *(const PG8_LAS bf16x8*)(lds + PG8_SA(b, h) + aoff + m * 2048 + k * 1024); } while (0)
; #define PG8_LDB(dst, b, h) do { _Pragma("unroll") for (int n = 0; n < 2; ++n) _Pragma("unroll") for (int k = 0; k < 2; ++k) dst[n][k] = *(const PG8_LAS bf16x8*)(lds + PG8_SB(b, h) + boff + n * 2048 + k * 1024); } while (0)
; #define PG8_MMA(ai, bj, At, Bt) do { __builtin_amdgcn_s_setprio(1); _Pragma("unroll") for (int m = 0; m < 4; ++m) _Pragma("unroll") for (int n = 0; n < 2; ++n) _Pragma("unroll") for (int k = 0; k < 2; ++k) \
;         acc[ai][bj][m][n] = __builtin_amdgcn_mfma_f32_16x16x32_bf16(Bt[n][k], At[m][k], acc[ai][bj][m][n], 0, 0, 0); __builtin_amdgcn_s_setprio(0); } while (0)
; #define PG8_WAIT_V(n) asm volatile("s_waitcnt vmcnt(" #n ")" ::: "memory")
; #define PG8_WAIT_L(n) asm volatile("s_waitcnt lgkmcnt(" #n ")" ::: "memory")
; #define PG8_BAR __builtin_amdgcn_s_barrier()
; #define PG8_SCHED __builtin_amdgcn_sched_barrier(0)
; template <class Epi, class Sched, bool ALIGN_EPI = false, bool SP2 = false>
; __device__ __forceinline__ void gemm_phase(PG8_LAS unsigned char* lds, const Gemm g, const Sched& S, const Epi& E, const int wave_s) {
;     ...
;             const bool last = (t == nt - 2);
;             const char* a1 = cA + (size_t)(t + 1) * kstep;
;             const char* a2 = last ? nA : cA + (size_t)(t + 2) * kstep; const char* b2 = last ? nB : cB + (size_t)(t + 2) * kstep;
;             const char* a3 = a2 + kstep; const char* b3 = b2 + kstep;
;             if (last && has_next) S.a_ready(nxt);
;             if constexpr (SP2) {
;             PG8_LDB(B0, 0, 0); PG8_LDB(B1, 0, 1); PG8_SCHED; PG8_LDA(At, 0, 0); PG8_STAGE(PG8_SA(1, 1), a1 + hstep, voffA);
;             PG8_WAIT_V(8); PG8_WAIT_L(0); PG8_BAR; PG8_MMA(0, 0, At, B0); PG8_MMA(0, 1, At, B1); PG8_BAR; PG8_SCHED;
;             PG8_LDA(At, 0, 1); PG8_STAGE(PG8_SB(0, 0), b2, voffB); PG8_STAGE(PG8_SB(0, 1), b2 + hstep, voffB); PG8_STAGE(PG8_SA(0, 0), a2, voffA);
.LBB0_182:
	ds_read_b128 v[144:147], v149
	ds_read_b128 v[152:155], v149 offset:1024
	ds_read_b128 v[156:159], v149 offset:2048
	ds_read_b128 v[160:163], v149 offset:3072
	ds_read_b128 v[164:167], v150
	ds_read_b128 v[168:171], v150 offset:1024
	ds_read_b128 v[172:175], v150 offset:2048
	ds_read_b128 v[176:179], v150 offset:3072
	s_add_u32 s28, s26, 0xfffc0080
	s_addc_u32 s29, s27, -1
	s_cmp_eq_u32 s56, 12
	s_cselect_b32 s31, s19, s29
	s_cselect_b32 s30, s25, s28
	s_cselect_b32 s29, s17, s55
	s_cselect_b32 s28, s53, s54
	v_lshl_add_u64 v[212:213], s[26:27], 0, v[138:139]
	s_add_i32 m0, s40, 0xc000
	ds_read_b128 v[180:183], v151
	ds_read_b128 v[184:187], v151 offset:1024
	ds_read_b128 v[188:191], v151 offset:2048
	ds_read_b128 v[192:195], v151 offset:3072
	ds_read_b128 v[196:199], v151 offset:4096
	ds_read_b128 v[200:203], v151 offset:5120
	ds_read_b128 v[204:207], v151 offset:6144
	ds_read_b128 v[208:211], v151 offset:7168
	global_load_lds_dwordx4 v[212:213], off
	v_lshl_add_u64 v[212:213], s[26:27], 0, v[136:137]
	s_add_i32 m0, s40, 0xe000
	s_nop 0
	global_load_lds_dwordx4 v[212:213], off
	v_lshl_add_u64 v[230:231], s[28:29], 0, v[132:133]
	s_add_u32 s58, s28, 0x40000
	v_lshl_add_u64 v[232:233], s[28:29], 0, v[128:129]
	s_addc_u32 s59, s29, 0
	v_lshl_add_u64 v[234:235], s[58:59], 0, v[132:133]
	v_lshl_add_u64 v[236:237], s[30:31], 0, v[130:131]
	v_lshl_add_u64 v[238:239], s[58:59], 0, v[128:129]
	v_lshl_add_u64 v[240:241], s[30:31], 0, v[134:135]
	s_waitcnt vmcnt(8)
	s_waitcnt lgkmcnt(0)
	s_barrier
	s_setprio 1
	s_waitcnt lgkmcnt(0)
	v_mfma_f32_16x16x32_bf16 v[124:127], v[144:147], v[180:183], v[124:127]
	v_mfma_f32_16x16x32_bf16 v[120:123], v[156:159], v[180:183], v[120:123]
	v_mfma_f32_16x16x32_bf16 v[112:115], v[144:147], v[188:191], v[112:115]
	v_mfma_f32_16x16x32_bf16 v[104:107], v[156:159], v[188:191], v[104:107]
	v_mfma_f32_16x16x32_bf16 v[96:99], v[144:147], v[196:199], v[96:99]
	v_mfma_f32_16x16x32_bf16 v[88:91], v[156:159], v[196:199], v[88:91]
	v_mfma_f32_16x16x32_bf16 v[80:83], v[144:147], v[204:207], v[80:83]
	v_mfma_f32_16x16x32_bf16 v[72:75], v[156:159], v[204:207], v[72:75]
	v_mfma_f32_16x16x32_bf16 v[124:127], v[152:155], v[184:187], v[124:127]
	v_mfma_f32_16x16x32_bf16 v[120:123], v[160:163], v[184:187], v[120:123]
	v_mfma_f32_16x16x32_bf16 v[112:115], v[152:155], v[192:195], v[112:115]
	v_mfma_f32_16x16x32_bf16 v[104:107], v[160:163], v[192:195], v[104:107]
	v_mfma_f32_16x16x32_bf16 v[96:99], v[152:155], v[200:203], v[96:99]
	v_mfma_f32_16x16x32_bf16 v[88:91], v[160:163], v[200:203], v[88:91]
	v_mfma_f32_16x16x32_bf16 v[80:83], v[152:155], v[208:211], v[80:83]
	v_mfma_f32_16x16x32_bf16 v[72:75], v[160:163], v[208:211], v[72:75]
	s_setprio 0
	s_setprio 1
	v_mfma_f32_16x16x32_bf16 v[116:119], v[164:167], v[180:183], v[116:119]
	v_mfma_f32_16x16x32_bf16 v[108:111], v[172:175], v[180:183], v[108:111]
	v_mfma_f32_16x16x32_bf16 v[100:103], v[164:167], v[188:191], v[100:103]
	v_mfma_f32_16x16x32_bf16 v[92:95], v[172:175], v[188:191], v[92:95]
	v_mfma_f32_16x16x32_bf16 v[84:87], v[164:167], v[196:199], v[84:87]
	v_mfma_f32_16x16x32_bf16 v[76:79], v[172:175], v[196:199], v[76:79]
	v_mfma_f32_16x16x32_bf16 v[68:71], v[164:167], v[204:207], v[68:71]
	v_mfma_f32_16x16x32_bf16 v[64:67], v[172:175], v[204:207], v[64:67]
	v_mfma_f32_16x16x32_bf16 v[116:119], v[168:171], v[184:187], v[116:119]
	v_mfma_f32_16x16x32_bf16 v[108:111], v[176:179], v[184:187], v[108:111]
	v_mfma_f32_16x16x32_bf16 v[100:103], v[168:171], v[192:195], v[100:103]
	v_mfma_f32_16x16x32_bf16 v[92:95], v[176:179], v[192:195], v[92:95]
	v_mfma_f32_16x16x32_bf16 v[84:87], v[168:171], v[200:203], v[84:87]
	v_mfma_f32_16x16x32_bf16 v[76:79], v[176:179], v[200:203], v[76:79]
	v_mfma_f32_16x16x32_bf16 v[68:71], v[168:171], v[208:211], v[68:71]
	v_mfma_f32_16x16x32_bf16 v[64:67], v[176:179], v[208:211], v[64:67]
	s_setprio 0
	s_barrier
	s_add_i32 s57, s50, s33
	s_mov_b32 m0, s57
	ds_read_b128 v[180:183], v151 offset:16384
	ds_read_b128 v[184:187], v151 offset:17408
	ds_read_b128 v[188:191], v151 offset:18432
	ds_read_b128 v[192:195], v151 offset:19456
	ds_read_b128 v[196:199], v151 offset:20480
	ds_read_b128 v[200:203], v151 offset:21504
	ds_read_b128 v[204:207], v151 offset:22528
	ds_read_b128 v[208:211], v151 offset:23552
	global_load_lds_dwordx4 v[230:231], off
	s_add_i32 m0, s57, 0x2000
	s_add_i32 s57, s51, s33
	global_load_lds_dwordx4 v[232:233], off
	s_mov_b32 m0, s57
	s_nop 0
	global_load_lds_dwordx4 v[234:235], off
	s_add_i32 m0, s57, 0x2000
	s_nop 0
	global_load_lds_dwordx4 v[238:239], off
	s_mov_b32 m0, s40
	s_nop 0
	global_load_lds_dwordx4 v[240:241], off
	s_mov_b32 m0, s41
	s_nop 0
	global_load_lds_dwordx4 v[236:237], off
	s_waitcnt vmcnt(8)
	s_waitcnt lgkmcnt(0)
	s_barrier
; #define PG8_STAGE(bufoff, gbase, voff) do { _Pragma("unroll") for (int _i = 0; _i < 2; ++_i) \
;         __builtin_amdgcn_global_load_lds((const unsigned*)((const char*)(gbase) + (voff)[_i]), (PG8_LAS unsigned*)(lds + (bufoff) + ldsw + _i * 8192), 16, 0, 0); } while (0)
; #define PG8_LDA(dst, b, h) do { _Pragma("unroll") for (int m = 0; m < 4; ++m) _Pragma("unroll") for (int k = 0; k < 2; ++k) dst[m][k] = *(const PG8_LAS bf16x8*)(lds + PG8_SA(b, h) + aoff + m * 2048 + k * 1024); } while (0)
; #define PG8_LDB(dst, b, h) do { _Pragma("unroll") for (int n = 0; n < 2; ++n) _Pragma("unroll") for (int k = 0; k < 2; ++k) dst[n][k] = *(const PG8_LAS bf16x8*)(lds + PG8_SB(b, h) + boff + n * 2048 + k * 1024); } while (0)
; #define PG8_MMA(ai, bj, At, Bt) do { __builtin_amdgcn_s_setprio(1); _Pragma("unroll") for (int m = 0; m < 4; ++m) _Pragma("unroll") for (int n = 0; n < 2; ++n) _Pragma("unroll") for (int k = 0; k < 2; ++k) \
;         acc[ai][bj][m][n] = __builtin_amdgcn_mfma_f32_16x16x32_bf16(Bt[n][k], At[m][k], acc[ai][bj][m][n], 0, 0, 0); __builtin_amdgcn_s_setprio(0); } while (0)
; #define PG8_WAIT_V(n) asm volatile("s_waitcnt vmcnt(" #n ")" ::: "memory")
; #define PG8_WAIT_L(n) asm volatile("s_waitcnt lgkmcnt(" #n ")" ::: "memory")
; #define PG8_BAR __builtin_amdgcn_s_barrier()
; #define PG8_SCHED __builtin_amdgcn_sched_barrier(0)
; template <class Epi, class Sched, bool ALIGN_EPI = false, bool SP2 = false>
; __device__ __forceinline__ void gemm_phase(PG8_LAS unsigned char* lds, const Gemm g, const Sched& S, const Epi& E, const int wave_s) {
;     ...
;             PG8_WAIT_V(8); PG8_WAIT_L(0); PG8_BAR; PG8_MMA(0, 0, At, B0); PG8_MMA(0, 1, At, B1); PG8_BAR; PG8_SCHED;
;             PG8_LDA(At, 0, 1); PG8_STAGE(PG8_SB(0, 0), b2, voffB); PG8_STAGE(PG8_SB(0, 1), b2 + hstep, voffB); PG8_STAGE(PG8_SA(0, 0), a2, voffA);
;             PG8_WAIT_V(8); PG8_WAIT_L(0); PG8_BAR; PG8_MMA(1, 0, At, B0); PG8_MMA(1, 1, At, B1); PG8_BAR; PG8_SCHED;
;             PG8_LDB(B0, 1, 0); PG8_LDB(B1, 1, 1); PG8_SCHED; PG8_LDA(At, 1, 0); PG8_STAGE(PG8_SA(0, 1), a2 + hstep, voffA);
;             PG8_WAIT_V(8); PG8_WAIT_L(0); PG8_BAR; PG8_MMA(0, 0, At, B0); PG8_MMA(0, 1, At, B1); PG8_BAR; PG8_SCHED;
	s_setprio 1
	s_waitcnt lgkmcnt(0)
	v_mfma_f32_16x16x32_bf16 v[60:63], v[144:147], v[180:183], v[60:63]
	v_mfma_f32_16x16x32_bf16 v[56:59], v[156:159], v[180:183], v[56:59]
	v_mfma_f32_16x16x32_bf16 v[48:51], v[144:147], v[188:191], v[48:51]
	v_mfma_f32_16x16x32_bf16 v[40:43], v[156:159], v[188:191], v[40:43]
	v_mfma_f32_16x16x32_bf16 v[32:35], v[144:147], v[196:199], v[32:35]
	v_mfma_f32_16x16x32_bf16 v[24:27], v[156:159], v[196:199], v[24:27]
	v_mfma_f32_16x16x32_bf16 v[16:19], v[144:147], v[204:207], v[16:19]
	v_mfma_f32_16x16x32_bf16 v[8:11], v[156:159], v[204:207], v[8:11]
	v_mfma_f32_16x16x32_bf16 v[60:63], v[152:155], v[184:187], v[60:63]
	v_mfma_f32_16x16x32_bf16 v[56:59], v[160:163], v[184:187], v[56:59]
	v_mfma_f32_16x16x32_bf16 v[48:51], v[152:155], v[192:195], v[48:51]
	v_mfma_f32_16x16x32_bf16 v[40:43], v[160:163], v[192:195], v[40:43]
	v_mfma_f32_16x16x32_bf16 v[32:35], v[152:155], v[200:203], v[32:35]
	v_mfma_f32_16x16x32_bf16 v[24:27], v[160:163], v[200:203], v[24:27]
	v_mfma_f32_16x16x32_bf16 v[16:19], v[152:155], v[208:211], v[16:19]
	v_mfma_f32_16x16x32_bf16 v[8:11], v[160:163], v[208:211], v[8:11]
	s_setprio 0
	s_setprio 1
	v_mfma_f32_16x16x32_bf16 v[52:55], v[164:167], v[180:183], v[52:55]
	v_mfma_f32_16x16x32_bf16 v[44:47], v[172:175], v[180:183], v[44:47]
	v_mfma_f32_16x16x32_bf16 v[36:39], v[164:167], v[188:191], v[36:39]
	v_mfma_f32_16x16x32_bf16 v[28:31], v[172:175], v[188:191], v[28:31]
	v_mfma_f32_16x16x32_bf16 v[20:23], v[164:167], v[196:199], v[20:23]
	v_mfma_f32_16x16x32_bf16 v[12:15], v[172:175], v[196:199], v[12:15]
	v_mfma_f32_16x16x32_bf16 v[4:7], v[164:167], v[204:207], v[4:7]
	v_mfma_f32_16x16x32_bf16 v[0:3], v[172:175], v[204:207], v[0:3]
	v_mfma_f32_16x16x32_bf16 v[52:55], v[168:171], v[184:187], v[52:55]
	v_mfma_f32_16x16x32_bf16 v[44:47], v[176:179], v[184:187], v[44:47]
	v_mfma_f32_16x16x32_bf16 v[36:39], v[168:171], v[192:195], v[36:39]
	v_mfma_f32_16x16x32_bf16 v[28:31], v[176:179], v[192:195], v[28:31]
	v_mfma_f32_16x16x32_bf16 v[20:23], v[168:171], v[200:203], v[20:23]
	v_mfma_f32_16x16x32_bf16 v[12:15], v[176:179], v[200:203], v[12:15]
	v_mfma_f32_16x16x32_bf16 v[4:7], v[168:171], v[208:211], v[4:7]
	v_mfma_f32_16x16x32_bf16 v[0:3], v[176:179], v[208:211], v[0:3]
	s_setprio 0
	s_barrier
	s_add_i32 s57, 0, 0x18000
	s_add_i32 s58, 0, 0x1c000
	v_add_u32_e32 v160, s57, v148
	v_add_u32_e32 v176, s58, v148
	ds_read_b128 v[144:147], v160
	ds_read_b128 v[152:155], v160 offset:1024
	ds_read_b128 v[156:159], v160 offset:2048
	ds_read_b128 v[160:163], v160 offset:3072
	ds_read_b128 v[164:167], v176
	ds_read_b128 v[168:171], v176 offset:1024
	ds_read_b128 v[172:175], v176 offset:2048
	ds_read_b128 v[176:179], v176 offset:3072
	s_add_u32 s30, s30, 0x40000
	s_addc_u32 s31, s31, 0
	s_mov_b32 m0, s42
	v_lshl_add_u64 v[220:221], s[30:31], 0, v[134:135]
	ds_read_b128 v[180:183], v151 offset:32768
	ds_read_b128 v[184:187], v151 offset:33792
	ds_read_b128 v[188:191], v151 offset:34816
	ds_read_b128 v[192:195], v151 offset:35840
	ds_read_b128 v[196:199], v151 offset:36864
	ds_read_b128 v[200:203], v151 offset:37888
	ds_read_b128 v[204:207], v151 offset:38912
	ds_read_b128 v[208:211], v151 offset:39936
	global_load_lds_dwordx4 v[220:221], off
	v_lshl_add_u64 v[220:221], s[30:31], 0, v[130:131]
	s_mov_b32 m0, s43
	s_nop 0
	global_load_lds_dwordx4 v[220:221], off
	v_lshl_add_u64 v[242:243], v[230:231], 0, s[12:13]
	s_add_u32 s28, s28, 0x40080
	v_lshl_add_u64 v[244:245], v[232:233], 0, s[12:13]
	s_addc_u32 s29, s29, 0
	v_lshl_add_u64 v[246:247], s[28:29], 0, v[132:133]
	v_lshl_add_u64 v[248:249], s[28:29], 0, v[128:129]
	v_lshl_add_u64 v[250:251], v[240:241], 0, s[12:13]
	v_lshl_add_u64 v[252:253], v[236:237], 0, s[12:13]
	s_waitcnt vmcnt(8)
	s_waitcnt lgkmcnt(0)
	s_barrier
	s_setprio 1
	s_waitcnt lgkmcnt(0)
	v_mfma_f32_16x16x32_bf16 v[124:127], v[144:147], v[180:183], v[124:127]
	v_mfma_f32_16x16x32_bf16 v[120:123], v[156:159], v[180:183], v[120:123]
	v_mfma_f32_16x16x32_bf16 v[112:115], v[144:147], v[188:191], v[112:115]
	v_mfma_f32_16x16x32_bf16 v[104:107], v[156:159], v[188:191], v[104:107]
	v_mfma_f32_16x16x32_bf16 v[96:99], v[144:147], v[196:199], v[96:99]
	v_mfma_f32_16x16x32_bf16 v[88:91], v[156:159], v[196:199], v[88:91]
	v_mfma_f32_16x16x32_bf16 v[80:83], v[144:147], v[204:207], v[80:83]
	v_mfma_f32_16x16x32_bf16 v[72:75], v[156:159], v[204:207], v[72:75]
	v_mfma_f32_16x16x32_bf16 v[124:127], v[152:155], v[184:187], v[124:127]
	v_mfma_f32_16x16x32_bf16 v[120:123], v[160:163], v[184:187], v[120:123]
	v_mfma_f32_16x16x32_bf16 v[112:115], v[152:155], v[192:195], v[112:115]
	v_mfma_f32_16x16x32_bf16 v[104:107], v[160:163], v[192:195], v[104:107]
	v_mfma_f32_16x16x32_bf16 v[96:99], v[152:155], v[200:203], v[96:99]
	v_mfma_f32_16x16x32_bf16 v[88:91], v[160:163], v[200:203], v[88:91]
	v_mfma_f32_16x16x32_bf16 v[80:83], v[152:155], v[208:211], v[80:83]
	v_mfma_f32_16x16x32_bf16 v[72:75], v[160:163], v[208:211], v[72:75]
	s_setprio 0
	s_setprio 1
	v_mfma_f32_16x16x32_bf16 v[116:119], v[164:167], v[180:183], v[116:119]
	v_mfma_f32_16x16x32_bf16 v[108:111], v[172:175], v[180:183], v[108:111]
	v_mfma_f32_16x16x32_bf16 v[100:103], v[164:167], v[188:191], v[100:103]
	v_mfma_f32_16x16x32_bf16 v[92:95], v[172:175], v[188:191], v[92:95]
	v_mfma_f32_16x16x32_bf16 v[84:87], v[164:167], v[196:199], v[84:87]
	v_mfma_f32_16x16x32_bf16 v[76:79], v[172:175], v[196:199], v[76:79]
	v_mfma_f32_16x16x32_bf16 v[68:71], v[164:167], v[204:207], v[68:71]
	v_mfma_f32_16x16x32_bf16 v[64:67], v[172:175], v[204:207], v[64:67]
	v_mfma_f32_16x16x32_bf16 v[116:119], v[168:171], v[184:187], v[116:119]
	v_mfma_f32_16x16x32_bf16 v[108:111], v[176:179], v[184:187], v[108:111]
	v_mfma_f32_16x16x32_bf16 v[100:103], v[168:171], v[192:195], v[100:103]
	v_mfma_f32_16x16x32_bf16 v[92:95], v[176:179], v[192:195], v[92:95]
	v_mfma_f32_16x16x32_bf16 v[84:87], v[168:171], v[200:203], v[84:87]
	v_mfma_f32_16x16x32_bf16 v[76:79], v[176:179], v[200:203], v[76:79]
	v_mfma_f32_16x16x32_bf16 v[68:71], v[168:171], v[208:211], v[68:71]
	v_mfma_f32_16x16x32_bf16 v[64:67], v[176:179], v[208:211], v[64:67]
	s_setprio 0
	s_barrier
; #define PG8_STAGE(bufoff, gbase, voff) do { _Pragma("unroll") for (int _i = 0; _i < 2; ++_i) \
;         __builtin_amdgcn_global_load_lds((const unsigned*)((const char*)(gbase) + (voff)[_i]), (PG8_LAS unsigned*)(lds + (bufoff) + ldsw + _i * 8192), 16, 0, 0); } while (0)
; #define PG8_LDA(dst, b, h) do { _Pragma("unroll") for (int m = 0; m < 4; ++m) _Pragma("unroll") for (int k = 0; k < 2; ++k) dst[m][k] = *(const PG8_LAS bf16x8*)(lds + PG8_SA(b, h) + aoff + m * 2048 + k * 1024); } while (0)
; #define PG8_MMA(ai, bj, At, Bt) do { __builtin_amdgcn_s_setprio(1); _Pragma("unroll") for (int m = 0; m < 4; ++m) _Pragma("unroll") for (int n = 0; n < 2; ++n) _Pragma("unroll") for (int k = 0; k < 2; ++k) \
;         acc[ai][bj][m][n] = __builtin_amdgcn_mfma_f32_16x16x32_bf16(Bt[n][k], At[m][k], acc[ai][bj][m][n], 0, 0, 0); __builtin_amdgcn_s_setprio(0); } while (0)
; #define PG8_WAIT_V(n) asm volatile("s_waitcnt vmcnt(" #n ")" ::: "memory")
; #define PG8_WAIT_L(n) asm volatile("s_waitcnt lgkmcnt(" #n ")" ::: "memory")
; #define PG8_BAR __builtin_amdgcn_s_barrier()
; #define PG8_SCHED __builtin_amdgcn_sched_barrier(0)
; template <class Epi, class Sched, bool ALIGN_EPI = false, bool SP2 = false>
; __device__ __forceinline__ void gemm_phase(PG8_LAS unsigned char* lds, const Gemm g, const Sched& S, const Epi& E, const int wave_s) {
;     ...
;             PG8_WAIT_V(8); PG8_WAIT_L(0); PG8_BAR; PG8_MMA(0, 0, At, B0); PG8_MMA(0, 1, At, B1); PG8_BAR; PG8_SCHED;
;             PG8_LDA(At, 1, 1); PG8_STAGE(PG8_SB(1, 0), b3, voffB); PG8_STAGE(PG8_SB(1, 1), b3 + hstep, voffB); PG8_STAGE(PG8_SA(1, 0), a3, voffA);
;             PG8_WAIT_V(8); PG8_WAIT_L(0); PG8_BAR; PG8_MMA(1, 0, At, B0); PG8_MMA(1, 1, At, B1); PG8_BAR; PG8_SCHED;
;     __device__ __forceinline__ void operator()(const af4 (&acc)[2][2][4][2], const pg8::Unit& u, int wr, int wc, int fr_, int fq_) const {
;     ...
;         } else if (wc == 0) {
; #pragma unroll
;             for (int ai = 0; ai < 2; ++ai)
; #pragma unroll
;                 for (int m = 0; m < 4; ++m) { const af4 v0 = acc[ai][0][m][0], v1 = acc[ai][0][m][1]; v4u w; w.x = cvtpk(v0[0], v0[1]); w.y = cvtpk(v0[2], v0[3]); w.z = cvtpk(v1[0], v1[1]); w.w = cvtpk(v1[2], v1[3]);
;                     *(v4u*)(Z + (size_t)(row0 + ai * 128 + m * 16) * 32 + 8 * fq) = w; }
	s_add_i32 s30, s57, s33
	s_mov_b32 m0, s30
	ds_read_b128 v[180:183], v151 offset:49152
	ds_read_b128 v[184:187], v151 offset:50176
	ds_read_b128 v[188:191], v151 offset:51200
	ds_read_b128 v[192:195], v151 offset:52224
	ds_read_b128 v[196:199], v151 offset:53248
	ds_read_b128 v[200:203], v151 offset:54272
	ds_read_b128 v[204:207], v151 offset:55296
	ds_read_b128 v[208:211], v151 offset:56320
	global_load_lds_dwordx4 v[242:243], off
	s_add_i32 m0, s30, 0x2000
	s_add_i32 s30, s58, s33
	global_load_lds_dwordx4 v[244:245], off
	s_mov_b32 m0, s30
	s_nop 0
	global_load_lds_dwordx4 v[246:247], off
	s_add_i32 m0, s30, 0x2000
	s_nop 0
	global_load_lds_dwordx4 v[248:249], off
	s_mov_b32 m0, s46
	s_nop 0
	global_load_lds_dwordx4 v[250:251], off
	s_mov_b32 m0, s47
	s_nop 0
	global_load_lds_dwordx4 v[252:253], off
	s_waitcnt vmcnt(8)
	s_waitcnt lgkmcnt(0)
	s_barrier
	s_setprio 1
	s_waitcnt lgkmcnt(0)
	v_mfma_f32_16x16x32_bf16 v[60:63], v[144:147], v[180:183], v[60:63]
	v_mfma_f32_16x16x32_bf16 v[56:59], v[156:159], v[180:183], v[56:59]
	v_mfma_f32_16x16x32_bf16 v[48:51], v[144:147], v[188:191], v[48:51]
	v_mfma_f32_16x16x32_bf16 v[40:43], v[156:159], v[188:191], v[40:43]
	v_mfma_f32_16x16x32_bf16 v[32:35], v[144:147], v[196:199], v[32:35]
	v_mfma_f32_16x16x32_bf16 v[24:27], v[156:159], v[196:199], v[24:27]
	v_mfma_f32_16x16x32_bf16 v[16:19], v[144:147], v[204:207], v[16:19]
	v_mfma_f32_16x16x32_bf16 v[8:11], v[156:159], v[204:207], v[8:11]
	v_mfma_f32_16x16x32_bf16 v[60:63], v[152:155], v[184:187], v[60:63]
	v_mfma_f32_16x16x32_bf16 v[56:59], v[160:163], v[184:187], v[56:59]
	v_mfma_f32_16x16x32_bf16 v[48:51], v[152:155], v[192:195], v[48:51]
	v_mfma_f32_16x16x32_bf16 v[40:43], v[160:163], v[192:195], v[40:43]
	v_mfma_f32_16x16x32_bf16 v[32:35], v[152:155], v[200:203], v[32:35]
	v_mfma_f32_16x16x32_bf16 v[24:27], v[160:163], v[200:203], v[24:27]
	v_mfma_f32_16x16x32_bf16 v[16:19], v[152:155], v[208:211], v[16:19]
	v_mfma_f32_16x16x32_bf16 v[8:11], v[160:163], v[208:211], v[8:11]
	s_setprio 0
	s_setprio 1
	v_mfma_f32_16x16x32_bf16 v[52:55], v[164:167], v[180:183], v[52:55]
	v_mfma_f32_16x16x32_bf16 v[44:47], v[172:175], v[180:183], v[44:47]
	v_mfma_f32_16x16x32_bf16 v[36:39], v[164:167], v[188:191], v[36:39]
	v_mfma_f32_16x16x32_bf16 v[28:31], v[172:175], v[188:191], v[28:31]
	v_mfma_f32_16x16x32_bf16 v[20:23], v[164:167], v[196:199], v[20:23]
	v_mfma_f32_16x16x32_bf16 v[12:15], v[172:175], v[196:199], v[12:15]
	v_mfma_f32_16x16x32_bf16 v[4:7], v[164:167], v[204:207], v[4:7]
	v_mfma_f32_16x16x32_bf16 v[0:3], v[172:175], v[204:207], v[0:3]
	v_mfma_f32_16x16x32_bf16 v[52:55], v[168:171], v[184:187], v[52:55]
	v_mfma_f32_16x16x32_bf16 v[44:47], v[176:179], v[184:187], v[44:47]
	v_mfma_f32_16x16x32_bf16 v[36:39], v[168:171], v[192:195], v[36:39]
	v_mfma_f32_16x16x32_bf16 v[28:31], v[176:179], v[192:195], v[28:31]
	v_mfma_f32_16x16x32_bf16 v[20:23], v[168:171], v[200:203], v[20:23]
	v_mfma_f32_16x16x32_bf16 v[12:15], v[176:179], v[200:203], v[12:15]
	v_mfma_f32_16x16x32_bf16 v[4:7], v[168:171], v[208:211], v[4:7]
	v_mfma_f32_16x16x32_bf16 v[0:3], v[176:179], v[208:211], v[0:3]
	s_setprio 0
	s_barrier
	s_add_i32 s56, s56, 2
	s_add_u32 s54, s54, 0x100
	s_addc_u32 s55, s55, 0
	s_add_u32 s26, s26, 0x100
	s_addc_u32 s27, s27, 0
	s_cmp_gt_u32 s56, 13
	s_cbranch_scc0 .LBB0_182
	s_lshl_b32 s17, s24, 8
	v_mbcnt_lo_u32_b32 v144, -1, 0
	v_mbcnt_hi_u32_b32 v144, -1, v144
	s_add_i32 s17, s17, s87
	v_ashrrev_i32_e32 v146, 4, v144
	v_and_or_b32 v144, v144, 15, s17
	s_cmp_gt_i32 s52, 7
	s_mov_b64 s[24:25], -1
	s_cbranch_scc0 .LBB0_187
	s_andn2_b64 vcc, exec, s[14:15]
	s_cbranch_vccnz .LBB0_186
	v_lshlrev_b32_e32 v156, 3, v146
	v_ashrrev_i32_e32 v145, 31, v144
	v_or_b32_e32 v160, 16, v144
	v_ashrrev_i32_e32 v157, 31, v156
	v_lshlrev_b64 v[158:159], 6, v[144:145]
	v_ashrrev_i32_e32 v161, 31, v160
	v_lshl_add_u64 v[158:159], s[10:11], 0, v[158:159]
	v_lshlrev_b64 v[156:157], 1, v[156:157]
	v_lshlrev_b64 v[160:161], 6, v[160:161]
	v_cvt_pk_bf16_f32 v152, v124, v125
	v_cvt_pk_bf16_f32 v153, v126, v127
	v_cvt_pk_bf16_f32 v154, v120, v121
	v_cvt_pk_bf16_f32 v155, v122, v123
	v_lshl_add_u64 v[158:159], v[158:159], 0, v[156:157]
	v_lshl_add_u64 v[160:161], s[10:11], 0, v[160:161]
	global_store_dwordx4 v[158:159], v[152:155], off
	v_lshl_add_u64 v[160:161], v[160:161], 0, v[156:157]
	s_nop 0
	v_cvt_pk_bf16_f32 v152, v112, v113
	v_cvt_pk_bf16_f32 v153, v114, v115
	v_cvt_pk_bf16_f32 v154, v104, v105
	v_cvt_pk_bf16_f32 v155, v106, v107
	global_store_dwordx4 v[160:161], v[152:155], off
	v_or_b32_e32 v160, 32, v144
	v_ashrrev_i32_e32 v161, 31, v160
	v_lshlrev_b64 v[160:161], 6, v[160:161]
	v_lshl_add_u64 v[160:161], s[10:11], 0, v[160:161]
	v_cvt_pk_bf16_f32 v152, v96, v97
	v_cvt_pk_bf16_f32 v153, v98, v99
	v_cvt_pk_bf16_f32 v154, v88, v89
	v_cvt_pk_bf16_f32 v155, v90, v91
	v_lshl_add_u64 v[160:161], v[160:161], 0, v[156:157]
	global_store_dwordx4 v[160:161], v[152:155], off
	v_or_b32_e32 v160, 48, v144
	v_ashrrev_i32_e32 v161, 31, v160
	v_lshlrev_b64 v[160:161], 6, v[160:161]
	v_lshl_add_u64 v[160:161], s[10:11], 0, v[160:161]
	v_cvt_pk_bf16_f32 v152, v80, v81
	v_cvt_pk_bf16_f32 v153, v82, v83
	v_cvt_pk_bf16_f32 v154, v72, v73
	v_cvt_pk_bf16_f32 v155, v74, v75
	v_lshl_add_u64 v[156:157], v[160:161], 0, v[156:157]
	global_store_dwordx4 v[156:157], v[152:155], off
	v_add_co_u32_e32 v156, vcc, s44, v158
	s_nop 0
	v_cvt_pk_bf16_f32 v152, v60, v61
	v_cvt_pk_bf16_f32 v153, v62, v63
	v_cvt_pk_bf16_f32 v154, v56, v57
	v_cvt_pk_bf16_f32 v155, v58, v59
	v_addc_co_u32_e32 v157, vcc, 0, v159, vcc
	global_store_dwordx4 v[156:157], v[152:155], off
	s_nop 1
	v_cvt_pk_bf16_f32 v152, v48, v49
	v_cvt_pk_bf16_f32 v153, v50, v51
	v_cvt_pk_bf16_f32 v154, v40, v41
	v_cvt_pk_bf16_f32 v155, v42, v43
	global_store_dwordx4 v[156:157], v[152:155], off offset:1024
	s_nop 1
	v_cvt_pk_bf16_f32 v152, v32, v33
	v_cvt_pk_bf16_f32 v153, v34, v35
	v_cvt_pk_bf16_f32 v154, v24, v25
	v_cvt_pk_bf16_f32 v155, v26, v27
	global_store_dwordx4 v[156:157], v[152:155], off offset:2048
	s_nop 1
	v_cvt_pk_bf16_f32 v152, v16, v17
	v_cvt_pk_bf16_f32 v153, v18, v19
	v_cvt_pk_bf16_f32 v154, v8, v9
	v_cvt_pk_bf16_f32 v155, v10, v11
	global_store_dwordx4 v[156:157], v[152:155], off offset:3072

; #define PG8_STAGE(bufoff, gbase, voff) do { _Pragma("unroll") for (int _i = 0; _i < 2; ++_i) \
;         __builtin_amdgcn_global_load_lds((const unsigned*)((const char*)(gbase) + (voff)[_i]), (PG8_LAS unsigned*)(lds + (bufoff) + ldsw + _i * 8192), 16, 0, 0); } while (0)
; #define PG8_LDA(dst, b, h) do { _Pragma("unroll") for (int m = 0; m < 4; ++m) _Pragma("unroll") for (int k = 0; k < 2; ++k) dst[m][k] = *(const PG8_LAS bf16x8*)(lds + PG8_SA(b, h) + aoff + m * 2048 + k * 1024); } while (0)
; #define PG8_LDB(dst, b, h) do { _Pragma("unroll") for (int n = 0; n < 2; ++n) _Pragma("unroll") for (int k = 0; k < 2; ++k) dst[n][k] = *(const PG8_LAS bf16x8*)(lds + PG8_SB(b, h) + boff + n * 2048 + k * 1024); } while (0)
; #define PG8_MMA(ai, bj, At, Bt) do { __builtin_amdgcn_s_setprio(1); _Pragma("unroll") for (int m = 0; m < 4; ++m) _Pragma("unroll") for (int n = 0; n < 2; ++n) _Pragma("unroll") for (int k = 0; k < 2; ++k) \
;         acc[ai][bj][m][n] = __builtin_amdgcn_mfma_f32_16x16x32_bf16(Bt[n][k], At[m][k], acc[ai][bj][m][n], 0, 0, 0); __builtin_amdgcn_s_setprio(0); } while (0)
; #define PG8_WAIT_V(n) asm volatile("s_waitcnt vmcnt(" #n ")" ::: "memory")
; #define PG8_WAIT_L(n) asm volatile("s_waitcnt lgkmcnt(" #n ")" ::: "memory")
; #define PG8_BAR __builtin_amdgcn_s_barrier()
; #define PG8_SCHED __builtin_amdgcn_sched_barrier(0)
; template <class Epi, class Sched, bool ALIGN_EPI = false, bool SP2 = false>
; __device__ __forceinline__ void gemm_phase(PG8_LAS unsigned char* lds, const Gemm g, const Sched& S, const Epi& E, const int wave_s) {
;     ...
;             const bool last = (t == nt - 2);
;             const char* a1 = cA + (size_t)(t + 1) * kstep;
;             const char* a2 = last ? nA : cA + (size_t)(t + 2) * kstep; const char* b2 = last ? nB : cB + (size_t)(t + 2) * kstep;
;             const char* a3 = a2 + kstep; const char* b3 = b2 + kstep;
;             if (last && has_next) S.a_ready(nxt);
;             if constexpr (SP2) {
;             PG8_LDB(B0, 0, 0); PG8_LDB(B1, 0, 1); PG8_SCHED; PG8_LDA(At, 0, 0); PG8_STAGE(PG8_SA(1, 1), a1 + hstep, voffA);
;             PG8_WAIT_V(8); PG8_WAIT_L(0); PG8_BAR; PG8_MMA(0, 0, At, B0); PG8_MMA(0, 1, At, B1); PG8_BAR; PG8_SCHED;
;             PG8_LDA(At, 0, 1); PG8_STAGE(PG8_SB(0, 0), b2, voffB); PG8_STAGE(PG8_SB(0, 1), b2 + hstep, voffB); PG8_STAGE(PG8_SA(0, 0), a2, voffA);
.LBB0_483:
	ds_read_b128 v[128:131], v155
	ds_read_b128 v[132:135], v155 offset:1024
	ds_read_b128 v[158:161], v155 offset:2048
	ds_read_b128 v[162:165], v155 offset:3072
	ds_read_b128 v[166:169], v156
	ds_read_b128 v[170:173], v156 offset:1024
	ds_read_b128 v[174:177], v156 offset:2048
	ds_read_b128 v[178:181], v156 offset:3072
	s_add_u32 s20, s18, 0xfffe0080
	s_addc_u32 s21, s19, -1
	s_cmp_eq_u32 s48, 4
	s_cselect_b32 s23, s11, s21
	s_cselect_b32 s22, s44, s20
	s_cselect_b32 s21, s9, s47
	s_cselect_b32 s20, s45, s46
	v_lshl_add_u64 v[152:153], s[18:19], 0, v[146:147]
	s_add_i32 m0, s17, 0xc000
	ds_read_b128 v[182:185], v157
	ds_read_b128 v[186:189], v157 offset:1024
	ds_read_b128 v[190:193], v157 offset:2048
	ds_read_b128 v[194:197], v157 offset:3072
	ds_read_b128 v[198:201], v157 offset:4096
	ds_read_b128 v[202:205], v157 offset:5120
	ds_read_b128 v[206:209], v157 offset:6144
	ds_read_b128 v[210:213], v157 offset:7168
	global_load_lds_dwordx4 v[152:153], off
	v_lshl_add_u64 v[152:153], s[18:19], 0, v[144:145]
	s_add_i32 m0, s17, 0xe000
	s_nop 0
	global_load_lds_dwordx4 v[152:153], off
	v_lshl_add_u64 v[230:231], s[20:21], 0, v[140:141]
	s_add_u32 s50, s20, 0x20000
	v_lshl_add_u64 v[232:233], s[20:21], 0, v[136:137]
	s_addc_u32 s51, s21, 0
	v_lshl_add_u64 v[234:235], s[50:51], 0, v[140:141]
	v_lshl_add_u64 v[236:237], s[22:23], 0, v[138:139]
	v_lshl_add_u64 v[238:239], s[50:51], 0, v[136:137]
	v_lshl_add_u64 v[240:241], s[22:23], 0, v[142:143]
	s_waitcnt vmcnt(8)
	s_waitcnt lgkmcnt(0)
	s_barrier
	s_setprio 1
	s_waitcnt lgkmcnt(0)
	v_mfma_f32_16x16x32_bf16 v[124:127], v[128:131], v[182:185], v[124:127]
	v_mfma_f32_16x16x32_bf16 v[120:123], v[158:161], v[182:185], v[120:123]
	v_mfma_f32_16x16x32_bf16 v[108:111], v[128:131], v[190:193], v[108:111]
	v_mfma_f32_16x16x32_bf16 v[104:107], v[158:161], v[190:193], v[104:107]
	v_mfma_f32_16x16x32_bf16 v[92:95], v[128:131], v[198:201], v[92:95]
	v_mfma_f32_16x16x32_bf16 v[88:91], v[158:161], v[198:201], v[88:91]
	v_mfma_f32_16x16x32_bf16 v[80:83], v[128:131], v[206:209], v[80:83]
	v_mfma_f32_16x16x32_bf16 v[72:75], v[158:161], v[206:209], v[72:75]
	v_mfma_f32_16x16x32_bf16 v[124:127], v[132:135], v[186:189], v[124:127]
	v_mfma_f32_16x16x32_bf16 v[120:123], v[162:165], v[186:189], v[120:123]
	v_mfma_f32_16x16x32_bf16 v[108:111], v[132:135], v[194:197], v[108:111]
	v_mfma_f32_16x16x32_bf16 v[104:107], v[162:165], v[194:197], v[104:107]
	v_mfma_f32_16x16x32_bf16 v[92:95], v[132:135], v[202:205], v[92:95]
	v_mfma_f32_16x16x32_bf16 v[88:91], v[162:165], v[202:205], v[88:91]
	v_mfma_f32_16x16x32_bf16 v[80:83], v[132:135], v[210:213], v[80:83]
	v_mfma_f32_16x16x32_bf16 v[72:75], v[162:165], v[210:213], v[72:75]
	s_setprio 0
	s_setprio 1
	v_mfma_f32_16x16x32_bf16 v[116:119], v[166:169], v[182:185], v[116:119]
	v_mfma_f32_16x16x32_bf16 v[112:115], v[174:177], v[182:185], v[112:115]
	v_mfma_f32_16x16x32_bf16 v[100:103], v[166:169], v[190:193], v[100:103]
	v_mfma_f32_16x16x32_bf16 v[96:99], v[174:177], v[190:193], v[96:99]
	v_mfma_f32_16x16x32_bf16 v[84:87], v[166:169], v[198:201], v[84:87]
	v_mfma_f32_16x16x32_bf16 v[76:79], v[174:177], v[198:201], v[76:79]
	v_mfma_f32_16x16x32_bf16 v[68:71], v[166:169], v[206:209], v[68:71]
	v_mfma_f32_16x16x32_bf16 v[64:67], v[174:177], v[206:209], v[64:67]
	v_mfma_f32_16x16x32_bf16 v[116:119], v[170:173], v[186:189], v[116:119]
	v_mfma_f32_16x16x32_bf16 v[112:115], v[178:181], v[186:189], v[112:115]
	v_mfma_f32_16x16x32_bf16 v[100:103], v[170:173], v[194:197], v[100:103]
	v_mfma_f32_16x16x32_bf16 v[96:99], v[178:181], v[194:197], v[96:99]
	v_mfma_f32_16x16x32_bf16 v[84:87], v[170:173], v[202:205], v[84:87]
	v_mfma_f32_16x16x32_bf16 v[76:79], v[178:181], v[202:205], v[76:79]
	v_mfma_f32_16x16x32_bf16 v[68:71], v[170:173], v[210:213], v[68:71]
	v_mfma_f32_16x16x32_bf16 v[64:67], v[178:181], v[210:213], v[64:67]
	s_setprio 0
	s_barrier
	s_add_i32 s49, s41, s33
	s_mov_b32 m0, s49
	ds_read_b128 v[182:185], v157 offset:16384
	ds_read_b128 v[186:189], v157 offset:17408
	ds_read_b128 v[190:193], v157 offset:18432
	ds_read_b128 v[194:197], v157 offset:19456
	ds_read_b128 v[198:201], v157 offset:20480
	ds_read_b128 v[202:205], v157 offset:21504
	ds_read_b128 v[206:209], v157 offset:22528
	ds_read_b128 v[210:213], v157 offset:23552
	global_load_lds_dwordx4 v[230:231], off
	s_add_i32 m0, s49, 0x2000
	s_add_i32 s49, s42, s33
	global_load_lds_dwordx4 v[232:233], off
	s_mov_b32 m0, s49
	s_nop 0
	global_load_lds_dwordx4 v[234:235], off
	s_add_i32 m0, s49, 0x2000
	s_nop 0
	global_load_lds_dwordx4 v[238:239], off
	s_mov_b32 m0, s17
	s_nop 0
	global_load_lds_dwordx4 v[240:241], off
	s_mov_b32 m0, s30
	s_nop 0
	global_load_lds_dwordx4 v[236:237], off
	s_waitcnt vmcnt(8)
	s_waitcnt lgkmcnt(0)
	s_barrier
; #define PG8_STAGE(bufoff, gbase, voff) do { _Pragma("unroll") for (int _i = 0; _i < 2; ++_i) \
;         __builtin_amdgcn_global_load_lds((const unsigned*)((const char*)(gbase) + (voff)[_i]), (PG8_LAS unsigned*)(lds + (bufoff) + ldsw + _i * 8192), 16, 0, 0); } while (0)
; #define PG8_LDA(dst, b, h) do { _Pragma("unroll") for (int m = 0; m < 4; ++m) _Pragma("unroll") for (int k = 0; k < 2; ++k) dst[m][k] = *(const PG8_LAS bf16x8*)(lds + PG8_SA(b, h) + aoff + m * 2048 + k * 1024); } while (0)
; #define PG8_LDB(dst, b, h) do { _Pragma("unroll") for (int n = 0; n < 2; ++n) _Pragma("unroll") for (int k = 0; k < 2; ++k) dst[n][k] = *(const PG8_LAS bf16x8*)(lds + PG8_SB(b, h) + boff + n * 2048 + k * 1024); } while (0)
; #define PG8_MMA(ai, bj, At, Bt) do { __builtin_amdgcn_s_setprio(1); _Pragma("unroll") for (int m = 0; m < 4; ++m) _Pragma("unroll") for (int n = 0; n < 2; ++n) _Pragma("unroll") for (int k = 0; k < 2; ++k) \
;         acc[ai][bj][m][n] = __builtin_amdgcn_mfma_f32_16x16x32_bf16(Bt[n][k], At[m][k], acc[ai][bj][m][n], 0, 0, 0); __builtin_amdgcn_s_setprio(0); } while (0)
; #define PG8_WAIT_V(n) asm volatile("s_waitcnt vmcnt(" #n ")" ::: "memory")
; #define PG8_WAIT_L(n) asm volatile("s_waitcnt lgkmcnt(" #n ")" ::: "memory")
; #define PG8_BAR __builtin_amdgcn_s_barrier()
; #define PG8_SCHED __builtin_amdgcn_sched_barrier(0)
; template <class Epi, class Sched, bool ALIGN_EPI = false, bool SP2 = false>
; __device__ __forceinline__ void gemm_phase(PG8_LAS unsigned char* lds, const Gemm g, const Sched& S, const Epi& E, const int wave_s) {
;     ...
;             PG8_WAIT_V(8); PG8_WAIT_L(0); PG8_BAR; PG8_MMA(0, 0, At, B0); PG8_MMA(0, 1, At, B1); PG8_BAR; PG8_SCHED;
;             PG8_LDA(At, 0, 1); PG8_STAGE(PG8_SB(0, 0), b2, voffB); PG8_STAGE(PG8_SB(0, 1), b2 + hstep, voffB); PG8_STAGE(PG8_SA(0, 0), a2, voffA);
;             PG8_WAIT_V(8); PG8_WAIT_L(0); PG8_BAR; PG8_MMA(1, 0, At, B0); PG8_MMA(1, 1, At, B1); PG8_BAR; PG8_SCHED;
;             PG8_LDB(B0, 1, 0); PG8_LDB(B1, 1, 1); PG8_SCHED; PG8_LDA(At, 1, 0); PG8_STAGE(PG8_SA(0, 1), a2 + hstep, voffA);
;             PG8_WAIT_V(8); PG8_WAIT_L(0); PG8_BAR; PG8_MMA(0, 0, At, B0); PG8_MMA(0, 1, At, B1); PG8_BAR; PG8_SCHED;
	s_setprio 1
	s_waitcnt lgkmcnt(0)
	v_mfma_f32_16x16x32_bf16 v[60:63], v[128:131], v[182:185], v[60:63]
	v_mfma_f32_16x16x32_bf16 v[56:59], v[158:161], v[182:185], v[56:59]
	v_mfma_f32_16x16x32_bf16 v[48:51], v[128:131], v[190:193], v[48:51]
	v_mfma_f32_16x16x32_bf16 v[40:43], v[158:161], v[190:193], v[40:43]
	v_mfma_f32_16x16x32_bf16 v[32:35], v[128:131], v[198:201], v[32:35]
	v_mfma_f32_16x16x32_bf16 v[24:27], v[158:161], v[198:201], v[24:27]
	v_mfma_f32_16x16x32_bf16 v[16:19], v[128:131], v[206:209], v[16:19]
	v_mfma_f32_16x16x32_bf16 v[8:11], v[158:161], v[206:209], v[8:11]
	v_mfma_f32_16x16x32_bf16 v[60:63], v[132:135], v[186:189], v[60:63]
	v_mfma_f32_16x16x32_bf16 v[56:59], v[162:165], v[186:189], v[56:59]
	v_mfma_f32_16x16x32_bf16 v[48:51], v[132:135], v[194:197], v[48:51]
	v_mfma_f32_16x16x32_bf16 v[40:43], v[162:165], v[194:197], v[40:43]
	v_mfma_f32_16x16x32_bf16 v[32:35], v[132:135], v[202:205], v[32:35]
	v_mfma_f32_16x16x32_bf16 v[24:27], v[162:165], v[202:205], v[24:27]
	v_mfma_f32_16x16x32_bf16 v[16:19], v[132:135], v[210:213], v[16:19]
	v_mfma_f32_16x16x32_bf16 v[8:11], v[162:165], v[210:213], v[8:11]
	s_setprio 0
	s_setprio 1
	v_mfma_f32_16x16x32_bf16 v[52:55], v[166:169], v[182:185], v[52:55]
	v_mfma_f32_16x16x32_bf16 v[44:47], v[174:177], v[182:185], v[44:47]
	v_mfma_f32_16x16x32_bf16 v[36:39], v[166:169], v[190:193], v[36:39]
	v_mfma_f32_16x16x32_bf16 v[28:31], v[174:177], v[190:193], v[28:31]
	v_mfma_f32_16x16x32_bf16 v[20:23], v[166:169], v[198:201], v[20:23]
	v_mfma_f32_16x16x32_bf16 v[12:15], v[174:177], v[198:201], v[12:15]
	v_mfma_f32_16x16x32_bf16 v[4:7], v[166:169], v[206:209], v[4:7]
	v_mfma_f32_16x16x32_bf16 v[0:3], v[174:177], v[206:209], v[0:3]
	v_mfma_f32_16x16x32_bf16 v[52:55], v[170:173], v[186:189], v[52:55]
	v_mfma_f32_16x16x32_bf16 v[44:47], v[178:181], v[186:189], v[44:47]
	v_mfma_f32_16x16x32_bf16 v[36:39], v[170:173], v[194:197], v[36:39]
	v_mfma_f32_16x16x32_bf16 v[28:31], v[178:181], v[194:197], v[28:31]
	v_mfma_f32_16x16x32_bf16 v[20:23], v[170:173], v[202:205], v[20:23]
	v_mfma_f32_16x16x32_bf16 v[12:15], v[178:181], v[202:205], v[12:15]
	v_mfma_f32_16x16x32_bf16 v[4:7], v[170:173], v[210:213], v[4:7]
	v_mfma_f32_16x16x32_bf16 v[0:3], v[178:181], v[210:213], v[0:3]
	s_setprio 0
	s_barrier
	s_add_i32 s49, 0, 0x18000
	s_add_i32 s50, 0, 0x1c000
	v_add_u32_e32 v162, s49, v154
	v_add_u32_e32 v178, s50, v154
	ds_read_b128 v[128:131], v162
	ds_read_b128 v[132:135], v162 offset:1024
	ds_read_b128 v[158:161], v162 offset:2048
	ds_read_b128 v[162:165], v162 offset:3072
	ds_read_b128 v[166:169], v178
	ds_read_b128 v[170:173], v178 offset:1024
	ds_read_b128 v[174:177], v178 offset:2048
	ds_read_b128 v[178:181], v178 offset:3072
	s_add_u32 s22, s22, 0x20000
	s_addc_u32 s23, s23, 0
	s_mov_b32 m0, s31
	v_lshl_add_u64 v[220:221], s[22:23], 0, v[142:143]
	ds_read_b128 v[182:185], v157 offset:32768
	ds_read_b128 v[186:189], v157 offset:33792
	ds_read_b128 v[190:193], v157 offset:34816
	ds_read_b128 v[194:197], v157 offset:35840
	ds_read_b128 v[198:201], v157 offset:36864
	ds_read_b128 v[202:205], v157 offset:37888
	ds_read_b128 v[206:209], v157 offset:38912
	ds_read_b128 v[210:213], v157 offset:39936
	global_load_lds_dwordx4 v[220:221], off
	v_lshl_add_u64 v[220:221], s[22:23], 0, v[138:139]
	s_mov_b32 m0, s34
	s_nop 0
	global_load_lds_dwordx4 v[220:221], off
	v_lshl_add_u64 v[242:243], v[230:231], 0, s[6:7]
	s_add_u32 s20, s20, 0x20080
	v_lshl_add_u64 v[244:245], v[232:233], 0, s[6:7]
	s_addc_u32 s21, s21, 0
	v_lshl_add_u64 v[246:247], s[20:21], 0, v[140:141]
	v_lshl_add_u64 v[248:249], s[20:21], 0, v[136:137]
	v_lshl_add_u64 v[250:251], v[240:241], 0, s[6:7]
	v_lshl_add_u64 v[252:253], v[236:237], 0, s[6:7]
	s_waitcnt vmcnt(8)
	s_waitcnt lgkmcnt(0)
	s_barrier
	s_setprio 1
	s_waitcnt lgkmcnt(0)
	v_mfma_f32_16x16x32_bf16 v[124:127], v[128:131], v[182:185], v[124:127]
	v_mfma_f32_16x16x32_bf16 v[120:123], v[158:161], v[182:185], v[120:123]
	v_mfma_f32_16x16x32_bf16 v[108:111], v[128:131], v[190:193], v[108:111]
	v_mfma_f32_16x16x32_bf16 v[104:107], v[158:161], v[190:193], v[104:107]
	v_mfma_f32_16x16x32_bf16 v[92:95], v[128:131], v[198:201], v[92:95]
	v_mfma_f32_16x16x32_bf16 v[88:91], v[158:161], v[198:201], v[88:91]
	v_mfma_f32_16x16x32_bf16 v[80:83], v[128:131], v[206:209], v[80:83]
	v_mfma_f32_16x16x32_bf16 v[72:75], v[158:161], v[206:209], v[72:75]
	v_mfma_f32_16x16x32_bf16 v[124:127], v[132:135], v[186:189], v[124:127]
	v_mfma_f32_16x16x32_bf16 v[120:123], v[162:165], v[186:189], v[120:123]
	v_mfma_f32_16x16x32_bf16 v[108:111], v[132:135], v[194:197], v[108:111]
	v_mfma_f32_16x16x32_bf16 v[104:107], v[162:165], v[194:197], v[104:107]
	v_mfma_f32_16x16x32_bf16 v[92:95], v[132:135], v[202:205], v[92:95]
	v_mfma_f32_16x16x32_bf16 v[88:91], v[162:165], v[202:205], v[88:91]
	v_mfma_f32_16x16x32_bf16 v[80:83], v[132:135], v[210:213], v[80:83]
	v_mfma_f32_16x16x32_bf16 v[72:75], v[162:165], v[210:213], v[72:75]
	s_setprio 0
	s_setprio 1
	v_mfma_f32_16x16x32_bf16 v[116:119], v[166:169], v[182:185], v[116:119]
	v_mfma_f32_16x16x32_bf16 v[112:115], v[174:177], v[182:185], v[112:115]
	v_mfma_f32_16x16x32_bf16 v[100:103], v[166:169], v[190:193], v[100:103]
	v_mfma_f32_16x16x32_bf16 v[96:99], v[174:177], v[190:193], v[96:99]
	v_mfma_f32_16x16x32_bf16 v[84:87], v[166:169], v[198:201], v[84:87]
	v_mfma_f32_16x16x32_bf16 v[76:79], v[174:177], v[198:201], v[76:79]
	v_mfma_f32_16x16x32_bf16 v[68:71], v[166:169], v[206:209], v[68:71]
	v_mfma_f32_16x16x32_bf16 v[64:67], v[174:177], v[206:209], v[64:67]
	v_mfma_f32_16x16x32_bf16 v[116:119], v[170:173], v[186:189], v[116:119]
	v_mfma_f32_16x16x32_bf16 v[112:115], v[178:181], v[186:189], v[112:115]
	v_mfma_f32_16x16x32_bf16 v[100:103], v[170:173], v[194:197], v[100:103]
	v_mfma_f32_16x16x32_bf16 v[96:99], v[178:181], v[194:197], v[96:99]
	v_mfma_f32_16x16x32_bf16 v[84:87], v[170:173], v[202:205], v[84:87]
	v_mfma_f32_16x16x32_bf16 v[76:79], v[178:181], v[202:205], v[76:79]
	v_mfma_f32_16x16x32_bf16 v[68:71], v[170:173], v[210:213], v[68:71]
	v_mfma_f32_16x16x32_bf16 v[64:67], v[178:181], v[210:213], v[64:67]
	s_setprio 0
	s_barrier
; #define PG8_STAGE(bufoff, gbase, voff) do { _Pragma("unroll") for (int _i = 0; _i < 2; ++_i) \
;         __builtin_amdgcn_global_load_lds((const unsigned*)((const char*)(gbase) + (voff)[_i]), (PG8_LAS unsigned*)(lds + (bufoff) + ldsw + _i * 8192), 16, 0, 0); } while (0)
; #define PG8_LDA(dst, b, h) do { _Pragma("unroll") for (int m = 0; m < 4; ++m) _Pragma("unroll") for (int k = 0; k < 2; ++k) dst[m][k] = *(const PG8_LAS bf16x8*)(lds + PG8_SA(b, h) + aoff + m * 2048 + k * 1024); } while (0)
; #define PG8_MMA(ai, bj, At, Bt) do { __builtin_amdgcn_s_setprio(1); _Pragma("unroll") for (int m = 0; m < 4; ++m) _Pragma("unroll") for (int n = 0; n < 2; ++n) _Pragma("unroll") for (int k = 0; k < 2; ++k) \
;         acc[ai][bj][m][n] = __builtin_amdgcn_mfma_f32_16x16x32_bf16(Bt[n][k], At[m][k], acc[ai][bj][m][n], 0, 0, 0); __builtin_amdgcn_s_setprio(0); } while (0)
; #define PG8_WAIT_V(n) asm volatile("s_waitcnt vmcnt(" #n ")" ::: "memory")
; #define PG8_WAIT_L(n) asm volatile("s_waitcnt lgkmcnt(" #n ")" ::: "memory")
; #define PG8_BAR __builtin_amdgcn_s_barrier()
; #define PG8_SCHED __builtin_amdgcn_sched_barrier(0)
; template <class Epi, class Sched, bool ALIGN_EPI = false, bool SP2 = false>
; __device__ __forceinline__ void gemm_phase(PG8_LAS unsigned char* lds, const Gemm g, const Sched& S, const Epi& E, const int wave_s) {
;     ...
;             PG8_WAIT_V(8); PG8_WAIT_L(0); PG8_BAR; PG8_MMA(0, 0, At, B0); PG8_MMA(0, 1, At, B1); PG8_BAR; PG8_SCHED;
;             PG8_LDA(At, 1, 1); PG8_STAGE(PG8_SB(1, 0), b3, voffB); PG8_STAGE(PG8_SB(1, 1), b3 + hstep, voffB); PG8_STAGE(PG8_SA(1, 0), a3, voffA);
;             PG8_WAIT_V(8); PG8_WAIT_L(0); PG8_BAR; PG8_MMA(1, 0, At, B0); PG8_MMA(1, 1, At, B1); PG8_BAR; PG8_SCHED;
;     __device__ __forceinline__ void operator()(const af4 (&acc)[2][2][4][2], const pg8::Unit& u, int wr, int wc, int fr_, int fq_) const {
;     ...
;         const int row0 = u.pm * 256 + wr * 64 + fr, col0 = u.pn * 256 + wc * 32 + 8 * fq;
;         v4u o[2][2][2];
;     ...
;         MUL_LOAD(0, 0);
; #pragma unroll
;         for (int b_ = 0; b_ < 4; ++b_) {
;             const int ai = b_ >> 1, mp = b_ & 1, cur = b_ & 1;
;             if (b_ + 1 < 4) { if (cur == 0) MUL_LOAD(1, b_ + 1); else MUL_LOAD(0, b_ + 1); }
	s_add_i32 s22, s49, s33
	s_mov_b32 m0, s22
	ds_read_b128 v[182:185], v157 offset:49152
	ds_read_b128 v[186:189], v157 offset:50176
	ds_read_b128 v[190:193], v157 offset:51200
	ds_read_b128 v[194:197], v157 offset:52224
	ds_read_b128 v[198:201], v157 offset:53248
	ds_read_b128 v[202:205], v157 offset:54272
	ds_read_b128 v[206:209], v157 offset:55296
	ds_read_b128 v[210:213], v157 offset:56320
	global_load_lds_dwordx4 v[242:243], off
	s_add_i32 m0, s22, 0x2000
	s_add_i32 s22, s50, s33
	global_load_lds_dwordx4 v[244:245], off
	s_mov_b32 m0, s22
	s_nop 0
	global_load_lds_dwordx4 v[246:247], off
	s_add_i32 m0, s22, 0x2000
	s_nop 0
	global_load_lds_dwordx4 v[248:249], off
	s_mov_b32 m0, s36
	s_nop 0
	global_load_lds_dwordx4 v[250:251], off
	s_mov_b32 m0, s37
	s_nop 0
	global_load_lds_dwordx4 v[252:253], off
	s_waitcnt vmcnt(8)
	s_waitcnt lgkmcnt(0)
	s_barrier
	s_setprio 1
	s_waitcnt lgkmcnt(0)
	v_mfma_f32_16x16x32_bf16 v[60:63], v[128:131], v[182:185], v[60:63]
	v_mfma_f32_16x16x32_bf16 v[56:59], v[158:161], v[182:185], v[56:59]
	v_mfma_f32_16x16x32_bf16 v[48:51], v[128:131], v[190:193], v[48:51]
	v_mfma_f32_16x16x32_bf16 v[40:43], v[158:161], v[190:193], v[40:43]
	v_mfma_f32_16x16x32_bf16 v[32:35], v[128:131], v[198:201], v[32:35]
	v_mfma_f32_16x16x32_bf16 v[24:27], v[158:161], v[198:201], v[24:27]
	v_mfma_f32_16x16x32_bf16 v[16:19], v[128:131], v[206:209], v[16:19]
	v_mfma_f32_16x16x32_bf16 v[8:11], v[158:161], v[206:209], v[8:11]
	v_mfma_f32_16x16x32_bf16 v[60:63], v[132:135], v[186:189], v[60:63]
	v_mfma_f32_16x16x32_bf16 v[56:59], v[162:165], v[186:189], v[56:59]
	v_mfma_f32_16x16x32_bf16 v[48:51], v[132:135], v[194:197], v[48:51]
	v_mfma_f32_16x16x32_bf16 v[40:43], v[162:165], v[194:197], v[40:43]
	v_mfma_f32_16x16x32_bf16 v[32:35], v[132:135], v[202:205], v[32:35]
	v_mfma_f32_16x16x32_bf16 v[24:27], v[162:165], v[202:205], v[24:27]
	v_mfma_f32_16x16x32_bf16 v[16:19], v[132:135], v[210:213], v[16:19]
	v_mfma_f32_16x16x32_bf16 v[8:11], v[162:165], v[210:213], v[8:11]
	s_setprio 0
	s_setprio 1
	v_mfma_f32_16x16x32_bf16 v[52:55], v[166:169], v[182:185], v[52:55]
	v_mfma_f32_16x16x32_bf16 v[44:47], v[174:177], v[182:185], v[44:47]
	v_mfma_f32_16x16x32_bf16 v[36:39], v[166:169], v[190:193], v[36:39]
	v_mfma_f32_16x16x32_bf16 v[28:31], v[174:177], v[190:193], v[28:31]
	v_mfma_f32_16x16x32_bf16 v[20:23], v[166:169], v[198:201], v[20:23]
	v_mfma_f32_16x16x32_bf16 v[12:15], v[174:177], v[198:201], v[12:15]
	v_mfma_f32_16x16x32_bf16 v[4:7], v[166:169], v[206:209], v[4:7]
	v_mfma_f32_16x16x32_bf16 v[0:3], v[174:177], v[206:209], v[0:3]
	v_mfma_f32_16x16x32_bf16 v[52:55], v[170:173], v[186:189], v[52:55]
	v_mfma_f32_16x16x32_bf16 v[44:47], v[178:181], v[186:189], v[44:47]
	v_mfma_f32_16x16x32_bf16 v[36:39], v[170:173], v[194:197], v[36:39]
	v_mfma_f32_16x16x32_bf16 v[28:31], v[178:181], v[194:197], v[28:31]
	v_mfma_f32_16x16x32_bf16 v[20:23], v[170:173], v[202:205], v[20:23]
	v_mfma_f32_16x16x32_bf16 v[12:15], v[178:181], v[202:205], v[12:15]
	v_mfma_f32_16x16x32_bf16 v[4:7], v[170:173], v[210:213], v[4:7]
	v_mfma_f32_16x16x32_bf16 v[0:3], v[178:181], v[210:213], v[0:3]
	s_setprio 0
	s_barrier
	s_add_i32 s48, s48, 2
	s_add_u32 s46, s46, 0x100
	s_addc_u32 s47, s47, 0
	s_add_u32 s18, s18, 0x100
	s_addc_u32 s19, s19, 0
	s_cmp_gt_u32 s48, 5
	s_cbranch_scc0 .LBB0_483
	s_lshl_b32 s9, s16, 8
	v_mbcnt_lo_u32_b32 v128, -1, 0
	v_mbcnt_hi_u32_b32 v128, -1, v128
	s_add_i32 s9, s9, s87
	v_and_or_b32 v194, v128, 15, s9
	s_lshl_b32 s9, s43, 8
	v_ashrrev_i32_e32 v128, 1, v128
	s_or_b32 s9, s9, s79
	v_and_b32_e32 v128, -8, v128
	v_mov_b32_e32 v130, v194
	v_add_u32_e32 v128, s9, v128
	v_ashrrev_i32_e32 v129, 31, v128
	v_ashrrev_i32_e32 v131, 31, v130
	v_lshlrev_b64 v[130:131], 11, v[130:131]
	v_lshl_add_u64 v[130:131], s[2:3], 0, v[130:131]
	v_lshlrev_b64 v[152:153], 1, v[128:129]
	v_lshl_add_u64 v[128:129], v[130:131], 0, v[152:153]
	global_load_dwordx4 v[158:161], v[128:129], off
	global_load_dwordx4 v[162:165], v[128:129], off offset:256
	v_add_co_u32_e32 v128, vcc, s38, v128
	v_or_b32_e32 v182, 32, v194
	s_nop 0
	v_addc_co_u32_e32 v129, vcc, 0, v129, vcc
	global_load_dwordx4 v[166:169], v[128:129], off
	global_load_dwordx4 v[170:173], v[128:129], off offset:256
	v_mov_b32_e32 v128, v182
	v_mov_b32_e32 v184, v194
	v_ashrrev_i32_e32 v129, 31, v128
	v_lshlrev_b64 v[128:129], 11, v[128:129]
	v_lshl_add_u64 v[128:129], s[2:3], 0, v[128:129]
	v_lshl_add_u64 v[128:129], v[128:129], 0, v[152:153]
	global_load_dwordx4 v[174:177], v[128:129], off
	global_load_dwordx4 v[178:181], v[128:129], off offset:256
	v_add_co_u32_e32 v128, vcc, s38, v128
	s_mov_b32 s43, s8
	s_nop 0
	v_addc_co_u32_e32 v129, vcc, 0, v129, vcc
	global_load_dwordx4 v[132:135], v[128:129], off
	s_nop 0
	global_load_dwordx4 v[128:131], v[128:129], off offset:256
	s_mov_b32 s16, s10
	v_ashrrev_i32_e32 v185, 31, v184
	v_lshlrev_b64 v[184:185], 11, v[184:185]
	v_lshl_add_u64 v[184:185], s[2:3], 0, v[184:185]
	v_lshl_add_u64 v[184:185], v[184:185], 0, v[152:153]
	s_mov_b64 s[18:19], s[14:15]
	s_mov_b64 s[20:21], s[12:13]
	s_waitcnt vmcnt(0)
; __device__ __forceinline__ unsigned cvtpk(float lo, float hi) { f32x2 v = {lo, hi}; bf16x2_t b = __builtin_convertvector(v, bf16x2_t); return __builtin_bit_cast(unsigned, b); }
; __device__ __forceinline__ float bflo(unsigned u) { return __uint_as_float(u << 16); }
; __device__ __forceinline__ float bfhi(unsigned u) { return __uint_as_float(u & 0xffff0000u); }
; #define MUL_LOAD(buf, b_) do { int RRl = row0 + ((b_) >> 1) * 128 + ((b_) & 1) * 32; asm volatile("" : "+v"(RRl)); const bf16* pl = G + (size_t)RRl * 1024 + col0; \
;             _Pragma("unroll") for (int mi = 0; mi < 2; ++mi) _Pragma("unroll") for (int bj = 0; bj < 2; ++bj) o[buf][mi][bj] = *(const v4u*)(pl + mi * 16 * 1024 + bj * 128); } while (0)
;     __device__ __forceinline__ void operator()(const af4 (&acc)[2][2][4][2], const pg8::Unit& u, int wr, int wc, int fr_, int fq_) const {
;     ...
;         MUL_LOAD(0, 0);
; #pragma unroll
;         for (int b_ = 0; b_ < 4; ++b_) {
;             const int ai = b_ >> 1, mp = b_ & 1, cur = b_ & 1;
;             if (b_ + 1 < 4) { if (cur == 0) MUL_LOAD(1, b_ + 1); else MUL_LOAD(0, b_ + 1); }
;             int RRb = row0 + ai * 128 + mp * 32; asm volatile("" : "+v"(RRb));
;             bf16* pb = G + (size_t)RRb * 1024 + col0;
; #pragma unroll
;             for (int mi = 0; mi < 2; ++mi)
; #pragma unroll
;                 for (int bj = 0; bj < 2; ++bj) { const af4 v0 = acc[ai][bj][mp * 2 + mi][0], v1 = acc[ai][bj][mp * 2 + mi][1]; const v4u oo = o[cur][mi][bj];
;                     v4u w; w.x = cvtpk(v0[0] * bflo(oo.x), v0[1] * bfhi(oo.x)); w.y = cvtpk(v0[2] * bflo(oo.y), v0[3] * bfhi(oo.y)); w.z = cvtpk(v1[0] * bflo(oo.z), v1[1] * bfhi(oo.z)); w.w = cvtpk(v1[2] * bflo(oo.w), v1[3] * bfhi(oo.w));
;                     *(v4u*)(pb + mi * 16 * 1024 + bj * 128) = w; }
	v_lshlrev_b32_e32 v188, 16, v160
	v_and_b32_e32 v189, 0xffff0000, v160
	v_lshlrev_b32_e32 v160, 16, v161
	v_and_b32_e32 v161, 0xffff0000, v161
	v_lshlrev_b32_e32 v190, 16, v162
	v_and_b32_e32 v191, 0xffff0000, v162
	v_lshlrev_b32_e32 v162, 16, v163
	v_and_b32_e32 v163, 0xffff0000, v163
	v_lshlrev_b32_e32 v192, 16, v164
	v_and_b32_e32 v193, 0xffff0000, v164
	v_lshlrev_b32_e32 v164, 16, v165
	v_and_b32_e32 v165, 0xffff0000, v165
	v_pk_mul_f32 v[122:123], v[122:123], v[160:161]
	v_pk_mul_f32 v[118:119], v[118:119], v[162:163]
	v_pk_mul_f32 v[160:161], v[114:115], v[164:165]
	v_lshlrev_b32_e32 v162, 16, v166
	v_and_b32_e32 v163, 0xffff0000, v166
	v_lshlrev_b32_e32 v164, 16, v167
	v_and_b32_e32 v165, 0xffff0000, v167
	v_lshlrev_b32_e32 v166, 16, v168
	v_and_b32_e32 v167, 0xffff0000, v168
	v_lshlrev_b32_e32 v168, 16, v169
	v_pk_mul_f32 v[108:109], v[108:109], v[162:163]
	v_pk_mul_f32 v[110:111], v[110:111], v[164:165]
	v_pk_mul_f32 v[104:105], v[104:105], v[166:167]
	v_and_b32_e32 v169, 0xffff0000, v169
	v_cvt_pk_bf16_f32 v108, v108, v109
	v_cvt_pk_bf16_f32 v109, v110, v111
	v_cvt_pk_bf16_f32 v110, v104, v105
	v_pk_mul_f32 v[104:105], v[106:107], v[168:169]
	v_lshlrev_b32_e32 v106, 16, v170
	v_and_b32_e32 v107, 0xffff0000, v170
	v_pk_mul_f32 v[100:101], v[100:101], v[106:107]
	v_lshlrev_b32_e32 v106, 16, v171
	v_and_b32_e32 v107, 0xffff0000, v171
	v_pk_mul_f32 v[102:103], v[102:103], v[106:107]
	v_cvt_pk_bf16_f32 v100, v100, v101
	v_cvt_pk_bf16_f32 v101, v102, v103
	v_lshlrev_b32_e32 v102, 16, v172
	v_and_b32_e32 v103, 0xffff0000, v172
	v_lshlrev_b32_e32 v186, 16, v158
	v_and_b32_e32 v187, 0xffff0000, v158
	v_lshlrev_b32_e32 v158, 16, v159
	v_and_b32_e32 v159, 0xffff0000, v159
	v_pk_mul_f32 v[96:97], v[96:97], v[102:103]
	v_pk_mul_f32 v[124:125], v[124:125], v[186:187]
	v_pk_mul_f32 v[126:127], v[126:127], v[158:159]
	v_pk_mul_f32 v[120:121], v[120:121], v[188:189]
	v_cvt_pk_bf16_f32 v102, v96, v97
	v_lshlrev_b32_e32 v96, 16, v173
	v_and_b32_e32 v97, 0xffff0000, v173
	v_pk_mul_f32 v[116:117], v[116:117], v[190:191]
	v_pk_mul_f32 v[158:159], v[112:113], v[192:193]
	v_cvt_pk_bf16_f32 v112, v124, v125
	v_cvt_pk_bf16_f32 v113, v126, v127
	v_cvt_pk_bf16_f32 v114, v120, v121
	v_cvt_pk_bf16_f32 v115, v122, v123
	v_cvt_pk_bf16_f32 v111, v104, v105
	v_add_co_u32_e32 v104, vcc, s38, v184
	v_pk_mul_f32 v[96:97], v[98:99], v[96:97]
	v_cvt_pk_bf16_f32 v116, v116, v117
	v_cvt_pk_bf16_f32 v117, v118, v119
	v_cvt_pk_bf16_f32 v118, v158, v159
	v_cvt_pk_bf16_f32 v119, v160, v161
	global_store_dwordx4 v[184:185], v[112:115], off
	global_store_dwordx4 v[184:185], v[116:119], off offset:256
	v_addc_co_u32_e32 v105, vcc, 0, v185, vcc
	v_cvt_pk_bf16_f32 v103, v96, v97
	v_add_u32_e32 v112, 0x80, v194
	global_store_dwordx4 v[104:105], v[108:111], off
	global_store_dwordx4 v[104:105], v[100:103], off offset:256
	v_mov_b32_e32 v96, v112
	v_lshlrev_b32_e32 v116, 16, v174
	v_ashrrev_i32_e32 v97, 31, v96
	v_lshlrev_b64 v[96:97], 11, v[96:97]
	v_lshl_add_u64 v[96:97], s[2:3], 0, v[96:97]
	v_lshl_add_u64 v[96:97], v[96:97], 0, v[152:153]
	v_and_b32_e32 v117, 0xffff0000, v174
	global_load_dwordx4 v[104:107], v[96:97], off
	global_load_dwordx4 v[108:111], v[96:97], off offset:256
	v_pk_mul_f32 v[92:93], v[92:93], v[116:117]
	v_lshlrev_b32_e32 v116, 16, v175
	v_and_b32_e32 v117, 0xffff0000, v175
	v_pk_mul_f32 v[94:95], v[94:95], v[116:117]
	v_cvt_pk_bf16_f32 v92, v92, v93
	v_cvt_pk_bf16_f32 v93, v94, v95
	v_lshlrev_b32_e32 v94, 16, v176
	v_and_b32_e32 v95, 0xffff0000, v176
	v_pk_mul_f32 v[88:89], v[88:89], v[94:95]
	v_add_co_u32_e32 v96, vcc, s38, v96
	v_cvt_pk_bf16_f32 v94, v88, v89
	v_lshlrev_b32_e32 v88, 16, v177
	v_and_b32_e32 v89, 0xffff0000, v177
	v_pk_mul_f32 v[88:89], v[90:91], v[88:89]
	v_addc_co_u32_e32 v97, vcc, 0, v97, vcc
	v_cvt_pk_bf16_f32 v95, v88, v89
	v_lshlrev_b32_e32 v88, 16, v178
	v_and_b32_e32 v89, 0xffff0000, v178
	v_pk_mul_f32 v[84:85], v[84:85], v[88:89]
	v_lshlrev_b32_e32 v88, 16, v179
	v_and_b32_e32 v89, 0xffff0000, v179
	v_pk_mul_f32 v[86:87], v[86:87], v[88:89]
	v_cvt_pk_bf16_f32 v84, v84, v85
	v_cvt_pk_bf16_f32 v85, v86, v87
	v_lshlrev_b32_e32 v86, 16, v180
	v_and_b32_e32 v87, 0xffff0000, v180
	v_pk_mul_f32 v[76:77], v[76:77], v[86:87]
	global_load_dwordx4 v[100:103], v[96:97], off
	s_nop 0
	global_load_dwordx4 v[96:99], v[96:97], off offset:256
	v_cvt_pk_bf16_f32 v86, v76, v77
	v_lshlrev_b32_e32 v76, 16, v181
	v_and_b32_e32 v77, 0xffff0000, v181
	v_pk_mul_f32 v[76:77], v[78:79], v[76:77]
	v_lshlrev_b32_e32 v78, 16, v133
	v_cvt_pk_bf16_f32 v87, v76, v77
	v_lshlrev_b32_e32 v76, 16, v132
	v_and_b32_e32 v77, 0xffff0000, v132
	v_and_b32_e32 v79, 0xffff0000, v133
	v_pk_mul_f32 v[76:77], v[80:81], v[76:77]
	v_pk_mul_f32 v[78:79], v[82:83], v[78:79]
	v_cvt_pk_bf16_f32 v76, v76, v77
	v_cvt_pk_bf16_f32 v77, v78, v79
	v_lshlrev_b32_e32 v78, 16, v134
	v_and_b32_e32 v79, 0xffff0000, v134
	v_pk_mul_f32 v[72:73], v[72:73], v[78:79]
	v_add_u32_e32 v80, 0xa0, v194
	v_cvt_pk_bf16_f32 v78, v72, v73
	v_lshlrev_b32_e32 v72, 16, v135
	v_and_b32_e32 v73, 0xffff0000, v135
	v_pk_mul_f32 v[72:73], v[74:75], v[72:73]
	v_lshlrev_b32_e32 v74, 16, v128
	v_and_b32_e32 v75, 0xffff0000, v128
	v_pk_mul_f32 v[68:69], v[68:69], v[74:75]
	v_lshlrev_b32_e32 v74, 16, v129
	v_and_b32_e32 v75, 0xffff0000, v129
	v_ashrrev_i32_e32 v183, 31, v182
	v_pk_mul_f32 v[70:71], v[70:71], v[74:75]
	v_lshlrev_b64 v[114:115], 11, v[182:183]
	v_cvt_pk_bf16_f32 v68, v68, v69
	v_cvt_pk_bf16_f32 v69, v70, v71
	v_lshlrev_b32_e32 v70, 16, v130
	v_and_b32_e32 v71, 0xffff0000, v130
	v_lshl_add_u64 v[114:115], s[2:3], 0, v[114:115]
	v_pk_mul_f32 v[64:65], v[64:65], v[70:71]
	v_lshl_add_u64 v[114:115], v[114:115], 0, v[152:153]
	v_cvt_pk_bf16_f32 v70, v64, v65
	v_lshlrev_b32_e32 v64, 16, v131
	v_and_b32_e32 v65, 0xffff0000, v131
	v_cvt_pk_bf16_f32 v79, v72, v73
	v_add_co_u32_e32 v72, vcc, s38, v114
	v_pk_mul_f32 v[64:65], v[66:67], v[64:65]
	s_nop 0
	v_addc_co_u32_e32 v73, vcc, 0, v115, vcc
	v_cvt_pk_bf16_f32 v71, v64, v65
	global_store_dwordx4 v[114:115], v[92:95], off
	global_store_dwordx4 v[114:115], v[84:87], off offset:256
	global_store_dwordx4 v[72:73], v[76:79], off
	global_store_dwordx4 v[72:73], v[68:71], off offset:256
	v_mov_b32_e32 v64, v80
	s_waitcnt vmcnt(7)
; #define PG8_WAIT_V(n) asm volatile("s_waitcnt vmcnt(" #n ")" ::: "memory")
; #define PG8_BAR __builtin_amdgcn_s_barrier()
; __device__ __forceinline__ unsigned cvtpk(float lo, float hi) { f32x2 v = {lo, hi}; bf16x2_t b = __builtin_convertvector(v, bf16x2_t); return __builtin_bit_cast(unsigned, b); }
; __device__ __forceinline__ float bflo(unsigned u) { return __uint_as_float(u << 16); }
; __device__ __forceinline__ float bfhi(unsigned u) { return __uint_as_float(u & 0xffff0000u); }
; #define MUL_LOAD(buf, b_) do { int RRl = row0 + ((b_) >> 1) * 128 + ((b_) & 1) * 32; asm volatile("" : "+v"(RRl)); const bf16* pl = G + (size_t)RRl * 1024 + col0; \
;             _Pragma("unroll") for (int mi = 0; mi < 2; ++mi) _Pragma("unroll") for (int bj = 0; bj < 2; ++bj) o[buf][mi][bj] = *(const v4u*)(pl + mi * 16 * 1024 + bj * 128); } while (0)
; template <class Epi, class Sched, bool ALIGN_EPI = false, bool SP2 = false>
; __device__ __forceinline__ void gemm_phase(PG8_LAS unsigned char* lds, const Gemm g, const Sched& S, const Epi& E, const int wave_s) {
;     ...
;     PG8_WAIT_V(0);
;     if constexpr (!ALIGN_EPI) { if (wr == 0) PG8_BAR; }
;     PG8_BAR;
;     __device__ __forceinline__ void operator()(const af4 (&acc)[2][2][4][2], const pg8::Unit& u, int wr, int wc, int fr_, int fq_) const {
;     ...
;         for (int b_ = 0; b_ < 4; ++b_) {
;             const int ai = b_ >> 1, mp = b_ & 1, cur = b_ & 1;
;             if (b_ + 1 < 4) { if (cur == 0) MUL_LOAD(1, b_ + 1); else MUL_LOAD(0, b_ + 1); }
;             int RRb = row0 + ai * 128 + mp * 32; asm volatile("" : "+v"(RRb));
;             bf16* pb = G + (size_t)RRb * 1024 + col0;
; #pragma unroll
;             for (int mi = 0; mi < 2; ++mi)
; #pragma unroll
;                 for (int bj = 0; bj < 2; ++bj) { const af4 v0 = acc[ai][bj][mp * 2 + mi][0], v1 = acc[ai][bj][mp * 2 + mi][1]; const v4u oo = o[cur][mi][bj];
;                     v4u w; w.x = cvtpk(v0[0] * bflo(oo.x), v0[1] * bfhi(oo.x)); w.y = cvtpk(v0[2] * bflo(oo.y), v0[3] * bfhi(oo.y)); w.z = cvtpk(v1[0] * bflo(oo.z), v1[1] * bfhi(oo.z)); w.w = cvtpk(v1[2] * bflo(oo.w), v1[3] * bfhi(oo.w));
;                     *(v4u*)(pb + mi * 16 * 1024 + bj * 128) = w; }
;             asm volatile("" ::: "memory");
;         }
	v_lshlrev_b32_e32 v84, 16, v104
	v_ashrrev_i32_e32 v65, 31, v64
	v_lshlrev_b64 v[64:65], 11, v[64:65]
	v_lshl_add_u64 v[64:65], s[2:3], 0, v[64:65]
	v_lshl_add_u64 v[64:65], v[64:65], 0, v[152:153]
	global_load_dwordx4 v[68:71], v[64:65], off
	global_load_dwordx4 v[72:75], v[64:65], off offset:256
	v_add_co_u32_e32 v64, vcc, s38, v64
	v_and_b32_e32 v85, 0xffff0000, v104
	s_nop 0
	v_addc_co_u32_e32 v65, vcc, 0, v65, vcc
	global_load_dwordx4 v[76:79], v[64:65], off
	s_nop 0
	global_load_dwordx4 v[64:67], v[64:65], off offset:256
	v_pk_mul_f32 v[60:61], v[60:61], v[84:85]
	v_lshlrev_b32_e32 v84, 16, v105
	v_and_b32_e32 v85, 0xffff0000, v105
	v_pk_mul_f32 v[62:63], v[62:63], v[84:85]
	v_cvt_pk_bf16_f32 v60, v60, v61
	v_cvt_pk_bf16_f32 v61, v62, v63
	v_lshlrev_b32_e32 v62, 16, v106
	v_and_b32_e32 v63, 0xffff0000, v106
	v_pk_mul_f32 v[56:57], v[56:57], v[62:63]
	s_nop 0
	v_cvt_pk_bf16_f32 v62, v56, v57
	v_lshlrev_b32_e32 v56, 16, v107
	v_and_b32_e32 v57, 0xffff0000, v107
	v_pk_mul_f32 v[56:57], v[58:59], v[56:57]
	v_ashrrev_i32_e32 v113, 31, v112
	v_cvt_pk_bf16_f32 v63, v56, v57
	s_waitcnt vmcnt(10)
	v_lshlrev_b32_e32 v56, 16, v108
	v_and_b32_e32 v57, 0xffff0000, v108
	v_pk_mul_f32 v[52:53], v[52:53], v[56:57]
	v_lshlrev_b32_e32 v56, 16, v109
	v_and_b32_e32 v57, 0xffff0000, v109
	v_pk_mul_f32 v[54:55], v[54:55], v[56:57]
	v_cvt_pk_bf16_f32 v52, v52, v53
	v_cvt_pk_bf16_f32 v53, v54, v55
	v_lshlrev_b32_e32 v54, 16, v110
	v_and_b32_e32 v55, 0xffff0000, v110
	v_pk_mul_f32 v[44:45], v[44:45], v[54:55]
	v_lshlrev_b64 v[82:83], 11, v[112:113]
	v_cvt_pk_bf16_f32 v54, v44, v45
	v_lshlrev_b32_e32 v44, 16, v111
	v_and_b32_e32 v45, 0xffff0000, v111
	v_pk_mul_f32 v[44:45], v[46:47], v[44:45]
	s_waitcnt vmcnt(9)
	v_lshlrev_b32_e32 v46, 16, v101
	v_cvt_pk_bf16_f32 v55, v44, v45
	v_lshlrev_b32_e32 v44, 16, v100
	v_and_b32_e32 v45, 0xffff0000, v100
	v_and_b32_e32 v47, 0xffff0000, v101
	v_pk_mul_f32 v[44:45], v[48:49], v[44:45]
	v_pk_mul_f32 v[46:47], v[50:51], v[46:47]
	v_cvt_pk_bf16_f32 v44, v44, v45
	v_cvt_pk_bf16_f32 v45, v46, v47
	v_lshlrev_b32_e32 v46, 16, v102
	v_and_b32_e32 v47, 0xffff0000, v102
	v_pk_mul_f32 v[40:41], v[40:41], v[46:47]
	v_lshl_add_u64 v[82:83], s[2:3], 0, v[82:83]
	v_cvt_pk_bf16_f32 v46, v40, v41
	v_lshlrev_b32_e32 v40, 16, v103
	v_and_b32_e32 v41, 0xffff0000, v103
	v_pk_mul_f32 v[40:41], v[42:43], v[40:41]
	s_waitcnt vmcnt(8)
	v_lshlrev_b32_e32 v42, 16, v96
	v_and_b32_e32 v43, 0xffff0000, v96
	v_pk_mul_f32 v[36:37], v[36:37], v[42:43]
	v_lshlrev_b32_e32 v42, 16, v97
	v_and_b32_e32 v43, 0xffff0000, v97
	v_pk_mul_f32 v[38:39], v[38:39], v[42:43]
	v_cvt_pk_bf16_f32 v36, v36, v37
	v_cvt_pk_bf16_f32 v37, v38, v39
	v_lshlrev_b32_e32 v38, 16, v98
	v_and_b32_e32 v39, 0xffff0000, v98
	v_pk_mul_f32 v[28:29], v[28:29], v[38:39]
	v_lshl_add_u64 v[82:83], v[82:83], 0, v[152:153]
	v_cvt_pk_bf16_f32 v38, v28, v29
	v_lshlrev_b32_e32 v28, 16, v99
	v_and_b32_e32 v29, 0xffff0000, v99
	v_cvt_pk_bf16_f32 v47, v40, v41
	v_add_co_u32_e32 v40, vcc, s38, v82
	v_pk_mul_f32 v[28:29], v[30:31], v[28:29]
	s_nop 0
	v_addc_co_u32_e32 v41, vcc, 0, v83, vcc
	v_cvt_pk_bf16_f32 v39, v28, v29
	global_store_dwordx4 v[82:83], v[60:63], off
	global_store_dwordx4 v[82:83], v[52:55], off offset:256
	global_store_dwordx4 v[40:41], v[44:47], off
	global_store_dwordx4 v[40:41], v[36:39], off offset:256
	s_waitcnt vmcnt(7)
	v_lshlrev_b32_e32 v30, 16, v69
	v_ashrrev_i32_e32 v81, 31, v80
	v_lshlrev_b64 v[28:29], 11, v[80:81]
	v_lshl_add_u64 v[28:29], s[2:3], 0, v[28:29]
	v_lshl_add_u64 v[36:37], v[28:29], 0, v[152:153]
	v_lshlrev_b32_e32 v28, 16, v68
	v_and_b32_e32 v29, 0xffff0000, v68
	v_and_b32_e32 v31, 0xffff0000, v69
	v_pk_mul_f32 v[28:29], v[32:33], v[28:29]
	v_pk_mul_f32 v[30:31], v[34:35], v[30:31]
	v_cvt_pk_bf16_f32 v28, v28, v29
	v_cvt_pk_bf16_f32 v29, v30, v31
	v_lshlrev_b32_e32 v30, 16, v70
	v_and_b32_e32 v31, 0xffff0000, v70
	v_pk_mul_f32 v[24:25], v[24:25], v[30:31]
	s_nop 0
	v_cvt_pk_bf16_f32 v30, v24, v25
	v_lshlrev_b32_e32 v24, 16, v71
	v_and_b32_e32 v25, 0xffff0000, v71
	v_pk_mul_f32 v[24:25], v[26:27], v[24:25]
	s_nop 0
	v_cvt_pk_bf16_f32 v31, v24, v25
	s_waitcnt vmcnt(6)
	v_lshlrev_b32_e32 v24, 16, v72
	v_and_b32_e32 v25, 0xffff0000, v72
	v_pk_mul_f32 v[20:21], v[20:21], v[24:25]
	v_lshlrev_b32_e32 v24, 16, v73
	v_and_b32_e32 v25, 0xffff0000, v73
	v_pk_mul_f32 v[22:23], v[22:23], v[24:25]
	v_cvt_pk_bf16_f32 v20, v20, v21
	v_cvt_pk_bf16_f32 v21, v22, v23
	v_lshlrev_b32_e32 v22, 16, v74
	v_and_b32_e32 v23, 0xffff0000, v74
	v_pk_mul_f32 v[12:13], v[12:13], v[22:23]
	global_store_dwordx4 v[36:37], v[28:31], off
	v_cvt_pk_bf16_f32 v22, v12, v13
	v_lshlrev_b32_e32 v12, 16, v75
	v_and_b32_e32 v13, 0xffff0000, v75
	v_pk_mul_f32 v[12:13], v[14:15], v[12:13]
	s_waitcnt vmcnt(6)
	v_lshlrev_b32_e32 v14, 16, v77
	v_cvt_pk_bf16_f32 v23, v12, v13
	v_lshlrev_b32_e32 v12, 16, v76
	v_and_b32_e32 v13, 0xffff0000, v76
	v_and_b32_e32 v15, 0xffff0000, v77
	v_pk_mul_f32 v[12:13], v[16:17], v[12:13]
	v_pk_mul_f32 v[14:15], v[18:19], v[14:15]
	v_cvt_pk_bf16_f32 v12, v12, v13
	v_cvt_pk_bf16_f32 v13, v14, v15
	v_lshlrev_b32_e32 v14, 16, v78
	v_and_b32_e32 v15, 0xffff0000, v78
	v_pk_mul_f32 v[8:9], v[8:9], v[14:15]
	global_store_dwordx4 v[36:37], v[20:23], off offset:256
	v_cvt_pk_bf16_f32 v14, v8, v9
	v_lshlrev_b32_e32 v8, 16, v79
	v_and_b32_e32 v9, 0xffff0000, v79
	v_pk_mul_f32 v[8:9], v[10:11], v[8:9]
	s_waitcnt vmcnt(6)
	v_lshlrev_b32_e32 v10, 16, v64
	v_and_b32_e32 v11, 0xffff0000, v64
	v_pk_mul_f32 v[4:5], v[4:5], v[10:11]
	v_lshlrev_b32_e32 v10, 16, v65
	v_and_b32_e32 v11, 0xffff0000, v65
	v_pk_mul_f32 v[6:7], v[6:7], v[10:11]
	v_cvt_pk_bf16_f32 v4, v4, v5
	v_cvt_pk_bf16_f32 v5, v6, v7
	v_lshlrev_b32_e32 v6, 16, v66
	v_and_b32_e32 v7, 0xffff0000, v66
	v_pk_mul_f32 v[0:1], v[0:1], v[6:7]
	v_cvt_pk_bf16_f32 v15, v8, v9
	v_cvt_pk_bf16_f32 v6, v0, v1
	v_lshlrev_b32_e32 v0, 16, v67
	v_and_b32_e32 v1, 0xffff0000, v67
	v_add_co_u32_e32 v8, vcc, s38, v36
	v_pk_mul_f32 v[0:1], v[2:3], v[0:1]
	s_nop 0
	v_addc_co_u32_e32 v9, vcc, 0, v37, vcc
	v_cvt_pk_bf16_f32 v7, v0, v1
	global_store_dwordx4 v[8:9], v[12:15], off
	global_store_dwordx4 v[8:9], v[4:7], off offset:256
	s_and_b64 vcc, exec, s[4:5]
	s_cbranch_vccz .LBB0_480
	s_waitcnt vmcnt(0)
	s_cmpk_gt_u32 s86, 0xff
	s_cbranch_scc1 .LBB0_487
	s_barrier

; #define PG8_STAGE(bufoff, gbase, voff) do { _Pragma("unroll") for (int _i = 0; _i < 2; ++_i) \
;         __builtin_amdgcn_global_load_lds((const unsigned*)((const char*)(gbase) + (voff)[_i]), (PG8_LAS unsigned*)(lds + (bufoff) + ldsw + _i * 8192), 16, 0, 0); } while (0)
; #define PG8_LDA(dst, b, h) do { _Pragma("unroll") for (int m = 0; m < 4; ++m) _Pragma("unroll") for (int k = 0; k < 2; ++k) dst[m][k] = *(const PG8_LAS bf16x8*)(lds + PG8_SA(b, h) + aoff + m * 2048 + k * 1024); } while (0)
; #define PG8_LDB(dst, b, h) do { _Pragma("unroll") for (int n = 0; n < 2; ++n) _Pragma("unroll") for (int k = 0; k < 2; ++k) dst[n][k] = *(const PG8_LAS bf16x8*)(lds + PG8_SB(b, h) + boff + n * 2048 + k * 1024); } while (0)
; #define PG8_MMA(ai, bj, At, Bt) do { __builtin_amdgcn_s_setprio(1); _Pragma("unroll") for (int m = 0; m < 4; ++m) _Pragma("unroll") for (int n = 0; n < 2; ++n) _Pragma("unroll") for (int k = 0; k < 2; ++k) \
;         acc[ai][bj][m][n] = __builtin_amdgcn_mfma_f32_16x16x32_bf16(Bt[n][k], At[m][k], acc[ai][bj][m][n], 0, 0, 0); __builtin_amdgcn_s_setprio(0); } while (0)
; #define PG8_WAIT_V(n) asm volatile("s_waitcnt vmcnt(" #n ")" ::: "memory")
; #define PG8_WAIT_L(n) asm volatile("s_waitcnt lgkmcnt(" #n ")" ::: "memory")
; #define PG8_BAR __builtin_amdgcn_s_barrier()
; #define PG8_SCHED __builtin_amdgcn_sched_barrier(0)
; template <class Epi, class Sched, bool ALIGN_EPI = false, bool SP2 = false>
; __device__ __forceinline__ void gemm_phase(PG8_LAS unsigned char* lds, const Gemm g, const Sched& S, const Epi& E, const int wave_s) {
;     ...
;             const bool last = (t == nt - 2);
;             const char* a1 = cA + (size_t)(t + 1) * kstep;
;             const char* a2 = last ? nA : cA + (size_t)(t + 2) * kstep; const char* b2 = last ? nB : cB + (size_t)(t + 2) * kstep;
;             const char* a3 = a2 + kstep; const char* b3 = b2 + kstep;
;             if (last && has_next) S.a_ready(nxt);
;             if constexpr (SP2) {
;             PG8_LDB(B0, 0, 0); PG8_LDB(B1, 0, 1); PG8_SCHED; PG8_LDA(At, 0, 0); PG8_STAGE(PG8_SA(1, 1), a1 + hstep, voffA);
;             PG8_WAIT_V(8); PG8_WAIT_L(0); PG8_BAR; PG8_MMA(0, 0, At, B0); PG8_MMA(0, 1, At, B1); PG8_BAR; PG8_SCHED;
;             PG8_LDA(At, 0, 1); PG8_STAGE(PG8_SB(0, 0), b2, voffB); PG8_STAGE(PG8_SB(0, 1), b2 + hstep, voffB); PG8_STAGE(PG8_SA(0, 0), a2, voffA);
.LBB0_495:
	ds_read_b128 v[128:131], v185
	ds_read_b128 v[132:135], v185 offset:1024
	ds_read_b128 v[136:139], v185 offset:2048
	ds_read_b128 v[140:143], v185 offset:3072
	ds_read_b128 v[144:147], v186
	ds_read_b128 v[148:151], v186 offset:1024
	ds_read_b128 v[152:155], v186 offset:2048
	ds_read_b128 v[156:159], v186 offset:3072
	s_add_u32 s20, s18, 0xfffc0080
	s_addc_u32 s21, s19, -1
	s_cmp_eq_u32 s48, 12
	s_cselect_b32 s23, s11, s21
	s_cselect_b32 s22, s44, s20
	s_cselect_b32 s21, s9, s47
	s_cselect_b32 s20, s45, s46
	v_lshl_add_u64 v[212:213], s[18:19], 0, v[170:171]
	s_add_i32 m0, s17, 0xc000
	ds_read_b128 v[176:179], v187
	ds_read_b128 v[180:183], v187 offset:1024
	ds_read_b128 v[188:191], v187 offset:2048
	ds_read_b128 v[192:195], v187 offset:3072
	ds_read_b128 v[196:199], v187 offset:4096
	ds_read_b128 v[200:203], v187 offset:5120
	ds_read_b128 v[204:207], v187 offset:6144
	ds_read_b128 v[208:211], v187 offset:7168
	global_load_lds_dwordx4 v[212:213], off
	v_lshl_add_u64 v[212:213], s[18:19], 0, v[168:169]
	s_add_i32 m0, s17, 0xe000
	s_nop 0
	global_load_lds_dwordx4 v[212:213], off
	v_lshl_add_u64 v[230:231], s[20:21], 0, v[164:165]
	s_add_u32 s50, s20, 0x40000
	v_lshl_add_u64 v[232:233], s[20:21], 0, v[160:161]
	s_addc_u32 s51, s21, 0
	v_lshl_add_u64 v[234:235], s[50:51], 0, v[164:165]
	v_lshl_add_u64 v[236:237], s[22:23], 0, v[162:163]
	v_lshl_add_u64 v[238:239], s[50:51], 0, v[160:161]
	v_lshl_add_u64 v[240:241], s[22:23], 0, v[166:167]
	s_waitcnt vmcnt(8)
	s_waitcnt lgkmcnt(0)
	s_barrier
	s_setprio 1
	s_waitcnt lgkmcnt(0)
	v_mfma_f32_16x16x32_bf16 v[124:127], v[128:131], v[176:179], v[124:127]
	v_mfma_f32_16x16x32_bf16 v[120:123], v[136:139], v[176:179], v[120:123]
	v_mfma_f32_16x16x32_bf16 v[112:115], v[128:131], v[188:191], v[112:115]
	v_mfma_f32_16x16x32_bf16 v[104:107], v[136:139], v[188:191], v[104:107]
	v_mfma_f32_16x16x32_bf16 v[92:95], v[128:131], v[196:199], v[92:95]
	v_mfma_f32_16x16x32_bf16 v[88:91], v[136:139], v[196:199], v[88:91]
	v_mfma_f32_16x16x32_bf16 v[80:83], v[128:131], v[204:207], v[80:83]
	v_mfma_f32_16x16x32_bf16 v[72:75], v[136:139], v[204:207], v[72:75]
	v_mfma_f32_16x16x32_bf16 v[124:127], v[132:135], v[180:183], v[124:127]
	v_mfma_f32_16x16x32_bf16 v[120:123], v[140:143], v[180:183], v[120:123]
	v_mfma_f32_16x16x32_bf16 v[112:115], v[132:135], v[192:195], v[112:115]
	v_mfma_f32_16x16x32_bf16 v[104:107], v[140:143], v[192:195], v[104:107]
	v_mfma_f32_16x16x32_bf16 v[92:95], v[132:135], v[200:203], v[92:95]
	v_mfma_f32_16x16x32_bf16 v[88:91], v[140:143], v[200:203], v[88:91]
	v_mfma_f32_16x16x32_bf16 v[80:83], v[132:135], v[208:211], v[80:83]
	v_mfma_f32_16x16x32_bf16 v[72:75], v[140:143], v[208:211], v[72:75]
	s_setprio 0
	s_setprio 1
	v_mfma_f32_16x16x32_bf16 v[116:119], v[144:147], v[176:179], v[116:119]
	v_mfma_f32_16x16x32_bf16 v[108:111], v[152:155], v[176:179], v[108:111]
	v_mfma_f32_16x16x32_bf16 v[100:103], v[144:147], v[188:191], v[100:103]
	v_mfma_f32_16x16x32_bf16 v[96:99], v[152:155], v[188:191], v[96:99]
	v_mfma_f32_16x16x32_bf16 v[84:87], v[144:147], v[196:199], v[84:87]
	v_mfma_f32_16x16x32_bf16 v[76:79], v[152:155], v[196:199], v[76:79]
	v_mfma_f32_16x16x32_bf16 v[68:71], v[144:147], v[204:207], v[68:71]
	v_mfma_f32_16x16x32_bf16 v[64:67], v[152:155], v[204:207], v[64:67]
	v_mfma_f32_16x16x32_bf16 v[116:119], v[148:151], v[180:183], v[116:119]
	v_mfma_f32_16x16x32_bf16 v[108:111], v[156:159], v[180:183], v[108:111]
	v_mfma_f32_16x16x32_bf16 v[100:103], v[148:151], v[192:195], v[100:103]
	v_mfma_f32_16x16x32_bf16 v[96:99], v[156:159], v[192:195], v[96:99]
	v_mfma_f32_16x16x32_bf16 v[84:87], v[148:151], v[200:203], v[84:87]
	v_mfma_f32_16x16x32_bf16 v[76:79], v[156:159], v[200:203], v[76:79]
	v_mfma_f32_16x16x32_bf16 v[68:71], v[148:151], v[208:211], v[68:71]
	v_mfma_f32_16x16x32_bf16 v[64:67], v[156:159], v[208:211], v[64:67]
	s_setprio 0
	s_barrier
	s_add_i32 s49, s41, s33
	s_mov_b32 m0, s49
	ds_read_b128 v[176:179], v187 offset:16384
	ds_read_b128 v[180:183], v187 offset:17408
	ds_read_b128 v[188:191], v187 offset:18432
	ds_read_b128 v[192:195], v187 offset:19456
	ds_read_b128 v[196:199], v187 offset:20480
	ds_read_b128 v[200:203], v187 offset:21504
	ds_read_b128 v[204:207], v187 offset:22528
	ds_read_b128 v[208:211], v187 offset:23552
	global_load_lds_dwordx4 v[230:231], off
	s_add_i32 m0, s49, 0x2000
	s_add_i32 s49, s42, s33
	global_load_lds_dwordx4 v[232:233], off
	s_mov_b32 m0, s49
	s_nop 0
	global_load_lds_dwordx4 v[234:235], off
	s_add_i32 m0, s49, 0x2000
	s_nop 0
	global_load_lds_dwordx4 v[238:239], off
	s_mov_b32 m0, s17
	s_nop 0
	global_load_lds_dwordx4 v[240:241], off
	s_mov_b32 m0, s30
	s_nop 0
	global_load_lds_dwordx4 v[236:237], off
	s_waitcnt vmcnt(8)
	s_waitcnt lgkmcnt(0)
	s_barrier
; #define PG8_STAGE(bufoff, gbase, voff) do { _Pragma("unroll") for (int _i = 0; _i < 2; ++_i) \
;         __builtin_amdgcn_global_load_lds((const unsigned*)((const char*)(gbase) + (voff)[_i]), (PG8_LAS unsigned*)(lds + (bufoff) + ldsw + _i * 8192), 16, 0, 0); } while (0)
; #define PG8_LDA(dst, b, h) do { _Pragma("unroll") for (int m = 0; m < 4; ++m) _Pragma("unroll") for (int k = 0; k < 2; ++k) dst[m][k] = *(const PG8_LAS bf16x8*)(lds + PG8_SA(b, h) + aoff + m * 2048 + k * 1024); } while (0)
; #define PG8_LDB(dst, b, h) do { _Pragma("unroll") for (int n = 0; n < 2; ++n) _Pragma("unroll") for (int k = 0; k < 2; ++k) dst[n][k] = *(const PG8_LAS bf16x8*)(lds + PG8_SB(b, h) + boff + n * 2048 + k * 1024); } while (0)
; #define PG8_MMA(ai, bj, At, Bt) do { __builtin_amdgcn_s_setprio(1); _Pragma("unroll") for (int m = 0; m < 4; ++m) _Pragma("unroll") for (int n = 0; n < 2; ++n) _Pragma("unroll") for (int k = 0; k < 2; ++k) \
;         acc[ai][bj][m][n] = __builtin_amdgcn_mfma_f32_16x16x32_bf16(Bt[n][k], At[m][k], acc[ai][bj][m][n], 0, 0, 0); __builtin_amdgcn_s_setprio(0); } while (0)
; #define PG8_WAIT_V(n) asm volatile("s_waitcnt vmcnt(" #n ")" ::: "memory")
; #define PG8_WAIT_L(n) asm volatile("s_waitcnt lgkmcnt(" #n ")" ::: "memory")
; #define PG8_BAR __builtin_amdgcn_s_barrier()
; #define PG8_SCHED __builtin_amdgcn_sched_barrier(0)
; template <class Epi, class Sched, bool ALIGN_EPI = false, bool SP2 = false>
; __device__ __forceinline__ void gemm_phase(PG8_LAS unsigned char* lds, const Gemm g, const Sched& S, const Epi& E, const int wave_s) {
;     ...
;             PG8_WAIT_V(8); PG8_WAIT_L(0); PG8_BAR; PG8_MMA(0, 0, At, B0); PG8_MMA(0, 1, At, B1); PG8_BAR; PG8_SCHED;
;             PG8_LDA(At, 0, 1); PG8_STAGE(PG8_SB(0, 0), b2, voffB); PG8_STAGE(PG8_SB(0, 1), b2 + hstep, voffB); PG8_STAGE(PG8_SA(0, 0), a2, voffA);
;             PG8_WAIT_V(8); PG8_WAIT_L(0); PG8_BAR; PG8_MMA(1, 0, At, B0); PG8_MMA(1, 1, At, B1); PG8_BAR; PG8_SCHED;
;             PG8_LDB(B0, 1, 0); PG8_LDB(B1, 1, 1); PG8_SCHED; PG8_LDA(At, 1, 0); PG8_STAGE(PG8_SA(0, 1), a2 + hstep, voffA);
;             PG8_WAIT_V(8); PG8_WAIT_L(0); PG8_BAR; PG8_MMA(0, 0, At, B0); PG8_MMA(0, 1, At, B1); PG8_BAR; PG8_SCHED;
	s_setprio 1
	s_waitcnt lgkmcnt(0)
	v_mfma_f32_16x16x32_bf16 v[60:63], v[128:131], v[176:179], v[60:63]
	v_mfma_f32_16x16x32_bf16 v[56:59], v[136:139], v[176:179], v[56:59]
	v_mfma_f32_16x16x32_bf16 v[48:51], v[128:131], v[188:191], v[48:51]
	v_mfma_f32_16x16x32_bf16 v[40:43], v[136:139], v[188:191], v[40:43]
	v_mfma_f32_16x16x32_bf16 v[28:31], v[128:131], v[196:199], v[28:31]
	v_mfma_f32_16x16x32_bf16 v[24:27], v[136:139], v[196:199], v[24:27]
	v_mfma_f32_16x16x32_bf16 v[16:19], v[128:131], v[204:207], v[16:19]
	v_mfma_f32_16x16x32_bf16 v[8:11], v[136:139], v[204:207], v[8:11]
	v_mfma_f32_16x16x32_bf16 v[60:63], v[132:135], v[180:183], v[60:63]
	v_mfma_f32_16x16x32_bf16 v[56:59], v[140:143], v[180:183], v[56:59]
	v_mfma_f32_16x16x32_bf16 v[48:51], v[132:135], v[192:195], v[48:51]
	v_mfma_f32_16x16x32_bf16 v[40:43], v[140:143], v[192:195], v[40:43]
	v_mfma_f32_16x16x32_bf16 v[28:31], v[132:135], v[200:203], v[28:31]
	v_mfma_f32_16x16x32_bf16 v[24:27], v[140:143], v[200:203], v[24:27]
	v_mfma_f32_16x16x32_bf16 v[16:19], v[132:135], v[208:211], v[16:19]
	v_mfma_f32_16x16x32_bf16 v[8:11], v[140:143], v[208:211], v[8:11]
	s_setprio 0
	s_setprio 1
	v_mfma_f32_16x16x32_bf16 v[52:55], v[144:147], v[176:179], v[52:55]
	v_mfma_f32_16x16x32_bf16 v[44:47], v[152:155], v[176:179], v[44:47]
	v_mfma_f32_16x16x32_bf16 v[36:39], v[144:147], v[188:191], v[36:39]
	v_mfma_f32_16x16x32_bf16 v[32:35], v[152:155], v[188:191], v[32:35]
	v_mfma_f32_16x16x32_bf16 v[20:23], v[144:147], v[196:199], v[20:23]
	v_mfma_f32_16x16x32_bf16 v[12:15], v[152:155], v[196:199], v[12:15]
	v_mfma_f32_16x16x32_bf16 v[4:7], v[144:147], v[204:207], v[4:7]
	v_mfma_f32_16x16x32_bf16 v[0:3], v[152:155], v[204:207], v[0:3]
	v_mfma_f32_16x16x32_bf16 v[52:55], v[148:151], v[180:183], v[52:55]
	v_mfma_f32_16x16x32_bf16 v[44:47], v[156:159], v[180:183], v[44:47]
	v_mfma_f32_16x16x32_bf16 v[36:39], v[148:151], v[192:195], v[36:39]
	v_mfma_f32_16x16x32_bf16 v[32:35], v[156:159], v[192:195], v[32:35]
	v_mfma_f32_16x16x32_bf16 v[20:23], v[148:151], v[200:203], v[20:23]
	v_mfma_f32_16x16x32_bf16 v[12:15], v[156:159], v[200:203], v[12:15]
	v_mfma_f32_16x16x32_bf16 v[4:7], v[148:151], v[208:211], v[4:7]
	v_mfma_f32_16x16x32_bf16 v[0:3], v[156:159], v[208:211], v[0:3]
	s_setprio 0
	s_barrier
	s_add_i32 s49, 0, 0x18000
	s_add_i32 s50, 0, 0x1c000
	v_add_u32_e32 v140, s49, v184
	v_add_u32_e32 v156, s50, v184
	ds_read_b128 v[128:131], v140
	ds_read_b128 v[132:135], v140 offset:1024
	ds_read_b128 v[136:139], v140 offset:2048
	ds_read_b128 v[140:143], v140 offset:3072
	ds_read_b128 v[144:147], v156
	ds_read_b128 v[148:151], v156 offset:1024
	ds_read_b128 v[152:155], v156 offset:2048
	ds_read_b128 v[156:159], v156 offset:3072
	s_add_u32 s22, s22, 0x40000
	s_addc_u32 s23, s23, 0
	s_mov_b32 m0, s31
	v_lshl_add_u64 v[220:221], s[22:23], 0, v[166:167]
	ds_read_b128 v[176:179], v187 offset:32768
	ds_read_b128 v[180:183], v187 offset:33792
	ds_read_b128 v[188:191], v187 offset:34816
	ds_read_b128 v[192:195], v187 offset:35840
	ds_read_b128 v[196:199], v187 offset:36864
	ds_read_b128 v[200:203], v187 offset:37888
	ds_read_b128 v[204:207], v187 offset:38912
	ds_read_b128 v[208:211], v187 offset:39936
	global_load_lds_dwordx4 v[220:221], off
	v_lshl_add_u64 v[220:221], s[22:23], 0, v[162:163]
	s_mov_b32 m0, s34
	s_nop 0
	global_load_lds_dwordx4 v[220:221], off
	v_lshl_add_u64 v[242:243], v[230:231], 0, s[4:5]
	s_add_u32 s20, s20, 0x40080
	v_lshl_add_u64 v[244:245], v[232:233], 0, s[4:5]
	s_addc_u32 s21, s21, 0
	v_lshl_add_u64 v[246:247], s[20:21], 0, v[164:165]
	v_lshl_add_u64 v[248:249], s[20:21], 0, v[160:161]
	v_lshl_add_u64 v[250:251], v[240:241], 0, s[4:5]
	v_lshl_add_u64 v[252:253], v[236:237], 0, s[4:5]
	s_waitcnt vmcnt(8)
	s_waitcnt lgkmcnt(0)
	s_barrier
	s_setprio 1
	s_waitcnt lgkmcnt(0)
	v_mfma_f32_16x16x32_bf16 v[124:127], v[128:131], v[176:179], v[124:127]
	v_mfma_f32_16x16x32_bf16 v[120:123], v[136:139], v[176:179], v[120:123]
	v_mfma_f32_16x16x32_bf16 v[112:115], v[128:131], v[188:191], v[112:115]
	v_mfma_f32_16x16x32_bf16 v[104:107], v[136:139], v[188:191], v[104:107]
	v_mfma_f32_16x16x32_bf16 v[92:95], v[128:131], v[196:199], v[92:95]
	v_mfma_f32_16x16x32_bf16 v[88:91], v[136:139], v[196:199], v[88:91]
	v_mfma_f32_16x16x32_bf16 v[80:83], v[128:131], v[204:207], v[80:83]
	v_mfma_f32_16x16x32_bf16 v[72:75], v[136:139], v[204:207], v[72:75]
	v_mfma_f32_16x16x32_bf16 v[124:127], v[132:135], v[180:183], v[124:127]
	v_mfma_f32_16x16x32_bf16 v[120:123], v[140:143], v[180:183], v[120:123]
	v_mfma_f32_16x16x32_bf16 v[112:115], v[132:135], v[192:195], v[112:115]
	v_mfma_f32_16x16x32_bf16 v[104:107], v[140:143], v[192:195], v[104:107]
	v_mfma_f32_16x16x32_bf16 v[92:95], v[132:135], v[200:203], v[92:95]
	v_mfma_f32_16x16x32_bf16 v[88:91], v[140:143], v[200:203], v[88:91]
	v_mfma_f32_16x16x32_bf16 v[80:83], v[132:135], v[208:211], v[80:83]
	v_mfma_f32_16x16x32_bf16 v[72:75], v[140:143], v[208:211], v[72:75]
	s_setprio 0
	s_setprio 1
	v_mfma_f32_16x16x32_bf16 v[116:119], v[144:147], v[176:179], v[116:119]
	v_mfma_f32_16x16x32_bf16 v[108:111], v[152:155], v[176:179], v[108:111]
	v_mfma_f32_16x16x32_bf16 v[100:103], v[144:147], v[188:191], v[100:103]
	v_mfma_f32_16x16x32_bf16 v[96:99], v[152:155], v[188:191], v[96:99]
	v_mfma_f32_16x16x32_bf16 v[84:87], v[144:147], v[196:199], v[84:87]
	v_mfma_f32_16x16x32_bf16 v[76:79], v[152:155], v[196:199], v[76:79]
	v_mfma_f32_16x16x32_bf16 v[68:71], v[144:147], v[204:207], v[68:71]
	v_mfma_f32_16x16x32_bf16 v[64:67], v[152:155], v[204:207], v[64:67]
	v_mfma_f32_16x16x32_bf16 v[116:119], v[148:151], v[180:183], v[116:119]
	v_mfma_f32_16x16x32_bf16 v[108:111], v[156:159], v[180:183], v[108:111]
	v_mfma_f32_16x16x32_bf16 v[100:103], v[148:151], v[192:195], v[100:103]
	v_mfma_f32_16x16x32_bf16 v[96:99], v[156:159], v[192:195], v[96:99]
	v_mfma_f32_16x16x32_bf16 v[84:87], v[148:151], v[200:203], v[84:87]
	v_mfma_f32_16x16x32_bf16 v[76:79], v[156:159], v[200:203], v[76:79]
	v_mfma_f32_16x16x32_bf16 v[68:71], v[148:151], v[208:211], v[68:71]
	v_mfma_f32_16x16x32_bf16 v[64:67], v[156:159], v[208:211], v[64:67]
	s_setprio 0
	s_barrier
; #define PG8_STAGE(bufoff, gbase, voff) do { _Pragma("unroll") for (int _i = 0; _i < 2; ++_i) \
;         __builtin_amdgcn_global_load_lds((const unsigned*)((const char*)(gbase) + (voff)[_i]), (PG8_LAS unsigned*)(lds + (bufoff) + ldsw + _i * 8192), 16, 0, 0); } while (0)
; #define PG8_LDA(dst, b, h) do { _Pragma("unroll") for (int m = 0; m < 4; ++m) _Pragma("unroll") for (int k = 0; k < 2; ++k) dst[m][k] = *(const PG8_LAS bf16x8*)(lds + PG8_SA(b, h) + aoff + m * 2048 + k * 1024); } while (0)
; #define PG8_MMA(ai, bj, At, Bt) do { __builtin_amdgcn_s_setprio(1); _Pragma("unroll") for (int m = 0; m < 4; ++m) _Pragma("unroll") for (int n = 0; n < 2; ++n) _Pragma("unroll") for (int k = 0; k < 2; ++k) \
;         acc[ai][bj][m][n] = __builtin_amdgcn_mfma_f32_16x16x32_bf16(Bt[n][k], At[m][k], acc[ai][bj][m][n], 0, 0, 0); __builtin_amdgcn_s_setprio(0); } while (0)
; #define PG8_WAIT_V(n) asm volatile("s_waitcnt vmcnt(" #n ")" ::: "memory")
; #define PG8_WAIT_L(n) asm volatile("s_waitcnt lgkmcnt(" #n ")" ::: "memory")
; #define PG8_BAR __builtin_amdgcn_s_barrier()
; #define PG8_SCHED __builtin_amdgcn_sched_barrier(0)
; template <class Epi, class Sched, bool ALIGN_EPI = false, bool SP2 = false>
; __device__ __forceinline__ void gemm_phase(PG8_LAS unsigned char* lds, const Gemm g, const Sched& S, const Epi& E, const int wave_s) {
;     ...
;             PG8_WAIT_V(8); PG8_WAIT_L(0); PG8_BAR; PG8_MMA(0, 0, At, B0); PG8_MMA(0, 1, At, B1); PG8_BAR; PG8_SCHED;
;             PG8_LDA(At, 1, 1); PG8_STAGE(PG8_SB(1, 0), b3, voffB); PG8_STAGE(PG8_SB(1, 1), b3 + hstep, voffB); PG8_STAGE(PG8_SA(1, 0), a3, voffA);
;             PG8_WAIT_V(8); PG8_WAIT_L(0); PG8_BAR; PG8_MMA(1, 0, At, B0); PG8_MMA(1, 1, At, B1); PG8_BAR; PG8_SCHED;
;     __device__ __forceinline__ void operator()(const af4 (&acc)[2][2][4][2], const pg8::Unit& u, int wr, int wc, int fr_, int fq_) const {
;     ...
;         const int row0 = u.pm * 256 + wr * 64 + fr, col0 = u.pn * 256 + wc * 32 + 8 * fq;
;         v4u o[2][2][2], yv[2][2][2];
;     ...
;         MA_LOAD(0, 0);
; #pragma unroll
;         for (int b_ = 0; b_ < 4; ++b_) {
;             const int ai = b_ >> 1, mp = b_ & 1, cur = b_ & 1;
;             if (b_ + 1 < 4) { if (cur == 0) MA_LOAD(1, b_ + 1); else MA_LOAD(0, b_ + 1); }
	s_add_i32 s22, s49, s33
	s_mov_b32 m0, s22
	ds_read_b128 v[176:179], v187 offset:49152
	ds_read_b128 v[180:183], v187 offset:50176
	ds_read_b128 v[188:191], v187 offset:51200
	ds_read_b128 v[192:195], v187 offset:52224
	ds_read_b128 v[196:199], v187 offset:53248
	ds_read_b128 v[200:203], v187 offset:54272
	ds_read_b128 v[204:207], v187 offset:55296
	ds_read_b128 v[208:211], v187 offset:56320
	global_load_lds_dwordx4 v[242:243], off
	s_add_i32 m0, s22, 0x2000
	s_add_i32 s22, s50, s33
	global_load_lds_dwordx4 v[244:245], off
	s_mov_b32 m0, s22
	s_nop 0
	global_load_lds_dwordx4 v[246:247], off
	s_add_i32 m0, s22, 0x2000
	s_nop 0
	global_load_lds_dwordx4 v[248:249], off
	s_mov_b32 m0, s36
	s_nop 0
	global_load_lds_dwordx4 v[250:251], off
	s_mov_b32 m0, s37
	s_nop 0
	global_load_lds_dwordx4 v[252:253], off
	s_waitcnt vmcnt(8)
	s_waitcnt lgkmcnt(0)
	s_barrier
	s_setprio 1
	s_waitcnt lgkmcnt(0)
	v_mfma_f32_16x16x32_bf16 v[60:63], v[128:131], v[176:179], v[60:63]
	v_mfma_f32_16x16x32_bf16 v[56:59], v[136:139], v[176:179], v[56:59]
	v_mfma_f32_16x16x32_bf16 v[48:51], v[128:131], v[188:191], v[48:51]
	v_mfma_f32_16x16x32_bf16 v[40:43], v[136:139], v[188:191], v[40:43]
	v_mfma_f32_16x16x32_bf16 v[28:31], v[128:131], v[196:199], v[28:31]
	v_mfma_f32_16x16x32_bf16 v[24:27], v[136:139], v[196:199], v[24:27]
	v_mfma_f32_16x16x32_bf16 v[16:19], v[128:131], v[204:207], v[16:19]
	v_mfma_f32_16x16x32_bf16 v[8:11], v[136:139], v[204:207], v[8:11]
	v_mfma_f32_16x16x32_bf16 v[60:63], v[132:135], v[180:183], v[60:63]
	v_mfma_f32_16x16x32_bf16 v[56:59], v[140:143], v[180:183], v[56:59]
	v_mfma_f32_16x16x32_bf16 v[48:51], v[132:135], v[192:195], v[48:51]
	v_mfma_f32_16x16x32_bf16 v[40:43], v[140:143], v[192:195], v[40:43]
	v_mfma_f32_16x16x32_bf16 v[28:31], v[132:135], v[200:203], v[28:31]
	v_mfma_f32_16x16x32_bf16 v[24:27], v[140:143], v[200:203], v[24:27]
	v_mfma_f32_16x16x32_bf16 v[16:19], v[132:135], v[208:211], v[16:19]
	v_mfma_f32_16x16x32_bf16 v[8:11], v[140:143], v[208:211], v[8:11]
	s_setprio 0
	s_setprio 1
	v_mfma_f32_16x16x32_bf16 v[52:55], v[144:147], v[176:179], v[52:55]
	v_mfma_f32_16x16x32_bf16 v[44:47], v[152:155], v[176:179], v[44:47]
	v_mfma_f32_16x16x32_bf16 v[36:39], v[144:147], v[188:191], v[36:39]
	v_mfma_f32_16x16x32_bf16 v[32:35], v[152:155], v[188:191], v[32:35]
	v_mfma_f32_16x16x32_bf16 v[20:23], v[144:147], v[196:199], v[20:23]
	v_mfma_f32_16x16x32_bf16 v[12:15], v[152:155], v[196:199], v[12:15]
	v_mfma_f32_16x16x32_bf16 v[4:7], v[144:147], v[204:207], v[4:7]
	v_mfma_f32_16x16x32_bf16 v[0:3], v[152:155], v[204:207], v[0:3]
	v_mfma_f32_16x16x32_bf16 v[52:55], v[148:151], v[180:183], v[52:55]
	v_mfma_f32_16x16x32_bf16 v[44:47], v[156:159], v[180:183], v[44:47]
	v_mfma_f32_16x16x32_bf16 v[36:39], v[148:151], v[192:195], v[36:39]
	v_mfma_f32_16x16x32_bf16 v[32:35], v[156:159], v[192:195], v[32:35]
	v_mfma_f32_16x16x32_bf16 v[20:23], v[148:151], v[200:203], v[20:23]
	v_mfma_f32_16x16x32_bf16 v[12:15], v[156:159], v[200:203], v[12:15]
	v_mfma_f32_16x16x32_bf16 v[4:7], v[148:151], v[208:211], v[4:7]
	v_mfma_f32_16x16x32_bf16 v[0:3], v[156:159], v[208:211], v[0:3]
	s_setprio 0
	s_barrier
	s_add_i32 s48, s48, 2
	s_add_u32 s46, s46, 0x100
	s_addc_u32 s47, s47, 0
	s_add_u32 s18, s18, 0x100
	s_addc_u32 s19, s19, 0
	s_cmp_gt_u32 s48, 13
	s_cbranch_scc0 .LBB0_495
	s_lshl_b32 s9, s16, 8
	v_mbcnt_lo_u32_b32 v128, -1, 0
	v_mbcnt_hi_u32_b32 v128, -1, v128
	s_add_i32 s9, s9, s87
	v_and_or_b32 v183, v128, 15, s9
	s_lshl_b32 s9, s43, 8
	v_ashrrev_i32_e32 v128, 1, v128
	s_or_b32 s9, s9, s79
	v_and_b32_e32 v128, -8, v128
	v_add_u32_e32 v178, s9, v128
	v_mov_b32_e32 v128, v183
	v_ashrrev_i32_e32 v179, 31, v178
	v_ashrrev_i32_e32 v129, 31, v128
	v_lshlrev_b64 v[128:129], 10, v[128:129]
	v_lshl_add_u64 v[128:129], v[128:129], 0, v[178:179]
	v_lshlrev_b64 v[128:129], 1, v[128:129]
	v_lshl_add_u64 v[130:131], s[2:3], 0, v[128:129]
	global_load_dwordx4 v[188:191], v[130:131], off
	v_lshl_add_u64 v[128:129], s[0:1], 0, v[128:129]
	global_load_dwordx4 v[192:195], v[128:129], off
	global_load_dwordx4 v[196:199], v[130:131], off offset:256
	global_load_dwordx4 v[200:203], v[128:129], off offset:256
	v_add_co_u32_e32 v128, vcc, s38, v128
	v_or_b32_e32 v180, 32, v183
	s_nop 0
	v_addc_co_u32_e32 v129, vcc, 0, v129, vcc
	v_add_co_u32_e32 v130, vcc, s38, v130
	v_mov_b32_e32 v132, v180
	s_nop 0
	v_addc_co_u32_e32 v131, vcc, 0, v131, vcc
	global_load_dwordx4 v[204:207], v[128:129], off
	global_load_dwordx4 v[208:211], v[128:129], off offset:256
	global_load_dwordx4 v[212:215], v[130:131], off
	global_load_dwordx4 v[216:219], v[130:131], off offset:256
	v_mov_b32_e32 v220, v183
	v_ashrrev_i32_e32 v133, 31, v132
	v_lshlrev_b64 v[128:129], 10, v[132:133]
	v_lshl_add_u64 v[128:129], v[128:129], 0, v[178:179]
	v_lshlrev_b64 v[128:129], 1, v[128:129]
	v_lshl_add_u64 v[130:131], s[0:1], 0, v[128:129]
	v_lshl_add_u64 v[128:129], s[2:3], 0, v[128:129]
	global_load_dwordx4 v[152:155], v[130:131], off
	global_load_dwordx4 v[144:147], v[130:131], off offset:256
	global_load_dwordx4 v[156:159], v[128:129], off
	global_load_dwordx4 v[148:151], v[128:129], off offset:256
	v_add_co_u32_e32 v130, vcc, s38, v130
	v_lshlrev_b64 v[176:177], 1, v[178:179]
	s_nop 0
	v_addc_co_u32_e32 v131, vcc, 0, v131, vcc
	v_add_co_u32_e32 v132, vcc, s38, v128
	v_add_u32_e32 v182, 0x80, v183
	s_nop 0
	v_addc_co_u32_e32 v133, vcc, 0, v129, vcc
	global_load_dwordx4 v[136:139], v[130:131], off
	s_nop 0
	global_load_dwordx4 v[128:131], v[130:131], off offset:256
	s_nop 0
	global_load_dwordx4 v[140:143], v[132:133], off
	s_nop 0
	global_load_dwordx4 v[132:135], v[132:133], off offset:256
	s_mov_b32 s43, s8
	v_ashrrev_i32_e32 v221, 31, v220
	v_lshlrev_b64 v[220:221], 11, v[220:221]
	v_lshl_add_u64 v[220:221], s[0:1], 0, v[220:221]
	v_lshl_add_u64 v[220:221], v[220:221], 0, v[176:177]
	s_mov_b32 s16, s10
	s_mov_b64 s[18:19], s[14:15]
	s_mov_b64 s[20:21], s[12:13]
	s_waitcnt vmcnt(0)
; __device__ __forceinline__ unsigned cvtpk(float lo, float hi) { f32x2 v = {lo, hi}; bf16x2_t b = __builtin_convertvector(v, bf16x2_t); return __builtin_bit_cast(unsigned, b); }
; __device__ __forceinline__ float bflo(unsigned u) { return __uint_as_float(u << 16); }
; __device__ __forceinline__ float bfhi(unsigned u) { return __uint_as_float(u & 0xffff0000u); }
;     __device__ __forceinline__ void operator()(const af4 (&acc)[2][2][4][2], const pg8::Unit& u, int wr, int wc, int fr_, int fq_) const {
;     ...
;         MA_LOAD(0, 0);
; #pragma unroll
;         for (int b_ = 0; b_ < 4; ++b_) {
;             const int ai = b_ >> 1, mp = b_ & 1, cur = b_ & 1;
;             if (b_ + 1 < 4) { if (cur == 0) MA_LOAD(1, b_ + 1); else MA_LOAD(0, b_ + 1); }
;             int RRb = row0 + ai * 128 + mp * 32; asm volatile("" : "+v"(RRb));
;             const size_t ob = (size_t)RRb * 1024 + col0;
; #pragma unroll
;             for (int mi = 0; mi < 2; ++mi)
; #pragma unroll
;                 for (int bj = 0; bj < 2; ++bj) { const af4 v0 = acc[ai][bj][mp * 2 + mi][0], v1 = acc[ai][bj][mp * 2 + mi][1]; const v4u oo = o[cur][mi][bj], y = yv[cur][mi][bj];
;                     v4u w; w.x = cvtpk(bflo(y.x) + v0[0] * bflo(oo.x), bfhi(y.x) + v0[1] * bfhi(oo.x)); w.y = cvtpk(bflo(y.y) + v0[2] * bflo(oo.y), bfhi(y.y) + v0[3] * bfhi(oo.y));
;                     w.z = cvtpk(bflo(y.z) + v1[0] * bflo(oo.z), bfhi(y.z) + v1[1] * bfhi(oo.z)); w.w = cvtpk(bflo(y.w) + v1[2] * bflo(oo.w), bfhi(y.w) + v1[3] * bfhi(oo.w));
;                     *(v4u*)(G + ob + mi * 16 * 1024 + bj * 128) = w; }
	v_lshlrev_b32_e32 v224, 16, v192
	v_lshlrev_b32_e32 v222, 16, v188
	v_and_b32_e32 v223, 0xffff0000, v188
	v_and_b32_e32 v225, 0xffff0000, v192
	v_lshlrev_b32_e32 v188, 16, v189
	v_and_b32_e32 v189, 0xffff0000, v189
	v_lshlrev_b32_e32 v192, 16, v193
	v_and_b32_e32 v193, 0xffff0000, v193
	v_lshlrev_b32_e32 v226, 16, v190
	v_and_b32_e32 v227, 0xffff0000, v190
	v_lshlrev_b32_e32 v228, 16, v194
	v_and_b32_e32 v229, 0xffff0000, v194
	v_lshlrev_b32_e32 v190, 16, v191
	v_and_b32_e32 v191, 0xffff0000, v191
	v_lshlrev_b32_e32 v194, 16, v195
	v_and_b32_e32 v195, 0xffff0000, v195
	v_pk_fma_f32 v[124:125], v[124:125], v[224:225], v[222:223]
	v_pk_fma_f32 v[126:127], v[126:127], v[192:193], v[188:189]
	v_pk_fma_f32 v[188:189], v[120:121], v[228:229], v[226:227]
	v_pk_fma_f32 v[190:191], v[122:123], v[194:195], v[190:191]
	v_cvt_pk_bf16_f32 v120, v124, v125
	v_cvt_pk_bf16_f32 v121, v126, v127
	v_cvt_pk_bf16_f32 v122, v188, v189
	v_cvt_pk_bf16_f32 v123, v190, v191
	v_lshlrev_b32_e32 v230, 16, v196
	v_and_b32_e32 v231, 0xffff0000, v196
	v_lshlrev_b32_e32 v232, 16, v200
	global_store_dwordx4 v[220:221], v[120:123], off
	v_and_b32_e32 v233, 0xffff0000, v200
	v_pk_fma_f32 v[116:117], v[116:117], v[232:233], v[230:231]
	v_lshlrev_b32_e32 v120, 16, v197
	v_and_b32_e32 v121, 0xffff0000, v197
	v_lshlrev_b32_e32 v122, 16, v201
	v_and_b32_e32 v123, 0xffff0000, v201
	v_pk_fma_f32 v[118:119], v[118:119], v[122:123], v[120:121]
	v_cvt_pk_bf16_f32 v116, v116, v117
	v_cvt_pk_bf16_f32 v117, v118, v119
	v_lshlrev_b32_e32 v118, 16, v198
	v_and_b32_e32 v119, 0xffff0000, v198
	v_lshlrev_b32_e32 v120, 16, v202
	v_and_b32_e32 v121, 0xffff0000, v202
	v_pk_fma_f32 v[108:109], v[108:109], v[120:121], v[118:119]
	v_lshlrev_b32_e32 v120, 16, v203
	v_cvt_pk_bf16_f32 v118, v108, v109
	v_lshlrev_b32_e32 v108, 16, v199
	v_and_b32_e32 v109, 0xffff0000, v199
	v_and_b32_e32 v121, 0xffff0000, v203
	v_pk_fma_f32 v[108:109], v[110:111], v[120:121], v[108:109]
	v_lshlrev_b32_e32 v110, 16, v204
	v_cvt_pk_bf16_f32 v119, v108, v109
	v_lshlrev_b32_e32 v108, 16, v212
	v_and_b32_e32 v109, 0xffff0000, v212
	v_and_b32_e32 v111, 0xffff0000, v204
	v_pk_fma_f32 v[108:109], v[112:113], v[110:111], v[108:109]
	v_lshlrev_b32_e32 v110, 16, v213
	v_and_b32_e32 v111, 0xffff0000, v213
	v_lshlrev_b32_e32 v112, 16, v205
	v_and_b32_e32 v113, 0xffff0000, v205
	v_pk_fma_f32 v[110:111], v[114:115], v[112:113], v[110:111]
	v_cvt_pk_bf16_f32 v108, v108, v109
	v_cvt_pk_bf16_f32 v109, v110, v111
	v_lshlrev_b32_e32 v110, 16, v214
	v_and_b32_e32 v111, 0xffff0000, v214
	v_lshlrev_b32_e32 v112, 16, v206
	v_and_b32_e32 v113, 0xffff0000, v206
	v_pk_fma_f32 v[104:105], v[104:105], v[112:113], v[110:111]
	v_lshlrev_b32_e32 v112, 16, v207
	v_cvt_pk_bf16_f32 v110, v104, v105
	v_lshlrev_b32_e32 v104, 16, v215
	v_and_b32_e32 v105, 0xffff0000, v215
	v_and_b32_e32 v113, 0xffff0000, v207
	v_pk_fma_f32 v[104:105], v[106:107], v[112:113], v[104:105]
	v_lshlrev_b32_e32 v106, 16, v216
	v_cvt_pk_bf16_f32 v111, v104, v105
	v_add_co_u32_e32 v104, vcc, s38, v220
	v_and_b32_e32 v107, 0xffff0000, v216
	s_nop 0
	v_addc_co_u32_e32 v105, vcc, 0, v221, vcc
	global_store_dwordx4 v[104:105], v[108:111], off
	global_store_dwordx4 v[220:221], v[116:119], off offset:256
	v_lshlrev_b32_e32 v188, 16, v156
	v_lshlrev_b32_e32 v108, 16, v208
	v_and_b32_e32 v109, 0xffff0000, v208
	v_pk_fma_f32 v[100:101], v[100:101], v[108:109], v[106:107]
	v_lshlrev_b32_e32 v106, 16, v217
	v_and_b32_e32 v107, 0xffff0000, v217
	v_lshlrev_b32_e32 v108, 16, v209
	v_and_b32_e32 v109, 0xffff0000, v209
	v_pk_fma_f32 v[102:103], v[102:103], v[108:109], v[106:107]
	v_cvt_pk_bf16_f32 v100, v100, v101
	v_cvt_pk_bf16_f32 v101, v102, v103
	v_lshlrev_b32_e32 v102, 16, v218
	v_and_b32_e32 v103, 0xffff0000, v218
	v_lshlrev_b32_e32 v106, 16, v210
	v_and_b32_e32 v107, 0xffff0000, v210
	v_pk_fma_f32 v[96:97], v[96:97], v[106:107], v[102:103]
	v_lshlrev_b32_e32 v106, 16, v211
	v_cvt_pk_bf16_f32 v102, v96, v97
	v_lshlrev_b32_e32 v96, 16, v219
	v_and_b32_e32 v97, 0xffff0000, v219
	v_and_b32_e32 v107, 0xffff0000, v211
	v_pk_fma_f32 v[96:97], v[98:99], v[106:107], v[96:97]
	v_and_b32_e32 v189, 0xffff0000, v156
	v_cvt_pk_bf16_f32 v103, v96, v97
	global_store_dwordx4 v[104:105], v[100:103], off offset:256
	v_mov_b32_e32 v96, v182
	v_lshlrev_b32_e32 v190, 16, v152
	v_ashrrev_i32_e32 v97, 31, v96
	v_lshlrev_b64 v[96:97], 10, v[96:97]
	v_lshl_add_u64 v[96:97], v[96:97], 0, v[178:179]
	v_lshlrev_b64 v[96:97], 1, v[96:97]
	v_lshl_add_u64 v[98:99], s[0:1], 0, v[96:97]
	v_lshl_add_u64 v[96:97], s[2:3], 0, v[96:97]
	global_load_dwordx4 v[120:123], v[98:99], off
	global_load_dwordx4 v[112:115], v[98:99], off offset:256
	global_load_dwordx4 v[124:127], v[96:97], off
	global_load_dwordx4 v[116:119], v[96:97], off offset:256
	v_add_co_u32_e32 v98, vcc, s38, v98
	v_and_b32_e32 v191, 0xffff0000, v152
	v_lshlrev_b32_e32 v156, 16, v157
	v_and_b32_e32 v157, 0xffff0000, v157
	v_lshlrev_b32_e32 v152, 16, v153
	v_and_b32_e32 v153, 0xffff0000, v153
	v_addc_co_u32_e32 v99, vcc, 0, v99, vcc
	v_pk_fma_f32 v[92:93], v[92:93], v[190:191], v[188:189]
	v_pk_fma_f32 v[94:95], v[94:95], v[152:153], v[156:157]
	v_add_co_u32_e32 v100, vcc, s38, v96
	v_cvt_pk_bf16_f32 v92, v92, v93
	v_cvt_pk_bf16_f32 v93, v94, v95
	v_lshlrev_b32_e32 v94, 16, v158
	v_and_b32_e32 v95, 0xffff0000, v158
	v_lshlrev_b32_e32 v152, 16, v154
	v_and_b32_e32 v153, 0xffff0000, v154
	v_addc_co_u32_e32 v101, vcc, 0, v97, vcc
	v_pk_fma_f32 v[88:89], v[88:89], v[152:153], v[94:95]
	global_load_dwordx4 v[104:107], v[98:99], off
	s_nop 0
	global_load_dwordx4 v[96:99], v[98:99], off offset:256
	s_nop 0
	global_load_dwordx4 v[108:111], v[100:101], off
	s_nop 0
; __device__ __forceinline__ unsigned cvtpk(float lo, float hi) { f32x2 v = {lo, hi}; bf16x2_t b = __builtin_convertvector(v, bf16x2_t); return __builtin_bit_cast(unsigned, b); }
; __device__ __forceinline__ float bflo(unsigned u) { return __uint_as_float(u << 16); }
; __device__ __forceinline__ float bfhi(unsigned u) { return __uint_as_float(u & 0xffff0000u); }
;     __device__ __forceinline__ void operator()(const af4 (&acc)[2][2][4][2], const pg8::Unit& u, int wr, int wc, int fr_, int fq_) const {
;     ...
;         MA_LOAD(0, 0);
; #pragma unroll
;         for (int b_ = 0; b_ < 4; ++b_) {
;             const int ai = b_ >> 1, mp = b_ & 1, cur = b_ & 1;
;             if (b_ + 1 < 4) { if (cur == 0) MA_LOAD(1, b_ + 1); else MA_LOAD(0, b_ + 1); }
;             int RRb = row0 + ai * 128 + mp * 32; asm volatile("" : "+v"(RRb));
;             const size_t ob = (size_t)RRb * 1024 + col0;
; #pragma unroll
;             for (int mi = 0; mi < 2; ++mi)
; #pragma unroll
;                 for (int bj = 0; bj < 2; ++bj) { const af4 v0 = acc[ai][bj][mp * 2 + mi][0], v1 = acc[ai][bj][mp * 2 + mi][1]; const v4u oo = o[cur][mi][bj], y = yv[cur][mi][bj];
;                     v4u w; w.x = cvtpk(bflo(y.x) + v0[0] * bflo(oo.x), bfhi(y.x) + v0[1] * bfhi(oo.x)); w.y = cvtpk(bflo(y.y) + v0[2] * bflo(oo.y), bfhi(y.y) + v0[3] * bfhi(oo.y));
;                     w.z = cvtpk(bflo(y.z) + v1[0] * bflo(oo.z), bfhi(y.z) + v1[1] * bfhi(oo.z)); w.w = cvtpk(bflo(y.w) + v1[2] * bflo(oo.w), bfhi(y.w) + v1[3] * bfhi(oo.w));
;                     *(v4u*)(G + ob + mi * 16 * 1024 + bj * 128) = w; }
	global_load_dwordx4 v[100:103], v[100:101], off offset:256
	v_cvt_pk_bf16_f32 v94, v88, v89
	v_ashrrev_i32_e32 v181, 31, v180
	v_lshlrev_b32_e32 v88, 16, v159
	v_and_b32_e32 v89, 0xffff0000, v159
	v_lshlrev_b32_e32 v152, 16, v155
	v_and_b32_e32 v153, 0xffff0000, v155
	v_lshlrev_b64 v[180:181], 11, v[180:181]
	v_pk_fma_f32 v[88:89], v[90:91], v[152:153], v[88:89]
	v_lshlrev_b32_e32 v90, 16, v148
	v_cvt_pk_bf16_f32 v95, v88, v89
	v_lshl_add_u64 v[88:89], s[0:1], 0, v[180:181]
	v_lshl_add_u64 v[88:89], v[88:89], 0, v[176:177]
	global_store_dwordx4 v[88:89], v[92:95], off
	v_and_b32_e32 v91, 0xffff0000, v148
	s_nop 0
	v_lshlrev_b32_e32 v92, 16, v144
	v_and_b32_e32 v93, 0xffff0000, v144
	v_pk_fma_f32 v[84:85], v[84:85], v[92:93], v[90:91]
	v_lshlrev_b32_e32 v90, 16, v149
	v_and_b32_e32 v91, 0xffff0000, v149
	v_lshlrev_b32_e32 v92, 16, v145
	v_and_b32_e32 v93, 0xffff0000, v145
	v_pk_fma_f32 v[86:87], v[86:87], v[92:93], v[90:91]
	v_cvt_pk_bf16_f32 v84, v84, v85
	v_cvt_pk_bf16_f32 v85, v86, v87
	v_lshlrev_b32_e32 v86, 16, v150
	v_and_b32_e32 v87, 0xffff0000, v150
	v_lshlrev_b32_e32 v90, 16, v146
	v_and_b32_e32 v91, 0xffff0000, v146
	v_pk_fma_f32 v[76:77], v[76:77], v[90:91], v[86:87]
	v_lshlrev_b32_e32 v90, 16, v147
	v_cvt_pk_bf16_f32 v86, v76, v77
	v_lshlrev_b32_e32 v76, 16, v151
	v_and_b32_e32 v77, 0xffff0000, v151
	v_and_b32_e32 v91, 0xffff0000, v147
	v_pk_fma_f32 v[76:77], v[78:79], v[90:91], v[76:77]
	v_lshlrev_b32_e32 v78, 16, v136
	v_cvt_pk_bf16_f32 v87, v76, v77
	v_lshlrev_b32_e32 v76, 16, v140
	v_and_b32_e32 v77, 0xffff0000, v140
	v_and_b32_e32 v79, 0xffff0000, v136
	v_pk_fma_f32 v[76:77], v[80:81], v[78:79], v[76:77]
	v_lshlrev_b32_e32 v78, 16, v141
	v_and_b32_e32 v79, 0xffff0000, v141
	v_lshlrev_b32_e32 v80, 16, v137
	v_and_b32_e32 v81, 0xffff0000, v137
	v_pk_fma_f32 v[78:79], v[82:83], v[80:81], v[78:79]
	v_cvt_pk_bf16_f32 v76, v76, v77
	v_cvt_pk_bf16_f32 v77, v78, v79
	v_lshlrev_b32_e32 v78, 16, v142
	v_and_b32_e32 v79, 0xffff0000, v142
	v_lshlrev_b32_e32 v80, 16, v138
	v_and_b32_e32 v81, 0xffff0000, v138
	v_pk_fma_f32 v[72:73], v[72:73], v[80:81], v[78:79]
	v_lshlrev_b32_e32 v80, 16, v139
	v_cvt_pk_bf16_f32 v78, v72, v73
	v_lshlrev_b32_e32 v72, 16, v143
	v_and_b32_e32 v73, 0xffff0000, v143
	v_and_b32_e32 v81, 0xffff0000, v139
	v_pk_fma_f32 v[72:73], v[74:75], v[80:81], v[72:73]
	v_lshlrev_b32_e32 v74, 16, v132
	v_cvt_pk_bf16_f32 v79, v72, v73
	v_add_co_u32_e32 v72, vcc, s38, v88
	v_and_b32_e32 v75, 0xffff0000, v132
	s_nop 0
	v_addc_co_u32_e32 v73, vcc, 0, v89, vcc
	global_store_dwordx4 v[72:73], v[76:79], off
	global_store_dwordx4 v[88:89], v[84:87], off offset:256
	s_waitcnt vmcnt(8)
	v_lshlrev_b32_e32 v132, 16, v124
	v_lshlrev_b32_e32 v76, 16, v128
	v_and_b32_e32 v77, 0xffff0000, v128
	v_pk_fma_f32 v[68:69], v[68:69], v[76:77], v[74:75]
	v_lshlrev_b32_e32 v74, 16, v133
	v_and_b32_e32 v75, 0xffff0000, v133
	v_lshlrev_b32_e32 v76, 16, v129
	v_and_b32_e32 v77, 0xffff0000, v129
	v_pk_fma_f32 v[70:71], v[70:71], v[76:77], v[74:75]
	v_cvt_pk_bf16_f32 v68, v68, v69
	v_cvt_pk_bf16_f32 v69, v70, v71
	v_lshlrev_b32_e32 v70, 16, v134
	v_and_b32_e32 v71, 0xffff0000, v134
	v_lshlrev_b32_e32 v74, 16, v130
	v_and_b32_e32 v75, 0xffff0000, v130
	v_pk_fma_f32 v[64:65], v[64:65], v[74:75], v[70:71]
	v_lshlrev_b32_e32 v74, 16, v131
	v_cvt_pk_bf16_f32 v70, v64, v65
	v_lshlrev_b32_e32 v64, 16, v135
	v_and_b32_e32 v65, 0xffff0000, v135
	v_and_b32_e32 v75, 0xffff0000, v131
	v_pk_fma_f32 v[64:65], v[66:67], v[74:75], v[64:65]
	v_add_u32_e32 v128, 0xa0, v183
	v_cvt_pk_bf16_f32 v71, v64, v65
	global_store_dwordx4 v[72:73], v[68:71], off offset:256
	v_mov_b32_e32 v64, v128
	v_and_b32_e32 v133, 0xffff0000, v124
	v_ashrrev_i32_e32 v65, 31, v64
	v_lshlrev_b64 v[64:65], 10, v[64:65]
	v_lshl_add_u64 v[64:65], v[64:65], 0, v[178:179]
	v_lshlrev_b64 v[64:65], 1, v[64:65]
	v_lshl_add_u64 v[66:67], s[0:1], 0, v[64:65]
	v_lshl_add_u64 v[64:65], s[2:3], 0, v[64:65]
	global_load_dwordx4 v[88:91], v[66:67], off
	global_load_dwordx4 v[80:83], v[66:67], off offset:256
	global_load_dwordx4 v[92:95], v[64:65], off
	global_load_dwordx4 v[84:87], v[64:65], off offset:256
	v_add_co_u32_e32 v66, vcc, s38, v66
	v_lshlrev_b32_e32 v134, 16, v120
	s_nop 0
	v_addc_co_u32_e32 v67, vcc, 0, v67, vcc
	v_add_co_u32_e32 v68, vcc, s38, v64
	v_and_b32_e32 v135, 0xffff0000, v120
	s_nop 0
	v_addc_co_u32_e32 v69, vcc, 0, v65, vcc
	global_load_dwordx4 v[72:75], v[66:67], off
	s_nop 0
	global_load_dwordx4 v[64:67], v[66:67], off offset:256
	s_nop 0
	global_load_dwordx4 v[76:79], v[68:69], off
	s_nop 0
	global_load_dwordx4 v[68:71], v[68:69], off offset:256
	v_lshlrev_b32_e32 v124, 16, v125
	v_and_b32_e32 v125, 0xffff0000, v125
	v_lshlrev_b32_e32 v120, 16, v121
	v_and_b32_e32 v121, 0xffff0000, v121
	v_pk_fma_f32 v[60:61], v[60:61], v[134:135], v[132:133]
	v_pk_fma_f32 v[62:63], v[62:63], v[120:121], v[124:125]
	v_cvt_pk_bf16_f32 v60, v60, v61
	v_cvt_pk_bf16_f32 v61, v62, v63
	v_lshlrev_b32_e32 v62, 16, v126
	v_and_b32_e32 v63, 0xffff0000, v126
	v_lshlrev_b32_e32 v120, 16, v122
	v_and_b32_e32 v121, 0xffff0000, v122
	v_pk_fma_f32 v[56:57], v[56:57], v[120:121], v[62:63]
	v_lshlrev_b32_e32 v120, 16, v123
	v_ashrrev_i32_e32 v183, 31, v182
	v_cvt_pk_bf16_f32 v62, v56, v57
	v_lshlrev_b32_e32 v56, 16, v127
	v_and_b32_e32 v57, 0xffff0000, v127
	v_and_b32_e32 v121, 0xffff0000, v123
	v_lshlrev_b64 v[130:131], 11, v[182:183]
	v_pk_fma_f32 v[56:57], v[58:59], v[120:121], v[56:57]
	s_waitcnt vmcnt(16)
; __device__ __forceinline__ unsigned cvtpk(float lo, float hi) { f32x2 v = {lo, hi}; bf16x2_t b = __builtin_convertvector(v, bf16x2_t); return __builtin_bit_cast(unsigned, b); }
; __device__ __forceinline__ float bflo(unsigned u) { return __uint_as_float(u << 16); }
; __device__ __forceinline__ float bfhi(unsigned u) { return __uint_as_float(u & 0xffff0000u); }
;     __device__ __forceinline__ void operator()(const af4 (&acc)[2][2][4][2], const pg8::Unit& u, int wr, int wc, int fr_, int fq_) const {
;     ...
;         for (int b_ = 0; b_ < 4; ++b_) {
;             const int ai = b_ >> 1, mp = b_ & 1, cur = b_ & 1;
;             if (b_ + 1 < 4) { if (cur == 0) MA_LOAD(1, b_ + 1); else MA_LOAD(0, b_ + 1); }
;             int RRb = row0 + ai * 128 + mp * 32; asm volatile("" : "+v"(RRb));
;             const size_t ob = (size_t)RRb * 1024 + col0;
; #pragma unroll
;             for (int mi = 0; mi < 2; ++mi)
; #pragma unroll
;                 for (int bj = 0; bj < 2; ++bj) { const af4 v0 = acc[ai][bj][mp * 2 + mi][0], v1 = acc[ai][bj][mp * 2 + mi][1]; const v4u oo = o[cur][mi][bj], y = yv[cur][mi][bj];
;                     v4u w; w.x = cvtpk(bflo(y.x) + v0[0] * bflo(oo.x), bfhi(y.x) + v0[1] * bfhi(oo.x)); w.y = cvtpk(bflo(y.y) + v0[2] * bflo(oo.y), bfhi(y.y) + v0[3] * bfhi(oo.y));
;                     w.z = cvtpk(bflo(y.z) + v1[0] * bflo(oo.z), bfhi(y.z) + v1[1] * bfhi(oo.z)); w.w = cvtpk(bflo(y.w) + v1[2] * bflo(oo.w), bfhi(y.w) + v1[3] * bfhi(oo.w));
;                     *(v4u*)(G + ob + mi * 16 * 1024 + bj * 128) = w; }
	v_lshlrev_b32_e32 v58, 16, v116
	v_cvt_pk_bf16_f32 v63, v56, v57
	v_lshl_add_u64 v[56:57], s[0:1], 0, v[130:131]
	v_lshl_add_u64 v[56:57], v[56:57], 0, v[176:177]
	global_store_dwordx4 v[56:57], v[60:63], off
	v_and_b32_e32 v59, 0xffff0000, v116
	s_nop 0
	v_lshlrev_b32_e32 v60, 16, v112
	v_and_b32_e32 v61, 0xffff0000, v112
	v_pk_fma_f32 v[52:53], v[52:53], v[60:61], v[58:59]
	v_lshlrev_b32_e32 v58, 16, v117
	v_and_b32_e32 v59, 0xffff0000, v117
	v_lshlrev_b32_e32 v60, 16, v113
	v_and_b32_e32 v61, 0xffff0000, v113
	v_pk_fma_f32 v[54:55], v[54:55], v[60:61], v[58:59]
	v_cvt_pk_bf16_f32 v52, v52, v53
	v_cvt_pk_bf16_f32 v53, v54, v55
	v_lshlrev_b32_e32 v54, 16, v118
	v_and_b32_e32 v55, 0xffff0000, v118
	v_lshlrev_b32_e32 v58, 16, v114
	v_and_b32_e32 v59, 0xffff0000, v114
	v_pk_fma_f32 v[44:45], v[44:45], v[58:59], v[54:55]
	v_lshlrev_b32_e32 v58, 16, v115
	v_cvt_pk_bf16_f32 v54, v44, v45
	v_lshlrev_b32_e32 v44, 16, v119
	v_and_b32_e32 v45, 0xffff0000, v119
	v_and_b32_e32 v59, 0xffff0000, v115
	v_pk_fma_f32 v[44:45], v[46:47], v[58:59], v[44:45]
	s_waitcnt vmcnt(16)
	v_lshlrev_b32_e32 v46, 16, v104
	v_cvt_pk_bf16_f32 v55, v44, v45
	s_waitcnt vmcnt(14)
	v_lshlrev_b32_e32 v44, 16, v108
	v_and_b32_e32 v45, 0xffff0000, v108
	v_and_b32_e32 v47, 0xffff0000, v104
	v_pk_fma_f32 v[44:45], v[48:49], v[46:47], v[44:45]
	v_lshlrev_b32_e32 v46, 16, v109
	v_and_b32_e32 v47, 0xffff0000, v109
	v_lshlrev_b32_e32 v48, 16, v105
	v_and_b32_e32 v49, 0xffff0000, v105
	v_pk_fma_f32 v[46:47], v[50:51], v[48:49], v[46:47]
	v_cvt_pk_bf16_f32 v44, v44, v45
	v_cvt_pk_bf16_f32 v45, v46, v47
	v_lshlrev_b32_e32 v46, 16, v110
	v_and_b32_e32 v47, 0xffff0000, v110
	v_lshlrev_b32_e32 v48, 16, v106
	v_and_b32_e32 v49, 0xffff0000, v106
	v_pk_fma_f32 v[40:41], v[40:41], v[48:49], v[46:47]
	v_lshlrev_b32_e32 v48, 16, v107
	v_cvt_pk_bf16_f32 v46, v40, v41
	v_lshlrev_b32_e32 v40, 16, v111
	v_and_b32_e32 v41, 0xffff0000, v111
	v_and_b32_e32 v49, 0xffff0000, v107
	v_pk_fma_f32 v[40:41], v[42:43], v[48:49], v[40:41]
	s_waitcnt vmcnt(13)
	v_lshlrev_b32_e32 v42, 16, v100
	v_cvt_pk_bf16_f32 v47, v40, v41
	v_add_co_u32_e32 v40, vcc, s38, v56
	v_and_b32_e32 v43, 0xffff0000, v100
	s_nop 0
	v_addc_co_u32_e32 v41, vcc, 0, v57, vcc
	global_store_dwordx4 v[40:41], v[44:47], off
	global_store_dwordx4 v[56:57], v[52:55], off offset:256
	s_nop 0
	v_lshlrev_b32_e32 v44, 16, v96
	v_and_b32_e32 v45, 0xffff0000, v96
	v_pk_fma_f32 v[36:37], v[36:37], v[44:45], v[42:43]
	v_lshlrev_b32_e32 v42, 16, v101
	v_and_b32_e32 v43, 0xffff0000, v101
	v_lshlrev_b32_e32 v44, 16, v97
	v_and_b32_e32 v45, 0xffff0000, v97
	v_pk_fma_f32 v[38:39], v[38:39], v[44:45], v[42:43]
	v_cvt_pk_bf16_f32 v36, v36, v37
	v_cvt_pk_bf16_f32 v37, v38, v39
	v_lshlrev_b32_e32 v38, 16, v102
	v_and_b32_e32 v39, 0xffff0000, v102
	v_lshlrev_b32_e32 v42, 16, v98
	v_and_b32_e32 v43, 0xffff0000, v98
	v_pk_fma_f32 v[32:33], v[32:33], v[42:43], v[38:39]
	v_lshlrev_b32_e32 v42, 16, v99
	v_cvt_pk_bf16_f32 v38, v32, v33
	v_lshlrev_b32_e32 v32, 16, v103
	v_and_b32_e32 v33, 0xffff0000, v103
	v_and_b32_e32 v43, 0xffff0000, v99
	v_pk_fma_f32 v[32:33], v[34:35], v[42:43], v[32:33]
	s_waitcnt vmcnt(8)
	v_lshlrev_b32_e32 v34, 16, v92
	v_cvt_pk_bf16_f32 v39, v32, v33
	global_store_dwordx4 v[40:41], v[36:39], off offset:256
	v_and_b32_e32 v35, 0xffff0000, v92
	s_nop 0
	v_lshlrev_b32_e32 v36, 16, v88
	v_and_b32_e32 v37, 0xffff0000, v88
	v_pk_fma_f32 v[28:29], v[28:29], v[36:37], v[34:35]
	v_lshlrev_b32_e32 v34, 16, v93
	v_and_b32_e32 v35, 0xffff0000, v93
	v_lshlrev_b32_e32 v36, 16, v89
	v_and_b32_e32 v37, 0xffff0000, v89
	v_pk_fma_f32 v[30:31], v[30:31], v[36:37], v[34:35]
	v_cvt_pk_bf16_f32 v28, v28, v29
	v_cvt_pk_bf16_f32 v29, v30, v31
	v_lshlrev_b32_e32 v30, 16, v94
	v_and_b32_e32 v31, 0xffff0000, v94
	v_lshlrev_b32_e32 v34, 16, v90
	v_and_b32_e32 v35, 0xffff0000, v90
	v_pk_fma_f32 v[24:25], v[24:25], v[34:35], v[30:31]
	v_ashrrev_i32_e32 v129, 31, v128
	v_cvt_pk_bf16_f32 v30, v24, v25
	v_lshlrev_b32_e32 v24, 16, v95
	v_and_b32_e32 v25, 0xffff0000, v95
	v_lshlrev_b32_e32 v34, 16, v91
	v_and_b32_e32 v35, 0xffff0000, v91
	v_lshlrev_b64 v[32:33], 11, v[128:129]
	v_pk_fma_f32 v[24:25], v[26:27], v[34:35], v[24:25]
	s_waitcnt vmcnt(8)
; #define PG8_WAIT_V(n) asm volatile("s_waitcnt vmcnt(" #n ")" ::: "memory")
; #define PG8_BAR __builtin_amdgcn_s_barrier()
; __device__ __forceinline__ unsigned cvtpk(float lo, float hi) { f32x2 v = {lo, hi}; bf16x2_t b = __builtin_convertvector(v, bf16x2_t); return __builtin_bit_cast(unsigned, b); }
; __device__ __forceinline__ float bflo(unsigned u) { return __uint_as_float(u << 16); }
; __device__ __forceinline__ float bfhi(unsigned u) { return __uint_as_float(u & 0xffff0000u); }
; template <class Epi, class Sched, bool ALIGN_EPI = false, bool SP2 = false>
; __device__ __forceinline__ void gemm_phase(PG8_LAS unsigned char* lds, const Gemm g, const Sched& S, const Epi& E, const int wave_s) {
;     ...
;     PG8_WAIT_V(0);
;     if constexpr (!ALIGN_EPI) { if (wr == 0) PG8_BAR; }
;     PG8_BAR;
;     __device__ __forceinline__ void operator()(const af4 (&acc)[2][2][4][2], const pg8::Unit& u, int wr, int wc, int fr_, int fq_) const {
;     ...
;         for (int b_ = 0; b_ < 4; ++b_) {
;             const int ai = b_ >> 1, mp = b_ & 1, cur = b_ & 1;
;             if (b_ + 1 < 4) { if (cur == 0) MA_LOAD(1, b_ + 1); else MA_LOAD(0, b_ + 1); }
;             int RRb = row0 + ai * 128 + mp * 32; asm volatile("" : "+v"(RRb));
;             const size_t ob = (size_t)RRb * 1024 + col0;
; #pragma unroll
;             for (int mi = 0; mi < 2; ++mi)
; #pragma unroll
;                 for (int bj = 0; bj < 2; ++bj) { const af4 v0 = acc[ai][bj][mp * 2 + mi][0], v1 = acc[ai][bj][mp * 2 + mi][1]; const v4u oo = o[cur][mi][bj], y = yv[cur][mi][bj];
;                     v4u w; w.x = cvtpk(bflo(y.x) + v0[0] * bflo(oo.x), bfhi(y.x) + v0[1] * bfhi(oo.x)); w.y = cvtpk(bflo(y.y) + v0[2] * bflo(oo.y), bfhi(y.y) + v0[3] * bfhi(oo.y));
;                     w.z = cvtpk(bflo(y.z) + v1[0] * bflo(oo.z), bfhi(y.z) + v1[1] * bfhi(oo.z)); w.w = cvtpk(bflo(y.w) + v1[2] * bflo(oo.w), bfhi(y.w) + v1[3] * bfhi(oo.w));
;                     *(v4u*)(G + ob + mi * 16 * 1024 + bj * 128) = w; }
;             asm volatile("" ::: "memory");
;         }
	v_lshlrev_b32_e32 v26, 16, v84
	v_cvt_pk_bf16_f32 v31, v24, v25
	v_lshl_add_u64 v[24:25], s[0:1], 0, v[32:33]
	v_lshl_add_u64 v[24:25], v[24:25], 0, v[176:177]
	global_store_dwordx4 v[24:25], v[28:31], off
	v_and_b32_e32 v27, 0xffff0000, v84
	s_nop 0
	v_lshlrev_b32_e32 v28, 16, v80
	v_and_b32_e32 v29, 0xffff0000, v80
	v_pk_fma_f32 v[20:21], v[20:21], v[28:29], v[26:27]
	v_lshlrev_b32_e32 v26, 16, v85
	v_and_b32_e32 v27, 0xffff0000, v85
	v_lshlrev_b32_e32 v28, 16, v81
	v_and_b32_e32 v29, 0xffff0000, v81
	v_pk_fma_f32 v[22:23], v[22:23], v[28:29], v[26:27]
	v_cvt_pk_bf16_f32 v20, v20, v21
	v_cvt_pk_bf16_f32 v21, v22, v23
	v_lshlrev_b32_e32 v22, 16, v86
	v_and_b32_e32 v23, 0xffff0000, v86
	v_lshlrev_b32_e32 v26, 16, v82
	v_and_b32_e32 v27, 0xffff0000, v82
	v_pk_fma_f32 v[12:13], v[12:13], v[26:27], v[22:23]
	v_lshlrev_b32_e32 v26, 16, v83
	v_cvt_pk_bf16_f32 v22, v12, v13
	v_lshlrev_b32_e32 v12, 16, v87
	v_and_b32_e32 v13, 0xffff0000, v87
	v_and_b32_e32 v27, 0xffff0000, v83
	v_pk_fma_f32 v[12:13], v[14:15], v[26:27], v[12:13]
	s_waitcnt vmcnt(8)
	v_lshlrev_b32_e32 v14, 16, v72
	v_cvt_pk_bf16_f32 v23, v12, v13
	s_waitcnt vmcnt(6)
	v_lshlrev_b32_e32 v12, 16, v76
	v_and_b32_e32 v13, 0xffff0000, v76
	v_and_b32_e32 v15, 0xffff0000, v72
	v_pk_fma_f32 v[12:13], v[16:17], v[14:15], v[12:13]
	v_lshlrev_b32_e32 v14, 16, v77
	v_and_b32_e32 v15, 0xffff0000, v77
	v_lshlrev_b32_e32 v16, 16, v73
	v_and_b32_e32 v17, 0xffff0000, v73
	v_pk_fma_f32 v[14:15], v[18:19], v[16:17], v[14:15]
	v_cvt_pk_bf16_f32 v12, v12, v13
	v_cvt_pk_bf16_f32 v13, v14, v15
	v_lshlrev_b32_e32 v14, 16, v78
	v_and_b32_e32 v15, 0xffff0000, v78
	v_lshlrev_b32_e32 v16, 16, v74
	v_and_b32_e32 v17, 0xffff0000, v74
	v_pk_fma_f32 v[8:9], v[8:9], v[16:17], v[14:15]
	v_lshlrev_b32_e32 v16, 16, v75
	v_cvt_pk_bf16_f32 v14, v8, v9
	v_lshlrev_b32_e32 v8, 16, v79
	v_and_b32_e32 v9, 0xffff0000, v79
	v_and_b32_e32 v17, 0xffff0000, v75
	v_pk_fma_f32 v[8:9], v[10:11], v[16:17], v[8:9]
	s_waitcnt vmcnt(5)
	v_lshlrev_b32_e32 v10, 16, v68
	v_cvt_pk_bf16_f32 v15, v8, v9
	v_add_co_u32_e32 v8, vcc, s38, v24
	v_and_b32_e32 v11, 0xffff0000, v68
	s_nop 0
	v_addc_co_u32_e32 v9, vcc, 0, v25, vcc
	global_store_dwordx4 v[8:9], v[12:15], off
	global_store_dwordx4 v[24:25], v[20:23], off offset:256
	s_and_b64 vcc, exec, s[6:7]
	v_lshlrev_b32_e32 v12, 16, v64
	v_and_b32_e32 v13, 0xffff0000, v64
	v_pk_fma_f32 v[4:5], v[4:5], v[12:13], v[10:11]
	v_lshlrev_b32_e32 v10, 16, v69
	v_and_b32_e32 v11, 0xffff0000, v69
	v_lshlrev_b32_e32 v12, 16, v65
	v_and_b32_e32 v13, 0xffff0000, v65
	v_pk_fma_f32 v[6:7], v[6:7], v[12:13], v[10:11]
	v_cvt_pk_bf16_f32 v4, v4, v5
	v_cvt_pk_bf16_f32 v5, v6, v7
	v_lshlrev_b32_e32 v6, 16, v70
	v_and_b32_e32 v7, 0xffff0000, v70
	v_lshlrev_b32_e32 v10, 16, v66
	v_and_b32_e32 v11, 0xffff0000, v66
	v_pk_fma_f32 v[0:1], v[0:1], v[10:11], v[6:7]
	v_lshlrev_b32_e32 v10, 16, v67
	v_cvt_pk_bf16_f32 v6, v0, v1
	v_lshlrev_b32_e32 v0, 16, v71
	v_and_b32_e32 v1, 0xffff0000, v71
	v_and_b32_e32 v11, 0xffff0000, v67
	v_pk_fma_f32 v[0:1], v[2:3], v[10:11], v[0:1]
	s_nop 0
	v_cvt_pk_bf16_f32 v7, v0, v1
	global_store_dwordx4 v[8:9], v[4:7], off offset:256
	s_cbranch_vccz .LBB0_492
	s_waitcnt vmcnt(0)
	s_cmpk_gt_u32 s86, 0xff
	s_cbranch_scc1 .LBB0_499
	s_barrier

; #define PG8_STAGE(bufoff, gbase, voff) do { _Pragma("unroll") for (int _i = 0; _i < 2; ++_i) \
;         __builtin_amdgcn_global_load_lds((const unsigned*)((const char*)(gbase) + (voff)[_i]), (PG8_LAS unsigned*)(lds + (bufoff) + ldsw + _i * 8192), 16, 0, 0); } while (0)
; #define PG8_LDA(dst, b, h) do { _Pragma("unroll") for (int m = 0; m < 4; ++m) _Pragma("unroll") for (int k = 0; k < 2; ++k) dst[m][k] = *(const PG8_LAS bf16x8*)(lds + PG8_SA(b, h) + aoff + m * 2048 + k * 1024); } while (0)
; #define PG8_LDB(dst, b, h) do { _Pragma("unroll") for (int n = 0; n < 2; ++n) _Pragma("unroll") for (int k = 0; k < 2; ++k) dst[n][k] = *(const PG8_LAS bf16x8*)(lds + PG8_SB(b, h) + boff + n * 2048 + k * 1024); } while (0)
; #define PG8_MMA(ai, bj, At, Bt) do { __builtin_amdgcn_s_setprio(1); _Pragma("unroll") for (int m = 0; m < 4; ++m) _Pragma("unroll") for (int n = 0; n < 2; ++n) _Pragma("unroll") for (int k = 0; k < 2; ++k) \
;         acc[ai][bj][m][n] = __builtin_amdgcn_mfma_f32_16x16x32_bf16(Bt[n][k], At[m][k], acc[ai][bj][m][n], 0, 0, 0); __builtin_amdgcn_s_setprio(0); } while (0)
; #define PG8_WAIT_V(n) asm volatile("s_waitcnt vmcnt(" #n ")" ::: "memory")
; #define PG8_WAIT_L(n) asm volatile("s_waitcnt lgkmcnt(" #n ")" ::: "memory")
; #define PG8_BAR __builtin_amdgcn_s_barrier()
; #define PG8_SCHED __builtin_amdgcn_sched_barrier(0)
; template <class Epi, class Sched, bool ALIGN_EPI = false, bool SP2 = false>
; __device__ __forceinline__ void gemm_phase(PG8_LAS unsigned char* lds, const Gemm g, const Sched& S, const Epi& E, const int wave_s) {
;     ...
;             const bool last = (t == nt - 2);
;             const char* a1 = cA + (size_t)(t + 1) * kstep;
;             const char* a2 = last ? nA : cA + (size_t)(t + 2) * kstep; const char* b2 = last ? nB : cB + (size_t)(t + 2) * kstep;
;             const char* a3 = a2 + kstep; const char* b3 = b2 + kstep;
;             if (last && has_next) S.a_ready(nxt);
;             if constexpr (SP2) {
;             PG8_LDB(B0, 0, 0); PG8_LDB(B1, 0, 1); PG8_SCHED; PG8_LDA(At, 0, 0); PG8_STAGE(PG8_SA(1, 1), a1 + hstep, voffA);
;             PG8_WAIT_V(8); PG8_WAIT_L(0); PG8_BAR; PG8_MMA(0, 0, At, B0); PG8_MMA(0, 1, At, B1); PG8_BAR; PG8_SCHED;
;             PG8_LDA(At, 0, 1); PG8_STAGE(PG8_SB(0, 0), b2, voffB); PG8_STAGE(PG8_SB(0, 1), b2 + hstep, voffB); PG8_STAGE(PG8_SA(0, 0), a2, voffA);
.LBB0_706:
	ds_read_b128 v[36:39], v187
	ds_read_b128 v[40:43], v187 offset:1024
	ds_read_b128 v[44:47], v187 offset:2048
	ds_read_b128 v[48:51], v187 offset:3072
	ds_read_b128 v[80:83], v188
	ds_read_b128 v[84:87], v188 offset:1024
	ds_read_b128 v[88:91], v188 offset:2048
	ds_read_b128 v[92:95], v188 offset:3072
	s_add_u32 s16, s14, 0xfffc0080
	s_addc_u32 s17, s15, -1
	s_cmp_eq_u32 s74, 12
	s_cselect_b32 s19, s13, s17
	s_cselect_b32 s18, s49, s16
	s_cselect_b32 s17, s47, s73
	s_cselect_b32 s16, s56, s57
	v_lshl_add_u64 v[184:185], s[14:15], 0, v[178:179]
	s_add_i32 m0, s41, 0xc000
	ds_read_b128 v[160:163], v189
	ds_read_b128 v[164:167], v189 offset:1024
	ds_read_b128 v[190:193], v189 offset:2048
	ds_read_b128 v[194:197], v189 offset:3072
	ds_read_b128 v[198:201], v189 offset:4096
	ds_read_b128 v[202:205], v189 offset:5120
	ds_read_b128 v[206:209], v189 offset:6144
	ds_read_b128 v[210:213], v189 offset:7168
	global_load_lds_dwordx4 v[184:185], off
	v_lshl_add_u64 v[184:185], s[14:15], 0, v[176:177]
	s_add_i32 m0, s41, 0xe000
	s_nop 0
	global_load_lds_dwordx4 v[184:185], off
	v_lshl_add_u64 v[230:231], s[16:17], 0, v[170:171]
	s_add_u32 s76, s16, 0x40000
	v_lshl_add_u64 v[232:233], s[16:17], 0, v[174:175]
	s_addc_u32 s77, s17, 0
	v_lshl_add_u64 v[234:235], s[76:77], 0, v[170:171]
	v_lshl_add_u64 v[236:237], s[18:19], 0, v[172:173]
	v_lshl_add_u64 v[238:239], s[76:77], 0, v[174:175]
	v_lshl_add_u64 v[240:241], s[18:19], 0, v[168:169]
	s_waitcnt vmcnt(8)
	s_waitcnt lgkmcnt(0)
	s_barrier
	s_setprio 1
	s_waitcnt lgkmcnt(0)
	v_mfma_f32_16x16x32_bf16 v[152:155], v[36:39], v[160:163], v[152:155]
	v_mfma_f32_16x16x32_bf16 v[120:123], v[44:47], v[160:163], v[120:123]
	v_mfma_f32_16x16x32_bf16 v[148:151], v[36:39], v[190:193], v[148:151]
	v_mfma_f32_16x16x32_bf16 v[116:119], v[44:47], v[190:193], v[116:119]
	v_mfma_f32_16x16x32_bf16 v[140:143], v[36:39], v[198:201], v[140:143]
	v_mfma_f32_16x16x32_bf16 v[108:111], v[44:47], v[198:201], v[108:111]
	v_mfma_f32_16x16x32_bf16 v[132:135], v[36:39], v[206:209], v[132:135]
	v_mfma_f32_16x16x32_bf16 v[96:99], v[44:47], v[206:209], v[96:99]
	v_mfma_f32_16x16x32_bf16 v[152:155], v[40:43], v[164:167], v[152:155]
	v_mfma_f32_16x16x32_bf16 v[120:123], v[48:51], v[164:167], v[120:123]
	v_mfma_f32_16x16x32_bf16 v[148:151], v[40:43], v[194:197], v[148:151]
	v_mfma_f32_16x16x32_bf16 v[116:119], v[48:51], v[194:197], v[116:119]
	v_mfma_f32_16x16x32_bf16 v[140:143], v[40:43], v[202:205], v[140:143]
	v_mfma_f32_16x16x32_bf16 v[108:111], v[48:51], v[202:205], v[108:111]
	v_mfma_f32_16x16x32_bf16 v[132:135], v[40:43], v[210:213], v[132:135]
	v_mfma_f32_16x16x32_bf16 v[96:99], v[48:51], v[210:213], v[96:99]
	s_setprio 0
	s_setprio 1
	v_mfma_f32_16x16x32_bf16 v[156:159], v[80:83], v[160:163], v[156:159]
	v_mfma_f32_16x16x32_bf16 v[124:127], v[88:91], v[160:163], v[124:127]
	v_mfma_f32_16x16x32_bf16 v[144:147], v[80:83], v[190:193], v[144:147]
	v_mfma_f32_16x16x32_bf16 v[112:115], v[88:91], v[190:193], v[112:115]
	v_mfma_f32_16x16x32_bf16 v[136:139], v[80:83], v[198:201], v[136:139]
	v_mfma_f32_16x16x32_bf16 v[104:107], v[88:91], v[198:201], v[104:107]
	v_mfma_f32_16x16x32_bf16 v[128:131], v[80:83], v[206:209], v[128:131]
	v_mfma_f32_16x16x32_bf16 v[100:103], v[88:91], v[206:209], v[100:103]
	v_mfma_f32_16x16x32_bf16 v[156:159], v[84:87], v[164:167], v[156:159]
	v_mfma_f32_16x16x32_bf16 v[124:127], v[92:95], v[164:167], v[124:127]
	v_mfma_f32_16x16x32_bf16 v[144:147], v[84:87], v[194:197], v[144:147]
	v_mfma_f32_16x16x32_bf16 v[112:115], v[92:95], v[194:197], v[112:115]
	v_mfma_f32_16x16x32_bf16 v[136:139], v[84:87], v[202:205], v[136:139]
	v_mfma_f32_16x16x32_bf16 v[104:107], v[92:95], v[202:205], v[104:107]
	v_mfma_f32_16x16x32_bf16 v[128:131], v[84:87], v[210:213], v[128:131]
	v_mfma_f32_16x16x32_bf16 v[100:103], v[92:95], v[210:213], v[100:103]
	s_setprio 0
	s_barrier
	s_add_i32 s75, s70, s33
	s_mov_b32 m0, s75
	ds_read_b128 v[160:163], v189 offset:16384
	ds_read_b128 v[164:167], v189 offset:17408
	ds_read_b128 v[190:193], v189 offset:18432
	ds_read_b128 v[194:197], v189 offset:19456
	ds_read_b128 v[198:201], v189 offset:20480
	ds_read_b128 v[202:205], v189 offset:21504
	ds_read_b128 v[206:209], v189 offset:22528
	ds_read_b128 v[210:213], v189 offset:23552
	global_load_lds_dwordx4 v[230:231], off
	s_add_i32 m0, s75, 0x2000
	s_add_i32 s75, s71, s33
	global_load_lds_dwordx4 v[232:233], off
	s_mov_b32 m0, s75
	s_nop 0
	global_load_lds_dwordx4 v[234:235], off
	s_add_i32 m0, s75, 0x2000
	s_nop 0
	global_load_lds_dwordx4 v[238:239], off
	s_mov_b32 m0, s41
	s_nop 0
	global_load_lds_dwordx4 v[240:241], off
	s_mov_b32 m0, s43
	s_nop 0
	global_load_lds_dwordx4 v[236:237], off
	s_waitcnt vmcnt(8)
	s_waitcnt lgkmcnt(0)
	s_barrier
; #define PG8_STAGE(bufoff, gbase, voff) do { _Pragma("unroll") for (int _i = 0; _i < 2; ++_i) \
;         __builtin_amdgcn_global_load_lds((const unsigned*)((const char*)(gbase) + (voff)[_i]), (PG8_LAS unsigned*)(lds + (bufoff) + ldsw + _i * 8192), 16, 0, 0); } while (0)
; #define PG8_LDA(dst, b, h) do { _Pragma("unroll") for (int m = 0; m < 4; ++m) _Pragma("unroll") for (int k = 0; k < 2; ++k) dst[m][k] = *(const PG8_LAS bf16x8*)(lds + PG8_SA(b, h) + aoff + m * 2048 + k * 1024); } while (0)
; #define PG8_LDB(dst, b, h) do { _Pragma("unroll") for (int n = 0; n < 2; ++n) _Pragma("unroll") for (int k = 0; k < 2; ++k) dst[n][k] = *(const PG8_LAS bf16x8*)(lds + PG8_SB(b, h) + boff + n * 2048 + k * 1024); } while (0)
; #define PG8_MMA(ai, bj, At, Bt) do { __builtin_amdgcn_s_setprio(1); _Pragma("unroll") for (int m = 0; m < 4; ++m) _Pragma("unroll") for (int n = 0; n < 2; ++n) _Pragma("unroll") for (int k = 0; k < 2; ++k) \
;         acc[ai][bj][m][n] = __builtin_amdgcn_mfma_f32_16x16x32_bf16(Bt[n][k], At[m][k], acc[ai][bj][m][n], 0, 0, 0); __builtin_amdgcn_s_setprio(0); } while (0)
; #define PG8_WAIT_V(n) asm volatile("s_waitcnt vmcnt(" #n ")" ::: "memory")
; #define PG8_WAIT_L(n) asm volatile("s_waitcnt lgkmcnt(" #n ")" ::: "memory")
; #define PG8_BAR __builtin_amdgcn_s_barrier()
; #define PG8_SCHED __builtin_amdgcn_sched_barrier(0)
; template <class Epi, class Sched, bool ALIGN_EPI = false, bool SP2 = false>
; __device__ __forceinline__ void gemm_phase(PG8_LAS unsigned char* lds, const Gemm g, const Sched& S, const Epi& E, const int wave_s) {
;     ...
;             PG8_WAIT_V(8); PG8_WAIT_L(0); PG8_BAR; PG8_MMA(0, 0, At, B0); PG8_MMA(0, 1, At, B1); PG8_BAR; PG8_SCHED;
;             PG8_LDA(At, 0, 1); PG8_STAGE(PG8_SB(0, 0), b2, voffB); PG8_STAGE(PG8_SB(0, 1), b2 + hstep, voffB); PG8_STAGE(PG8_SA(0, 0), a2, voffA);
;             PG8_WAIT_V(8); PG8_WAIT_L(0); PG8_BAR; PG8_MMA(1, 0, At, B0); PG8_MMA(1, 1, At, B1); PG8_BAR; PG8_SCHED;
;             PG8_LDB(B0, 1, 0); PG8_LDB(B1, 1, 1); PG8_SCHED; PG8_LDA(At, 1, 0); PG8_STAGE(PG8_SA(0, 1), a2 + hstep, voffA);
;             PG8_WAIT_V(8); PG8_WAIT_L(0); PG8_BAR; PG8_MMA(0, 0, At, B0); PG8_MMA(0, 1, At, B1); PG8_BAR; PG8_SCHED;
	s_setprio 1
	s_waitcnt lgkmcnt(0)
	v_mfma_f32_16x16x32_bf16 v[76:79], v[36:39], v[160:163], v[76:79]
	v_mfma_f32_16x16x32_bf16 v[28:31], v[44:47], v[160:163], v[28:31]
	v_mfma_f32_16x16x32_bf16 v[68:71], v[36:39], v[190:193], v[68:71]
	v_mfma_f32_16x16x32_bf16 v[20:23], v[44:47], v[190:193], v[20:23]
	v_mfma_f32_16x16x32_bf16 v[60:63], v[36:39], v[198:201], v[60:63]
	v_mfma_f32_16x16x32_bf16 v[12:15], v[44:47], v[198:201], v[12:15]
	v_mfma_f32_16x16x32_bf16 v[4:7], v[44:47], v[206:209], v[4:7]
	v_mfma_f32_16x16x32_bf16 v[76:79], v[40:43], v[164:167], v[76:79]
	v_mfma_f32_16x16x32_bf16 v[28:31], v[48:51], v[164:167], v[28:31]
	v_mfma_f32_16x16x32_bf16 v[68:71], v[40:43], v[194:197], v[68:71]
	v_mfma_f32_16x16x32_bf16 v[20:23], v[48:51], v[194:197], v[20:23]
	v_mfma_f32_16x16x32_bf16 v[60:63], v[40:43], v[202:205], v[60:63]
	v_mfma_f32_16x16x32_bf16 v[12:15], v[48:51], v[202:205], v[12:15]
	v_mfma_f32_16x16x32_bf16 v[36:39], v[36:39], v[206:209], v[52:55]
	v_mfma_f32_16x16x32_bf16 v[4:7], v[48:51], v[210:213], v[4:7]
	v_mfma_f32_16x16x32_bf16 v[36:39], v[40:43], v[210:213], v[36:39]
	s_setprio 0
	s_setprio 1
	v_mfma_f32_16x16x32_bf16 v[24:27], v[88:91], v[160:163], v[24:27]
	v_mfma_f32_16x16x32_bf16 v[16:19], v[88:91], v[190:193], v[16:19]
	v_mfma_f32_16x16x32_bf16 v[8:11], v[88:91], v[198:201], v[8:11]
	v_mfma_f32_16x16x32_bf16 v[32:35], v[80:83], v[206:209], v[32:35]
	v_mfma_f32_16x16x32_bf16 v[0:3], v[88:91], v[206:209], v[0:3]
	v_mfma_f32_16x16x32_bf16 v[40:43], v[80:83], v[160:163], v[72:75]
	v_mfma_f32_16x16x32_bf16 v[24:27], v[92:95], v[164:167], v[24:27]
	v_mfma_f32_16x16x32_bf16 v[44:47], v[80:83], v[190:193], v[64:67]
	v_mfma_f32_16x16x32_bf16 v[16:19], v[92:95], v[194:197], v[16:19]
	v_mfma_f32_16x16x32_bf16 v[48:51], v[80:83], v[198:201], v[56:59]
	v_mfma_f32_16x16x32_bf16 v[8:11], v[92:95], v[202:205], v[8:11]
	v_mfma_f32_16x16x32_bf16 v[32:35], v[84:87], v[210:213], v[32:35]
	v_mfma_f32_16x16x32_bf16 v[0:3], v[92:95], v[210:213], v[0:3]
	v_mfma_f32_16x16x32_bf16 v[40:43], v[84:87], v[164:167], v[40:43]
	v_mfma_f32_16x16x32_bf16 v[44:47], v[84:87], v[194:197], v[44:47]
	v_mfma_f32_16x16x32_bf16 v[48:51], v[84:87], v[202:205], v[48:51]
	s_setprio 0
	s_barrier
	s_add_i32 s75, 0, 0x18000
	s_add_i32 s76, 0, 0x1c000
	v_add_u32_e32 v72, s75, v186
	v_add_u32_e32 v92, s76, v186
	ds_read_b128 v[52:55], v72
	ds_read_b128 v[56:59], v72 offset:1024
	ds_read_b128 v[64:67], v72 offset:2048
	ds_read_b128 v[72:75], v72 offset:3072
	ds_read_b128 v[80:83], v92
	ds_read_b128 v[84:87], v92 offset:1024
	ds_read_b128 v[88:91], v92 offset:2048
	ds_read_b128 v[92:95], v92 offset:3072
	s_add_u32 s18, s18, 0x40000
	s_addc_u32 s19, s19, 0
	s_mov_b32 m0, s45
	v_lshl_add_u64 v[220:221], s[18:19], 0, v[168:169]
	ds_read_b128 v[160:163], v189 offset:32768
	ds_read_b128 v[164:167], v189 offset:33792
	ds_read_b128 v[190:193], v189 offset:34816
	ds_read_b128 v[194:197], v189 offset:35840
	ds_read_b128 v[198:201], v189 offset:36864
	ds_read_b128 v[202:205], v189 offset:37888
	ds_read_b128 v[206:209], v189 offset:38912
	ds_read_b128 v[210:213], v189 offset:39936
	global_load_lds_dwordx4 v[220:221], off
	v_lshl_add_u64 v[220:221], s[18:19], 0, v[172:173]
	s_mov_b32 m0, s55
	s_nop 0
	global_load_lds_dwordx4 v[220:221], off
	v_lshl_add_u64 v[242:243], v[230:231], 0, s[8:9]
	s_add_u32 s16, s16, 0x40080
	v_lshl_add_u64 v[244:245], v[232:233], 0, s[8:9]
	s_addc_u32 s17, s17, 0
	v_lshl_add_u64 v[246:247], s[16:17], 0, v[170:171]
	v_lshl_add_u64 v[248:249], s[16:17], 0, v[174:175]
	v_lshl_add_u64 v[250:251], v[240:241], 0, s[8:9]
	v_lshl_add_u64 v[252:253], v[236:237], 0, s[8:9]
	s_waitcnt vmcnt(8)
	s_waitcnt lgkmcnt(0)
	s_barrier
; #define PG8_STAGE(bufoff, gbase, voff) do { _Pragma("unroll") for (int _i = 0; _i < 2; ++_i) \
;         __builtin_amdgcn_global_load_lds((const unsigned*)((const char*)(gbase) + (voff)[_i]), (PG8_LAS unsigned*)(lds + (bufoff) + ldsw + _i * 8192), 16, 0, 0); } while (0)
; #define PG8_LDA(dst, b, h) do { _Pragma("unroll") for (int m = 0; m < 4; ++m) _Pragma("unroll") for (int k = 0; k < 2; ++k) dst[m][k] = *(const PG8_LAS bf16x8*)(lds + PG8_SA(b, h) + aoff + m * 2048 + k * 1024); } while (0)
; #define PG8_LDB(dst, b, h) do { _Pragma("unroll") for (int n = 0; n < 2; ++n) _Pragma("unroll") for (int k = 0; k < 2; ++k) dst[n][k] = *(const PG8_LAS bf16x8*)(lds + PG8_SB(b, h) + boff + n * 2048 + k * 1024); } while (0)
; #define PG8_MMA(ai, bj, At, Bt) do { __builtin_amdgcn_s_setprio(1); _Pragma("unroll") for (int m = 0; m < 4; ++m) _Pragma("unroll") for (int n = 0; n < 2; ++n) _Pragma("unroll") for (int k = 0; k < 2; ++k) \
;         acc[ai][bj][m][n] = __builtin_amdgcn_mfma_f32_16x16x32_bf16(Bt[n][k], At[m][k], acc[ai][bj][m][n], 0, 0, 0); __builtin_amdgcn_s_setprio(0); } while (0)
; #define PG8_WAIT_V(n) asm volatile("s_waitcnt vmcnt(" #n ")" ::: "memory")
; #define PG8_WAIT_L(n) asm volatile("s_waitcnt lgkmcnt(" #n ")" ::: "memory")
; #define PG8_BAR __builtin_amdgcn_s_barrier()
; #define PG8_SCHED __builtin_amdgcn_sched_barrier(0)
; template <class Epi, class Sched, bool ALIGN_EPI = false, bool SP2 = false>
; __device__ __forceinline__ void gemm_phase(PG8_LAS unsigned char* lds, const Gemm g, const Sched& S, const Epi& E, const int wave_s) {
;     ...
;             PG8_WAIT_V(8); PG8_WAIT_L(0); PG8_BAR; PG8_MMA(1, 0, At, B0); PG8_MMA(1, 1, At, B1); PG8_BAR; PG8_SCHED;
;             PG8_LDB(B0, 1, 0); PG8_LDB(B1, 1, 1); PG8_SCHED; PG8_LDA(At, 1, 0); PG8_STAGE(PG8_SA(0, 1), a2 + hstep, voffA);
;             PG8_WAIT_V(8); PG8_WAIT_L(0); PG8_BAR; PG8_MMA(0, 0, At, B0); PG8_MMA(0, 1, At, B1); PG8_BAR; PG8_SCHED;
;             PG8_LDA(At, 1, 1); PG8_STAGE(PG8_SB(1, 0), b3, voffB); PG8_STAGE(PG8_SB(1, 1), b3 + hstep, voffB); PG8_STAGE(PG8_SA(1, 0), a3, voffA);
;             PG8_WAIT_V(8); PG8_WAIT_L(0); PG8_BAR; PG8_MMA(1, 0, At, B0); PG8_MMA(1, 1, At, B1); PG8_BAR; PG8_SCHED;
;     ...
;         if constexpr (ALIGN_EPI) { if (wr == 0) PG8_BAR; }
	s_setprio 1
	s_waitcnt lgkmcnt(0)
	v_mfma_f32_16x16x32_bf16 v[152:155], v[52:55], v[160:163], v[152:155]
	v_mfma_f32_16x16x32_bf16 v[120:123], v[64:67], v[160:163], v[120:123]
	v_mfma_f32_16x16x32_bf16 v[148:151], v[52:55], v[190:193], v[148:151]
	v_mfma_f32_16x16x32_bf16 v[116:119], v[64:67], v[190:193], v[116:119]
	v_mfma_f32_16x16x32_bf16 v[140:143], v[52:55], v[198:201], v[140:143]
	v_mfma_f32_16x16x32_bf16 v[108:111], v[64:67], v[198:201], v[108:111]
	v_mfma_f32_16x16x32_bf16 v[132:135], v[52:55], v[206:209], v[132:135]
	v_mfma_f32_16x16x32_bf16 v[96:99], v[64:67], v[206:209], v[96:99]
	v_mfma_f32_16x16x32_bf16 v[152:155], v[56:59], v[164:167], v[152:155]
	v_mfma_f32_16x16x32_bf16 v[120:123], v[72:75], v[164:167], v[120:123]
	v_mfma_f32_16x16x32_bf16 v[148:151], v[56:59], v[194:197], v[148:151]
	v_mfma_f32_16x16x32_bf16 v[116:119], v[72:75], v[194:197], v[116:119]
	v_mfma_f32_16x16x32_bf16 v[140:143], v[56:59], v[202:205], v[140:143]
	v_mfma_f32_16x16x32_bf16 v[108:111], v[72:75], v[202:205], v[108:111]
	v_mfma_f32_16x16x32_bf16 v[132:135], v[56:59], v[210:213], v[132:135]
	v_mfma_f32_16x16x32_bf16 v[96:99], v[72:75], v[210:213], v[96:99]
	s_setprio 0
	s_setprio 1
	v_mfma_f32_16x16x32_bf16 v[156:159], v[80:83], v[160:163], v[156:159]
	v_mfma_f32_16x16x32_bf16 v[124:127], v[88:91], v[160:163], v[124:127]
	v_mfma_f32_16x16x32_bf16 v[144:147], v[80:83], v[190:193], v[144:147]
	v_mfma_f32_16x16x32_bf16 v[112:115], v[88:91], v[190:193], v[112:115]
	v_mfma_f32_16x16x32_bf16 v[136:139], v[80:83], v[198:201], v[136:139]
	v_mfma_f32_16x16x32_bf16 v[104:107], v[88:91], v[198:201], v[104:107]
	v_mfma_f32_16x16x32_bf16 v[128:131], v[80:83], v[206:209], v[128:131]
	v_mfma_f32_16x16x32_bf16 v[100:103], v[88:91], v[206:209], v[100:103]
	v_mfma_f32_16x16x32_bf16 v[156:159], v[84:87], v[164:167], v[156:159]
	v_mfma_f32_16x16x32_bf16 v[124:127], v[92:95], v[164:167], v[124:127]
	v_mfma_f32_16x16x32_bf16 v[144:147], v[84:87], v[194:197], v[144:147]
	v_mfma_f32_16x16x32_bf16 v[112:115], v[92:95], v[194:197], v[112:115]
	v_mfma_f32_16x16x32_bf16 v[136:139], v[84:87], v[202:205], v[136:139]
	v_mfma_f32_16x16x32_bf16 v[104:107], v[92:95], v[202:205], v[104:107]
	v_mfma_f32_16x16x32_bf16 v[128:131], v[84:87], v[210:213], v[128:131]
	v_mfma_f32_16x16x32_bf16 v[100:103], v[92:95], v[210:213], v[100:103]
	s_setprio 0
	s_barrier
	s_add_i32 s18, s75, s33
	s_mov_b32 m0, s18
	ds_read_b128 v[160:163], v189 offset:49152
	ds_read_b128 v[164:167], v189 offset:50176
	ds_read_b128 v[190:193], v189 offset:51200
	ds_read_b128 v[194:197], v189 offset:52224
	ds_read_b128 v[198:201], v189 offset:53248
	ds_read_b128 v[202:205], v189 offset:54272
	ds_read_b128 v[206:209], v189 offset:55296
	ds_read_b128 v[210:213], v189 offset:56320
	global_load_lds_dwordx4 v[242:243], off
	s_add_i32 m0, s18, 0x2000
	s_add_i32 s18, s76, s33
	global_load_lds_dwordx4 v[244:245], off
	s_mov_b32 m0, s18
	s_nop 0
	global_load_lds_dwordx4 v[246:247], off
	s_add_i32 m0, s18, 0x2000
	s_nop 0
	global_load_lds_dwordx4 v[248:249], off
	s_mov_b32 m0, s59
	s_nop 0
	global_load_lds_dwordx4 v[250:251], off
	s_mov_b32 m0, s60
	s_nop 0
	global_load_lds_dwordx4 v[252:253], off
	s_waitcnt vmcnt(8)
	s_waitcnt lgkmcnt(0)
	s_barrier
	s_setprio 1
	s_waitcnt lgkmcnt(0)
	v_mfma_f32_16x16x32_bf16 v[76:79], v[52:55], v[160:163], v[76:79]
	v_mfma_f32_16x16x32_bf16 v[28:31], v[64:67], v[160:163], v[28:31]
	v_mfma_f32_16x16x32_bf16 v[68:71], v[52:55], v[190:193], v[68:71]
	v_mfma_f32_16x16x32_bf16 v[20:23], v[64:67], v[190:193], v[20:23]
	v_mfma_f32_16x16x32_bf16 v[60:63], v[52:55], v[198:201], v[60:63]
	v_mfma_f32_16x16x32_bf16 v[12:15], v[64:67], v[198:201], v[12:15]
	v_mfma_f32_16x16x32_bf16 v[36:39], v[52:55], v[206:209], v[36:39]
	v_mfma_f32_16x16x32_bf16 v[4:7], v[64:67], v[206:209], v[4:7]
	v_mfma_f32_16x16x32_bf16 v[76:79], v[56:59], v[164:167], v[76:79]
	v_mfma_f32_16x16x32_bf16 v[28:31], v[72:75], v[164:167], v[28:31]
	v_mfma_f32_16x16x32_bf16 v[68:71], v[56:59], v[194:197], v[68:71]
	v_mfma_f32_16x16x32_bf16 v[20:23], v[72:75], v[194:197], v[20:23]
	v_mfma_f32_16x16x32_bf16 v[60:63], v[56:59], v[202:205], v[60:63]
	v_mfma_f32_16x16x32_bf16 v[12:15], v[72:75], v[202:205], v[12:15]
	v_mfma_f32_16x16x32_bf16 v[52:55], v[56:59], v[210:213], v[36:39]
	v_mfma_f32_16x16x32_bf16 v[4:7], v[72:75], v[210:213], v[4:7]
	s_setprio 0
	s_setprio 1
	v_mfma_f32_16x16x32_bf16 v[36:39], v[80:83], v[160:163], v[40:43]
	v_mfma_f32_16x16x32_bf16 v[72:75], v[84:87], v[164:167], v[36:39]
	v_mfma_f32_16x16x32_bf16 v[36:39], v[80:83], v[190:193], v[44:47]
	v_mfma_f32_16x16x32_bf16 v[24:27], v[88:91], v[160:163], v[24:27]
	v_mfma_f32_16x16x32_bf16 v[64:67], v[84:87], v[194:197], v[36:39]
	v_mfma_f32_16x16x32_bf16 v[16:19], v[88:91], v[190:193], v[16:19]
	v_mfma_f32_16x16x32_bf16 v[36:39], v[80:83], v[198:201], v[48:51]
	v_mfma_f32_16x16x32_bf16 v[8:11], v[88:91], v[198:201], v[8:11]
	v_mfma_f32_16x16x32_bf16 v[32:35], v[80:83], v[206:209], v[32:35]
	v_mfma_f32_16x16x32_bf16 v[0:3], v[88:91], v[206:209], v[0:3]
	v_mfma_f32_16x16x32_bf16 v[24:27], v[92:95], v[164:167], v[24:27]
	v_mfma_f32_16x16x32_bf16 v[16:19], v[92:95], v[194:197], v[16:19]
	v_mfma_f32_16x16x32_bf16 v[56:59], v[84:87], v[202:205], v[36:39]
	v_mfma_f32_16x16x32_bf16 v[8:11], v[92:95], v[202:205], v[8:11]
	v_mfma_f32_16x16x32_bf16 v[32:35], v[84:87], v[210:213], v[32:35]
	v_mfma_f32_16x16x32_bf16 v[0:3], v[92:95], v[210:213], v[0:3]
	s_setprio 0
	s_barrier
	s_add_i32 s74, s74, 2
	s_add_u32 s57, s57, 0x100
	s_addc_u32 s73, s73, 0
	s_add_u32 s14, s14, 0x100
	s_addc_u32 s15, s15, 0
	s_cmp_gt_u32 s74, 13
	s_cbranch_scc0 .LBB0_706
	s_and_b64 vcc, exec, s[20:21]
	s_cbranch_vccz .LBB0_709
	s_barrier

; #define PG8_STAGE(bufoff, gbase, voff) do { _Pragma("unroll") for (int _i = 0; _i < 2; ++_i) \
;         __builtin_amdgcn_global_load_lds((const unsigned*)((const char*)(gbase) + (voff)[_i]), (PG8_LAS unsigned*)(lds + (bufoff) + ldsw + _i * 8192), 16, 0, 0); } while (0)
; #define PG8_LDA(dst, b, h) do { _Pragma("unroll") for (int m = 0; m < 4; ++m) _Pragma("unroll") for (int k = 0; k < 2; ++k) dst[m][k] = *(const PG8_LAS bf16x8*)(lds + PG8_SA(b, h) + aoff + m * 2048 + k * 1024); } while (0)
; #define PG8_LDB(dst, b, h) do { _Pragma("unroll") for (int n = 0; n < 2; ++n) _Pragma("unroll") for (int k = 0; k < 2; ++k) dst[n][k] = *(const PG8_LAS bf16x8*)(lds + PG8_SB(b, h) + boff + n * 2048 + k * 1024); } while (0)
; #define PG8_MMA(ai, bj, At, Bt) do { __builtin_amdgcn_s_setprio(1); _Pragma("unroll") for (int m = 0; m < 4; ++m) _Pragma("unroll") for (int n = 0; n < 2; ++n) _Pragma("unroll") for (int k = 0; k < 2; ++k) \
;         acc[ai][bj][m][n] = __builtin_amdgcn_mfma_f32_16x16x32_bf16(Bt[n][k], At[m][k], acc[ai][bj][m][n], 0, 0, 0); __builtin_amdgcn_s_setprio(0); } while (0)
; #define PG8_WAIT_V(n) asm volatile("s_waitcnt vmcnt(" #n ")" ::: "memory")
; #define PG8_BAR __builtin_amdgcn_s_barrier()
; template <class Epi, class Sched, bool ALIGN_EPI = false, bool SP2 = false>
; __device__ __forceinline__ void gemm_phase(PG8_LAS unsigned char* lds, const Gemm g, const Sched& S, const Epi& E, const int wave_s) {
;     ...
;         for (int t = 0; t < nt; t += 2) {
;             const bool last = (t == nt - 2);
;             const char* a1 = cA + (size_t)(t + 1) * kstep;
;             const char* a2 = last ? nA : cA + (size_t)(t + 2) * kstep; const char* b2 = last ? nB : cB + (size_t)(t + 2) * kstep;
;             const char* a3 = a2 + kstep; const char* b3 = b2 + kstep;
;             if (last && has_next) S.a_ready(nxt);
;             if constexpr (SP2) {
;             PG8_LDB(B0, 0, 0); PG8_LDB(B1, 0, 1); PG8_SCHED; PG8_LDA(At, 0, 0); PG8_STAGE(PG8_SA(1, 1), a1 + hstep, voffA);
;             PG8_WAIT_V(8); PG8_WAIT_L(0); PG8_BAR; PG8_MMA(0, 0, At, B0); PG8_MMA(0, 1, At, B1); PG8_BAR; PG8_SCHED;
;             PG8_LDA(At, 0, 1); PG8_STAGE(PG8_SB(0, 0), b2, voffB); PG8_STAGE(PG8_SB(0, 1), b2 + hstep, voffB); PG8_STAGE(PG8_SA(0, 0), a2, voffA);
;             PG8_WAIT_V(8); PG8_WAIT_L(0); PG8_BAR; PG8_MMA(1, 0, At, B0); PG8_MMA(1, 1, At, B1); PG8_BAR; PG8_SCHED;
.LBB0_960:
	ds_read_b128 v[144:147], v149
	ds_read_b128 v[152:155], v149 offset:1024
	ds_read_b128 v[156:159], v149 offset:2048
	ds_read_b128 v[160:163], v149 offset:3072
	ds_read_b128 v[164:167], v150
	ds_read_b128 v[168:171], v150 offset:1024
	ds_read_b128 v[172:175], v150 offset:2048
	ds_read_b128 v[176:179], v150 offset:3072
	s_add_u32 s26, s24, 0xfffc0080
	s_addc_u32 s27, s25, -1
	s_cmp_eq_u32 s54, 12
	s_cselect_b32 s29, s17, s27
	s_cselect_b32 s28, s23, s26
	s_cselect_b32 s27, s15, s53
	s_cselect_b32 s26, s51, s52
	v_lshl_add_u64 v[212:213], s[24:25], 0, v[138:139]
	s_add_i32 m0, s38, 0xc000
	ds_read_b128 v[180:183], v151
	ds_read_b128 v[184:187], v151 offset:1024
	ds_read_b128 v[188:191], v151 offset:2048
	ds_read_b128 v[192:195], v151 offset:3072
	ds_read_b128 v[196:199], v151 offset:4096
	ds_read_b128 v[200:203], v151 offset:5120
	ds_read_b128 v[204:207], v151 offset:6144
	ds_read_b128 v[208:211], v151 offset:7168
	global_load_lds_dwordx4 v[212:213], off
	v_lshl_add_u64 v[212:213], s[24:25], 0, v[136:137]
	s_add_i32 m0, s38, 0xe000
	s_nop 0
	global_load_lds_dwordx4 v[212:213], off
	v_lshl_add_u64 v[230:231], s[26:27], 0, v[132:133]
	s_add_u32 s56, s26, 0x40000
	v_lshl_add_u64 v[232:233], s[26:27], 0, v[128:129]
	s_addc_u32 s57, s27, 0
	v_lshl_add_u64 v[234:235], s[56:57], 0, v[132:133]
	v_lshl_add_u64 v[236:237], s[28:29], 0, v[130:131]
	v_lshl_add_u64 v[238:239], s[56:57], 0, v[128:129]
	v_lshl_add_u64 v[240:241], s[28:29], 0, v[134:135]
	s_waitcnt vmcnt(8)
	s_waitcnt lgkmcnt(0)
	s_barrier
	s_setprio 1
	s_waitcnt lgkmcnt(0)
	v_mfma_f32_16x16x32_bf16 v[124:127], v[144:147], v[180:183], v[124:127]
	v_mfma_f32_16x16x32_bf16 v[120:123], v[156:159], v[180:183], v[120:123]
	v_mfma_f32_16x16x32_bf16 v[112:115], v[144:147], v[188:191], v[112:115]
	v_mfma_f32_16x16x32_bf16 v[104:107], v[156:159], v[188:191], v[104:107]
	v_mfma_f32_16x16x32_bf16 v[96:99], v[144:147], v[196:199], v[96:99]
	v_mfma_f32_16x16x32_bf16 v[88:91], v[156:159], v[196:199], v[88:91]
	v_mfma_f32_16x16x32_bf16 v[80:83], v[144:147], v[204:207], v[80:83]
	v_mfma_f32_16x16x32_bf16 v[72:75], v[156:159], v[204:207], v[72:75]
	v_mfma_f32_16x16x32_bf16 v[124:127], v[152:155], v[184:187], v[124:127]
	v_mfma_f32_16x16x32_bf16 v[120:123], v[160:163], v[184:187], v[120:123]
	v_mfma_f32_16x16x32_bf16 v[112:115], v[152:155], v[192:195], v[112:115]
	v_mfma_f32_16x16x32_bf16 v[104:107], v[160:163], v[192:195], v[104:107]
	v_mfma_f32_16x16x32_bf16 v[96:99], v[152:155], v[200:203], v[96:99]
	v_mfma_f32_16x16x32_bf16 v[88:91], v[160:163], v[200:203], v[88:91]
	v_mfma_f32_16x16x32_bf16 v[80:83], v[152:155], v[208:211], v[80:83]
	v_mfma_f32_16x16x32_bf16 v[72:75], v[160:163], v[208:211], v[72:75]
	s_setprio 0
	s_setprio 1
	v_mfma_f32_16x16x32_bf16 v[116:119], v[164:167], v[180:183], v[116:119]
	v_mfma_f32_16x16x32_bf16 v[108:111], v[172:175], v[180:183], v[108:111]
	v_mfma_f32_16x16x32_bf16 v[100:103], v[164:167], v[188:191], v[100:103]
	v_mfma_f32_16x16x32_bf16 v[92:95], v[172:175], v[188:191], v[92:95]
	v_mfma_f32_16x16x32_bf16 v[84:87], v[164:167], v[196:199], v[84:87]
	v_mfma_f32_16x16x32_bf16 v[76:79], v[172:175], v[196:199], v[76:79]
	v_mfma_f32_16x16x32_bf16 v[68:71], v[164:167], v[204:207], v[68:71]
	v_mfma_f32_16x16x32_bf16 v[64:67], v[172:175], v[204:207], v[64:67]
	v_mfma_f32_16x16x32_bf16 v[116:119], v[168:171], v[184:187], v[116:119]
	v_mfma_f32_16x16x32_bf16 v[108:111], v[176:179], v[184:187], v[108:111]
	v_mfma_f32_16x16x32_bf16 v[100:103], v[168:171], v[192:195], v[100:103]
	v_mfma_f32_16x16x32_bf16 v[92:95], v[176:179], v[192:195], v[92:95]
	v_mfma_f32_16x16x32_bf16 v[84:87], v[168:171], v[200:203], v[84:87]
	v_mfma_f32_16x16x32_bf16 v[76:79], v[176:179], v[200:203], v[76:79]
	v_mfma_f32_16x16x32_bf16 v[68:71], v[168:171], v[208:211], v[68:71]
	v_mfma_f32_16x16x32_bf16 v[64:67], v[176:179], v[208:211], v[64:67]
	s_setprio 0
	s_barrier
	s_add_i32 s55, s48, s33
	s_mov_b32 m0, s55
	ds_read_b128 v[180:183], v151 offset:16384
	ds_read_b128 v[184:187], v151 offset:17408
	ds_read_b128 v[188:191], v151 offset:18432
	ds_read_b128 v[192:195], v151 offset:19456
	ds_read_b128 v[196:199], v151 offset:20480
	ds_read_b128 v[200:203], v151 offset:21504
	ds_read_b128 v[204:207], v151 offset:22528
	ds_read_b128 v[208:211], v151 offset:23552
	global_load_lds_dwordx4 v[230:231], off
	s_add_i32 m0, s55, 0x2000
	s_add_i32 s55, s49, s33
	global_load_lds_dwordx4 v[232:233], off
	s_mov_b32 m0, s55
	s_nop 0
	global_load_lds_dwordx4 v[234:235], off
	s_add_i32 m0, s55, 0x2000
	s_nop 0
	global_load_lds_dwordx4 v[238:239], off
	s_mov_b32 m0, s38
	s_nop 0
	global_load_lds_dwordx4 v[240:241], off
	s_mov_b32 m0, s39
	s_nop 0
	global_load_lds_dwordx4 v[236:237], off
	s_waitcnt vmcnt(8)
	s_waitcnt lgkmcnt(0)
	s_barrier
; #define PG8_STAGE(bufoff, gbase, voff) do { _Pragma("unroll") for (int _i = 0; _i < 2; ++_i) \
;         __builtin_amdgcn_global_load_lds((const unsigned*)((const char*)(gbase) + (voff)[_i]), (PG8_LAS unsigned*)(lds + (bufoff) + ldsw + _i * 8192), 16, 0, 0); } while (0)
; #define PG8_LDA(dst, b, h) do { _Pragma("unroll") for (int m = 0; m < 4; ++m) _Pragma("unroll") for (int k = 0; k < 2; ++k) dst[m][k] = *(const PG8_LAS bf16x8*)(lds + PG8_SA(b, h) + aoff + m * 2048 + k * 1024); } while (0)
; #define PG8_LDB(dst, b, h) do { _Pragma("unroll") for (int n = 0; n < 2; ++n) _Pragma("unroll") for (int k = 0; k < 2; ++k) dst[n][k] = *(const PG8_LAS bf16x8*)(lds + PG8_SB(b, h) + boff + n * 2048 + k * 1024); } while (0)
; #define PG8_MMA(ai, bj, At, Bt) do { __builtin_amdgcn_s_setprio(1); _Pragma("unroll") for (int m = 0; m < 4; ++m) _Pragma("unroll") for (int n = 0; n < 2; ++n) _Pragma("unroll") for (int k = 0; k < 2; ++k) \
;         acc[ai][bj][m][n] = __builtin_amdgcn_mfma_f32_16x16x32_bf16(Bt[n][k], At[m][k], acc[ai][bj][m][n], 0, 0, 0); __builtin_amdgcn_s_setprio(0); } while (0)
; #define PG8_WAIT_V(n) asm volatile("s_waitcnt vmcnt(" #n ")" ::: "memory")
; #define PG8_WAIT_L(n) asm volatile("s_waitcnt lgkmcnt(" #n ")" ::: "memory")
; #define PG8_BAR __builtin_amdgcn_s_barrier()
; #define PG8_SCHED __builtin_amdgcn_sched_barrier(0)
; template <class Epi, class Sched, bool ALIGN_EPI = false, bool SP2 = false>
; __device__ __forceinline__ void gemm_phase(PG8_LAS unsigned char* lds, const Gemm g, const Sched& S, const Epi& E, const int wave_s) {
;     ...
;             PG8_WAIT_V(8); PG8_WAIT_L(0); PG8_BAR; PG8_MMA(1, 0, At, B0); PG8_MMA(1, 1, At, B1); PG8_BAR; PG8_SCHED;
;             PG8_LDB(B0, 1, 0); PG8_LDB(B1, 1, 1); PG8_SCHED; PG8_LDA(At, 1, 0); PG8_STAGE(PG8_SA(0, 1), a2 + hstep, voffA);
;             PG8_WAIT_V(8); PG8_WAIT_L(0); PG8_BAR; PG8_MMA(0, 0, At, B0); PG8_MMA(0, 1, At, B1); PG8_BAR; PG8_SCHED;
;             PG8_LDA(At, 1, 1); PG8_STAGE(PG8_SB(1, 0), b3, voffB); PG8_STAGE(PG8_SB(1, 1), b3 + hstep, voffB); PG8_STAGE(PG8_SA(1, 0), a3, voffA);
	s_setprio 1
	s_waitcnt lgkmcnt(0)
	v_mfma_f32_16x16x32_bf16 v[60:63], v[144:147], v[180:183], v[60:63]
	v_mfma_f32_16x16x32_bf16 v[56:59], v[156:159], v[180:183], v[56:59]
	v_mfma_f32_16x16x32_bf16 v[48:51], v[144:147], v[188:191], v[48:51]
	v_mfma_f32_16x16x32_bf16 v[40:43], v[156:159], v[188:191], v[40:43]
	v_mfma_f32_16x16x32_bf16 v[32:35], v[144:147], v[196:199], v[32:35]
	v_mfma_f32_16x16x32_bf16 v[24:27], v[156:159], v[196:199], v[24:27]
	v_mfma_f32_16x16x32_bf16 v[16:19], v[144:147], v[204:207], v[16:19]
	v_mfma_f32_16x16x32_bf16 v[8:11], v[156:159], v[204:207], v[8:11]
	v_mfma_f32_16x16x32_bf16 v[60:63], v[152:155], v[184:187], v[60:63]
	v_mfma_f32_16x16x32_bf16 v[56:59], v[160:163], v[184:187], v[56:59]
	v_mfma_f32_16x16x32_bf16 v[48:51], v[152:155], v[192:195], v[48:51]
	v_mfma_f32_16x16x32_bf16 v[40:43], v[160:163], v[192:195], v[40:43]
	v_mfma_f32_16x16x32_bf16 v[32:35], v[152:155], v[200:203], v[32:35]
	v_mfma_f32_16x16x32_bf16 v[24:27], v[160:163], v[200:203], v[24:27]
	v_mfma_f32_16x16x32_bf16 v[16:19], v[152:155], v[208:211], v[16:19]
	v_mfma_f32_16x16x32_bf16 v[8:11], v[160:163], v[208:211], v[8:11]
	s_setprio 0
	s_setprio 1
	v_mfma_f32_16x16x32_bf16 v[52:55], v[164:167], v[180:183], v[52:55]
	v_mfma_f32_16x16x32_bf16 v[44:47], v[172:175], v[180:183], v[44:47]
	v_mfma_f32_16x16x32_bf16 v[36:39], v[164:167], v[188:191], v[36:39]
	v_mfma_f32_16x16x32_bf16 v[28:31], v[172:175], v[188:191], v[28:31]
	v_mfma_f32_16x16x32_bf16 v[20:23], v[164:167], v[196:199], v[20:23]
	v_mfma_f32_16x16x32_bf16 v[12:15], v[172:175], v[196:199], v[12:15]
	v_mfma_f32_16x16x32_bf16 v[4:7], v[164:167], v[204:207], v[4:7]
	v_mfma_f32_16x16x32_bf16 v[0:3], v[172:175], v[204:207], v[0:3]
	v_mfma_f32_16x16x32_bf16 v[52:55], v[168:171], v[184:187], v[52:55]
	v_mfma_f32_16x16x32_bf16 v[44:47], v[176:179], v[184:187], v[44:47]
	v_mfma_f32_16x16x32_bf16 v[36:39], v[168:171], v[192:195], v[36:39]
	v_mfma_f32_16x16x32_bf16 v[28:31], v[176:179], v[192:195], v[28:31]
	v_mfma_f32_16x16x32_bf16 v[20:23], v[168:171], v[200:203], v[20:23]
	v_mfma_f32_16x16x32_bf16 v[12:15], v[176:179], v[200:203], v[12:15]
	v_mfma_f32_16x16x32_bf16 v[4:7], v[168:171], v[208:211], v[4:7]
	v_mfma_f32_16x16x32_bf16 v[0:3], v[176:179], v[208:211], v[0:3]
	s_setprio 0
	s_barrier
	s_add_i32 s55, 0, 0x18000
	s_add_i32 s56, 0, 0x1c000
	v_add_u32_e32 v160, s55, v148
	v_add_u32_e32 v176, s56, v148
	ds_read_b128 v[144:147], v160
	ds_read_b128 v[152:155], v160 offset:1024
	ds_read_b128 v[156:159], v160 offset:2048
	ds_read_b128 v[160:163], v160 offset:3072
	ds_read_b128 v[164:167], v176
	ds_read_b128 v[168:171], v176 offset:1024
	ds_read_b128 v[172:175], v176 offset:2048
	ds_read_b128 v[176:179], v176 offset:3072
	s_add_u32 s28, s28, 0x40000
	s_addc_u32 s29, s29, 0
	s_mov_b32 m0, s40
	v_lshl_add_u64 v[220:221], s[28:29], 0, v[134:135]
	ds_read_b128 v[180:183], v151 offset:32768
	ds_read_b128 v[184:187], v151 offset:33792
	ds_read_b128 v[188:191], v151 offset:34816
	ds_read_b128 v[192:195], v151 offset:35840
	ds_read_b128 v[196:199], v151 offset:36864
	ds_read_b128 v[200:203], v151 offset:37888
	ds_read_b128 v[204:207], v151 offset:38912
	ds_read_b128 v[208:211], v151 offset:39936
	global_load_lds_dwordx4 v[220:221], off
	v_lshl_add_u64 v[220:221], s[28:29], 0, v[130:131]
	s_mov_b32 m0, s41
	s_nop 0
	global_load_lds_dwordx4 v[220:221], off
	v_lshl_add_u64 v[242:243], v[230:231], 0, s[8:9]
	s_add_u32 s26, s26, 0x40080
	v_lshl_add_u64 v[244:245], v[232:233], 0, s[8:9]
	s_addc_u32 s27, s27, 0
	v_lshl_add_u64 v[246:247], s[26:27], 0, v[132:133]
	v_lshl_add_u64 v[248:249], s[26:27], 0, v[128:129]
	v_lshl_add_u64 v[250:251], v[240:241], 0, s[8:9]
	v_lshl_add_u64 v[252:253], v[236:237], 0, s[8:9]
	s_waitcnt vmcnt(8)
	s_waitcnt lgkmcnt(0)
	s_barrier
	s_setprio 1
	s_waitcnt lgkmcnt(0)
	v_mfma_f32_16x16x32_bf16 v[124:127], v[144:147], v[180:183], v[124:127]
	v_mfma_f32_16x16x32_bf16 v[120:123], v[156:159], v[180:183], v[120:123]
	v_mfma_f32_16x16x32_bf16 v[112:115], v[144:147], v[188:191], v[112:115]
	v_mfma_f32_16x16x32_bf16 v[104:107], v[156:159], v[188:191], v[104:107]
	v_mfma_f32_16x16x32_bf16 v[96:99], v[144:147], v[196:199], v[96:99]
	v_mfma_f32_16x16x32_bf16 v[88:91], v[156:159], v[196:199], v[88:91]
	v_mfma_f32_16x16x32_bf16 v[80:83], v[144:147], v[204:207], v[80:83]
	v_mfma_f32_16x16x32_bf16 v[72:75], v[156:159], v[204:207], v[72:75]
	v_mfma_f32_16x16x32_bf16 v[124:127], v[152:155], v[184:187], v[124:127]
	v_mfma_f32_16x16x32_bf16 v[120:123], v[160:163], v[184:187], v[120:123]
	v_mfma_f32_16x16x32_bf16 v[112:115], v[152:155], v[192:195], v[112:115]
	v_mfma_f32_16x16x32_bf16 v[104:107], v[160:163], v[192:195], v[104:107]
	v_mfma_f32_16x16x32_bf16 v[96:99], v[152:155], v[200:203], v[96:99]
	v_mfma_f32_16x16x32_bf16 v[88:91], v[160:163], v[200:203], v[88:91]
	v_mfma_f32_16x16x32_bf16 v[80:83], v[152:155], v[208:211], v[80:83]
	v_mfma_f32_16x16x32_bf16 v[72:75], v[160:163], v[208:211], v[72:75]
	s_setprio 0
	s_setprio 1
	v_mfma_f32_16x16x32_bf16 v[116:119], v[164:167], v[180:183], v[116:119]
	v_mfma_f32_16x16x32_bf16 v[108:111], v[172:175], v[180:183], v[108:111]
	v_mfma_f32_16x16x32_bf16 v[100:103], v[164:167], v[188:191], v[100:103]
	v_mfma_f32_16x16x32_bf16 v[92:95], v[172:175], v[188:191], v[92:95]
	v_mfma_f32_16x16x32_bf16 v[84:87], v[164:167], v[196:199], v[84:87]
	v_mfma_f32_16x16x32_bf16 v[76:79], v[172:175], v[196:199], v[76:79]
	v_mfma_f32_16x16x32_bf16 v[68:71], v[164:167], v[204:207], v[68:71]
	v_mfma_f32_16x16x32_bf16 v[64:67], v[172:175], v[204:207], v[64:67]
	v_mfma_f32_16x16x32_bf16 v[116:119], v[168:171], v[184:187], v[116:119]
	v_mfma_f32_16x16x32_bf16 v[108:111], v[176:179], v[184:187], v[108:111]
	v_mfma_f32_16x16x32_bf16 v[100:103], v[168:171], v[192:195], v[100:103]
	v_mfma_f32_16x16x32_bf16 v[92:95], v[176:179], v[192:195], v[92:95]
	v_mfma_f32_16x16x32_bf16 v[84:87], v[168:171], v[200:203], v[84:87]
	v_mfma_f32_16x16x32_bf16 v[76:79], v[176:179], v[200:203], v[76:79]
	v_mfma_f32_16x16x32_bf16 v[68:71], v[168:171], v[208:211], v[68:71]
	v_mfma_f32_16x16x32_bf16 v[64:67], v[176:179], v[208:211], v[64:67]
	s_setprio 0
	s_barrier
; #define PG8_STAGE(bufoff, gbase, voff) do { _Pragma("unroll") for (int _i = 0; _i < 2; ++_i) \
;         __builtin_amdgcn_global_load_lds((const unsigned*)((const char*)(gbase) + (voff)[_i]), (PG8_LAS unsigned*)(lds + (bufoff) + ldsw + _i * 8192), 16, 0, 0); } while (0)
; #define PG8_LDA(dst, b, h) do { _Pragma("unroll") for (int m = 0; m < 4; ++m) _Pragma("unroll") for (int k = 0; k < 2; ++k) dst[m][k] = *(const PG8_LAS bf16x8*)(lds + PG8_SA(b, h) + aoff + m * 2048 + k * 1024); } while (0)
; #define PG8_MMA(ai, bj, At, Bt) do { __builtin_amdgcn_s_setprio(1); _Pragma("unroll") for (int m = 0; m < 4; ++m) _Pragma("unroll") for (int n = 0; n < 2; ++n) _Pragma("unroll") for (int k = 0; k < 2; ++k) \
;         acc[ai][bj][m][n] = __builtin_amdgcn_mfma_f32_16x16x32_bf16(Bt[n][k], At[m][k], acc[ai][bj][m][n], 0, 0, 0); __builtin_amdgcn_s_setprio(0); } while (0)
; #define PG8_WAIT_V(n) asm volatile("s_waitcnt vmcnt(" #n ")" ::: "memory")
; #define PG8_WAIT_L(n) asm volatile("s_waitcnt lgkmcnt(" #n ")" ::: "memory")
; #define PG8_BAR __builtin_amdgcn_s_barrier()
; #define PG8_SCHED __builtin_amdgcn_sched_barrier(0)
; __device__ __forceinline__ unsigned cvtpk(float lo, float hi) { f32x2 v = {lo, hi}; bf16x2_t b = __builtin_convertvector(v, bf16x2_t); return __builtin_bit_cast(unsigned, b); }
; template <class Epi, class Sched, bool ALIGN_EPI = false, bool SP2 = false>
; __device__ __forceinline__ void gemm_phase(PG8_LAS unsigned char* lds, const Gemm g, const Sched& S, const Epi& E, const int wave_s) {
;     ...
;             PG8_LDA(At, 1, 1); PG8_STAGE(PG8_SB(1, 0), b3, voffB); PG8_STAGE(PG8_SB(1, 1), b3 + hstep, voffB); PG8_STAGE(PG8_SA(1, 0), a3, voffA);
;             PG8_WAIT_V(8); PG8_WAIT_L(0); PG8_BAR; PG8_MMA(1, 0, At, B0); PG8_MMA(1, 1, At, B1); PG8_BAR; PG8_SCHED;
;     __device__ __forceinline__ void operator()(const af4 (&acc)[2][2][4][2], const pg8::Unit& u, int wr, int wc, int fr_, int fq_) const {
;     ...
;         } else if (wc == 0) {
; #pragma unroll
;             for (int ai = 0; ai < 2; ++ai)
; #pragma unroll
;                 for (int m = 0; m < 4; ++m) { const af4 v0 = acc[ai][0][m][0], v1 = acc[ai][0][m][1]; v4u w; w.x = cvtpk(v0[0], v0[1]); w.y = cvtpk(v0[2], v0[3]); w.z = cvtpk(v1[0], v1[1]); w.w = cvtpk(v1[2], v1[3]);
;                     *(v4u*)(Z + (size_t)(row0 + ai * 128 + m * 16) * 32 + 8 * fq) = w; }
	s_add_i32 s28, s55, s33
	s_mov_b32 m0, s28
	ds_read_b128 v[180:183], v151 offset:49152
	ds_read_b128 v[184:187], v151 offset:50176
	ds_read_b128 v[188:191], v151 offset:51200
	ds_read_b128 v[192:195], v151 offset:52224
	ds_read_b128 v[196:199], v151 offset:53248
	ds_read_b128 v[200:203], v151 offset:54272
	ds_read_b128 v[204:207], v151 offset:55296
	ds_read_b128 v[208:211], v151 offset:56320
	global_load_lds_dwordx4 v[242:243], off
	s_add_i32 m0, s28, 0x2000
	s_add_i32 s28, s56, s33
	global_load_lds_dwordx4 v[244:245], off
	s_mov_b32 m0, s28
	s_nop 0
	global_load_lds_dwordx4 v[246:247], off
	s_add_i32 m0, s28, 0x2000
	s_nop 0
	global_load_lds_dwordx4 v[248:249], off
	s_mov_b32 m0, s44
	s_nop 0
	global_load_lds_dwordx4 v[250:251], off
	s_mov_b32 m0, s45
	s_nop 0
	global_load_lds_dwordx4 v[252:253], off
	s_waitcnt vmcnt(8)
	s_waitcnt lgkmcnt(0)
	s_barrier
	s_setprio 1
	s_waitcnt lgkmcnt(0)
	v_mfma_f32_16x16x32_bf16 v[60:63], v[144:147], v[180:183], v[60:63]
	v_mfma_f32_16x16x32_bf16 v[56:59], v[156:159], v[180:183], v[56:59]
	v_mfma_f32_16x16x32_bf16 v[48:51], v[144:147], v[188:191], v[48:51]
	v_mfma_f32_16x16x32_bf16 v[40:43], v[156:159], v[188:191], v[40:43]
	v_mfma_f32_16x16x32_bf16 v[32:35], v[144:147], v[196:199], v[32:35]
	v_mfma_f32_16x16x32_bf16 v[24:27], v[156:159], v[196:199], v[24:27]
	v_mfma_f32_16x16x32_bf16 v[16:19], v[144:147], v[204:207], v[16:19]
	v_mfma_f32_16x16x32_bf16 v[8:11], v[156:159], v[204:207], v[8:11]
	v_mfma_f32_16x16x32_bf16 v[60:63], v[152:155], v[184:187], v[60:63]
	v_mfma_f32_16x16x32_bf16 v[56:59], v[160:163], v[184:187], v[56:59]
	v_mfma_f32_16x16x32_bf16 v[48:51], v[152:155], v[192:195], v[48:51]
	v_mfma_f32_16x16x32_bf16 v[40:43], v[160:163], v[192:195], v[40:43]
	v_mfma_f32_16x16x32_bf16 v[32:35], v[152:155], v[200:203], v[32:35]
	v_mfma_f32_16x16x32_bf16 v[24:27], v[160:163], v[200:203], v[24:27]
	v_mfma_f32_16x16x32_bf16 v[16:19], v[152:155], v[208:211], v[16:19]
	v_mfma_f32_16x16x32_bf16 v[8:11], v[160:163], v[208:211], v[8:11]
	s_setprio 0
	s_setprio 1
	v_mfma_f32_16x16x32_bf16 v[52:55], v[164:167], v[180:183], v[52:55]
	v_mfma_f32_16x16x32_bf16 v[44:47], v[172:175], v[180:183], v[44:47]
	v_mfma_f32_16x16x32_bf16 v[36:39], v[164:167], v[188:191], v[36:39]
	v_mfma_f32_16x16x32_bf16 v[28:31], v[172:175], v[188:191], v[28:31]
	v_mfma_f32_16x16x32_bf16 v[20:23], v[164:167], v[196:199], v[20:23]
	v_mfma_f32_16x16x32_bf16 v[12:15], v[172:175], v[196:199], v[12:15]
	v_mfma_f32_16x16x32_bf16 v[4:7], v[164:167], v[204:207], v[4:7]
	v_mfma_f32_16x16x32_bf16 v[0:3], v[172:175], v[204:207], v[0:3]
	v_mfma_f32_16x16x32_bf16 v[52:55], v[168:171], v[184:187], v[52:55]
	v_mfma_f32_16x16x32_bf16 v[44:47], v[176:179], v[184:187], v[44:47]
	v_mfma_f32_16x16x32_bf16 v[36:39], v[168:171], v[192:195], v[36:39]
	v_mfma_f32_16x16x32_bf16 v[28:31], v[176:179], v[192:195], v[28:31]
	v_mfma_f32_16x16x32_bf16 v[20:23], v[168:171], v[200:203], v[20:23]
	v_mfma_f32_16x16x32_bf16 v[12:15], v[176:179], v[200:203], v[12:15]
	v_mfma_f32_16x16x32_bf16 v[4:7], v[168:171], v[208:211], v[4:7]
	v_mfma_f32_16x16x32_bf16 v[0:3], v[176:179], v[208:211], v[0:3]
	s_setprio 0
	s_barrier
	s_add_i32 s54, s54, 2
	s_add_u32 s52, s52, 0x100
	s_addc_u32 s53, s53, 0
	s_add_u32 s24, s24, 0x100
	s_addc_u32 s25, s25, 0
	s_cmp_gt_u32 s54, 13
	s_cbranch_scc0 .LBB0_960
	s_lshl_b32 s15, s22, 8
	v_mbcnt_lo_u32_b32 v144, -1, 0
	v_mbcnt_hi_u32_b32 v144, -1, v144
	s_add_i32 s15, s15, s87
	v_ashrrev_i32_e32 v146, 4, v144
	v_and_or_b32 v144, v144, 15, s15
	s_cmp_gt_i32 s50, 7
	s_mov_b64 s[22:23], -1
	s_cbranch_scc0 .LBB0_965
	s_andn2_b64 vcc, exec, s[10:11]
	s_cbranch_vccnz .LBB0_964
	v_lshlrev_b32_e32 v156, 3, v146
	v_ashrrev_i32_e32 v145, 31, v144
	v_or_b32_e32 v160, 16, v144
	v_ashrrev_i32_e32 v157, 31, v156
	v_lshlrev_b64 v[158:159], 6, v[144:145]
	v_ashrrev_i32_e32 v161, 31, v160
	v_lshl_add_u64 v[158:159], s[6:7], 0, v[158:159]
	v_lshlrev_b64 v[156:157], 1, v[156:157]
	v_lshlrev_b64 v[160:161], 6, v[160:161]
	v_cvt_pk_bf16_f32 v152, v124, v125
	v_cvt_pk_bf16_f32 v153, v126, v127
	v_cvt_pk_bf16_f32 v154, v120, v121
	v_cvt_pk_bf16_f32 v155, v122, v123
	v_lshl_add_u64 v[158:159], v[158:159], 0, v[156:157]
	v_lshl_add_u64 v[160:161], s[6:7], 0, v[160:161]
	global_store_dwordx4 v[158:159], v[152:155], off
	v_lshl_add_u64 v[160:161], v[160:161], 0, v[156:157]
	s_nop 0
	v_cvt_pk_bf16_f32 v152, v112, v113
	v_cvt_pk_bf16_f32 v153, v114, v115
	v_cvt_pk_bf16_f32 v154, v104, v105
	v_cvt_pk_bf16_f32 v155, v106, v107
	global_store_dwordx4 v[160:161], v[152:155], off
	v_or_b32_e32 v160, 32, v144
	v_ashrrev_i32_e32 v161, 31, v160
	v_lshlrev_b64 v[160:161], 6, v[160:161]
	v_lshl_add_u64 v[160:161], s[6:7], 0, v[160:161]
	v_cvt_pk_bf16_f32 v152, v96, v97
	v_cvt_pk_bf16_f32 v153, v98, v99
	v_cvt_pk_bf16_f32 v154, v88, v89
	v_cvt_pk_bf16_f32 v155, v90, v91
	v_lshl_add_u64 v[160:161], v[160:161], 0, v[156:157]
	global_store_dwordx4 v[160:161], v[152:155], off
	v_or_b32_e32 v160, 48, v144
	v_ashrrev_i32_e32 v161, 31, v160
	v_lshlrev_b64 v[160:161], 6, v[160:161]
	v_lshl_add_u64 v[160:161], s[6:7], 0, v[160:161]
	v_cvt_pk_bf16_f32 v152, v80, v81
	v_cvt_pk_bf16_f32 v153, v82, v83
	v_cvt_pk_bf16_f32 v154, v72, v73
	v_cvt_pk_bf16_f32 v155, v74, v75
	v_lshl_add_u64 v[156:157], v[160:161], 0, v[156:157]
	global_store_dwordx4 v[156:157], v[152:155], off
	v_add_co_u32_e32 v156, vcc, s42, v158
	s_nop 0
	v_cvt_pk_bf16_f32 v152, v60, v61
	v_cvt_pk_bf16_f32 v153, v62, v63
	v_cvt_pk_bf16_f32 v154, v56, v57
	v_cvt_pk_bf16_f32 v155, v58, v59
	v_addc_co_u32_e32 v157, vcc, 0, v159, vcc
	global_store_dwordx4 v[156:157], v[152:155], off
	s_nop 1
	v_cvt_pk_bf16_f32 v152, v48, v49
	v_cvt_pk_bf16_f32 v153, v50, v51
	v_cvt_pk_bf16_f32 v154, v40, v41
	v_cvt_pk_bf16_f32 v155, v42, v43
	global_store_dwordx4 v[156:157], v[152:155], off offset:1024
	s_nop 1
	v_cvt_pk_bf16_f32 v152, v32, v33
	v_cvt_pk_bf16_f32 v153, v34, v35
	v_cvt_pk_bf16_f32 v154, v24, v25
	v_cvt_pk_bf16_f32 v155, v26, v27
	global_store_dwordx4 v[156:157], v[152:155], off offset:2048
	s_nop 1
	v_cvt_pk_bf16_f32 v152, v16, v17
	v_cvt_pk_bf16_f32 v153, v18, v19
	v_cvt_pk_bf16_f32 v154, v8, v9
	v_cvt_pk_bf16_f32 v155, v10, v11
	global_store_dwordx4 v[156:157], v[152:155], off offset:3072

; #define PG8_STAGE(bufoff, gbase, voff) do { _Pragma("unroll") for (int _i = 0; _i < 2; ++_i) \
;         __builtin_amdgcn_global_load_lds((const unsigned*)((const char*)(gbase) + (voff)[_i]), (PG8_LAS unsigned*)(lds + (bufoff) + ldsw + _i * 8192), 16, 0, 0); } while (0)
; #define PG8_LDA(dst, b, h) do { _Pragma("unroll") for (int m = 0; m < 4; ++m) _Pragma("unroll") for (int k = 0; k < 2; ++k) dst[m][k] = *(const PG8_LAS bf16x8*)(lds + PG8_SA(b, h) + aoff + m * 2048 + k * 1024); } while (0)
; #define PG8_LDB(dst, b, h) do { _Pragma("unroll") for (int n = 0; n < 2; ++n) _Pragma("unroll") for (int k = 0; k < 2; ++k) dst[n][k] = *(const PG8_LAS bf16x8*)(lds + PG8_SB(b, h) + boff + n * 2048 + k * 1024); } while (0)
; #define PG8_MMA(ai, bj, At, Bt) do { __builtin_amdgcn_s_setprio(1); _Pragma("unroll") for (int m = 0; m < 4; ++m) _Pragma("unroll") for (int n = 0; n < 2; ++n) _Pragma("unroll") for (int k = 0; k < 2; ++k) \
;         acc[ai][bj][m][n] = __builtin_amdgcn_mfma_f32_16x16x32_bf16(Bt[n][k], At[m][k], acc[ai][bj][m][n], 0, 0, 0); __builtin_amdgcn_s_setprio(0); } while (0)
; #define PG8_WAIT_V(n) asm volatile("s_waitcnt vmcnt(" #n ")" ::: "memory")
; #define PG8_BAR __builtin_amdgcn_s_barrier()
; template <class Epi, class Sched, bool ALIGN_EPI = false, bool SP2 = false>
; __device__ __forceinline__ void gemm_phase(PG8_LAS unsigned char* lds, const Gemm g, const Sched& S, const Epi& E, const int wave_s) {
;     ...
;         for (int t = 0; t < nt; t += 2) {
;             const bool last = (t == nt - 2);
;             const char* a1 = cA + (size_t)(t + 1) * kstep;
;             const char* a2 = last ? nA : cA + (size_t)(t + 2) * kstep; const char* b2 = last ? nB : cB + (size_t)(t + 2) * kstep;
;             const char* a3 = a2 + kstep; const char* b3 = b2 + kstep;
;             if (last && has_next) S.a_ready(nxt);
;             if constexpr (SP2) {
;             PG8_LDB(B0, 0, 0); PG8_LDB(B1, 0, 1); PG8_SCHED; PG8_LDA(At, 0, 0); PG8_STAGE(PG8_SA(1, 1), a1 + hstep, voffA);
;             PG8_WAIT_V(8); PG8_WAIT_L(0); PG8_BAR; PG8_MMA(0, 0, At, B0); PG8_MMA(0, 1, At, B1); PG8_BAR; PG8_SCHED;
;             PG8_LDA(At, 0, 1); PG8_STAGE(PG8_SB(0, 0), b2, voffB); PG8_STAGE(PG8_SB(0, 1), b2 + hstep, voffB); PG8_STAGE(PG8_SA(0, 0), a2, voffA);
;             PG8_WAIT_V(8); PG8_WAIT_L(0); PG8_BAR; PG8_MMA(1, 0, At, B0); PG8_MMA(1, 1, At, B1); PG8_BAR; PG8_SCHED;
.LBB0_1261:
	ds_read_b128 v[128:131], v155
	ds_read_b128 v[132:135], v155 offset:1024
	ds_read_b128 v[158:161], v155 offset:2048
	ds_read_b128 v[162:165], v155 offset:3072
	ds_read_b128 v[166:169], v156
	ds_read_b128 v[170:173], v156 offset:1024
	ds_read_b128 v[174:177], v156 offset:2048
	ds_read_b128 v[178:181], v156 offset:3072
	s_add_u32 s16, s14, 0xfffe0080
	s_addc_u32 s17, s15, -1
	s_cmp_eq_u32 s46, 4
	s_cselect_b32 s21, s7, s17
	s_cselect_b32 s20, s42, s16
	s_cselect_b32 s17, s5, s45
	s_cselect_b32 s16, s43, s44
	v_lshl_add_u64 v[152:153], s[14:15], 0, v[146:147]
	s_add_i32 m0, s13, 0xc000
	ds_read_b128 v[182:185], v157
	ds_read_b128 v[186:189], v157 offset:1024
	ds_read_b128 v[190:193], v157 offset:2048
	ds_read_b128 v[194:197], v157 offset:3072
	ds_read_b128 v[198:201], v157 offset:4096
	ds_read_b128 v[202:205], v157 offset:5120
	ds_read_b128 v[206:209], v157 offset:6144
	ds_read_b128 v[210:213], v157 offset:7168
	global_load_lds_dwordx4 v[152:153], off
	v_lshl_add_u64 v[152:153], s[14:15], 0, v[144:145]
	s_add_i32 m0, s13, 0xe000
	s_nop 0
	global_load_lds_dwordx4 v[152:153], off
	v_lshl_add_u64 v[230:231], s[16:17], 0, v[140:141]
	s_add_u32 s48, s16, 0x20000
	v_lshl_add_u64 v[232:233], s[16:17], 0, v[136:137]
	s_addc_u32 s49, s17, 0
	v_lshl_add_u64 v[234:235], s[48:49], 0, v[140:141]
	v_lshl_add_u64 v[236:237], s[20:21], 0, v[138:139]
	v_lshl_add_u64 v[238:239], s[48:49], 0, v[136:137]
	v_lshl_add_u64 v[240:241], s[20:21], 0, v[142:143]
	s_waitcnt vmcnt(8)
	s_waitcnt lgkmcnt(0)
	s_barrier
	s_setprio 1
	s_waitcnt lgkmcnt(0)
	v_mfma_f32_16x16x32_bf16 v[124:127], v[128:131], v[182:185], v[124:127]
	v_mfma_f32_16x16x32_bf16 v[120:123], v[158:161], v[182:185], v[120:123]
	v_mfma_f32_16x16x32_bf16 v[108:111], v[128:131], v[190:193], v[108:111]
	v_mfma_f32_16x16x32_bf16 v[104:107], v[158:161], v[190:193], v[104:107]
	v_mfma_f32_16x16x32_bf16 v[92:95], v[128:131], v[198:201], v[92:95]
	v_mfma_f32_16x16x32_bf16 v[88:91], v[158:161], v[198:201], v[88:91]
	v_mfma_f32_16x16x32_bf16 v[80:83], v[128:131], v[206:209], v[80:83]
	v_mfma_f32_16x16x32_bf16 v[72:75], v[158:161], v[206:209], v[72:75]
	v_mfma_f32_16x16x32_bf16 v[124:127], v[132:135], v[186:189], v[124:127]
	v_mfma_f32_16x16x32_bf16 v[120:123], v[162:165], v[186:189], v[120:123]
	v_mfma_f32_16x16x32_bf16 v[108:111], v[132:135], v[194:197], v[108:111]
	v_mfma_f32_16x16x32_bf16 v[104:107], v[162:165], v[194:197], v[104:107]
	v_mfma_f32_16x16x32_bf16 v[92:95], v[132:135], v[202:205], v[92:95]
	v_mfma_f32_16x16x32_bf16 v[88:91], v[162:165], v[202:205], v[88:91]
	v_mfma_f32_16x16x32_bf16 v[80:83], v[132:135], v[210:213], v[80:83]
	v_mfma_f32_16x16x32_bf16 v[72:75], v[162:165], v[210:213], v[72:75]
	s_setprio 0
	s_setprio 1
	v_mfma_f32_16x16x32_bf16 v[116:119], v[166:169], v[182:185], v[116:119]
	v_mfma_f32_16x16x32_bf16 v[112:115], v[174:177], v[182:185], v[112:115]
	v_mfma_f32_16x16x32_bf16 v[100:103], v[166:169], v[190:193], v[100:103]
	v_mfma_f32_16x16x32_bf16 v[96:99], v[174:177], v[190:193], v[96:99]
	v_mfma_f32_16x16x32_bf16 v[84:87], v[166:169], v[198:201], v[84:87]
	v_mfma_f32_16x16x32_bf16 v[76:79], v[174:177], v[198:201], v[76:79]
	v_mfma_f32_16x16x32_bf16 v[68:71], v[166:169], v[206:209], v[68:71]
	v_mfma_f32_16x16x32_bf16 v[64:67], v[174:177], v[206:209], v[64:67]
	v_mfma_f32_16x16x32_bf16 v[116:119], v[170:173], v[186:189], v[116:119]
	v_mfma_f32_16x16x32_bf16 v[112:115], v[178:181], v[186:189], v[112:115]
	v_mfma_f32_16x16x32_bf16 v[100:103], v[170:173], v[194:197], v[100:103]
	v_mfma_f32_16x16x32_bf16 v[96:99], v[178:181], v[194:197], v[96:99]
	v_mfma_f32_16x16x32_bf16 v[84:87], v[170:173], v[202:205], v[84:87]
	v_mfma_f32_16x16x32_bf16 v[76:79], v[178:181], v[202:205], v[76:79]
	v_mfma_f32_16x16x32_bf16 v[68:71], v[170:173], v[210:213], v[68:71]
	v_mfma_f32_16x16x32_bf16 v[64:67], v[178:181], v[210:213], v[64:67]
	s_setprio 0
	s_barrier
	s_add_i32 s47, s39, s33
	s_mov_b32 m0, s47
	ds_read_b128 v[182:185], v157 offset:16384
	ds_read_b128 v[186:189], v157 offset:17408
	ds_read_b128 v[190:193], v157 offset:18432
	ds_read_b128 v[194:197], v157 offset:19456
	ds_read_b128 v[198:201], v157 offset:20480
	ds_read_b128 v[202:205], v157 offset:21504
	ds_read_b128 v[206:209], v157 offset:22528
	ds_read_b128 v[210:213], v157 offset:23552
	global_load_lds_dwordx4 v[230:231], off
	s_add_i32 m0, s47, 0x2000
	s_add_i32 s47, s40, s33
	global_load_lds_dwordx4 v[232:233], off
	s_mov_b32 m0, s47
	s_nop 0
	global_load_lds_dwordx4 v[234:235], off
	s_add_i32 m0, s47, 0x2000
	s_nop 0
	global_load_lds_dwordx4 v[238:239], off
	s_mov_b32 m0, s13
	s_nop 0
	global_load_lds_dwordx4 v[240:241], off
	s_mov_b32 m0, s28
	s_nop 0
	global_load_lds_dwordx4 v[236:237], off
	s_waitcnt vmcnt(8)
	s_waitcnt lgkmcnt(0)
	s_barrier
; #define PG8_STAGE(bufoff, gbase, voff) do { _Pragma("unroll") for (int _i = 0; _i < 2; ++_i) \
;         __builtin_amdgcn_global_load_lds((const unsigned*)((const char*)(gbase) + (voff)[_i]), (PG8_LAS unsigned*)(lds + (bufoff) + ldsw + _i * 8192), 16, 0, 0); } while (0)
; #define PG8_LDA(dst, b, h) do { _Pragma("unroll") for (int m = 0; m < 4; ++m) _Pragma("unroll") for (int k = 0; k < 2; ++k) dst[m][k] = *(const PG8_LAS bf16x8*)(lds + PG8_SA(b, h) + aoff + m * 2048 + k * 1024); } while (0)
; #define PG8_LDB(dst, b, h) do { _Pragma("unroll") for (int n = 0; n < 2; ++n) _Pragma("unroll") for (int k = 0; k < 2; ++k) dst[n][k] = *(const PG8_LAS bf16x8*)(lds + PG8_SB(b, h) + boff + n * 2048 + k * 1024); } while (0)
; #define PG8_MMA(ai, bj, At, Bt) do { __builtin_amdgcn_s_setprio(1); _Pragma("unroll") for (int m = 0; m < 4; ++m) _Pragma("unroll") for (int n = 0; n < 2; ++n) _Pragma("unroll") for (int k = 0; k < 2; ++k) \
;         acc[ai][bj][m][n] = __builtin_amdgcn_mfma_f32_16x16x32_bf16(Bt[n][k], At[m][k], acc[ai][bj][m][n], 0, 0, 0); __builtin_amdgcn_s_setprio(0); } while (0)
; #define PG8_WAIT_V(n) asm volatile("s_waitcnt vmcnt(" #n ")" ::: "memory")
; #define PG8_WAIT_L(n) asm volatile("s_waitcnt lgkmcnt(" #n ")" ::: "memory")
; #define PG8_BAR __builtin_amdgcn_s_barrier()
; #define PG8_SCHED __builtin_amdgcn_sched_barrier(0)
; template <class Epi, class Sched, bool ALIGN_EPI = false, bool SP2 = false>
; __device__ __forceinline__ void gemm_phase(PG8_LAS unsigned char* lds, const Gemm g, const Sched& S, const Epi& E, const int wave_s) {
;     ...
;             PG8_WAIT_V(8); PG8_WAIT_L(0); PG8_BAR; PG8_MMA(1, 0, At, B0); PG8_MMA(1, 1, At, B1); PG8_BAR; PG8_SCHED;
;             PG8_LDB(B0, 1, 0); PG8_LDB(B1, 1, 1); PG8_SCHED; PG8_LDA(At, 1, 0); PG8_STAGE(PG8_SA(0, 1), a2 + hstep, voffA);
;             PG8_WAIT_V(8); PG8_WAIT_L(0); PG8_BAR; PG8_MMA(0, 0, At, B0); PG8_MMA(0, 1, At, B1); PG8_BAR; PG8_SCHED;
;             PG8_LDA(At, 1, 1); PG8_STAGE(PG8_SB(1, 0), b3, voffB); PG8_STAGE(PG8_SB(1, 1), b3 + hstep, voffB); PG8_STAGE(PG8_SA(1, 0), a3, voffA);
	s_setprio 1
	s_waitcnt lgkmcnt(0)
	v_mfma_f32_16x16x32_bf16 v[60:63], v[128:131], v[182:185], v[60:63]
	v_mfma_f32_16x16x32_bf16 v[56:59], v[158:161], v[182:185], v[56:59]
	v_mfma_f32_16x16x32_bf16 v[48:51], v[128:131], v[190:193], v[48:51]
	v_mfma_f32_16x16x32_bf16 v[40:43], v[158:161], v[190:193], v[40:43]
	v_mfma_f32_16x16x32_bf16 v[32:35], v[128:131], v[198:201], v[32:35]
	v_mfma_f32_16x16x32_bf16 v[24:27], v[158:161], v[198:201], v[24:27]
	v_mfma_f32_16x16x32_bf16 v[16:19], v[128:131], v[206:209], v[16:19]
	v_mfma_f32_16x16x32_bf16 v[8:11], v[158:161], v[206:209], v[8:11]
	v_mfma_f32_16x16x32_bf16 v[60:63], v[132:135], v[186:189], v[60:63]
	v_mfma_f32_16x16x32_bf16 v[56:59], v[162:165], v[186:189], v[56:59]
	v_mfma_f32_16x16x32_bf16 v[48:51], v[132:135], v[194:197], v[48:51]
	v_mfma_f32_16x16x32_bf16 v[40:43], v[162:165], v[194:197], v[40:43]
	v_mfma_f32_16x16x32_bf16 v[32:35], v[132:135], v[202:205], v[32:35]
	v_mfma_f32_16x16x32_bf16 v[24:27], v[162:165], v[202:205], v[24:27]
	v_mfma_f32_16x16x32_bf16 v[16:19], v[132:135], v[210:213], v[16:19]
	v_mfma_f32_16x16x32_bf16 v[8:11], v[162:165], v[210:213], v[8:11]
	s_setprio 0
	s_setprio 1
	v_mfma_f32_16x16x32_bf16 v[52:55], v[166:169], v[182:185], v[52:55]
	v_mfma_f32_16x16x32_bf16 v[44:47], v[174:177], v[182:185], v[44:47]
	v_mfma_f32_16x16x32_bf16 v[36:39], v[166:169], v[190:193], v[36:39]
	v_mfma_f32_16x16x32_bf16 v[28:31], v[174:177], v[190:193], v[28:31]
	v_mfma_f32_16x16x32_bf16 v[20:23], v[166:169], v[198:201], v[20:23]
	v_mfma_f32_16x16x32_bf16 v[12:15], v[174:177], v[198:201], v[12:15]
	v_mfma_f32_16x16x32_bf16 v[4:7], v[166:169], v[206:209], v[4:7]
	v_mfma_f32_16x16x32_bf16 v[0:3], v[174:177], v[206:209], v[0:3]
	v_mfma_f32_16x16x32_bf16 v[52:55], v[170:173], v[186:189], v[52:55]
	v_mfma_f32_16x16x32_bf16 v[44:47], v[178:181], v[186:189], v[44:47]
	v_mfma_f32_16x16x32_bf16 v[36:39], v[170:173], v[194:197], v[36:39]
	v_mfma_f32_16x16x32_bf16 v[28:31], v[178:181], v[194:197], v[28:31]
	v_mfma_f32_16x16x32_bf16 v[20:23], v[170:173], v[202:205], v[20:23]
	v_mfma_f32_16x16x32_bf16 v[12:15], v[178:181], v[202:205], v[12:15]
	v_mfma_f32_16x16x32_bf16 v[4:7], v[170:173], v[210:213], v[4:7]
	v_mfma_f32_16x16x32_bf16 v[0:3], v[178:181], v[210:213], v[0:3]
	s_setprio 0
	s_barrier
	s_add_i32 s47, 0, 0x18000
	s_add_i32 s48, 0, 0x1c000
	v_add_u32_e32 v162, s47, v154
	v_add_u32_e32 v178, s48, v154
	ds_read_b128 v[128:131], v162
	ds_read_b128 v[132:135], v162 offset:1024
	ds_read_b128 v[158:161], v162 offset:2048
	ds_read_b128 v[162:165], v162 offset:3072
	ds_read_b128 v[166:169], v178
	ds_read_b128 v[170:173], v178 offset:1024
	ds_read_b128 v[174:177], v178 offset:2048
	ds_read_b128 v[178:181], v178 offset:3072
	s_add_u32 s20, s20, 0x20000
	s_addc_u32 s21, s21, 0
	s_mov_b32 m0, s29
	v_lshl_add_u64 v[220:221], s[20:21], 0, v[142:143]
	ds_read_b128 v[182:185], v157 offset:32768
	ds_read_b128 v[186:189], v157 offset:33792
	ds_read_b128 v[190:193], v157 offset:34816
	ds_read_b128 v[194:197], v157 offset:35840
	ds_read_b128 v[198:201], v157 offset:36864
	ds_read_b128 v[202:205], v157 offset:37888
	ds_read_b128 v[206:209], v157 offset:38912
	ds_read_b128 v[210:213], v157 offset:39936
	global_load_lds_dwordx4 v[220:221], off
	v_lshl_add_u64 v[220:221], s[20:21], 0, v[138:139]
	s_mov_b32 m0, s30
	s_nop 0
	global_load_lds_dwordx4 v[220:221], off
	v_lshl_add_u64 v[242:243], v[230:231], 0, s[2:3]
	s_add_u32 s16, s16, 0x20080
	v_lshl_add_u64 v[244:245], v[232:233], 0, s[2:3]
	s_addc_u32 s17, s17, 0
	v_lshl_add_u64 v[246:247], s[16:17], 0, v[140:141]
	v_lshl_add_u64 v[248:249], s[16:17], 0, v[136:137]
	v_lshl_add_u64 v[250:251], v[240:241], 0, s[2:3]
	v_lshl_add_u64 v[252:253], v[236:237], 0, s[2:3]
	s_waitcnt vmcnt(8)
	s_waitcnt lgkmcnt(0)
	s_barrier
	s_setprio 1
	s_waitcnt lgkmcnt(0)
	v_mfma_f32_16x16x32_bf16 v[124:127], v[128:131], v[182:185], v[124:127]
	v_mfma_f32_16x16x32_bf16 v[120:123], v[158:161], v[182:185], v[120:123]
	v_mfma_f32_16x16x32_bf16 v[108:111], v[128:131], v[190:193], v[108:111]
	v_mfma_f32_16x16x32_bf16 v[104:107], v[158:161], v[190:193], v[104:107]
	v_mfma_f32_16x16x32_bf16 v[92:95], v[128:131], v[198:201], v[92:95]
	v_mfma_f32_16x16x32_bf16 v[88:91], v[158:161], v[198:201], v[88:91]
	v_mfma_f32_16x16x32_bf16 v[80:83], v[128:131], v[206:209], v[80:83]
	v_mfma_f32_16x16x32_bf16 v[72:75], v[158:161], v[206:209], v[72:75]
	v_mfma_f32_16x16x32_bf16 v[124:127], v[132:135], v[186:189], v[124:127]
	v_mfma_f32_16x16x32_bf16 v[120:123], v[162:165], v[186:189], v[120:123]
	v_mfma_f32_16x16x32_bf16 v[108:111], v[132:135], v[194:197], v[108:111]
	v_mfma_f32_16x16x32_bf16 v[104:107], v[162:165], v[194:197], v[104:107]
	v_mfma_f32_16x16x32_bf16 v[92:95], v[132:135], v[202:205], v[92:95]
	v_mfma_f32_16x16x32_bf16 v[88:91], v[162:165], v[202:205], v[88:91]
	v_mfma_f32_16x16x32_bf16 v[80:83], v[132:135], v[210:213], v[80:83]
	v_mfma_f32_16x16x32_bf16 v[72:75], v[162:165], v[210:213], v[72:75]
	s_setprio 0
	s_setprio 1
	v_mfma_f32_16x16x32_bf16 v[116:119], v[166:169], v[182:185], v[116:119]
	v_mfma_f32_16x16x32_bf16 v[112:115], v[174:177], v[182:185], v[112:115]
	v_mfma_f32_16x16x32_bf16 v[100:103], v[166:169], v[190:193], v[100:103]
	v_mfma_f32_16x16x32_bf16 v[96:99], v[174:177], v[190:193], v[96:99]
	v_mfma_f32_16x16x32_bf16 v[84:87], v[166:169], v[198:201], v[84:87]
	v_mfma_f32_16x16x32_bf16 v[76:79], v[174:177], v[198:201], v[76:79]
	v_mfma_f32_16x16x32_bf16 v[68:71], v[166:169], v[206:209], v[68:71]
	v_mfma_f32_16x16x32_bf16 v[64:67], v[174:177], v[206:209], v[64:67]
	v_mfma_f32_16x16x32_bf16 v[116:119], v[170:173], v[186:189], v[116:119]
	v_mfma_f32_16x16x32_bf16 v[112:115], v[178:181], v[186:189], v[112:115]
	v_mfma_f32_16x16x32_bf16 v[100:103], v[170:173], v[194:197], v[100:103]
	v_mfma_f32_16x16x32_bf16 v[96:99], v[178:181], v[194:197], v[96:99]
	v_mfma_f32_16x16x32_bf16 v[84:87], v[170:173], v[202:205], v[84:87]
	v_mfma_f32_16x16x32_bf16 v[76:79], v[178:181], v[202:205], v[76:79]
	v_mfma_f32_16x16x32_bf16 v[68:71], v[170:173], v[210:213], v[68:71]
	v_mfma_f32_16x16x32_bf16 v[64:67], v[178:181], v[210:213], v[64:67]
	s_setprio 0
	s_barrier
; #define PG8_STAGE(bufoff, gbase, voff) do { _Pragma("unroll") for (int _i = 0; _i < 2; ++_i) \
;         __builtin_amdgcn_global_load_lds((const unsigned*)((const char*)(gbase) + (voff)[_i]), (PG8_LAS unsigned*)(lds + (bufoff) + ldsw + _i * 8192), 16, 0, 0); } while (0)
; #define PG8_LDA(dst, b, h) do { _Pragma("unroll") for (int m = 0; m < 4; ++m) _Pragma("unroll") for (int k = 0; k < 2; ++k) dst[m][k] = *(const PG8_LAS bf16x8*)(lds + PG8_SA(b, h) + aoff + m * 2048 + k * 1024); } while (0)
; #define PG8_MMA(ai, bj, At, Bt) do { __builtin_amdgcn_s_setprio(1); _Pragma("unroll") for (int m = 0; m < 4; ++m) _Pragma("unroll") for (int n = 0; n < 2; ++n) _Pragma("unroll") for (int k = 0; k < 2; ++k) \
;         acc[ai][bj][m][n] = __builtin_amdgcn_mfma_f32_16x16x32_bf16(Bt[n][k], At[m][k], acc[ai][bj][m][n], 0, 0, 0); __builtin_amdgcn_s_setprio(0); } while (0)
; #define PG8_WAIT_V(n) asm volatile("s_waitcnt vmcnt(" #n ")" ::: "memory")
; #define PG8_WAIT_L(n) asm volatile("s_waitcnt lgkmcnt(" #n ")" ::: "memory")
; #define PG8_BAR __builtin_amdgcn_s_barrier()
; #define PG8_SCHED __builtin_amdgcn_sched_barrier(0)
; #define MUL_LOAD(buf, b_) do { int RRl = row0 + ((b_) >> 1) * 128 + ((b_) & 1) * 32; asm volatile("" : "+v"(RRl)); const bf16* pl = G + (size_t)RRl * 1024 + col0; \
;             _Pragma("unroll") for (int mi = 0; mi < 2; ++mi) _Pragma("unroll") for (int bj = 0; bj < 2; ++bj) o[buf][mi][bj] = *(const v4u*)(pl + mi * 16 * 1024 + bj * 128); } while (0)
; template <class Epi, class Sched, bool ALIGN_EPI = false, bool SP2 = false>
; __device__ __forceinline__ void gemm_phase(PG8_LAS unsigned char* lds, const Gemm g, const Sched& S, const Epi& E, const int wave_s) {
;     ...
;             PG8_LDA(At, 1, 1); PG8_STAGE(PG8_SB(1, 0), b3, voffB); PG8_STAGE(PG8_SB(1, 1), b3 + hstep, voffB); PG8_STAGE(PG8_SA(1, 0), a3, voffA);
;             PG8_WAIT_V(8); PG8_WAIT_L(0); PG8_BAR; PG8_MMA(1, 0, At, B0); PG8_MMA(1, 1, At, B1); PG8_BAR; PG8_SCHED;
;     __device__ __forceinline__ void operator()(const af4 (&acc)[2][2][4][2], const pg8::Unit& u, int wr, int wc, int fr_, int fq_) const {
;     ...
;         const int row0 = u.pm * 256 + wr * 64 + fr, col0 = u.pn * 256 + wc * 32 + 8 * fq;
;         v4u o[2][2][2];
;     ...
;         MUL_LOAD(0, 0);
	s_add_i32 s20, s47, s33
	s_mov_b32 m0, s20
	ds_read_b128 v[182:185], v157 offset:49152
	ds_read_b128 v[186:189], v157 offset:50176
	ds_read_b128 v[190:193], v157 offset:51200
	ds_read_b128 v[194:197], v157 offset:52224
	ds_read_b128 v[198:201], v157 offset:53248
	ds_read_b128 v[202:205], v157 offset:54272
	ds_read_b128 v[206:209], v157 offset:55296
	ds_read_b128 v[210:213], v157 offset:56320
	global_load_lds_dwordx4 v[242:243], off
	s_add_i32 m0, s20, 0x2000
	s_add_i32 s20, s48, s33
	global_load_lds_dwordx4 v[244:245], off
	s_mov_b32 m0, s20
	s_nop 0
	global_load_lds_dwordx4 v[246:247], off
	s_add_i32 m0, s20, 0x2000
	s_nop 0
	global_load_lds_dwordx4 v[248:249], off
	s_mov_b32 m0, s34
	s_nop 0
	global_load_lds_dwordx4 v[250:251], off
	s_mov_b32 m0, s35
	s_nop 0
	global_load_lds_dwordx4 v[252:253], off
	s_waitcnt vmcnt(8)
	s_waitcnt lgkmcnt(0)
	s_barrier
	s_setprio 1
	s_waitcnt lgkmcnt(0)
	v_mfma_f32_16x16x32_bf16 v[60:63], v[128:131], v[182:185], v[60:63]
	v_mfma_f32_16x16x32_bf16 v[56:59], v[158:161], v[182:185], v[56:59]
	v_mfma_f32_16x16x32_bf16 v[48:51], v[128:131], v[190:193], v[48:51]
	v_mfma_f32_16x16x32_bf16 v[40:43], v[158:161], v[190:193], v[40:43]
	v_mfma_f32_16x16x32_bf16 v[32:35], v[128:131], v[198:201], v[32:35]
	v_mfma_f32_16x16x32_bf16 v[24:27], v[158:161], v[198:201], v[24:27]
	v_mfma_f32_16x16x32_bf16 v[16:19], v[128:131], v[206:209], v[16:19]
	v_mfma_f32_16x16x32_bf16 v[8:11], v[158:161], v[206:209], v[8:11]
	v_mfma_f32_16x16x32_bf16 v[60:63], v[132:135], v[186:189], v[60:63]
	v_mfma_f32_16x16x32_bf16 v[56:59], v[162:165], v[186:189], v[56:59]
	v_mfma_f32_16x16x32_bf16 v[48:51], v[132:135], v[194:197], v[48:51]
	v_mfma_f32_16x16x32_bf16 v[40:43], v[162:165], v[194:197], v[40:43]
	v_mfma_f32_16x16x32_bf16 v[32:35], v[132:135], v[202:205], v[32:35]
	v_mfma_f32_16x16x32_bf16 v[24:27], v[162:165], v[202:205], v[24:27]
	v_mfma_f32_16x16x32_bf16 v[16:19], v[132:135], v[210:213], v[16:19]
	v_mfma_f32_16x16x32_bf16 v[8:11], v[162:165], v[210:213], v[8:11]
	s_setprio 0
	s_setprio 1
	v_mfma_f32_16x16x32_bf16 v[52:55], v[166:169], v[182:185], v[52:55]
	v_mfma_f32_16x16x32_bf16 v[44:47], v[174:177], v[182:185], v[44:47]
	v_mfma_f32_16x16x32_bf16 v[36:39], v[166:169], v[190:193], v[36:39]
	v_mfma_f32_16x16x32_bf16 v[28:31], v[174:177], v[190:193], v[28:31]
	v_mfma_f32_16x16x32_bf16 v[20:23], v[166:169], v[198:201], v[20:23]
	v_mfma_f32_16x16x32_bf16 v[12:15], v[174:177], v[198:201], v[12:15]
	v_mfma_f32_16x16x32_bf16 v[4:7], v[166:169], v[206:209], v[4:7]
	v_mfma_f32_16x16x32_bf16 v[0:3], v[174:177], v[206:209], v[0:3]
	v_mfma_f32_16x16x32_bf16 v[52:55], v[170:173], v[186:189], v[52:55]
	v_mfma_f32_16x16x32_bf16 v[44:47], v[178:181], v[186:189], v[44:47]
	v_mfma_f32_16x16x32_bf16 v[36:39], v[170:173], v[194:197], v[36:39]
	v_mfma_f32_16x16x32_bf16 v[28:31], v[178:181], v[194:197], v[28:31]
	v_mfma_f32_16x16x32_bf16 v[20:23], v[170:173], v[202:205], v[20:23]
	v_mfma_f32_16x16x32_bf16 v[12:15], v[178:181], v[202:205], v[12:15]
	v_mfma_f32_16x16x32_bf16 v[4:7], v[170:173], v[210:213], v[4:7]
	v_mfma_f32_16x16x32_bf16 v[0:3], v[178:181], v[210:213], v[0:3]
	s_setprio 0
	s_barrier
	s_add_i32 s46, s46, 2
	s_add_u32 s44, s44, 0x100
	s_addc_u32 s45, s45, 0
	s_add_u32 s14, s14, 0x100
	s_addc_u32 s15, s15, 0
	s_cmp_gt_u32 s46, 5
	s_cbranch_scc0 .LBB0_1261
	s_lshl_b32 s5, s12, 8
	v_mbcnt_lo_u32_b32 v128, -1, 0
	v_mbcnt_hi_u32_b32 v128, -1, v128
	s_add_i32 s5, s5, s87
	v_and_or_b32 v194, v128, 15, s5
	s_lshl_b32 s5, s41, 8
	v_ashrrev_i32_e32 v128, 1, v128
	s_or_b32 s5, s5, s79
	v_and_b32_e32 v128, -8, v128
	v_mov_b32_e32 v130, v194
	v_add_u32_e32 v128, s5, v128
	v_ashrrev_i32_e32 v129, 31, v128
	v_ashrrev_i32_e32 v131, 31, v130
	v_lshlrev_b64 v[130:131], 11, v[130:131]
	v_lshl_add_u64 v[130:131], s[0:1], 0, v[130:131]
	v_lshlrev_b64 v[152:153], 1, v[128:129]
	v_lshl_add_u64 v[128:129], v[130:131], 0, v[152:153]
	global_load_dwordx4 v[158:161], v[128:129], off
	global_load_dwordx4 v[162:165], v[128:129], off offset:256
	v_add_co_u32_e32 v128, vcc, s36, v128
	v_or_b32_e32 v182, 32, v194
	s_nop 0
	v_addc_co_u32_e32 v129, vcc, 0, v129, vcc
	global_load_dwordx4 v[166:169], v[128:129], off
	global_load_dwordx4 v[170:173], v[128:129], off offset:256
	v_mov_b32_e32 v128, v182
	v_mov_b32_e32 v184, v194
	v_ashrrev_i32_e32 v129, 31, v128
	v_lshlrev_b64 v[128:129], 11, v[128:129]
	v_lshl_add_u64 v[128:129], s[0:1], 0, v[128:129]
	v_lshl_add_u64 v[128:129], v[128:129], 0, v[152:153]
	global_load_dwordx4 v[174:177], v[128:129], off
	global_load_dwordx4 v[178:181], v[128:129], off offset:256
	v_add_co_u32_e32 v128, vcc, s36, v128
	s_mov_b32 s41, s4
	s_nop 0
	v_addc_co_u32_e32 v129, vcc, 0, v129, vcc
	global_load_dwordx4 v[132:135], v[128:129], off
	s_nop 0
	global_load_dwordx4 v[128:131], v[128:129], off offset:256
	s_mov_b32 s12, s6
	v_ashrrev_i32_e32 v185, 31, v184
	v_lshlrev_b64 v[184:185], 11, v[184:185]
	v_lshl_add_u64 v[184:185], s[0:1], 0, v[184:185]
	v_lshl_add_u64 v[184:185], v[184:185], 0, v[152:153]
	s_mov_b64 s[14:15], s[10:11]
	s_mov_b64 s[16:17], s[8:9]
	s_waitcnt vmcnt(0)
; __device__ __forceinline__ unsigned cvtpk(float lo, float hi) { f32x2 v = {lo, hi}; bf16x2_t b = __builtin_convertvector(v, bf16x2_t); return __builtin_bit_cast(unsigned, b); }
; __device__ __forceinline__ float bflo(unsigned u) { return __uint_as_float(u << 16); }
; __device__ __forceinline__ float bfhi(unsigned u) { return __uint_as_float(u & 0xffff0000u); }
; #define MUL_LOAD(buf, b_) do { int RRl = row0 + ((b_) >> 1) * 128 + ((b_) & 1) * 32; asm volatile("" : "+v"(RRl)); const bf16* pl = G + (size_t)RRl * 1024 + col0; \
;             _Pragma("unroll") for (int mi = 0; mi < 2; ++mi) _Pragma("unroll") for (int bj = 0; bj < 2; ++bj) o[buf][mi][bj] = *(const v4u*)(pl + mi * 16 * 1024 + bj * 128); } while (0)
;     __device__ __forceinline__ void operator()(const af4 (&acc)[2][2][4][2], const pg8::Unit& u, int wr, int wc, int fr_, int fq_) const {
;     ...
;         for (int b_ = 0; b_ < 4; ++b_) {
;             const int ai = b_ >> 1, mp = b_ & 1, cur = b_ & 1;
;             if (b_ + 1 < 4) { if (cur == 0) MUL_LOAD(1, b_ + 1); else MUL_LOAD(0, b_ + 1); }
;             int RRb = row0 + ai * 128 + mp * 32; asm volatile("" : "+v"(RRb));
;             bf16* pb = G + (size_t)RRb * 1024 + col0;
; #pragma unroll
;             for (int mi = 0; mi < 2; ++mi)
; #pragma unroll
;                 for (int bj = 0; bj < 2; ++bj) { const af4 v0 = acc[ai][bj][mp * 2 + mi][0], v1 = acc[ai][bj][mp * 2 + mi][1]; const v4u oo = o[cur][mi][bj];
;                     v4u w; w.x = cvtpk(v0[0] * bflo(oo.x), v0[1] * bfhi(oo.x)); w.y = cvtpk(v0[2] * bflo(oo.y), v0[3] * bfhi(oo.y)); w.z = cvtpk(v1[0] * bflo(oo.z), v1[1] * bfhi(oo.z)); w.w = cvtpk(v1[2] * bflo(oo.w), v1[3] * bfhi(oo.w));
;                     *(v4u*)(pb + mi * 16 * 1024 + bj * 128) = w; }
	v_lshlrev_b32_e32 v188, 16, v160
	v_and_b32_e32 v189, 0xffff0000, v160
	v_lshlrev_b32_e32 v160, 16, v161
	v_and_b32_e32 v161, 0xffff0000, v161
	v_lshlrev_b32_e32 v190, 16, v162
	v_and_b32_e32 v191, 0xffff0000, v162
	v_lshlrev_b32_e32 v162, 16, v163
	v_and_b32_e32 v163, 0xffff0000, v163
	v_lshlrev_b32_e32 v192, 16, v164
	v_and_b32_e32 v193, 0xffff0000, v164
	v_lshlrev_b32_e32 v164, 16, v165
	v_and_b32_e32 v165, 0xffff0000, v165
	v_pk_mul_f32 v[122:123], v[122:123], v[160:161]
	v_pk_mul_f32 v[118:119], v[118:119], v[162:163]
	v_pk_mul_f32 v[160:161], v[114:115], v[164:165]
	v_lshlrev_b32_e32 v162, 16, v166
	v_and_b32_e32 v163, 0xffff0000, v166
	v_lshlrev_b32_e32 v164, 16, v167
	v_and_b32_e32 v165, 0xffff0000, v167
	v_lshlrev_b32_e32 v166, 16, v168
	v_and_b32_e32 v167, 0xffff0000, v168
	v_lshlrev_b32_e32 v168, 16, v169
	v_pk_mul_f32 v[108:109], v[108:109], v[162:163]
	v_pk_mul_f32 v[110:111], v[110:111], v[164:165]
	v_pk_mul_f32 v[104:105], v[104:105], v[166:167]
	v_and_b32_e32 v169, 0xffff0000, v169
	v_cvt_pk_bf16_f32 v108, v108, v109
	v_cvt_pk_bf16_f32 v109, v110, v111
	v_cvt_pk_bf16_f32 v110, v104, v105
	v_pk_mul_f32 v[104:105], v[106:107], v[168:169]
	v_lshlrev_b32_e32 v106, 16, v170
	v_and_b32_e32 v107, 0xffff0000, v170
	v_pk_mul_f32 v[100:101], v[100:101], v[106:107]
	v_lshlrev_b32_e32 v106, 16, v171
	v_and_b32_e32 v107, 0xffff0000, v171
	v_pk_mul_f32 v[102:103], v[102:103], v[106:107]
	v_cvt_pk_bf16_f32 v100, v100, v101
	v_cvt_pk_bf16_f32 v101, v102, v103
	v_lshlrev_b32_e32 v102, 16, v172
	v_and_b32_e32 v103, 0xffff0000, v172
	v_lshlrev_b32_e32 v186, 16, v158
	v_and_b32_e32 v187, 0xffff0000, v158
	v_lshlrev_b32_e32 v158, 16, v159
	v_and_b32_e32 v159, 0xffff0000, v159
	v_pk_mul_f32 v[96:97], v[96:97], v[102:103]
	v_pk_mul_f32 v[124:125], v[124:125], v[186:187]
	v_pk_mul_f32 v[126:127], v[126:127], v[158:159]
	v_pk_mul_f32 v[120:121], v[120:121], v[188:189]
	v_cvt_pk_bf16_f32 v102, v96, v97
	v_lshlrev_b32_e32 v96, 16, v173
	v_and_b32_e32 v97, 0xffff0000, v173
	v_pk_mul_f32 v[116:117], v[116:117], v[190:191]
	v_pk_mul_f32 v[158:159], v[112:113], v[192:193]
	v_cvt_pk_bf16_f32 v112, v124, v125
	v_cvt_pk_bf16_f32 v113, v126, v127
	v_cvt_pk_bf16_f32 v114, v120, v121
	v_cvt_pk_bf16_f32 v115, v122, v123
	v_cvt_pk_bf16_f32 v111, v104, v105
	v_add_co_u32_e32 v104, vcc, s36, v184
	v_pk_mul_f32 v[96:97], v[98:99], v[96:97]
	v_cvt_pk_bf16_f32 v116, v116, v117
	v_cvt_pk_bf16_f32 v117, v118, v119
	v_cvt_pk_bf16_f32 v118, v158, v159
	v_cvt_pk_bf16_f32 v119, v160, v161
	global_store_dwordx4 v[184:185], v[112:115], off
	global_store_dwordx4 v[184:185], v[116:119], off offset:256
	v_addc_co_u32_e32 v105, vcc, 0, v185, vcc
	v_cvt_pk_bf16_f32 v103, v96, v97
	v_add_u32_e32 v112, 0x80, v194
	global_store_dwordx4 v[104:105], v[108:111], off
	global_store_dwordx4 v[104:105], v[100:103], off offset:256
	v_mov_b32_e32 v96, v112
	v_lshlrev_b32_e32 v116, 16, v174
	v_ashrrev_i32_e32 v97, 31, v96
	v_lshlrev_b64 v[96:97], 11, v[96:97]
	v_lshl_add_u64 v[96:97], s[0:1], 0, v[96:97]
	v_lshl_add_u64 v[96:97], v[96:97], 0, v[152:153]
	v_and_b32_e32 v117, 0xffff0000, v174
	global_load_dwordx4 v[104:107], v[96:97], off
	global_load_dwordx4 v[108:111], v[96:97], off offset:256
	v_pk_mul_f32 v[92:93], v[92:93], v[116:117]
	v_lshlrev_b32_e32 v116, 16, v175
	v_and_b32_e32 v117, 0xffff0000, v175
	v_pk_mul_f32 v[94:95], v[94:95], v[116:117]
	v_cvt_pk_bf16_f32 v92, v92, v93
	v_cvt_pk_bf16_f32 v93, v94, v95
	v_lshlrev_b32_e32 v94, 16, v176
	v_and_b32_e32 v95, 0xffff0000, v176
	v_pk_mul_f32 v[88:89], v[88:89], v[94:95]
	v_add_co_u32_e32 v96, vcc, s36, v96
	v_cvt_pk_bf16_f32 v94, v88, v89
	v_lshlrev_b32_e32 v88, 16, v177
	v_and_b32_e32 v89, 0xffff0000, v177
	v_pk_mul_f32 v[88:89], v[90:91], v[88:89]
	v_addc_co_u32_e32 v97, vcc, 0, v97, vcc
	v_cvt_pk_bf16_f32 v95, v88, v89
	v_lshlrev_b32_e32 v88, 16, v178
	v_and_b32_e32 v89, 0xffff0000, v178
	v_pk_mul_f32 v[84:85], v[84:85], v[88:89]
	v_lshlrev_b32_e32 v88, 16, v179
	v_and_b32_e32 v89, 0xffff0000, v179
	v_pk_mul_f32 v[86:87], v[86:87], v[88:89]
	v_cvt_pk_bf16_f32 v84, v84, v85
	v_cvt_pk_bf16_f32 v85, v86, v87
	v_lshlrev_b32_e32 v86, 16, v180
	v_and_b32_e32 v87, 0xffff0000, v180
	v_pk_mul_f32 v[76:77], v[76:77], v[86:87]
	global_load_dwordx4 v[100:103], v[96:97], off
	s_nop 0
	global_load_dwordx4 v[96:99], v[96:97], off offset:256
	v_cvt_pk_bf16_f32 v86, v76, v77
	v_lshlrev_b32_e32 v76, 16, v181
	v_and_b32_e32 v77, 0xffff0000, v181
	v_pk_mul_f32 v[76:77], v[78:79], v[76:77]
	v_lshlrev_b32_e32 v78, 16, v133
	v_cvt_pk_bf16_f32 v87, v76, v77
	v_lshlrev_b32_e32 v76, 16, v132
	v_and_b32_e32 v77, 0xffff0000, v132
	v_and_b32_e32 v79, 0xffff0000, v133
	v_pk_mul_f32 v[76:77], v[80:81], v[76:77]
	v_pk_mul_f32 v[78:79], v[82:83], v[78:79]
	v_cvt_pk_bf16_f32 v76, v76, v77
	v_cvt_pk_bf16_f32 v77, v78, v79
	v_lshlrev_b32_e32 v78, 16, v134
	v_and_b32_e32 v79, 0xffff0000, v134
	v_pk_mul_f32 v[72:73], v[72:73], v[78:79]
	v_add_u32_e32 v80, 0xa0, v194
	v_cvt_pk_bf16_f32 v78, v72, v73
	v_lshlrev_b32_e32 v72, 16, v135
	v_and_b32_e32 v73, 0xffff0000, v135
	v_pk_mul_f32 v[72:73], v[74:75], v[72:73]
	v_lshlrev_b32_e32 v74, 16, v128
	v_and_b32_e32 v75, 0xffff0000, v128
	v_pk_mul_f32 v[68:69], v[68:69], v[74:75]
	v_lshlrev_b32_e32 v74, 16, v129
	v_and_b32_e32 v75, 0xffff0000, v129
	v_ashrrev_i32_e32 v183, 31, v182
	v_pk_mul_f32 v[70:71], v[70:71], v[74:75]
	v_lshlrev_b64 v[114:115], 11, v[182:183]
	v_cvt_pk_bf16_f32 v68, v68, v69
	v_cvt_pk_bf16_f32 v69, v70, v71
	v_lshlrev_b32_e32 v70, 16, v130
	v_and_b32_e32 v71, 0xffff0000, v130
	v_lshl_add_u64 v[114:115], s[0:1], 0, v[114:115]
	v_pk_mul_f32 v[64:65], v[64:65], v[70:71]
	v_lshl_add_u64 v[114:115], v[114:115], 0, v[152:153]
	v_cvt_pk_bf16_f32 v70, v64, v65
	v_lshlrev_b32_e32 v64, 16, v131
	v_and_b32_e32 v65, 0xffff0000, v131
	v_cvt_pk_bf16_f32 v79, v72, v73
	v_add_co_u32_e32 v72, vcc, s36, v114
	v_pk_mul_f32 v[64:65], v[66:67], v[64:65]
	s_nop 0
	v_addc_co_u32_e32 v73, vcc, 0, v115, vcc
	v_cvt_pk_bf16_f32 v71, v64, v65
	global_store_dwordx4 v[114:115], v[92:95], off
	global_store_dwordx4 v[114:115], v[84:87], off offset:256
	global_store_dwordx4 v[72:73], v[76:79], off
	global_store_dwordx4 v[72:73], v[68:71], off offset:256
	v_mov_b32_e32 v64, v80
	s_waitcnt vmcnt(7)
; #define PG8_WAIT_V(n) asm volatile("s_waitcnt vmcnt(" #n ")" ::: "memory")
; #define PG8_BAR __builtin_amdgcn_s_barrier()
; __device__ __forceinline__ unsigned cvtpk(float lo, float hi) { f32x2 v = {lo, hi}; bf16x2_t b = __builtin_convertvector(v, bf16x2_t); return __builtin_bit_cast(unsigned, b); }
; __device__ __forceinline__ float bflo(unsigned u) { return __uint_as_float(u << 16); }
; __device__ __forceinline__ float bfhi(unsigned u) { return __uint_as_float(u & 0xffff0000u); }
; #define MUL_LOAD(buf, b_) do { int RRl = row0 + ((b_) >> 1) * 128 + ((b_) & 1) * 32; asm volatile("" : "+v"(RRl)); const bf16* pl = G + (size_t)RRl * 1024 + col0; \
;             _Pragma("unroll") for (int mi = 0; mi < 2; ++mi) _Pragma("unroll") for (int bj = 0; bj < 2; ++bj) o[buf][mi][bj] = *(const v4u*)(pl + mi * 16 * 1024 + bj * 128); } while (0)
; template <class Epi, class Sched, bool ALIGN_EPI = false, bool SP2 = false>
; __device__ __forceinline__ void gemm_phase(PG8_LAS unsigned char* lds, const Gemm g, const Sched& S, const Epi& E, const int wave_s) {
;     ...
;     PG8_WAIT_V(0);
;     if constexpr (!ALIGN_EPI) { if (wr == 0) PG8_BAR; }
;     PG8_BAR;
;     __device__ __forceinline__ void operator()(const af4 (&acc)[2][2][4][2], const pg8::Unit& u, int wr, int wc, int fr_, int fq_) const {
;     ...
;         for (int b_ = 0; b_ < 4; ++b_) {
;             const int ai = b_ >> 1, mp = b_ & 1, cur = b_ & 1;
;             if (b_ + 1 < 4) { if (cur == 0) MUL_LOAD(1, b_ + 1); else MUL_LOAD(0, b_ + 1); }
;             int RRb = row0 + ai * 128 + mp * 32; asm volatile("" : "+v"(RRb));
;             bf16* pb = G + (size_t)RRb * 1024 + col0;
; #pragma unroll
;             for (int mi = 0; mi < 2; ++mi)
; #pragma unroll
;                 for (int bj = 0; bj < 2; ++bj) { const af4 v0 = acc[ai][bj][mp * 2 + mi][0], v1 = acc[ai][bj][mp * 2 + mi][1]; const v4u oo = o[cur][mi][bj];
;                     v4u w; w.x = cvtpk(v0[0] * bflo(oo.x), v0[1] * bfhi(oo.x)); w.y = cvtpk(v0[2] * bflo(oo.y), v0[3] * bfhi(oo.y)); w.z = cvtpk(v1[0] * bflo(oo.z), v1[1] * bfhi(oo.z)); w.w = cvtpk(v1[2] * bflo(oo.w), v1[3] * bfhi(oo.w));
;                     *(v4u*)(pb + mi * 16 * 1024 + bj * 128) = w; }
;             asm volatile("" ::: "memory");
;         }
	v_lshlrev_b32_e32 v84, 16, v104
	v_ashrrev_i32_e32 v65, 31, v64
	v_lshlrev_b64 v[64:65], 11, v[64:65]
	v_lshl_add_u64 v[64:65], s[0:1], 0, v[64:65]
	v_lshl_add_u64 v[64:65], v[64:65], 0, v[152:153]
	global_load_dwordx4 v[68:71], v[64:65], off
	global_load_dwordx4 v[72:75], v[64:65], off offset:256
	v_add_co_u32_e32 v64, vcc, s36, v64
	v_and_b32_e32 v85, 0xffff0000, v104
	s_nop 0
	v_addc_co_u32_e32 v65, vcc, 0, v65, vcc
	global_load_dwordx4 v[76:79], v[64:65], off
	s_nop 0
	global_load_dwordx4 v[64:67], v[64:65], off offset:256
	v_pk_mul_f32 v[60:61], v[60:61], v[84:85]
	v_lshlrev_b32_e32 v84, 16, v105
	v_and_b32_e32 v85, 0xffff0000, v105
	v_pk_mul_f32 v[62:63], v[62:63], v[84:85]
	v_cvt_pk_bf16_f32 v60, v60, v61
	v_cvt_pk_bf16_f32 v61, v62, v63
	v_lshlrev_b32_e32 v62, 16, v106
	v_and_b32_e32 v63, 0xffff0000, v106
	v_pk_mul_f32 v[56:57], v[56:57], v[62:63]
	s_nop 0
	v_cvt_pk_bf16_f32 v62, v56, v57
	v_lshlrev_b32_e32 v56, 16, v107
	v_and_b32_e32 v57, 0xffff0000, v107
	v_pk_mul_f32 v[56:57], v[58:59], v[56:57]
	v_ashrrev_i32_e32 v113, 31, v112
	v_cvt_pk_bf16_f32 v63, v56, v57
	s_waitcnt vmcnt(10)
	v_lshlrev_b32_e32 v56, 16, v108
	v_and_b32_e32 v57, 0xffff0000, v108
	v_pk_mul_f32 v[52:53], v[52:53], v[56:57]
	v_lshlrev_b32_e32 v56, 16, v109
	v_and_b32_e32 v57, 0xffff0000, v109
	v_pk_mul_f32 v[54:55], v[54:55], v[56:57]
	v_cvt_pk_bf16_f32 v52, v52, v53
	v_cvt_pk_bf16_f32 v53, v54, v55
	v_lshlrev_b32_e32 v54, 16, v110
	v_and_b32_e32 v55, 0xffff0000, v110
	v_pk_mul_f32 v[44:45], v[44:45], v[54:55]
	v_lshlrev_b64 v[82:83], 11, v[112:113]
	v_cvt_pk_bf16_f32 v54, v44, v45
	v_lshlrev_b32_e32 v44, 16, v111
	v_and_b32_e32 v45, 0xffff0000, v111
	v_pk_mul_f32 v[44:45], v[46:47], v[44:45]
	s_waitcnt vmcnt(9)
	v_lshlrev_b32_e32 v46, 16, v101
	v_cvt_pk_bf16_f32 v55, v44, v45
	v_lshlrev_b32_e32 v44, 16, v100
	v_and_b32_e32 v45, 0xffff0000, v100
	v_and_b32_e32 v47, 0xffff0000, v101
	v_pk_mul_f32 v[44:45], v[48:49], v[44:45]
	v_pk_mul_f32 v[46:47], v[50:51], v[46:47]
	v_cvt_pk_bf16_f32 v44, v44, v45
	v_cvt_pk_bf16_f32 v45, v46, v47
	v_lshlrev_b32_e32 v46, 16, v102
	v_and_b32_e32 v47, 0xffff0000, v102
	v_pk_mul_f32 v[40:41], v[40:41], v[46:47]
	v_lshl_add_u64 v[82:83], s[0:1], 0, v[82:83]
	v_cvt_pk_bf16_f32 v46, v40, v41
	v_lshlrev_b32_e32 v40, 16, v103
	v_and_b32_e32 v41, 0xffff0000, v103
	v_pk_mul_f32 v[40:41], v[42:43], v[40:41]
	s_waitcnt vmcnt(8)
	v_lshlrev_b32_e32 v42, 16, v96
	v_and_b32_e32 v43, 0xffff0000, v96
	v_pk_mul_f32 v[36:37], v[36:37], v[42:43]
	v_lshlrev_b32_e32 v42, 16, v97
	v_and_b32_e32 v43, 0xffff0000, v97
	v_pk_mul_f32 v[38:39], v[38:39], v[42:43]
	v_cvt_pk_bf16_f32 v36, v36, v37
	v_cvt_pk_bf16_f32 v37, v38, v39
	v_lshlrev_b32_e32 v38, 16, v98
	v_and_b32_e32 v39, 0xffff0000, v98
	v_pk_mul_f32 v[28:29], v[28:29], v[38:39]
	v_lshl_add_u64 v[82:83], v[82:83], 0, v[152:153]
	v_cvt_pk_bf16_f32 v38, v28, v29
	v_lshlrev_b32_e32 v28, 16, v99
	v_and_b32_e32 v29, 0xffff0000, v99
	v_cvt_pk_bf16_f32 v47, v40, v41
	v_add_co_u32_e32 v40, vcc, s36, v82
	v_pk_mul_f32 v[28:29], v[30:31], v[28:29]
	s_nop 0
	v_addc_co_u32_e32 v41, vcc, 0, v83, vcc
	v_cvt_pk_bf16_f32 v39, v28, v29
	global_store_dwordx4 v[82:83], v[60:63], off
	global_store_dwordx4 v[82:83], v[52:55], off offset:256
	global_store_dwordx4 v[40:41], v[44:47], off
	global_store_dwordx4 v[40:41], v[36:39], off offset:256
	s_waitcnt vmcnt(7)
	v_lshlrev_b32_e32 v30, 16, v69
	v_ashrrev_i32_e32 v81, 31, v80
	v_lshlrev_b64 v[28:29], 11, v[80:81]
	v_lshl_add_u64 v[28:29], s[0:1], 0, v[28:29]
	v_lshl_add_u64 v[36:37], v[28:29], 0, v[152:153]
	v_lshlrev_b32_e32 v28, 16, v68
	v_and_b32_e32 v29, 0xffff0000, v68
	v_and_b32_e32 v31, 0xffff0000, v69
	v_pk_mul_f32 v[28:29], v[32:33], v[28:29]
	v_pk_mul_f32 v[30:31], v[34:35], v[30:31]
	v_cvt_pk_bf16_f32 v28, v28, v29
	v_cvt_pk_bf16_f32 v29, v30, v31
	v_lshlrev_b32_e32 v30, 16, v70
	v_and_b32_e32 v31, 0xffff0000, v70
	v_pk_mul_f32 v[24:25], v[24:25], v[30:31]
	s_nop 0
	v_cvt_pk_bf16_f32 v30, v24, v25
	v_lshlrev_b32_e32 v24, 16, v71
	v_and_b32_e32 v25, 0xffff0000, v71
	v_pk_mul_f32 v[24:25], v[26:27], v[24:25]
	s_nop 0
	v_cvt_pk_bf16_f32 v31, v24, v25
	s_waitcnt vmcnt(6)
	v_lshlrev_b32_e32 v24, 16, v72
	v_and_b32_e32 v25, 0xffff0000, v72
	v_pk_mul_f32 v[20:21], v[20:21], v[24:25]
	v_lshlrev_b32_e32 v24, 16, v73
	v_and_b32_e32 v25, 0xffff0000, v73
	v_pk_mul_f32 v[22:23], v[22:23], v[24:25]
	v_cvt_pk_bf16_f32 v20, v20, v21
	v_cvt_pk_bf16_f32 v21, v22, v23
	v_lshlrev_b32_e32 v22, 16, v74
	v_and_b32_e32 v23, 0xffff0000, v74
	v_pk_mul_f32 v[12:13], v[12:13], v[22:23]
	global_store_dwordx4 v[36:37], v[28:31], off
	v_cvt_pk_bf16_f32 v22, v12, v13
	v_lshlrev_b32_e32 v12, 16, v75
	v_and_b32_e32 v13, 0xffff0000, v75
	v_pk_mul_f32 v[12:13], v[14:15], v[12:13]
	s_waitcnt vmcnt(6)
	v_lshlrev_b32_e32 v14, 16, v77
	v_cvt_pk_bf16_f32 v23, v12, v13
	v_lshlrev_b32_e32 v12, 16, v76
	v_and_b32_e32 v13, 0xffff0000, v76
	v_and_b32_e32 v15, 0xffff0000, v77
	v_pk_mul_f32 v[12:13], v[16:17], v[12:13]
	v_pk_mul_f32 v[14:15], v[18:19], v[14:15]
	v_cvt_pk_bf16_f32 v12, v12, v13
	v_cvt_pk_bf16_f32 v13, v14, v15
	v_lshlrev_b32_e32 v14, 16, v78
	v_and_b32_e32 v15, 0xffff0000, v78
	v_pk_mul_f32 v[8:9], v[8:9], v[14:15]
	global_store_dwordx4 v[36:37], v[20:23], off offset:256
	v_cvt_pk_bf16_f32 v14, v8, v9
	v_lshlrev_b32_e32 v8, 16, v79
	v_and_b32_e32 v9, 0xffff0000, v79
	v_pk_mul_f32 v[8:9], v[10:11], v[8:9]
	s_waitcnt vmcnt(6)
	v_lshlrev_b32_e32 v10, 16, v64
	v_and_b32_e32 v11, 0xffff0000, v64
	v_pk_mul_f32 v[4:5], v[4:5], v[10:11]
	v_lshlrev_b32_e32 v10, 16, v65
	v_and_b32_e32 v11, 0xffff0000, v65
	v_pk_mul_f32 v[6:7], v[6:7], v[10:11]
	v_cvt_pk_bf16_f32 v4, v4, v5
	v_cvt_pk_bf16_f32 v5, v6, v7
	v_lshlrev_b32_e32 v6, 16, v66
	v_and_b32_e32 v7, 0xffff0000, v66
	v_pk_mul_f32 v[0:1], v[0:1], v[6:7]
	v_cvt_pk_bf16_f32 v15, v8, v9
	v_cvt_pk_bf16_f32 v6, v0, v1
	v_lshlrev_b32_e32 v0, 16, v67
	v_and_b32_e32 v1, 0xffff0000, v67
	v_add_co_u32_e32 v8, vcc, s36, v36
	v_pk_mul_f32 v[0:1], v[2:3], v[0:1]
	s_nop 0
	v_addc_co_u32_e32 v9, vcc, 0, v37, vcc
	v_cvt_pk_bf16_f32 v7, v0, v1
	global_store_dwordx4 v[8:9], v[12:15], off
	global_store_dwordx4 v[8:9], v[4:7], off offset:256
	s_and_b64 vcc, exec, s[18:19]
	s_cbranch_vccz .LBB0_1258
	s_waitcnt vmcnt(0)
	s_cmpk_gt_u32 s86, 0xff
	s_cbranch_scc1 .LBB0_1265
	s_barrier

; #define PG8_STAGE(bufoff, gbase, voff) do { _Pragma("unroll") for (int _i = 0; _i < 2; ++_i) \
;         __builtin_amdgcn_global_load_lds((const unsigned*)((const char*)(gbase) + (voff)[_i]), (PG8_LAS unsigned*)(lds + (bufoff) + ldsw + _i * 8192), 16, 0, 0); } while (0)
; #define PG8_LDA(dst, b, h) do { _Pragma("unroll") for (int m = 0; m < 4; ++m) _Pragma("unroll") for (int k = 0; k < 2; ++k) dst[m][k] = *(const PG8_LAS bf16x8*)(lds + PG8_SA(b, h) + aoff + m * 2048 + k * 1024); } while (0)
; #define PG8_LDB(dst, b, h) do { _Pragma("unroll") for (int n = 0; n < 2; ++n) _Pragma("unroll") for (int k = 0; k < 2; ++k) dst[n][k] = *(const PG8_LAS bf16x8*)(lds + PG8_SB(b, h) + boff + n * 2048 + k * 1024); } while (0)
; #define PG8_MMA(ai, bj, At, Bt) do { __builtin_amdgcn_s_setprio(1); _Pragma("unroll") for (int m = 0; m < 4; ++m) _Pragma("unroll") for (int n = 0; n < 2; ++n) _Pragma("unroll") for (int k = 0; k < 2; ++k) \
;         acc[ai][bj][m][n] = __builtin_amdgcn_mfma_f32_16x16x32_bf16(Bt[n][k], At[m][k], acc[ai][bj][m][n], 0, 0, 0); __builtin_amdgcn_s_setprio(0); } while (0)
; #define PG8_WAIT_V(n) asm volatile("s_waitcnt vmcnt(" #n ")" ::: "memory")
; #define PG8_BAR __builtin_amdgcn_s_barrier()
; template <class Epi, class Sched, bool ALIGN_EPI = false, bool SP2 = false>
; __device__ __forceinline__ void gemm_phase(PG8_LAS unsigned char* lds, const Gemm g, const Sched& S, const Epi& E, const int wave_s) {
;     ...
;         for (int t = 0; t < nt; t += 2) {
;             const bool last = (t == nt - 2);
;             const char* a1 = cA + (size_t)(t + 1) * kstep;
;             const char* a2 = last ? nA : cA + (size_t)(t + 2) * kstep; const char* b2 = last ? nB : cB + (size_t)(t + 2) * kstep;
;             const char* a3 = a2 + kstep; const char* b3 = b2 + kstep;
;             if (last && has_next) S.a_ready(nxt);
;             if constexpr (SP2) {
;             PG8_LDB(B0, 0, 0); PG8_LDB(B1, 0, 1); PG8_SCHED; PG8_LDA(At, 0, 0); PG8_STAGE(PG8_SA(1, 1), a1 + hstep, voffA);
;             PG8_WAIT_V(8); PG8_WAIT_L(0); PG8_BAR; PG8_MMA(0, 0, At, B0); PG8_MMA(0, 1, At, B1); PG8_BAR; PG8_SCHED;
;             PG8_LDA(At, 0, 1); PG8_STAGE(PG8_SB(0, 0), b2, voffB); PG8_STAGE(PG8_SB(0, 1), b2 + hstep, voffB); PG8_STAGE(PG8_SA(0, 0), a2, voffA);
;             PG8_WAIT_V(8); PG8_WAIT_L(0); PG8_BAR; PG8_MMA(1, 0, At, B0); PG8_MMA(1, 1, At, B1); PG8_BAR; PG8_SCHED;
.LBB0_1273:
	ds_read_b128 v[128:131], v185
	ds_read_b128 v[132:135], v185 offset:1024
	ds_read_b128 v[136:139], v185 offset:2048
	ds_read_b128 v[140:143], v185 offset:3072
	ds_read_b128 v[144:147], v186
	ds_read_b128 v[148:151], v186 offset:1024
	ds_read_b128 v[152:155], v186 offset:2048
	ds_read_b128 v[156:159], v186 offset:3072
	s_add_u32 s20, s16, 0xfffc0080
	s_addc_u32 s21, s17, -1
	s_cmp_eq_u32 s48, 12
	s_cselect_b32 s23, s9, s21
	s_cselect_b32 s22, s44, s20
	s_cselect_b32 s21, s7, s47
	s_cselect_b32 s20, s45, s46
	v_lshl_add_u64 v[212:213], s[16:17], 0, v[170:171]
	s_add_i32 m0, s15, 0xc000
	ds_read_b128 v[176:179], v187
	ds_read_b128 v[180:183], v187 offset:1024
	ds_read_b128 v[188:191], v187 offset:2048
	ds_read_b128 v[192:195], v187 offset:3072
	ds_read_b128 v[196:199], v187 offset:4096
	ds_read_b128 v[200:203], v187 offset:5120
	ds_read_b128 v[204:207], v187 offset:6144
	ds_read_b128 v[208:211], v187 offset:7168
	global_load_lds_dwordx4 v[212:213], off
	v_lshl_add_u64 v[212:213], s[16:17], 0, v[168:169]
	s_add_i32 m0, s15, 0xe000
	s_nop 0
	global_load_lds_dwordx4 v[212:213], off
	v_lshl_add_u64 v[230:231], s[20:21], 0, v[164:165]
	s_add_u32 s50, s20, 0x40000
	v_lshl_add_u64 v[232:233], s[20:21], 0, v[160:161]
	s_addc_u32 s51, s21, 0
	v_lshl_add_u64 v[234:235], s[50:51], 0, v[164:165]
	v_lshl_add_u64 v[236:237], s[22:23], 0, v[162:163]
	v_lshl_add_u64 v[238:239], s[50:51], 0, v[160:161]
	v_lshl_add_u64 v[240:241], s[22:23], 0, v[166:167]
	s_waitcnt vmcnt(8)
	s_waitcnt lgkmcnt(0)
	s_barrier
	s_setprio 1
	s_waitcnt lgkmcnt(0)
	v_mfma_f32_16x16x32_bf16 v[124:127], v[128:131], v[176:179], v[124:127]
	v_mfma_f32_16x16x32_bf16 v[120:123], v[136:139], v[176:179], v[120:123]
	v_mfma_f32_16x16x32_bf16 v[112:115], v[128:131], v[188:191], v[112:115]
	v_mfma_f32_16x16x32_bf16 v[104:107], v[136:139], v[188:191], v[104:107]
	v_mfma_f32_16x16x32_bf16 v[92:95], v[128:131], v[196:199], v[92:95]
	v_mfma_f32_16x16x32_bf16 v[88:91], v[136:139], v[196:199], v[88:91]
	v_mfma_f32_16x16x32_bf16 v[80:83], v[128:131], v[204:207], v[80:83]
	v_mfma_f32_16x16x32_bf16 v[72:75], v[136:139], v[204:207], v[72:75]
	v_mfma_f32_16x16x32_bf16 v[124:127], v[132:135], v[180:183], v[124:127]
	v_mfma_f32_16x16x32_bf16 v[120:123], v[140:143], v[180:183], v[120:123]
	v_mfma_f32_16x16x32_bf16 v[112:115], v[132:135], v[192:195], v[112:115]
	v_mfma_f32_16x16x32_bf16 v[104:107], v[140:143], v[192:195], v[104:107]
	v_mfma_f32_16x16x32_bf16 v[92:95], v[132:135], v[200:203], v[92:95]
	v_mfma_f32_16x16x32_bf16 v[88:91], v[140:143], v[200:203], v[88:91]
	v_mfma_f32_16x16x32_bf16 v[80:83], v[132:135], v[208:211], v[80:83]
	v_mfma_f32_16x16x32_bf16 v[72:75], v[140:143], v[208:211], v[72:75]
	s_setprio 0
	s_setprio 1
	v_mfma_f32_16x16x32_bf16 v[116:119], v[144:147], v[176:179], v[116:119]
	v_mfma_f32_16x16x32_bf16 v[108:111], v[152:155], v[176:179], v[108:111]
	v_mfma_f32_16x16x32_bf16 v[100:103], v[144:147], v[188:191], v[100:103]
	v_mfma_f32_16x16x32_bf16 v[96:99], v[152:155], v[188:191], v[96:99]
	v_mfma_f32_16x16x32_bf16 v[84:87], v[144:147], v[196:199], v[84:87]
	v_mfma_f32_16x16x32_bf16 v[76:79], v[152:155], v[196:199], v[76:79]
	v_mfma_f32_16x16x32_bf16 v[68:71], v[144:147], v[204:207], v[68:71]
	v_mfma_f32_16x16x32_bf16 v[64:67], v[152:155], v[204:207], v[64:67]
	v_mfma_f32_16x16x32_bf16 v[116:119], v[148:151], v[180:183], v[116:119]
	v_mfma_f32_16x16x32_bf16 v[108:111], v[156:159], v[180:183], v[108:111]
	v_mfma_f32_16x16x32_bf16 v[100:103], v[148:151], v[192:195], v[100:103]
	v_mfma_f32_16x16x32_bf16 v[96:99], v[156:159], v[192:195], v[96:99]
	v_mfma_f32_16x16x32_bf16 v[84:87], v[148:151], v[200:203], v[84:87]
	v_mfma_f32_16x16x32_bf16 v[76:79], v[156:159], v[200:203], v[76:79]
	v_mfma_f32_16x16x32_bf16 v[68:71], v[148:151], v[208:211], v[68:71]
	v_mfma_f32_16x16x32_bf16 v[64:67], v[156:159], v[208:211], v[64:67]
	s_setprio 0
	s_barrier
	s_add_i32 s49, s41, s33
	s_mov_b32 m0, s49
	ds_read_b128 v[176:179], v187 offset:16384
	ds_read_b128 v[180:183], v187 offset:17408
	ds_read_b128 v[188:191], v187 offset:18432
	ds_read_b128 v[192:195], v187 offset:19456
	ds_read_b128 v[196:199], v187 offset:20480
	ds_read_b128 v[200:203], v187 offset:21504
	ds_read_b128 v[204:207], v187 offset:22528
	ds_read_b128 v[208:211], v187 offset:23552
	global_load_lds_dwordx4 v[230:231], off
	s_add_i32 m0, s49, 0x2000
	s_add_i32 s49, s42, s33
	global_load_lds_dwordx4 v[232:233], off
	s_mov_b32 m0, s49
	s_nop 0
	global_load_lds_dwordx4 v[234:235], off
	s_add_i32 m0, s49, 0x2000
	s_nop 0
	global_load_lds_dwordx4 v[238:239], off
	s_mov_b32 m0, s15
	s_nop 0
	global_load_lds_dwordx4 v[240:241], off
	s_mov_b32 m0, s30
	s_nop 0
	global_load_lds_dwordx4 v[236:237], off
	s_waitcnt vmcnt(8)
	s_waitcnt lgkmcnt(0)
	s_barrier
; #define PG8_STAGE(bufoff, gbase, voff) do { _Pragma("unroll") for (int _i = 0; _i < 2; ++_i) \
;         __builtin_amdgcn_global_load_lds((const unsigned*)((const char*)(gbase) + (voff)[_i]), (PG8_LAS unsigned*)(lds + (bufoff) + ldsw + _i * 8192), 16, 0, 0); } while (0)
; #define PG8_LDA(dst, b, h) do { _Pragma("unroll") for (int m = 0; m < 4; ++m) _Pragma("unroll") for (int k = 0; k < 2; ++k) dst[m][k] = *(const PG8_LAS bf16x8*)(lds + PG8_SA(b, h) + aoff + m * 2048 + k * 1024); } while (0)
; #define PG8_LDB(dst, b, h) do { _Pragma("unroll") for (int n = 0; n < 2; ++n) _Pragma("unroll") for (int k = 0; k < 2; ++k) dst[n][k] = *(const PG8_LAS bf16x8*)(lds + PG8_SB(b, h) + boff + n * 2048 + k * 1024); } while (0)
; #define PG8_MMA(ai, bj, At, Bt) do { __builtin_amdgcn_s_setprio(1); _Pragma("unroll") for (int m = 0; m < 4; ++m) _Pragma("unroll") for (int n = 0; n < 2; ++n) _Pragma("unroll") for (int k = 0; k < 2; ++k) \
;         acc[ai][bj][m][n] = __builtin_amdgcn_mfma_f32_16x16x32_bf16(Bt[n][k], At[m][k], acc[ai][bj][m][n], 0, 0, 0); __builtin_amdgcn_s_setprio(0); } while (0)
; #define PG8_WAIT_V(n) asm volatile("s_waitcnt vmcnt(" #n ")" ::: "memory")
; #define PG8_WAIT_L(n) asm volatile("s_waitcnt lgkmcnt(" #n ")" ::: "memory")
; #define PG8_BAR __builtin_amdgcn_s_barrier()
; #define PG8_SCHED __builtin_amdgcn_sched_barrier(0)
; template <class Epi, class Sched, bool ALIGN_EPI = false, bool SP2 = false>
; __device__ __forceinline__ void gemm_phase(PG8_LAS unsigned char* lds, const Gemm g, const Sched& S, const Epi& E, const int wave_s) {
;     ...
;             PG8_WAIT_V(8); PG8_WAIT_L(0); PG8_BAR; PG8_MMA(1, 0, At, B0); PG8_MMA(1, 1, At, B1); PG8_BAR; PG8_SCHED;
;             PG8_LDB(B0, 1, 0); PG8_LDB(B1, 1, 1); PG8_SCHED; PG8_LDA(At, 1, 0); PG8_STAGE(PG8_SA(0, 1), a2 + hstep, voffA);
;             PG8_WAIT_V(8); PG8_WAIT_L(0); PG8_BAR; PG8_MMA(0, 0, At, B0); PG8_MMA(0, 1, At, B1); PG8_BAR; PG8_SCHED;
;             PG8_LDA(At, 1, 1); PG8_STAGE(PG8_SB(1, 0), b3, voffB); PG8_STAGE(PG8_SB(1, 1), b3 + hstep, voffB); PG8_STAGE(PG8_SA(1, 0), a3, voffA);
	s_setprio 1
	s_waitcnt lgkmcnt(0)
	v_mfma_f32_16x16x32_bf16 v[60:63], v[128:131], v[176:179], v[60:63]
	v_mfma_f32_16x16x32_bf16 v[56:59], v[136:139], v[176:179], v[56:59]
	v_mfma_f32_16x16x32_bf16 v[48:51], v[128:131], v[188:191], v[48:51]
	v_mfma_f32_16x16x32_bf16 v[40:43], v[136:139], v[188:191], v[40:43]
	v_mfma_f32_16x16x32_bf16 v[28:31], v[128:131], v[196:199], v[28:31]
	v_mfma_f32_16x16x32_bf16 v[24:27], v[136:139], v[196:199], v[24:27]
	v_mfma_f32_16x16x32_bf16 v[16:19], v[128:131], v[204:207], v[16:19]
	v_mfma_f32_16x16x32_bf16 v[8:11], v[136:139], v[204:207], v[8:11]
	v_mfma_f32_16x16x32_bf16 v[60:63], v[132:135], v[180:183], v[60:63]
	v_mfma_f32_16x16x32_bf16 v[56:59], v[140:143], v[180:183], v[56:59]
	v_mfma_f32_16x16x32_bf16 v[48:51], v[132:135], v[192:195], v[48:51]
	v_mfma_f32_16x16x32_bf16 v[40:43], v[140:143], v[192:195], v[40:43]
	v_mfma_f32_16x16x32_bf16 v[28:31], v[132:135], v[200:203], v[28:31]
	v_mfma_f32_16x16x32_bf16 v[24:27], v[140:143], v[200:203], v[24:27]
	v_mfma_f32_16x16x32_bf16 v[16:19], v[132:135], v[208:211], v[16:19]
	v_mfma_f32_16x16x32_bf16 v[8:11], v[140:143], v[208:211], v[8:11]
	s_setprio 0
	s_setprio 1
	v_mfma_f32_16x16x32_bf16 v[52:55], v[144:147], v[176:179], v[52:55]
	v_mfma_f32_16x16x32_bf16 v[44:47], v[152:155], v[176:179], v[44:47]
	v_mfma_f32_16x16x32_bf16 v[36:39], v[144:147], v[188:191], v[36:39]
	v_mfma_f32_16x16x32_bf16 v[32:35], v[152:155], v[188:191], v[32:35]
	v_mfma_f32_16x16x32_bf16 v[20:23], v[144:147], v[196:199], v[20:23]
	v_mfma_f32_16x16x32_bf16 v[12:15], v[152:155], v[196:199], v[12:15]
	v_mfma_f32_16x16x32_bf16 v[4:7], v[144:147], v[204:207], v[4:7]
	v_mfma_f32_16x16x32_bf16 v[0:3], v[152:155], v[204:207], v[0:3]
	v_mfma_f32_16x16x32_bf16 v[52:55], v[148:151], v[180:183], v[52:55]
	v_mfma_f32_16x16x32_bf16 v[44:47], v[156:159], v[180:183], v[44:47]
	v_mfma_f32_16x16x32_bf16 v[36:39], v[148:151], v[192:195], v[36:39]
	v_mfma_f32_16x16x32_bf16 v[32:35], v[156:159], v[192:195], v[32:35]
	v_mfma_f32_16x16x32_bf16 v[20:23], v[148:151], v[200:203], v[20:23]
	v_mfma_f32_16x16x32_bf16 v[12:15], v[156:159], v[200:203], v[12:15]
	v_mfma_f32_16x16x32_bf16 v[4:7], v[148:151], v[208:211], v[4:7]
	v_mfma_f32_16x16x32_bf16 v[0:3], v[156:159], v[208:211], v[0:3]
	s_setprio 0
	s_barrier
	s_add_i32 s49, 0, 0x18000
	s_add_i32 s50, 0, 0x1c000
	v_add_u32_e32 v140, s49, v184
	v_add_u32_e32 v156, s50, v184
	ds_read_b128 v[128:131], v140
	ds_read_b128 v[132:135], v140 offset:1024
	ds_read_b128 v[136:139], v140 offset:2048
	ds_read_b128 v[140:143], v140 offset:3072
	ds_read_b128 v[144:147], v156
	ds_read_b128 v[148:151], v156 offset:1024
	ds_read_b128 v[152:155], v156 offset:2048
	ds_read_b128 v[156:159], v156 offset:3072
	s_add_u32 s22, s22, 0x40000
	s_addc_u32 s23, s23, 0
	s_mov_b32 m0, s31
	v_lshl_add_u64 v[220:221], s[22:23], 0, v[166:167]
	ds_read_b128 v[176:179], v187 offset:32768
	ds_read_b128 v[180:183], v187 offset:33792
	ds_read_b128 v[188:191], v187 offset:34816
	ds_read_b128 v[192:195], v187 offset:35840
	ds_read_b128 v[196:199], v187 offset:36864
	ds_read_b128 v[200:203], v187 offset:37888
	ds_read_b128 v[204:207], v187 offset:38912
	ds_read_b128 v[208:211], v187 offset:39936
	global_load_lds_dwordx4 v[220:221], off
	v_lshl_add_u64 v[220:221], s[22:23], 0, v[162:163]
	s_mov_b32 m0, s34
	s_nop 0
	global_load_lds_dwordx4 v[220:221], off
	v_lshl_add_u64 v[242:243], v[230:231], 0, s[4:5]
	s_add_u32 s20, s20, 0x40080
	v_lshl_add_u64 v[244:245], v[232:233], 0, s[4:5]
	s_addc_u32 s21, s21, 0
	v_lshl_add_u64 v[246:247], s[20:21], 0, v[164:165]
	v_lshl_add_u64 v[248:249], s[20:21], 0, v[160:161]
	v_lshl_add_u64 v[250:251], v[240:241], 0, s[4:5]
	v_lshl_add_u64 v[252:253], v[236:237], 0, s[4:5]
	s_waitcnt vmcnt(8)
	s_waitcnt lgkmcnt(0)
	s_barrier
	s_setprio 1
	s_waitcnt lgkmcnt(0)
	v_mfma_f32_16x16x32_bf16 v[124:127], v[128:131], v[176:179], v[124:127]
	v_mfma_f32_16x16x32_bf16 v[120:123], v[136:139], v[176:179], v[120:123]
	v_mfma_f32_16x16x32_bf16 v[112:115], v[128:131], v[188:191], v[112:115]
	v_mfma_f32_16x16x32_bf16 v[104:107], v[136:139], v[188:191], v[104:107]
	v_mfma_f32_16x16x32_bf16 v[92:95], v[128:131], v[196:199], v[92:95]
	v_mfma_f32_16x16x32_bf16 v[88:91], v[136:139], v[196:199], v[88:91]
	v_mfma_f32_16x16x32_bf16 v[80:83], v[128:131], v[204:207], v[80:83]
	v_mfma_f32_16x16x32_bf16 v[72:75], v[136:139], v[204:207], v[72:75]
	v_mfma_f32_16x16x32_bf16 v[124:127], v[132:135], v[180:183], v[124:127]
	v_mfma_f32_16x16x32_bf16 v[120:123], v[140:143], v[180:183], v[120:123]
	v_mfma_f32_16x16x32_bf16 v[112:115], v[132:135], v[192:195], v[112:115]
	v_mfma_f32_16x16x32_bf16 v[104:107], v[140:143], v[192:195], v[104:107]
	v_mfma_f32_16x16x32_bf16 v[92:95], v[132:135], v[200:203], v[92:95]
	v_mfma_f32_16x16x32_bf16 v[88:91], v[140:143], v[200:203], v[88:91]
	v_mfma_f32_16x16x32_bf16 v[80:83], v[132:135], v[208:211], v[80:83]
	v_mfma_f32_16x16x32_bf16 v[72:75], v[140:143], v[208:211], v[72:75]
	s_setprio 0
	s_setprio 1
	v_mfma_f32_16x16x32_bf16 v[116:119], v[144:147], v[176:179], v[116:119]
	v_mfma_f32_16x16x32_bf16 v[108:111], v[152:155], v[176:179], v[108:111]
	v_mfma_f32_16x16x32_bf16 v[100:103], v[144:147], v[188:191], v[100:103]
	v_mfma_f32_16x16x32_bf16 v[96:99], v[152:155], v[188:191], v[96:99]
	v_mfma_f32_16x16x32_bf16 v[84:87], v[144:147], v[196:199], v[84:87]
	v_mfma_f32_16x16x32_bf16 v[76:79], v[152:155], v[196:199], v[76:79]
	v_mfma_f32_16x16x32_bf16 v[68:71], v[144:147], v[204:207], v[68:71]
	v_mfma_f32_16x16x32_bf16 v[64:67], v[152:155], v[204:207], v[64:67]
	v_mfma_f32_16x16x32_bf16 v[116:119], v[148:151], v[180:183], v[116:119]
	v_mfma_f32_16x16x32_bf16 v[108:111], v[156:159], v[180:183], v[108:111]
	v_mfma_f32_16x16x32_bf16 v[100:103], v[148:151], v[192:195], v[100:103]
	v_mfma_f32_16x16x32_bf16 v[96:99], v[156:159], v[192:195], v[96:99]
	v_mfma_f32_16x16x32_bf16 v[84:87], v[148:151], v[200:203], v[84:87]
	v_mfma_f32_16x16x32_bf16 v[76:79], v[156:159], v[200:203], v[76:79]
	v_mfma_f32_16x16x32_bf16 v[68:71], v[148:151], v[208:211], v[68:71]
	v_mfma_f32_16x16x32_bf16 v[64:67], v[156:159], v[208:211], v[64:67]
	s_setprio 0
	s_barrier
; #define PG8_STAGE(bufoff, gbase, voff) do { _Pragma("unroll") for (int _i = 0; _i < 2; ++_i) \
;         __builtin_amdgcn_global_load_lds((const unsigned*)((const char*)(gbase) + (voff)[_i]), (PG8_LAS unsigned*)(lds + (bufoff) + ldsw + _i * 8192), 16, 0, 0); } while (0)
; #define PG8_LDA(dst, b, h) do { _Pragma("unroll") for (int m = 0; m < 4; ++m) _Pragma("unroll") for (int k = 0; k < 2; ++k) dst[m][k] = *(const PG8_LAS bf16x8*)(lds + PG8_SA(b, h) + aoff + m * 2048 + k * 1024); } while (0)
; #define PG8_MMA(ai, bj, At, Bt) do { __builtin_amdgcn_s_setprio(1); _Pragma("unroll") for (int m = 0; m < 4; ++m) _Pragma("unroll") for (int n = 0; n < 2; ++n) _Pragma("unroll") for (int k = 0; k < 2; ++k) \
;         acc[ai][bj][m][n] = __builtin_amdgcn_mfma_f32_16x16x32_bf16(Bt[n][k], At[m][k], acc[ai][bj][m][n], 0, 0, 0); __builtin_amdgcn_s_setprio(0); } while (0)
; #define PG8_WAIT_V(n) asm volatile("s_waitcnt vmcnt(" #n ")" ::: "memory")
; #define PG8_WAIT_L(n) asm volatile("s_waitcnt lgkmcnt(" #n ")" ::: "memory")
; #define PG8_BAR __builtin_amdgcn_s_barrier()
; #define PG8_SCHED __builtin_amdgcn_sched_barrier(0)
; template <class Epi, class Sched, bool ALIGN_EPI = false, bool SP2 = false>
; __device__ __forceinline__ void gemm_phase(PG8_LAS unsigned char* lds, const Gemm g, const Sched& S, const Epi& E, const int wave_s) {
;     ...
;             PG8_LDA(At, 1, 1); PG8_STAGE(PG8_SB(1, 0), b3, voffB); PG8_STAGE(PG8_SB(1, 1), b3 + hstep, voffB); PG8_STAGE(PG8_SA(1, 0), a3, voffA);
;             PG8_WAIT_V(8); PG8_WAIT_L(0); PG8_BAR; PG8_MMA(1, 0, At, B0); PG8_MMA(1, 1, At, B1); PG8_BAR; PG8_SCHED;
;     __device__ __forceinline__ void operator()(const af4 (&acc)[2][2][4][2], const pg8::Unit& u, int wr, int wc, int fr_, int fq_) const {
;     ...
;         const int row0 = u.pm * 256 + wr * 64 + fr, col0 = u.pn * 256 + wc * 32 + 8 * fq;
;         v4u o[2][2][2], yv[2][2][2];
;     ...
;         MA_LOAD(0, 0);
	s_add_i32 s22, s49, s33
	s_mov_b32 m0, s22
	ds_read_b128 v[176:179], v187 offset:49152
	ds_read_b128 v[180:183], v187 offset:50176
	ds_read_b128 v[188:191], v187 offset:51200
	ds_read_b128 v[192:195], v187 offset:52224
	ds_read_b128 v[196:199], v187 offset:53248
	ds_read_b128 v[200:203], v187 offset:54272
	ds_read_b128 v[204:207], v187 offset:55296
	ds_read_b128 v[208:211], v187 offset:56320
	global_load_lds_dwordx4 v[242:243], off
	s_add_i32 m0, s22, 0x2000
	s_add_i32 s22, s50, s33
	global_load_lds_dwordx4 v[244:245], off
	s_mov_b32 m0, s22
	s_nop 0
	global_load_lds_dwordx4 v[246:247], off
	s_add_i32 m0, s22, 0x2000
	s_nop 0
	global_load_lds_dwordx4 v[248:249], off
	s_mov_b32 m0, s36
	s_nop 0
	global_load_lds_dwordx4 v[250:251], off
	s_mov_b32 m0, s37
	s_nop 0
	global_load_lds_dwordx4 v[252:253], off
	s_waitcnt vmcnt(8)
	s_waitcnt lgkmcnt(0)
	s_barrier
	s_setprio 1
	s_waitcnt lgkmcnt(0)
	v_mfma_f32_16x16x32_bf16 v[60:63], v[128:131], v[176:179], v[60:63]
	v_mfma_f32_16x16x32_bf16 v[56:59], v[136:139], v[176:179], v[56:59]
	v_mfma_f32_16x16x32_bf16 v[48:51], v[128:131], v[188:191], v[48:51]
	v_mfma_f32_16x16x32_bf16 v[40:43], v[136:139], v[188:191], v[40:43]
	v_mfma_f32_16x16x32_bf16 v[28:31], v[128:131], v[196:199], v[28:31]
	v_mfma_f32_16x16x32_bf16 v[24:27], v[136:139], v[196:199], v[24:27]
	v_mfma_f32_16x16x32_bf16 v[16:19], v[128:131], v[204:207], v[16:19]
	v_mfma_f32_16x16x32_bf16 v[8:11], v[136:139], v[204:207], v[8:11]
	v_mfma_f32_16x16x32_bf16 v[60:63], v[132:135], v[180:183], v[60:63]
	v_mfma_f32_16x16x32_bf16 v[56:59], v[140:143], v[180:183], v[56:59]
	v_mfma_f32_16x16x32_bf16 v[48:51], v[132:135], v[192:195], v[48:51]
	v_mfma_f32_16x16x32_bf16 v[40:43], v[140:143], v[192:195], v[40:43]
	v_mfma_f32_16x16x32_bf16 v[28:31], v[132:135], v[200:203], v[28:31]
	v_mfma_f32_16x16x32_bf16 v[24:27], v[140:143], v[200:203], v[24:27]
	v_mfma_f32_16x16x32_bf16 v[16:19], v[132:135], v[208:211], v[16:19]
	v_mfma_f32_16x16x32_bf16 v[8:11], v[140:143], v[208:211], v[8:11]
	s_setprio 0
	s_setprio 1
	v_mfma_f32_16x16x32_bf16 v[52:55], v[144:147], v[176:179], v[52:55]
	v_mfma_f32_16x16x32_bf16 v[44:47], v[152:155], v[176:179], v[44:47]
	v_mfma_f32_16x16x32_bf16 v[36:39], v[144:147], v[188:191], v[36:39]
	v_mfma_f32_16x16x32_bf16 v[32:35], v[152:155], v[188:191], v[32:35]
	v_mfma_f32_16x16x32_bf16 v[20:23], v[144:147], v[196:199], v[20:23]
	v_mfma_f32_16x16x32_bf16 v[12:15], v[152:155], v[196:199], v[12:15]
	v_mfma_f32_16x16x32_bf16 v[4:7], v[144:147], v[204:207], v[4:7]
	v_mfma_f32_16x16x32_bf16 v[0:3], v[152:155], v[204:207], v[0:3]
	v_mfma_f32_16x16x32_bf16 v[52:55], v[148:151], v[180:183], v[52:55]
	v_mfma_f32_16x16x32_bf16 v[44:47], v[156:159], v[180:183], v[44:47]
	v_mfma_f32_16x16x32_bf16 v[36:39], v[148:151], v[192:195], v[36:39]
	v_mfma_f32_16x16x32_bf16 v[32:35], v[156:159], v[192:195], v[32:35]
	v_mfma_f32_16x16x32_bf16 v[20:23], v[148:151], v[200:203], v[20:23]
	v_mfma_f32_16x16x32_bf16 v[12:15], v[156:159], v[200:203], v[12:15]
	v_mfma_f32_16x16x32_bf16 v[4:7], v[148:151], v[208:211], v[4:7]
	v_mfma_f32_16x16x32_bf16 v[0:3], v[156:159], v[208:211], v[0:3]
	s_setprio 0
	s_barrier
	s_add_i32 s48, s48, 2
	s_add_u32 s46, s46, 0x100
	s_addc_u32 s47, s47, 0
	s_add_u32 s16, s16, 0x100
	s_addc_u32 s17, s17, 0
	s_cmp_gt_u32 s48, 13
	s_cbranch_scc0 .LBB0_1273
	s_lshl_b32 s7, s14, 8
	v_mbcnt_lo_u32_b32 v128, -1, 0
	v_mbcnt_hi_u32_b32 v128, -1, v128
	s_add_i32 s7, s7, s87
	v_and_or_b32 v183, v128, 15, s7
	s_lshl_b32 s7, s43, 8
	v_ashrrev_i32_e32 v128, 1, v128
	s_or_b32 s7, s7, s79
	v_and_b32_e32 v128, -8, v128
	v_add_u32_e32 v178, s7, v128
	v_mov_b32_e32 v128, v183
	v_ashrrev_i32_e32 v179, 31, v178
	v_ashrrev_i32_e32 v129, 31, v128
	v_lshlrev_b64 v[128:129], 10, v[128:129]
	v_lshl_add_u64 v[128:129], v[128:129], 0, v[178:179]
	v_lshlrev_b64 v[128:129], 1, v[128:129]
	v_lshl_add_u64 v[130:131], s[2:3], 0, v[128:129]
	global_load_dwordx4 v[188:191], v[130:131], off
	v_lshl_add_u64 v[128:129], s[0:1], 0, v[128:129]
	global_load_dwordx4 v[192:195], v[128:129], off
	global_load_dwordx4 v[196:199], v[130:131], off offset:256
	global_load_dwordx4 v[200:203], v[128:129], off offset:256
	v_add_co_u32_e32 v128, vcc, s38, v128
	v_or_b32_e32 v180, 32, v183
	s_nop 0
	v_addc_co_u32_e32 v129, vcc, 0, v129, vcc
	v_add_co_u32_e32 v130, vcc, s38, v130
	v_mov_b32_e32 v132, v180
	s_nop 0
	v_addc_co_u32_e32 v131, vcc, 0, v131, vcc
	global_load_dwordx4 v[204:207], v[128:129], off
	global_load_dwordx4 v[208:211], v[128:129], off offset:256
	global_load_dwordx4 v[212:215], v[130:131], off
	global_load_dwordx4 v[216:219], v[130:131], off offset:256
	v_mov_b32_e32 v220, v183
	v_ashrrev_i32_e32 v133, 31, v132
	v_lshlrev_b64 v[128:129], 10, v[132:133]
	v_lshl_add_u64 v[128:129], v[128:129], 0, v[178:179]
	v_lshlrev_b64 v[128:129], 1, v[128:129]
	v_lshl_add_u64 v[130:131], s[0:1], 0, v[128:129]
	v_lshl_add_u64 v[128:129], s[2:3], 0, v[128:129]
	global_load_dwordx4 v[152:155], v[130:131], off
	global_load_dwordx4 v[144:147], v[130:131], off offset:256
	global_load_dwordx4 v[156:159], v[128:129], off
	global_load_dwordx4 v[148:151], v[128:129], off offset:256
	v_add_co_u32_e32 v130, vcc, s38, v130
	v_lshlrev_b64 v[176:177], 1, v[178:179]
	s_nop 0
	v_addc_co_u32_e32 v131, vcc, 0, v131, vcc
	v_add_co_u32_e32 v132, vcc, s38, v128
	v_add_u32_e32 v182, 0x80, v183
	s_nop 0
	v_addc_co_u32_e32 v133, vcc, 0, v129, vcc
	global_load_dwordx4 v[136:139], v[130:131], off
	s_nop 0
	global_load_dwordx4 v[128:131], v[130:131], off offset:256
	s_nop 0
	global_load_dwordx4 v[140:143], v[132:133], off
	s_nop 0
	global_load_dwordx4 v[132:135], v[132:133], off offset:256
	s_mov_b32 s43, s6
	v_ashrrev_i32_e32 v221, 31, v220
	v_lshlrev_b64 v[220:221], 11, v[220:221]
	v_lshl_add_u64 v[220:221], s[0:1], 0, v[220:221]
	v_lshl_add_u64 v[220:221], v[220:221], 0, v[176:177]
	s_mov_b32 s14, s8
	s_mov_b64 s[16:17], s[12:13]
	s_mov_b64 s[20:21], s[10:11]
	s_waitcnt vmcnt(0)
; __device__ __forceinline__ unsigned cvtpk(float lo, float hi) { f32x2 v = {lo, hi}; bf16x2_t b = __builtin_convertvector(v, bf16x2_t); return __builtin_bit_cast(unsigned, b); }
; __device__ __forceinline__ float bflo(unsigned u) { return __uint_as_float(u << 16); }
; __device__ __forceinline__ float bfhi(unsigned u) { return __uint_as_float(u & 0xffff0000u); }
;     __device__ __forceinline__ void operator()(const af4 (&acc)[2][2][4][2], const pg8::Unit& u, int wr, int wc, int fr_, int fq_) const {
;     ...
;         MA_LOAD(0, 0);
; #pragma unroll
;         for (int b_ = 0; b_ < 4; ++b_) {
;             const int ai = b_ >> 1, mp = b_ & 1, cur = b_ & 1;
;             if (b_ + 1 < 4) { if (cur == 0) MA_LOAD(1, b_ + 1); else MA_LOAD(0, b_ + 1); }
;             int RRb = row0 + ai * 128 + mp * 32; asm volatile("" : "+v"(RRb));
;             const size_t ob = (size_t)RRb * 1024 + col0;
; #pragma unroll
;             for (int mi = 0; mi < 2; ++mi)
; #pragma unroll
;                 for (int bj = 0; bj < 2; ++bj) { const af4 v0 = acc[ai][bj][mp * 2 + mi][0], v1 = acc[ai][bj][mp * 2 + mi][1]; const v4u oo = o[cur][mi][bj], y = yv[cur][mi][bj];
;                     v4u w; w.x = cvtpk(bflo(y.x) + v0[0] * bflo(oo.x), bfhi(y.x) + v0[1] * bfhi(oo.x)); w.y = cvtpk(bflo(y.y) + v0[2] * bflo(oo.y), bfhi(y.y) + v0[3] * bfhi(oo.y));
;                     w.z = cvtpk(bflo(y.z) + v1[0] * bflo(oo.z), bfhi(y.z) + v1[1] * bfhi(oo.z)); w.w = cvtpk(bflo(y.w) + v1[2] * bflo(oo.w), bfhi(y.w) + v1[3] * bfhi(oo.w));
;                     *(v4u*)(G + ob + mi * 16 * 1024 + bj * 128) = w; }
	v_lshlrev_b32_e32 v224, 16, v192
	v_lshlrev_b32_e32 v222, 16, v188
	v_and_b32_e32 v223, 0xffff0000, v188
	v_and_b32_e32 v225, 0xffff0000, v192
	v_lshlrev_b32_e32 v188, 16, v189
	v_and_b32_e32 v189, 0xffff0000, v189
	v_lshlrev_b32_e32 v192, 16, v193
	v_and_b32_e32 v193, 0xffff0000, v193
	v_lshlrev_b32_e32 v226, 16, v190
	v_and_b32_e32 v227, 0xffff0000, v190
	v_lshlrev_b32_e32 v228, 16, v194
	v_and_b32_e32 v229, 0xffff0000, v194
	v_lshlrev_b32_e32 v190, 16, v191
	v_and_b32_e32 v191, 0xffff0000, v191
	v_lshlrev_b32_e32 v194, 16, v195
	v_and_b32_e32 v195, 0xffff0000, v195
	v_pk_fma_f32 v[124:125], v[124:125], v[224:225], v[222:223]
	v_pk_fma_f32 v[126:127], v[126:127], v[192:193], v[188:189]
	v_pk_fma_f32 v[188:189], v[120:121], v[228:229], v[226:227]
	v_pk_fma_f32 v[190:191], v[122:123], v[194:195], v[190:191]
	v_cvt_pk_bf16_f32 v120, v124, v125
	v_cvt_pk_bf16_f32 v121, v126, v127
	v_cvt_pk_bf16_f32 v122, v188, v189
	v_cvt_pk_bf16_f32 v123, v190, v191
	v_lshlrev_b32_e32 v230, 16, v196
	v_and_b32_e32 v231, 0xffff0000, v196
	v_lshlrev_b32_e32 v232, 16, v200
	global_store_dwordx4 v[220:221], v[120:123], off
	v_and_b32_e32 v233, 0xffff0000, v200
	v_pk_fma_f32 v[116:117], v[116:117], v[232:233], v[230:231]
	v_lshlrev_b32_e32 v120, 16, v197
	v_and_b32_e32 v121, 0xffff0000, v197
	v_lshlrev_b32_e32 v122, 16, v201
	v_and_b32_e32 v123, 0xffff0000, v201
	v_pk_fma_f32 v[118:119], v[118:119], v[122:123], v[120:121]
	v_cvt_pk_bf16_f32 v116, v116, v117
	v_cvt_pk_bf16_f32 v117, v118, v119
	v_lshlrev_b32_e32 v118, 16, v198
	v_and_b32_e32 v119, 0xffff0000, v198
	v_lshlrev_b32_e32 v120, 16, v202
	v_and_b32_e32 v121, 0xffff0000, v202
	v_pk_fma_f32 v[108:109], v[108:109], v[120:121], v[118:119]
	v_lshlrev_b32_e32 v120, 16, v203
	v_cvt_pk_bf16_f32 v118, v108, v109
	v_lshlrev_b32_e32 v108, 16, v199
	v_and_b32_e32 v109, 0xffff0000, v199
	v_and_b32_e32 v121, 0xffff0000, v203
	v_pk_fma_f32 v[108:109], v[110:111], v[120:121], v[108:109]
	v_lshlrev_b32_e32 v110, 16, v204
	v_cvt_pk_bf16_f32 v119, v108, v109
	v_lshlrev_b32_e32 v108, 16, v212
	v_and_b32_e32 v109, 0xffff0000, v212
	v_and_b32_e32 v111, 0xffff0000, v204
	v_pk_fma_f32 v[108:109], v[112:113], v[110:111], v[108:109]
	v_lshlrev_b32_e32 v110, 16, v213
	v_and_b32_e32 v111, 0xffff0000, v213
	v_lshlrev_b32_e32 v112, 16, v205
	v_and_b32_e32 v113, 0xffff0000, v205
	v_pk_fma_f32 v[110:111], v[114:115], v[112:113], v[110:111]
	v_cvt_pk_bf16_f32 v108, v108, v109
	v_cvt_pk_bf16_f32 v109, v110, v111
	v_lshlrev_b32_e32 v110, 16, v214
	v_and_b32_e32 v111, 0xffff0000, v214
	v_lshlrev_b32_e32 v112, 16, v206
	v_and_b32_e32 v113, 0xffff0000, v206
	v_pk_fma_f32 v[104:105], v[104:105], v[112:113], v[110:111]
	v_lshlrev_b32_e32 v112, 16, v207
	v_cvt_pk_bf16_f32 v110, v104, v105
	v_lshlrev_b32_e32 v104, 16, v215
	v_and_b32_e32 v105, 0xffff0000, v215
	v_and_b32_e32 v113, 0xffff0000, v207
	v_pk_fma_f32 v[104:105], v[106:107], v[112:113], v[104:105]
	v_lshlrev_b32_e32 v106, 16, v216
	v_cvt_pk_bf16_f32 v111, v104, v105
	v_add_co_u32_e32 v104, vcc, s38, v220
	v_and_b32_e32 v107, 0xffff0000, v216
	s_nop 0
	v_addc_co_u32_e32 v105, vcc, 0, v221, vcc
	global_store_dwordx4 v[104:105], v[108:111], off
	global_store_dwordx4 v[220:221], v[116:119], off offset:256
	v_lshlrev_b32_e32 v188, 16, v156
	v_lshlrev_b32_e32 v108, 16, v208
	v_and_b32_e32 v109, 0xffff0000, v208
	v_pk_fma_f32 v[100:101], v[100:101], v[108:109], v[106:107]
	v_lshlrev_b32_e32 v106, 16, v217
	v_and_b32_e32 v107, 0xffff0000, v217
	v_lshlrev_b32_e32 v108, 16, v209
	v_and_b32_e32 v109, 0xffff0000, v209
	v_pk_fma_f32 v[102:103], v[102:103], v[108:109], v[106:107]
	v_cvt_pk_bf16_f32 v100, v100, v101
	v_cvt_pk_bf16_f32 v101, v102, v103
	v_lshlrev_b32_e32 v102, 16, v218
	v_and_b32_e32 v103, 0xffff0000, v218
	v_lshlrev_b32_e32 v106, 16, v210
	v_and_b32_e32 v107, 0xffff0000, v210
	v_pk_fma_f32 v[96:97], v[96:97], v[106:107], v[102:103]
	v_lshlrev_b32_e32 v106, 16, v211
	v_cvt_pk_bf16_f32 v102, v96, v97
	v_lshlrev_b32_e32 v96, 16, v219
	v_and_b32_e32 v97, 0xffff0000, v219
	v_and_b32_e32 v107, 0xffff0000, v211
	v_pk_fma_f32 v[96:97], v[98:99], v[106:107], v[96:97]
	v_and_b32_e32 v189, 0xffff0000, v156
	v_cvt_pk_bf16_f32 v103, v96, v97
	global_store_dwordx4 v[104:105], v[100:103], off offset:256
	v_mov_b32_e32 v96, v182
	v_lshlrev_b32_e32 v190, 16, v152
	v_ashrrev_i32_e32 v97, 31, v96
	v_lshlrev_b64 v[96:97], 10, v[96:97]
	v_lshl_add_u64 v[96:97], v[96:97], 0, v[178:179]
	v_lshlrev_b64 v[96:97], 1, v[96:97]
	v_lshl_add_u64 v[98:99], s[0:1], 0, v[96:97]
	v_lshl_add_u64 v[96:97], s[2:3], 0, v[96:97]
	global_load_dwordx4 v[120:123], v[98:99], off
	global_load_dwordx4 v[112:115], v[98:99], off offset:256
	global_load_dwordx4 v[124:127], v[96:97], off
	global_load_dwordx4 v[116:119], v[96:97], off offset:256
	v_add_co_u32_e32 v98, vcc, s38, v98
	v_and_b32_e32 v191, 0xffff0000, v152
	v_lshlrev_b32_e32 v156, 16, v157
	v_and_b32_e32 v157, 0xffff0000, v157
	v_lshlrev_b32_e32 v152, 16, v153
	v_and_b32_e32 v153, 0xffff0000, v153
	v_addc_co_u32_e32 v99, vcc, 0, v99, vcc
	v_pk_fma_f32 v[92:93], v[92:93], v[190:191], v[188:189]
	v_pk_fma_f32 v[94:95], v[94:95], v[152:153], v[156:157]
	v_add_co_u32_e32 v100, vcc, s38, v96
	v_cvt_pk_bf16_f32 v92, v92, v93
	v_cvt_pk_bf16_f32 v93, v94, v95
	v_lshlrev_b32_e32 v94, 16, v158
	v_and_b32_e32 v95, 0xffff0000, v158
	v_lshlrev_b32_e32 v152, 16, v154
	v_and_b32_e32 v153, 0xffff0000, v154
	v_addc_co_u32_e32 v101, vcc, 0, v97, vcc
	v_pk_fma_f32 v[88:89], v[88:89], v[152:153], v[94:95]
	global_load_dwordx4 v[104:107], v[98:99], off
	s_nop 0
	global_load_dwordx4 v[96:99], v[98:99], off offset:256
	s_nop 0
	global_load_dwordx4 v[108:111], v[100:101], off
	s_nop 0
; __device__ __forceinline__ unsigned cvtpk(float lo, float hi) { f32x2 v = {lo, hi}; bf16x2_t b = __builtin_convertvector(v, bf16x2_t); return __builtin_bit_cast(unsigned, b); }
; __device__ __forceinline__ float bflo(unsigned u) { return __uint_as_float(u << 16); }
; __device__ __forceinline__ float bfhi(unsigned u) { return __uint_as_float(u & 0xffff0000u); }
;     __device__ __forceinline__ void operator()(const af4 (&acc)[2][2][4][2], const pg8::Unit& u, int wr, int wc, int fr_, int fq_) const {
;     ...
;         MA_LOAD(0, 0);
; #pragma unroll
;         for (int b_ = 0; b_ < 4; ++b_) {
;             const int ai = b_ >> 1, mp = b_ & 1, cur = b_ & 1;
;             if (b_ + 1 < 4) { if (cur == 0) MA_LOAD(1, b_ + 1); else MA_LOAD(0, b_ + 1); }
;             int RRb = row0 + ai * 128 + mp * 32; asm volatile("" : "+v"(RRb));
;             const size_t ob = (size_t)RRb * 1024 + col0;
; #pragma unroll
;             for (int mi = 0; mi < 2; ++mi)
; #pragma unroll
;                 for (int bj = 0; bj < 2; ++bj) { const af4 v0 = acc[ai][bj][mp * 2 + mi][0], v1 = acc[ai][bj][mp * 2 + mi][1]; const v4u oo = o[cur][mi][bj], y = yv[cur][mi][bj];
;                     v4u w; w.x = cvtpk(bflo(y.x) + v0[0] * bflo(oo.x), bfhi(y.x) + v0[1] * bfhi(oo.x)); w.y = cvtpk(bflo(y.y) + v0[2] * bflo(oo.y), bfhi(y.y) + v0[3] * bfhi(oo.y));
;                     w.z = cvtpk(bflo(y.z) + v1[0] * bflo(oo.z), bfhi(y.z) + v1[1] * bfhi(oo.z)); w.w = cvtpk(bflo(y.w) + v1[2] * bflo(oo.w), bfhi(y.w) + v1[3] * bfhi(oo.w));
;                     *(v4u*)(G + ob + mi * 16 * 1024 + bj * 128) = w; }
	global_load_dwordx4 v[100:103], v[100:101], off offset:256
	v_cvt_pk_bf16_f32 v94, v88, v89
	v_ashrrev_i32_e32 v181, 31, v180
	v_lshlrev_b32_e32 v88, 16, v159
	v_and_b32_e32 v89, 0xffff0000, v159
	v_lshlrev_b32_e32 v152, 16, v155
	v_and_b32_e32 v153, 0xffff0000, v155
	v_lshlrev_b64 v[180:181], 11, v[180:181]
	v_pk_fma_f32 v[88:89], v[90:91], v[152:153], v[88:89]
	v_lshlrev_b32_e32 v90, 16, v148
	v_cvt_pk_bf16_f32 v95, v88, v89
	v_lshl_add_u64 v[88:89], s[0:1], 0, v[180:181]
	v_lshl_add_u64 v[88:89], v[88:89], 0, v[176:177]
	global_store_dwordx4 v[88:89], v[92:95], off
	v_and_b32_e32 v91, 0xffff0000, v148
	s_nop 0
	v_lshlrev_b32_e32 v92, 16, v144
	v_and_b32_e32 v93, 0xffff0000, v144
	v_pk_fma_f32 v[84:85], v[84:85], v[92:93], v[90:91]
	v_lshlrev_b32_e32 v90, 16, v149
	v_and_b32_e32 v91, 0xffff0000, v149
	v_lshlrev_b32_e32 v92, 16, v145
	v_and_b32_e32 v93, 0xffff0000, v145
	v_pk_fma_f32 v[86:87], v[86:87], v[92:93], v[90:91]
	v_cvt_pk_bf16_f32 v84, v84, v85
	v_cvt_pk_bf16_f32 v85, v86, v87
	v_lshlrev_b32_e32 v86, 16, v150
	v_and_b32_e32 v87, 0xffff0000, v150
	v_lshlrev_b32_e32 v90, 16, v146
	v_and_b32_e32 v91, 0xffff0000, v146
	v_pk_fma_f32 v[76:77], v[76:77], v[90:91], v[86:87]
	v_lshlrev_b32_e32 v90, 16, v147
	v_cvt_pk_bf16_f32 v86, v76, v77
	v_lshlrev_b32_e32 v76, 16, v151
	v_and_b32_e32 v77, 0xffff0000, v151
	v_and_b32_e32 v91, 0xffff0000, v147
	v_pk_fma_f32 v[76:77], v[78:79], v[90:91], v[76:77]
	v_lshlrev_b32_e32 v78, 16, v136
	v_cvt_pk_bf16_f32 v87, v76, v77
	v_lshlrev_b32_e32 v76, 16, v140
	v_and_b32_e32 v77, 0xffff0000, v140
	v_and_b32_e32 v79, 0xffff0000, v136
	v_pk_fma_f32 v[76:77], v[80:81], v[78:79], v[76:77]
	v_lshlrev_b32_e32 v78, 16, v141
	v_and_b32_e32 v79, 0xffff0000, v141
	v_lshlrev_b32_e32 v80, 16, v137
	v_and_b32_e32 v81, 0xffff0000, v137
	v_pk_fma_f32 v[78:79], v[82:83], v[80:81], v[78:79]
	v_cvt_pk_bf16_f32 v76, v76, v77
	v_cvt_pk_bf16_f32 v77, v78, v79
	v_lshlrev_b32_e32 v78, 16, v142
	v_and_b32_e32 v79, 0xffff0000, v142
	v_lshlrev_b32_e32 v80, 16, v138
	v_and_b32_e32 v81, 0xffff0000, v138
	v_pk_fma_f32 v[72:73], v[72:73], v[80:81], v[78:79]
	v_lshlrev_b32_e32 v80, 16, v139
	v_cvt_pk_bf16_f32 v78, v72, v73
	v_lshlrev_b32_e32 v72, 16, v143
	v_and_b32_e32 v73, 0xffff0000, v143
	v_and_b32_e32 v81, 0xffff0000, v139
	v_pk_fma_f32 v[72:73], v[74:75], v[80:81], v[72:73]
	v_lshlrev_b32_e32 v74, 16, v132
	v_cvt_pk_bf16_f32 v79, v72, v73
	v_add_co_u32_e32 v72, vcc, s38, v88
	v_and_b32_e32 v75, 0xffff0000, v132
	s_nop 0
	v_addc_co_u32_e32 v73, vcc, 0, v89, vcc
	global_store_dwordx4 v[72:73], v[76:79], off
	global_store_dwordx4 v[88:89], v[84:87], off offset:256
	s_waitcnt vmcnt(8)
	v_lshlrev_b32_e32 v132, 16, v124
	v_lshlrev_b32_e32 v76, 16, v128
	v_and_b32_e32 v77, 0xffff0000, v128
	v_pk_fma_f32 v[68:69], v[68:69], v[76:77], v[74:75]
	v_lshlrev_b32_e32 v74, 16, v133
	v_and_b32_e32 v75, 0xffff0000, v133
	v_lshlrev_b32_e32 v76, 16, v129
	v_and_b32_e32 v77, 0xffff0000, v129
	v_pk_fma_f32 v[70:71], v[70:71], v[76:77], v[74:75]
	v_cvt_pk_bf16_f32 v68, v68, v69
	v_cvt_pk_bf16_f32 v69, v70, v71
	v_lshlrev_b32_e32 v70, 16, v134
	v_and_b32_e32 v71, 0xffff0000, v134
	v_lshlrev_b32_e32 v74, 16, v130
	v_and_b32_e32 v75, 0xffff0000, v130
	v_pk_fma_f32 v[64:65], v[64:65], v[74:75], v[70:71]
	v_lshlrev_b32_e32 v74, 16, v131
	v_cvt_pk_bf16_f32 v70, v64, v65
	v_lshlrev_b32_e32 v64, 16, v135
	v_and_b32_e32 v65, 0xffff0000, v135
	v_and_b32_e32 v75, 0xffff0000, v131
	v_pk_fma_f32 v[64:65], v[66:67], v[74:75], v[64:65]
	v_add_u32_e32 v128, 0xa0, v183
	v_cvt_pk_bf16_f32 v71, v64, v65
	global_store_dwordx4 v[72:73], v[68:71], off offset:256
	v_mov_b32_e32 v64, v128
	v_and_b32_e32 v133, 0xffff0000, v124
	v_ashrrev_i32_e32 v65, 31, v64
	v_lshlrev_b64 v[64:65], 10, v[64:65]
	v_lshl_add_u64 v[64:65], v[64:65], 0, v[178:179]
	v_lshlrev_b64 v[64:65], 1, v[64:65]
	v_lshl_add_u64 v[66:67], s[0:1], 0, v[64:65]
	v_lshl_add_u64 v[64:65], s[2:3], 0, v[64:65]
	global_load_dwordx4 v[88:91], v[66:67], off
	global_load_dwordx4 v[80:83], v[66:67], off offset:256
	global_load_dwordx4 v[92:95], v[64:65], off
	global_load_dwordx4 v[84:87], v[64:65], off offset:256
	v_add_co_u32_e32 v66, vcc, s38, v66
	v_lshlrev_b32_e32 v134, 16, v120
	s_nop 0
	v_addc_co_u32_e32 v67, vcc, 0, v67, vcc
	v_add_co_u32_e32 v68, vcc, s38, v64
	v_and_b32_e32 v135, 0xffff0000, v120
	s_nop 0
	v_addc_co_u32_e32 v69, vcc, 0, v65, vcc
	global_load_dwordx4 v[72:75], v[66:67], off
	s_nop 0
	global_load_dwordx4 v[64:67], v[66:67], off offset:256
	s_nop 0
	global_load_dwordx4 v[76:79], v[68:69], off
	s_nop 0
	global_load_dwordx4 v[68:71], v[68:69], off offset:256
	v_lshlrev_b32_e32 v124, 16, v125
	v_and_b32_e32 v125, 0xffff0000, v125
	v_lshlrev_b32_e32 v120, 16, v121
	v_and_b32_e32 v121, 0xffff0000, v121
	v_pk_fma_f32 v[60:61], v[60:61], v[134:135], v[132:133]
	v_pk_fma_f32 v[62:63], v[62:63], v[120:121], v[124:125]
	v_cvt_pk_bf16_f32 v60, v60, v61
	v_cvt_pk_bf16_f32 v61, v62, v63
	v_lshlrev_b32_e32 v62, 16, v126
	v_and_b32_e32 v63, 0xffff0000, v126
	v_lshlrev_b32_e32 v120, 16, v122
	v_and_b32_e32 v121, 0xffff0000, v122
	v_pk_fma_f32 v[56:57], v[56:57], v[120:121], v[62:63]
	v_lshlrev_b32_e32 v120, 16, v123
	v_ashrrev_i32_e32 v183, 31, v182
	v_cvt_pk_bf16_f32 v62, v56, v57
	v_lshlrev_b32_e32 v56, 16, v127
	v_and_b32_e32 v57, 0xffff0000, v127
	v_and_b32_e32 v121, 0xffff0000, v123
	v_lshlrev_b64 v[130:131], 11, v[182:183]
	v_pk_fma_f32 v[56:57], v[58:59], v[120:121], v[56:57]
	s_waitcnt vmcnt(16)
; __device__ __forceinline__ unsigned cvtpk(float lo, float hi) { f32x2 v = {lo, hi}; bf16x2_t b = __builtin_convertvector(v, bf16x2_t); return __builtin_bit_cast(unsigned, b); }
; __device__ __forceinline__ float bflo(unsigned u) { return __uint_as_float(u << 16); }
; __device__ __forceinline__ float bfhi(unsigned u) { return __uint_as_float(u & 0xffff0000u); }
;     __device__ __forceinline__ void operator()(const af4 (&acc)[2][2][4][2], const pg8::Unit& u, int wr, int wc, int fr_, int fq_) const {
;     ...
;         MA_LOAD(0, 0);
; #pragma unroll
;         for (int b_ = 0; b_ < 4; ++b_) {
;             const int ai = b_ >> 1, mp = b_ & 1, cur = b_ & 1;
;             if (b_ + 1 < 4) { if (cur == 0) MA_LOAD(1, b_ + 1); else MA_LOAD(0, b_ + 1); }
;             int RRb = row0 + ai * 128 + mp * 32; asm volatile("" : "+v"(RRb));
;             const size_t ob = (size_t)RRb * 1024 + col0;
; #pragma unroll
;             for (int mi = 0; mi < 2; ++mi)
; #pragma unroll
;                 for (int bj = 0; bj < 2; ++bj) { const af4 v0 = acc[ai][bj][mp * 2 + mi][0], v1 = acc[ai][bj][mp * 2 + mi][1]; const v4u oo = o[cur][mi][bj], y = yv[cur][mi][bj];
;                     v4u w; w.x = cvtpk(bflo(y.x) + v0[0] * bflo(oo.x), bfhi(y.x) + v0[1] * bfhi(oo.x)); w.y = cvtpk(bflo(y.y) + v0[2] * bflo(oo.y), bfhi(y.y) + v0[3] * bfhi(oo.y));
;                     w.z = cvtpk(bflo(y.z) + v1[0] * bflo(oo.z), bfhi(y.z) + v1[1] * bfhi(oo.z)); w.w = cvtpk(bflo(y.w) + v1[2] * bflo(oo.w), bfhi(y.w) + v1[3] * bfhi(oo.w));
;                     *(v4u*)(G + ob + mi * 16 * 1024 + bj * 128) = w; }
	v_lshlrev_b32_e32 v58, 16, v116
	v_cvt_pk_bf16_f32 v63, v56, v57
	v_lshl_add_u64 v[56:57], s[0:1], 0, v[130:131]
	v_lshl_add_u64 v[56:57], v[56:57], 0, v[176:177]
	global_store_dwordx4 v[56:57], v[60:63], off
	v_and_b32_e32 v59, 0xffff0000, v116
	s_nop 0
	v_lshlrev_b32_e32 v60, 16, v112
	v_and_b32_e32 v61, 0xffff0000, v112
	v_pk_fma_f32 v[52:53], v[52:53], v[60:61], v[58:59]
	v_lshlrev_b32_e32 v58, 16, v117
	v_and_b32_e32 v59, 0xffff0000, v117
	v_lshlrev_b32_e32 v60, 16, v113
	v_and_b32_e32 v61, 0xffff0000, v113
	v_pk_fma_f32 v[54:55], v[54:55], v[60:61], v[58:59]
	v_cvt_pk_bf16_f32 v52, v52, v53
	v_cvt_pk_bf16_f32 v53, v54, v55
	v_lshlrev_b32_e32 v54, 16, v118
	v_and_b32_e32 v55, 0xffff0000, v118
	v_lshlrev_b32_e32 v58, 16, v114
	v_and_b32_e32 v59, 0xffff0000, v114
	v_pk_fma_f32 v[44:45], v[44:45], v[58:59], v[54:55]
	v_lshlrev_b32_e32 v58, 16, v115
	v_cvt_pk_bf16_f32 v54, v44, v45
	v_lshlrev_b32_e32 v44, 16, v119
	v_and_b32_e32 v45, 0xffff0000, v119
	v_and_b32_e32 v59, 0xffff0000, v115
	v_pk_fma_f32 v[44:45], v[46:47], v[58:59], v[44:45]
	s_waitcnt vmcnt(16)
	v_lshlrev_b32_e32 v46, 16, v104
	v_cvt_pk_bf16_f32 v55, v44, v45
	s_waitcnt vmcnt(14)
	v_lshlrev_b32_e32 v44, 16, v108
	v_and_b32_e32 v45, 0xffff0000, v108
	v_and_b32_e32 v47, 0xffff0000, v104
	v_pk_fma_f32 v[44:45], v[48:49], v[46:47], v[44:45]
	v_lshlrev_b32_e32 v46, 16, v109
	v_and_b32_e32 v47, 0xffff0000, v109
	v_lshlrev_b32_e32 v48, 16, v105
	v_and_b32_e32 v49, 0xffff0000, v105
	v_pk_fma_f32 v[46:47], v[50:51], v[48:49], v[46:47]
	v_cvt_pk_bf16_f32 v44, v44, v45
	v_cvt_pk_bf16_f32 v45, v46, v47
	v_lshlrev_b32_e32 v46, 16, v110
	v_and_b32_e32 v47, 0xffff0000, v110
	v_lshlrev_b32_e32 v48, 16, v106
	v_and_b32_e32 v49, 0xffff0000, v106
	v_pk_fma_f32 v[40:41], v[40:41], v[48:49], v[46:47]
	v_lshlrev_b32_e32 v48, 16, v107
	v_cvt_pk_bf16_f32 v46, v40, v41
	v_lshlrev_b32_e32 v40, 16, v111
	v_and_b32_e32 v41, 0xffff0000, v111
	v_and_b32_e32 v49, 0xffff0000, v107
	v_pk_fma_f32 v[40:41], v[42:43], v[48:49], v[40:41]
	s_waitcnt vmcnt(13)
	v_lshlrev_b32_e32 v42, 16, v100
	v_cvt_pk_bf16_f32 v47, v40, v41
	v_add_co_u32_e32 v40, vcc, s38, v56
	v_and_b32_e32 v43, 0xffff0000, v100
	s_nop 0
	v_addc_co_u32_e32 v41, vcc, 0, v57, vcc
	global_store_dwordx4 v[40:41], v[44:47], off
	global_store_dwordx4 v[56:57], v[52:55], off offset:256
	s_nop 0
	v_lshlrev_b32_e32 v44, 16, v96
	v_and_b32_e32 v45, 0xffff0000, v96
	v_pk_fma_f32 v[36:37], v[36:37], v[44:45], v[42:43]
	v_lshlrev_b32_e32 v42, 16, v101
	v_and_b32_e32 v43, 0xffff0000, v101
	v_lshlrev_b32_e32 v44, 16, v97
	v_and_b32_e32 v45, 0xffff0000, v97
	v_pk_fma_f32 v[38:39], v[38:39], v[44:45], v[42:43]
	v_cvt_pk_bf16_f32 v36, v36, v37
	v_cvt_pk_bf16_f32 v37, v38, v39
	v_lshlrev_b32_e32 v38, 16, v102
	v_and_b32_e32 v39, 0xffff0000, v102
	v_lshlrev_b32_e32 v42, 16, v98
	v_and_b32_e32 v43, 0xffff0000, v98
	v_pk_fma_f32 v[32:33], v[32:33], v[42:43], v[38:39]
	v_lshlrev_b32_e32 v42, 16, v99
	v_cvt_pk_bf16_f32 v38, v32, v33
	v_lshlrev_b32_e32 v32, 16, v103
	v_and_b32_e32 v33, 0xffff0000, v103
	v_and_b32_e32 v43, 0xffff0000, v99
	v_pk_fma_f32 v[32:33], v[34:35], v[42:43], v[32:33]
	s_waitcnt vmcnt(8)
	v_lshlrev_b32_e32 v34, 16, v92
	v_cvt_pk_bf16_f32 v39, v32, v33
	global_store_dwordx4 v[40:41], v[36:39], off offset:256
	v_and_b32_e32 v35, 0xffff0000, v92
	s_nop 0
	v_lshlrev_b32_e32 v36, 16, v88
	v_and_b32_e32 v37, 0xffff0000, v88
	v_pk_fma_f32 v[28:29], v[28:29], v[36:37], v[34:35]
	v_lshlrev_b32_e32 v34, 16, v93
	v_and_b32_e32 v35, 0xffff0000, v93
	v_lshlrev_b32_e32 v36, 16, v89
	v_and_b32_e32 v37, 0xffff0000, v89
	v_pk_fma_f32 v[30:31], v[30:31], v[36:37], v[34:35]
	v_cvt_pk_bf16_f32 v28, v28, v29
	v_cvt_pk_bf16_f32 v29, v30, v31
	v_lshlrev_b32_e32 v30, 16, v94
	v_and_b32_e32 v31, 0xffff0000, v94
	v_lshlrev_b32_e32 v34, 16, v90
	v_and_b32_e32 v35, 0xffff0000, v90
	v_pk_fma_f32 v[24:25], v[24:25], v[34:35], v[30:31]
	v_ashrrev_i32_e32 v129, 31, v128
	v_cvt_pk_bf16_f32 v30, v24, v25
	v_lshlrev_b32_e32 v24, 16, v95
	v_and_b32_e32 v25, 0xffff0000, v95
	v_lshlrev_b32_e32 v34, 16, v91
	v_and_b32_e32 v35, 0xffff0000, v91
	v_lshlrev_b64 v[32:33], 11, v[128:129]
	v_pk_fma_f32 v[24:25], v[26:27], v[34:35], v[24:25]
	s_waitcnt vmcnt(8)
; #define PG8_WAIT_V(n) asm volatile("s_waitcnt vmcnt(" #n ")" ::: "memory")
; #define PG8_BAR __builtin_amdgcn_s_barrier()
; __device__ __forceinline__ unsigned cvtpk(float lo, float hi) { f32x2 v = {lo, hi}; bf16x2_t b = __builtin_convertvector(v, bf16x2_t); return __builtin_bit_cast(unsigned, b); }
; __device__ __forceinline__ float bflo(unsigned u) { return __uint_as_float(u << 16); }
; __device__ __forceinline__ float bfhi(unsigned u) { return __uint_as_float(u & 0xffff0000u); }
; template <class Epi, class Sched, bool ALIGN_EPI = false, bool SP2 = false>
; __device__ __forceinline__ void gemm_phase(PG8_LAS unsigned char* lds, const Gemm g, const Sched& S, const Epi& E, const int wave_s) {
;     ...
;     PG8_WAIT_V(0);
;     if constexpr (!ALIGN_EPI) { if (wr == 0) PG8_BAR; }
;     PG8_BAR;
;     __device__ __forceinline__ void operator()(const af4 (&acc)[2][2][4][2], const pg8::Unit& u, int wr, int wc, int fr_, int fq_) const {
;     ...
;         for (int b_ = 0; b_ < 4; ++b_) {
;             const int ai = b_ >> 1, mp = b_ & 1, cur = b_ & 1;
;             if (b_ + 1 < 4) { if (cur == 0) MA_LOAD(1, b_ + 1); else MA_LOAD(0, b_ + 1); }
;             int RRb = row0 + ai * 128 + mp * 32; asm volatile("" : "+v"(RRb));
;             const size_t ob = (size_t)RRb * 1024 + col0;
; #pragma unroll
;             for (int mi = 0; mi < 2; ++mi)
; #pragma unroll
;                 for (int bj = 0; bj < 2; ++bj) { const af4 v0 = acc[ai][bj][mp * 2 + mi][0], v1 = acc[ai][bj][mp * 2 + mi][1]; const v4u oo = o[cur][mi][bj], y = yv[cur][mi][bj];
;                     v4u w; w.x = cvtpk(bflo(y.x) + v0[0] * bflo(oo.x), bfhi(y.x) + v0[1] * bfhi(oo.x)); w.y = cvtpk(bflo(y.y) + v0[2] * bflo(oo.y), bfhi(y.y) + v0[3] * bfhi(oo.y));
;                     w.z = cvtpk(bflo(y.z) + v1[0] * bflo(oo.z), bfhi(y.z) + v1[1] * bfhi(oo.z)); w.w = cvtpk(bflo(y.w) + v1[2] * bflo(oo.w), bfhi(y.w) + v1[3] * bfhi(oo.w));
;                     *(v4u*)(G + ob + mi * 16 * 1024 + bj * 128) = w; }
;             asm volatile("" ::: "memory");
	v_lshlrev_b32_e32 v26, 16, v84
	v_cvt_pk_bf16_f32 v31, v24, v25
	v_lshl_add_u64 v[24:25], s[0:1], 0, v[32:33]
	v_lshl_add_u64 v[24:25], v[24:25], 0, v[176:177]
	global_store_dwordx4 v[24:25], v[28:31], off
	v_and_b32_e32 v27, 0xffff0000, v84
	s_nop 0
	v_lshlrev_b32_e32 v28, 16, v80
	v_and_b32_e32 v29, 0xffff0000, v80
	v_pk_fma_f32 v[20:21], v[20:21], v[28:29], v[26:27]
	v_lshlrev_b32_e32 v26, 16, v85
	v_and_b32_e32 v27, 0xffff0000, v85
	v_lshlrev_b32_e32 v28, 16, v81
	v_and_b32_e32 v29, 0xffff0000, v81
	v_pk_fma_f32 v[22:23], v[22:23], v[28:29], v[26:27]
	v_cvt_pk_bf16_f32 v20, v20, v21
	v_cvt_pk_bf16_f32 v21, v22, v23
	v_lshlrev_b32_e32 v22, 16, v86
	v_and_b32_e32 v23, 0xffff0000, v86
	v_lshlrev_b32_e32 v26, 16, v82
	v_and_b32_e32 v27, 0xffff0000, v82
	v_pk_fma_f32 v[12:13], v[12:13], v[26:27], v[22:23]
	v_lshlrev_b32_e32 v26, 16, v83
	v_cvt_pk_bf16_f32 v22, v12, v13
	v_lshlrev_b32_e32 v12, 16, v87
	v_and_b32_e32 v13, 0xffff0000, v87
	v_and_b32_e32 v27, 0xffff0000, v83
	v_pk_fma_f32 v[12:13], v[14:15], v[26:27], v[12:13]
	s_waitcnt vmcnt(8)
	v_lshlrev_b32_e32 v14, 16, v72
	v_cvt_pk_bf16_f32 v23, v12, v13
	s_waitcnt vmcnt(6)
	v_lshlrev_b32_e32 v12, 16, v76
	v_and_b32_e32 v13, 0xffff0000, v76
	v_and_b32_e32 v15, 0xffff0000, v72
	v_pk_fma_f32 v[12:13], v[16:17], v[14:15], v[12:13]
	v_lshlrev_b32_e32 v14, 16, v77
	v_and_b32_e32 v15, 0xffff0000, v77
	v_lshlrev_b32_e32 v16, 16, v73
	v_and_b32_e32 v17, 0xffff0000, v73
	v_pk_fma_f32 v[14:15], v[18:19], v[16:17], v[14:15]
	v_cvt_pk_bf16_f32 v12, v12, v13
	v_cvt_pk_bf16_f32 v13, v14, v15
	v_lshlrev_b32_e32 v14, 16, v78
	v_and_b32_e32 v15, 0xffff0000, v78
	v_lshlrev_b32_e32 v16, 16, v74
	v_and_b32_e32 v17, 0xffff0000, v74
	v_pk_fma_f32 v[8:9], v[8:9], v[16:17], v[14:15]
	v_lshlrev_b32_e32 v16, 16, v75
	v_cvt_pk_bf16_f32 v14, v8, v9
	v_lshlrev_b32_e32 v8, 16, v79
	v_and_b32_e32 v9, 0xffff0000, v79
	v_and_b32_e32 v17, 0xffff0000, v75
	v_pk_fma_f32 v[8:9], v[10:11], v[16:17], v[8:9]
	s_waitcnt vmcnt(5)
	v_lshlrev_b32_e32 v10, 16, v68
	v_cvt_pk_bf16_f32 v15, v8, v9
	v_add_co_u32_e32 v8, vcc, s38, v24
	v_and_b32_e32 v11, 0xffff0000, v68
	s_nop 0
	v_addc_co_u32_e32 v9, vcc, 0, v25, vcc
	global_store_dwordx4 v[8:9], v[12:15], off
	global_store_dwordx4 v[24:25], v[20:23], off offset:256
	s_and_b64 vcc, exec, s[18:19]
	v_lshlrev_b32_e32 v12, 16, v64
	v_and_b32_e32 v13, 0xffff0000, v64
	v_pk_fma_f32 v[4:5], v[4:5], v[12:13], v[10:11]
	v_lshlrev_b32_e32 v10, 16, v69
	v_and_b32_e32 v11, 0xffff0000, v69
	v_lshlrev_b32_e32 v12, 16, v65
	v_and_b32_e32 v13, 0xffff0000, v65
	v_pk_fma_f32 v[6:7], v[6:7], v[12:13], v[10:11]
	v_cvt_pk_bf16_f32 v4, v4, v5
	v_cvt_pk_bf16_f32 v5, v6, v7
	v_lshlrev_b32_e32 v6, 16, v70
	v_and_b32_e32 v7, 0xffff0000, v70
	v_lshlrev_b32_e32 v10, 16, v66
	v_and_b32_e32 v11, 0xffff0000, v66
	v_pk_fma_f32 v[0:1], v[0:1], v[10:11], v[6:7]
	v_lshlrev_b32_e32 v10, 16, v67
	v_cvt_pk_bf16_f32 v6, v0, v1
	v_lshlrev_b32_e32 v0, 16, v71
	v_and_b32_e32 v1, 0xffff0000, v71
	v_and_b32_e32 v11, 0xffff0000, v67
	v_pk_fma_f32 v[0:1], v[2:3], v[10:11], v[0:1]
	s_nop 0
	v_cvt_pk_bf16_f32 v7, v0, v1
	global_store_dwordx4 v[8:9], v[4:7], off offset:256
	s_cbranch_vccz .LBB0_1270
	s_waitcnt vmcnt(0)
	s_cmpk_gt_u32 s86, 0xff
	s_cbranch_scc1 .LBB0_1277
	s_barrier

; #define PG8_STAGE(bufoff, gbase, voff) do { _Pragma("unroll") for (int _i = 0; _i < 2; ++_i) \
;         __builtin_amdgcn_global_load_lds((const unsigned*)((const char*)(gbase) + (voff)[_i]), (PG8_LAS unsigned*)(lds + (bufoff) + ldsw + _i * 8192), 16, 0, 0); } while (0)
; #define PG8_LDA(dst, b, h) do { _Pragma("unroll") for (int m = 0; m < 4; ++m) _Pragma("unroll") for (int k = 0; k < 2; ++k) dst[m][k] = *(const PG8_LAS bf16x8*)(lds + PG8_SA(b, h) + aoff + m * 2048 + k * 1024); } while (0)
; #define PG8_LDB(dst, b, h) do { _Pragma("unroll") for (int n = 0; n < 2; ++n) _Pragma("unroll") for (int k = 0; k < 2; ++k) dst[n][k] = *(const PG8_LAS bf16x8*)(lds + PG8_SB(b, h) + boff + n * 2048 + k * 1024); } while (0)
; #define PG8_MMA(ai, bj, At, Bt) do { __builtin_amdgcn_s_setprio(1); _Pragma("unroll") for (int m = 0; m < 4; ++m) _Pragma("unroll") for (int n = 0; n < 2; ++n) _Pragma("unroll") for (int k = 0; k < 2; ++k) \
;         acc[ai][bj][m][n] = __builtin_amdgcn_mfma_f32_16x16x32_bf16(Bt[n][k], At[m][k], acc[ai][bj][m][n], 0, 0, 0); __builtin_amdgcn_s_setprio(0); } while (0)
; #define PG8_WAIT_V(n) asm volatile("s_waitcnt vmcnt(" #n ")" ::: "memory")
; #define PG8_BAR __builtin_amdgcn_s_barrier()
; template <class Epi, class Sched, bool ALIGN_EPI = false, bool SP2 = false>
; __device__ __forceinline__ void gemm_phase(PG8_LAS unsigned char* lds, const Gemm g, const Sched& S, const Epi& E, const int wave_s) {
;     ...
;         for (int t = 0; t < nt; t += 2) {
;             const bool last = (t == nt - 2);
;             const char* a1 = cA + (size_t)(t + 1) * kstep;
;             const char* a2 = last ? nA : cA + (size_t)(t + 2) * kstep; const char* b2 = last ? nB : cB + (size_t)(t + 2) * kstep;
;             const char* a3 = a2 + kstep; const char* b3 = b2 + kstep;
;             if (last && has_next) S.a_ready(nxt);
;             if constexpr (SP2) {
;             PG8_LDB(B0, 0, 0); PG8_LDB(B1, 0, 1); PG8_SCHED; PG8_LDA(At, 0, 0); PG8_STAGE(PG8_SA(1, 1), a1 + hstep, voffA);
;             PG8_WAIT_V(8); PG8_WAIT_L(0); PG8_BAR; PG8_MMA(0, 0, At, B0); PG8_MMA(0, 1, At, B1); PG8_BAR; PG8_SCHED;
;             PG8_LDA(At, 0, 1); PG8_STAGE(PG8_SB(0, 0), b2, voffB); PG8_STAGE(PG8_SB(0, 1), b2 + hstep, voffB); PG8_STAGE(PG8_SA(0, 0), a2, voffA);
;             PG8_WAIT_V(8); PG8_WAIT_L(0); PG8_BAR; PG8_MMA(1, 0, At, B0); PG8_MMA(1, 1, At, B1); PG8_BAR; PG8_SCHED;
.LBB0_1340:
	ds_read_b128 v[100:103], v215
	ds_read_b128 v[108:111], v215 offset:1024
	ds_read_b128 v[112:115], v215 offset:2048
	ds_read_b128 v[116:119], v215 offset:3072
	ds_read_b128 v[144:147], v216
	ds_read_b128 v[148:151], v216 offset:1024
	ds_read_b128 v[152:155], v216 offset:2048
	ds_read_b128 v[156:159], v216 offset:3072
	s_add_u32 s30, s20, 0xfffc0080
	s_addc_u32 s31, s21, -1
	s_cmp_eq_u32 s64, 12
	s_cselect_b32 s35, s25, s31
	s_cselect_b32 s34, s36, s30
	s_cselect_b32 s31, s23, s63
	s_cselect_b32 s30, s37, s62
	v_lshl_add_u64 v[208:209], s[20:21], 0, v[170:171]
	s_add_i32 m0, s43, 0xc000
	ds_read_b128 v[176:179], v217
	ds_read_b128 v[180:183], v217 offset:1024
	ds_read_b128 v[184:187], v217 offset:2048
	ds_read_b128 v[188:191], v217 offset:3072
	ds_read_b128 v[192:195], v217 offset:4096
	ds_read_b128 v[196:199], v217 offset:5120
	ds_read_b128 v[200:203], v217 offset:6144
	ds_read_b128 v[204:207], v217 offset:7168
	global_load_lds_dwordx4 v[208:209], off
	v_lshl_add_u64 v[208:209], s[20:21], 0, v[168:169]
	s_add_i32 m0, s43, 0xe000
	s_nop 0
	global_load_lds_dwordx4 v[208:209], off
	v_lshl_add_u64 v[230:231], s[30:31], 0, v[164:165]
	s_add_u32 s66, s30, 0x40000
	v_lshl_add_u64 v[232:233], s[30:31], 0, v[160:161]
	s_addc_u32 s67, s31, 0
	v_lshl_add_u64 v[234:235], s[66:67], 0, v[164:165]
	v_lshl_add_u64 v[236:237], s[34:35], 0, v[162:163]
	v_lshl_add_u64 v[238:239], s[66:67], 0, v[160:161]
	v_lshl_add_u64 v[240:241], s[34:35], 0, v[166:167]
	s_waitcnt vmcnt(8)
	s_waitcnt lgkmcnt(0)
	s_barrier
	s_setprio 1
	s_waitcnt lgkmcnt(0)
	v_mfma_f32_16x16x32_bf16 v[140:143], v[100:103], v[176:179], v[140:143]
	v_mfma_f32_16x16x32_bf16 v[136:139], v[112:115], v[176:179], v[136:139]
	v_mfma_f32_16x16x32_bf16 v[124:127], v[100:103], v[184:187], v[124:127]
	v_mfma_f32_16x16x32_bf16 v[120:123], v[112:115], v[184:187], v[120:123]
	v_mfma_f32_16x16x32_bf16 v[92:95], v[100:103], v[192:195], v[92:95]
	v_mfma_f32_16x16x32_bf16 v[88:91], v[112:115], v[192:195], v[88:91]
	v_mfma_f32_16x16x32_bf16 v[76:79], v[100:103], v[200:203], v[76:79]
	v_mfma_f32_16x16x32_bf16 v[72:75], v[112:115], v[200:203], v[72:75]
	v_mfma_f32_16x16x32_bf16 v[140:143], v[108:111], v[180:183], v[140:143]
	v_mfma_f32_16x16x32_bf16 v[136:139], v[116:119], v[180:183], v[136:139]
	v_mfma_f32_16x16x32_bf16 v[124:127], v[108:111], v[188:191], v[124:127]
	v_mfma_f32_16x16x32_bf16 v[120:123], v[116:119], v[188:191], v[120:123]
	v_mfma_f32_16x16x32_bf16 v[92:95], v[108:111], v[196:199], v[92:95]
	v_mfma_f32_16x16x32_bf16 v[88:91], v[116:119], v[196:199], v[88:91]
	v_mfma_f32_16x16x32_bf16 v[76:79], v[108:111], v[204:207], v[76:79]
	v_mfma_f32_16x16x32_bf16 v[72:75], v[116:119], v[204:207], v[72:75]
	s_setprio 0
	s_setprio 1
	v_mfma_f32_16x16x32_bf16 v[132:135], v[144:147], v[176:179], v[132:135]
	v_mfma_f32_16x16x32_bf16 v[128:131], v[152:155], v[176:179], v[128:131]
	v_mfma_f32_16x16x32_bf16 v[104:107], v[144:147], v[184:187], v[104:107]
	v_mfma_f32_16x16x32_bf16 v[96:99], v[152:155], v[184:187], v[96:99]
	v_mfma_f32_16x16x32_bf16 v[84:87], v[144:147], v[192:195], v[84:87]
	v_mfma_f32_16x16x32_bf16 v[80:83], v[152:155], v[192:195], v[80:83]
	v_mfma_f32_16x16x32_bf16 v[68:71], v[144:147], v[200:203], v[68:71]
	v_mfma_f32_16x16x32_bf16 v[64:67], v[152:155], v[200:203], v[64:67]
	v_mfma_f32_16x16x32_bf16 v[132:135], v[148:151], v[180:183], v[132:135]
	v_mfma_f32_16x16x32_bf16 v[128:131], v[156:159], v[180:183], v[128:131]
	v_mfma_f32_16x16x32_bf16 v[104:107], v[148:151], v[188:191], v[104:107]
	v_mfma_f32_16x16x32_bf16 v[96:99], v[156:159], v[188:191], v[96:99]
	v_mfma_f32_16x16x32_bf16 v[84:87], v[148:151], v[196:199], v[84:87]
	v_mfma_f32_16x16x32_bf16 v[80:83], v[156:159], v[196:199], v[80:83]
	v_mfma_f32_16x16x32_bf16 v[68:71], v[148:151], v[204:207], v[68:71]
	v_mfma_f32_16x16x32_bf16 v[64:67], v[156:159], v[204:207], v[64:67]
	s_setprio 0
	s_barrier
	s_add_i32 s65, s58, s33
	s_mov_b32 m0, s65
	ds_read_b128 v[176:179], v217 offset:16384
	ds_read_b128 v[180:183], v217 offset:17408
	ds_read_b128 v[184:187], v217 offset:18432
	ds_read_b128 v[188:191], v217 offset:19456
	ds_read_b128 v[192:195], v217 offset:20480
	ds_read_b128 v[196:199], v217 offset:21504
	ds_read_b128 v[200:203], v217 offset:22528
	ds_read_b128 v[204:207], v217 offset:23552
	global_load_lds_dwordx4 v[230:231], off
	s_add_i32 m0, s65, 0x2000
	s_add_i32 s65, s59, s33
	global_load_lds_dwordx4 v[232:233], off
	s_mov_b32 m0, s65
	s_nop 0
	global_load_lds_dwordx4 v[234:235], off
	s_add_i32 m0, s65, 0x2000
	s_nop 0
	global_load_lds_dwordx4 v[238:239], off
	s_mov_b32 m0, s43
	s_nop 0
	global_load_lds_dwordx4 v[240:241], off
	s_mov_b32 m0, s44
	s_nop 0
	global_load_lds_dwordx4 v[236:237], off
	s_waitcnt vmcnt(8)
	s_waitcnt lgkmcnt(0)
	s_barrier
; #define PG8_STAGE(bufoff, gbase, voff) do { _Pragma("unroll") for (int _i = 0; _i < 2; ++_i) \
;         __builtin_amdgcn_global_load_lds((const unsigned*)((const char*)(gbase) + (voff)[_i]), (PG8_LAS unsigned*)(lds + (bufoff) + ldsw + _i * 8192), 16, 0, 0); } while (0)
; #define PG8_LDA(dst, b, h) do { _Pragma("unroll") for (int m = 0; m < 4; ++m) _Pragma("unroll") for (int k = 0; k < 2; ++k) dst[m][k] = *(const PG8_LAS bf16x8*)(lds + PG8_SA(b, h) + aoff + m * 2048 + k * 1024); } while (0)
; #define PG8_LDB(dst, b, h) do { _Pragma("unroll") for (int n = 0; n < 2; ++n) _Pragma("unroll") for (int k = 0; k < 2; ++k) dst[n][k] = *(const PG8_LAS bf16x8*)(lds + PG8_SB(b, h) + boff + n * 2048 + k * 1024); } while (0)
; #define PG8_MMA(ai, bj, At, Bt) do { __builtin_amdgcn_s_setprio(1); _Pragma("unroll") for (int m = 0; m < 4; ++m) _Pragma("unroll") for (int n = 0; n < 2; ++n) _Pragma("unroll") for (int k = 0; k < 2; ++k) \
;         acc[ai][bj][m][n] = __builtin_amdgcn_mfma_f32_16x16x32_bf16(Bt[n][k], At[m][k], acc[ai][bj][m][n], 0, 0, 0); __builtin_amdgcn_s_setprio(0); } while (0)
; #define PG8_WAIT_V(n) asm volatile("s_waitcnt vmcnt(" #n ")" ::: "memory")
; #define PG8_WAIT_L(n) asm volatile("s_waitcnt lgkmcnt(" #n ")" ::: "memory")
; #define PG8_BAR __builtin_amdgcn_s_barrier()
; #define PG8_SCHED __builtin_amdgcn_sched_barrier(0)
; template <class Epi, class Sched, bool ALIGN_EPI = false, bool SP2 = false>
; __device__ __forceinline__ void gemm_phase(PG8_LAS unsigned char* lds, const Gemm g, const Sched& S, const Epi& E, const int wave_s) {
;     ...
;             PG8_WAIT_V(8); PG8_WAIT_L(0); PG8_BAR; PG8_MMA(1, 0, At, B0); PG8_MMA(1, 1, At, B1); PG8_BAR; PG8_SCHED;
;             PG8_LDB(B0, 1, 0); PG8_LDB(B1, 1, 1); PG8_SCHED; PG8_LDA(At, 1, 0); PG8_STAGE(PG8_SA(0, 1), a2 + hstep, voffA);
;             PG8_WAIT_V(8); PG8_WAIT_L(0); PG8_BAR; PG8_MMA(0, 0, At, B0); PG8_MMA(0, 1, At, B1); PG8_BAR; PG8_SCHED;
;             PG8_LDA(At, 1, 1); PG8_STAGE(PG8_SB(1, 0), b3, voffB); PG8_STAGE(PG8_SB(1, 1), b3 + hstep, voffB); PG8_STAGE(PG8_SA(1, 0), a3, voffA);
	s_setprio 1
	s_waitcnt lgkmcnt(0)
	v_mfma_f32_16x16x32_bf16 v[60:63], v[100:103], v[176:179], v[60:63]
	v_mfma_f32_16x16x32_bf16 v[56:59], v[112:115], v[176:179], v[56:59]
	v_mfma_f32_16x16x32_bf16 v[48:51], v[100:103], v[184:187], v[48:51]
	v_mfma_f32_16x16x32_bf16 v[40:43], v[112:115], v[184:187], v[40:43]
	v_mfma_f32_16x16x32_bf16 v[28:31], v[100:103], v[192:195], v[28:31]
	v_mfma_f32_16x16x32_bf16 v[24:27], v[112:115], v[192:195], v[24:27]
	v_mfma_f32_16x16x32_bf16 v[16:19], v[100:103], v[200:203], v[16:19]
	v_mfma_f32_16x16x32_bf16 v[8:11], v[112:115], v[200:203], v[8:11]
	v_mfma_f32_16x16x32_bf16 v[60:63], v[108:111], v[180:183], v[60:63]
	v_mfma_f32_16x16x32_bf16 v[56:59], v[116:119], v[180:183], v[56:59]
	v_mfma_f32_16x16x32_bf16 v[48:51], v[108:111], v[188:191], v[48:51]
	v_mfma_f32_16x16x32_bf16 v[40:43], v[116:119], v[188:191], v[40:43]
	v_mfma_f32_16x16x32_bf16 v[28:31], v[108:111], v[196:199], v[28:31]
	v_mfma_f32_16x16x32_bf16 v[24:27], v[116:119], v[196:199], v[24:27]
	v_mfma_f32_16x16x32_bf16 v[16:19], v[108:111], v[204:207], v[16:19]
	v_mfma_f32_16x16x32_bf16 v[8:11], v[116:119], v[204:207], v[8:11]
	s_setprio 0
	s_setprio 1
	v_mfma_f32_16x16x32_bf16 v[52:55], v[144:147], v[176:179], v[52:55]
	v_mfma_f32_16x16x32_bf16 v[44:47], v[152:155], v[176:179], v[44:47]
	v_mfma_f32_16x16x32_bf16 v[36:39], v[144:147], v[184:187], v[36:39]
	v_mfma_f32_16x16x32_bf16 v[32:35], v[152:155], v[184:187], v[32:35]
	v_mfma_f32_16x16x32_bf16 v[20:23], v[144:147], v[192:195], v[20:23]
	v_mfma_f32_16x16x32_bf16 v[12:15], v[152:155], v[192:195], v[12:15]
	v_mfma_f32_16x16x32_bf16 v[4:7], v[144:147], v[200:203], v[4:7]
	v_mfma_f32_16x16x32_bf16 v[0:3], v[152:155], v[200:203], v[0:3]
	v_mfma_f32_16x16x32_bf16 v[52:55], v[148:151], v[180:183], v[52:55]
	v_mfma_f32_16x16x32_bf16 v[44:47], v[156:159], v[180:183], v[44:47]
	v_mfma_f32_16x16x32_bf16 v[36:39], v[148:151], v[188:191], v[36:39]
	v_mfma_f32_16x16x32_bf16 v[32:35], v[156:159], v[188:191], v[32:35]
	v_mfma_f32_16x16x32_bf16 v[20:23], v[148:151], v[196:199], v[20:23]
	v_mfma_f32_16x16x32_bf16 v[12:15], v[156:159], v[196:199], v[12:15]
	v_mfma_f32_16x16x32_bf16 v[4:7], v[148:151], v[204:207], v[4:7]
	v_mfma_f32_16x16x32_bf16 v[0:3], v[156:159], v[204:207], v[0:3]
	s_setprio 0
	s_barrier
	s_add_i32 s65, 0, 0x18000
	s_add_i32 s66, 0, 0x1c000
	v_add_u32_e32 v116, s65, v214
	v_add_u32_e32 v156, s66, v214
	ds_read_b128 v[100:103], v116
	ds_read_b128 v[108:111], v116 offset:1024
	ds_read_b128 v[112:115], v116 offset:2048
	ds_read_b128 v[116:119], v116 offset:3072
	ds_read_b128 v[144:147], v156
	ds_read_b128 v[148:151], v156 offset:1024
	ds_read_b128 v[152:155], v156 offset:2048
	ds_read_b128 v[156:159], v156 offset:3072
	s_add_u32 s34, s34, 0x40000
	s_addc_u32 s35, s35, 0
	s_mov_b32 m0, s45
	v_lshl_add_u64 v[220:221], s[34:35], 0, v[166:167]
	ds_read_b128 v[176:179], v217 offset:32768
	ds_read_b128 v[180:183], v217 offset:33792
	ds_read_b128 v[184:187], v217 offset:34816
	ds_read_b128 v[188:191], v217 offset:35840
	ds_read_b128 v[192:195], v217 offset:36864
	ds_read_b128 v[196:199], v217 offset:37888
	ds_read_b128 v[200:203], v217 offset:38912
	ds_read_b128 v[204:207], v217 offset:39936
	global_load_lds_dwordx4 v[220:221], off
	v_lshl_add_u64 v[220:221], s[34:35], 0, v[162:163]
	s_mov_b32 m0, s46
	s_nop 0
	global_load_lds_dwordx4 v[220:221], off
	v_lshl_add_u64 v[242:243], v[230:231], 0, s[6:7]
	s_add_u32 s30, s30, 0x40080
	v_lshl_add_u64 v[244:245], v[232:233], 0, s[6:7]
	s_addc_u32 s31, s31, 0
	v_lshl_add_u64 v[246:247], s[30:31], 0, v[164:165]
	v_lshl_add_u64 v[248:249], s[30:31], 0, v[160:161]
	v_lshl_add_u64 v[250:251], v[240:241], 0, s[6:7]
	v_lshl_add_u64 v[252:253], v[236:237], 0, s[6:7]
	s_waitcnt vmcnt(8)
	s_waitcnt lgkmcnt(0)
	s_barrier
; #define PG8_STAGE(bufoff, gbase, voff) do { _Pragma("unroll") for (int _i = 0; _i < 2; ++_i) \
;         __builtin_amdgcn_global_load_lds((const unsigned*)((const char*)(gbase) + (voff)[_i]), (PG8_LAS unsigned*)(lds + (bufoff) + ldsw + _i * 8192), 16, 0, 0); } while (0)
; #define PG8_LDA(dst, b, h) do { _Pragma("unroll") for (int m = 0; m < 4; ++m) _Pragma("unroll") for (int k = 0; k < 2; ++k) dst[m][k] = *(const PG8_LAS bf16x8*)(lds + PG8_SA(b, h) + aoff + m * 2048 + k * 1024); } while (0)
; #define PG8_MMA(ai, bj, At, Bt) do { __builtin_amdgcn_s_setprio(1); _Pragma("unroll") for (int m = 0; m < 4; ++m) _Pragma("unroll") for (int n = 0; n < 2; ++n) _Pragma("unroll") for (int k = 0; k < 2; ++k) \
;         acc[ai][bj][m][n] = __builtin_amdgcn_mfma_f32_16x16x32_bf16(Bt[n][k], At[m][k], acc[ai][bj][m][n], 0, 0, 0); __builtin_amdgcn_s_setprio(0); } while (0)
; #define PG8_WAIT_V(n) asm volatile("s_waitcnt vmcnt(" #n ")" ::: "memory")
; #define PG8_WAIT_L(n) asm volatile("s_waitcnt lgkmcnt(" #n ")" ::: "memory")
; #define PG8_BAR __builtin_amdgcn_s_barrier()
; #define PG8_SCHED __builtin_amdgcn_sched_barrier(0)
; template <class Epi, class Sched, bool ALIGN_EPI = false, bool SP2 = false>
; __device__ __forceinline__ void gemm_phase(PG8_LAS unsigned char* lds, const Gemm g, const Sched& S, const Epi& E, const int wave_s) {
;     ...
;             PG8_LDA(At, 1, 1); PG8_STAGE(PG8_SB(1, 0), b3, voffB); PG8_STAGE(PG8_SB(1, 1), b3 + hstep, voffB); PG8_STAGE(PG8_SA(1, 0), a3, voffA);
;             PG8_WAIT_V(8); PG8_WAIT_L(0); PG8_BAR; PG8_MMA(1, 0, At, B0); PG8_MMA(1, 1, At, B1); PG8_BAR; PG8_SCHED;
;     __device__ __forceinline__ void operator()(const af4 (&acc)[2][2][4][2], const pg8::Unit& u, int wr, int wc, int fr_, int fq_) const {
;     ...
;         const int grow = rowbase + u.pm * 256; const int bi = grow < TL ? grow / LSEQ : NB;
;         float* xb = grow < TL ? xl + (size_t)grow * DM : xc + (size_t)(grow - TL) * DM;
;         const float* stb = stats + 2 * (size_t)grow;
;         const int col0 = u.pn * 256 + wc * 32 + 8 * fq; const float* gp = gate + (size_t)bi * 6144 + col0;
	s_setprio 1
	s_waitcnt lgkmcnt(0)
	v_mfma_f32_16x16x32_bf16 v[140:143], v[100:103], v[176:179], v[140:143]
	v_mfma_f32_16x16x32_bf16 v[136:139], v[112:115], v[176:179], v[136:139]
	v_mfma_f32_16x16x32_bf16 v[124:127], v[100:103], v[184:187], v[124:127]
	v_mfma_f32_16x16x32_bf16 v[120:123], v[112:115], v[184:187], v[120:123]
	v_mfma_f32_16x16x32_bf16 v[92:95], v[100:103], v[192:195], v[92:95]
	v_mfma_f32_16x16x32_bf16 v[88:91], v[112:115], v[192:195], v[88:91]
	v_mfma_f32_16x16x32_bf16 v[76:79], v[100:103], v[200:203], v[76:79]
	v_mfma_f32_16x16x32_bf16 v[72:75], v[112:115], v[200:203], v[72:75]
	v_mfma_f32_16x16x32_bf16 v[140:143], v[108:111], v[180:183], v[140:143]
	v_mfma_f32_16x16x32_bf16 v[136:139], v[116:119], v[180:183], v[136:139]
	v_mfma_f32_16x16x32_bf16 v[124:127], v[108:111], v[188:191], v[124:127]
	v_mfma_f32_16x16x32_bf16 v[120:123], v[116:119], v[188:191], v[120:123]
	v_mfma_f32_16x16x32_bf16 v[92:95], v[108:111], v[196:199], v[92:95]
	v_mfma_f32_16x16x32_bf16 v[88:91], v[116:119], v[196:199], v[88:91]
	v_mfma_f32_16x16x32_bf16 v[76:79], v[108:111], v[204:207], v[76:79]
	v_mfma_f32_16x16x32_bf16 v[72:75], v[116:119], v[204:207], v[72:75]
	s_setprio 0
	s_setprio 1
	v_mfma_f32_16x16x32_bf16 v[132:135], v[144:147], v[176:179], v[132:135]
	v_mfma_f32_16x16x32_bf16 v[128:131], v[152:155], v[176:179], v[128:131]
	v_mfma_f32_16x16x32_bf16 v[104:107], v[144:147], v[184:187], v[104:107]
	v_mfma_f32_16x16x32_bf16 v[96:99], v[152:155], v[184:187], v[96:99]
	v_mfma_f32_16x16x32_bf16 v[84:87], v[144:147], v[192:195], v[84:87]
	v_mfma_f32_16x16x32_bf16 v[80:83], v[152:155], v[192:195], v[80:83]
	v_mfma_f32_16x16x32_bf16 v[68:71], v[144:147], v[200:203], v[68:71]
	v_mfma_f32_16x16x32_bf16 v[64:67], v[152:155], v[200:203], v[64:67]
	v_mfma_f32_16x16x32_bf16 v[132:135], v[148:151], v[180:183], v[132:135]
	v_mfma_f32_16x16x32_bf16 v[128:131], v[156:159], v[180:183], v[128:131]
	v_mfma_f32_16x16x32_bf16 v[104:107], v[148:151], v[188:191], v[104:107]
	v_mfma_f32_16x16x32_bf16 v[96:99], v[156:159], v[188:191], v[96:99]
	v_mfma_f32_16x16x32_bf16 v[84:87], v[148:151], v[196:199], v[84:87]
	v_mfma_f32_16x16x32_bf16 v[80:83], v[156:159], v[196:199], v[80:83]
	v_mfma_f32_16x16x32_bf16 v[68:71], v[148:151], v[204:207], v[68:71]
	v_mfma_f32_16x16x32_bf16 v[64:67], v[156:159], v[204:207], v[64:67]
	s_setprio 0
	s_barrier
	s_add_i32 s34, s65, s33
	s_mov_b32 m0, s34
	ds_read_b128 v[176:179], v217 offset:49152
	ds_read_b128 v[180:183], v217 offset:50176
	ds_read_b128 v[184:187], v217 offset:51200
	ds_read_b128 v[188:191], v217 offset:52224
	ds_read_b128 v[192:195], v217 offset:53248
	ds_read_b128 v[196:199], v217 offset:54272
	ds_read_b128 v[200:203], v217 offset:55296
	ds_read_b128 v[204:207], v217 offset:56320
	global_load_lds_dwordx4 v[242:243], off
	s_add_i32 m0, s34, 0x2000
	s_add_i32 s34, s66, s33
	global_load_lds_dwordx4 v[244:245], off
	s_mov_b32 m0, s34
	s_nop 0
	global_load_lds_dwordx4 v[246:247], off
	s_add_i32 m0, s34, 0x2000
	s_nop 0
	global_load_lds_dwordx4 v[248:249], off
	s_mov_b32 m0, s54
	s_nop 0
	global_load_lds_dwordx4 v[250:251], off
	s_mov_b32 m0, s55
	s_nop 0
	global_load_lds_dwordx4 v[252:253], off
	s_waitcnt vmcnt(8)
	s_waitcnt lgkmcnt(0)
	s_barrier
	s_setprio 1
	s_waitcnt lgkmcnt(0)
	v_mfma_f32_16x16x32_bf16 v[60:63], v[100:103], v[176:179], v[60:63]
	v_mfma_f32_16x16x32_bf16 v[56:59], v[112:115], v[176:179], v[56:59]
	v_mfma_f32_16x16x32_bf16 v[48:51], v[100:103], v[184:187], v[48:51]
	v_mfma_f32_16x16x32_bf16 v[40:43], v[112:115], v[184:187], v[40:43]
	v_mfma_f32_16x16x32_bf16 v[28:31], v[100:103], v[192:195], v[28:31]
	v_mfma_f32_16x16x32_bf16 v[24:27], v[112:115], v[192:195], v[24:27]
	v_mfma_f32_16x16x32_bf16 v[16:19], v[100:103], v[200:203], v[16:19]
	v_mfma_f32_16x16x32_bf16 v[8:11], v[112:115], v[200:203], v[8:11]
	v_mfma_f32_16x16x32_bf16 v[60:63], v[108:111], v[180:183], v[60:63]
	v_mfma_f32_16x16x32_bf16 v[56:59], v[116:119], v[180:183], v[56:59]
	v_mfma_f32_16x16x32_bf16 v[48:51], v[108:111], v[188:191], v[48:51]
	v_mfma_f32_16x16x32_bf16 v[40:43], v[116:119], v[188:191], v[40:43]
	v_mfma_f32_16x16x32_bf16 v[28:31], v[108:111], v[196:199], v[28:31]
	v_mfma_f32_16x16x32_bf16 v[24:27], v[116:119], v[196:199], v[24:27]
	v_mfma_f32_16x16x32_bf16 v[16:19], v[108:111], v[204:207], v[16:19]
	v_mfma_f32_16x16x32_bf16 v[8:11], v[116:119], v[204:207], v[8:11]
	s_setprio 0
	s_setprio 1
	v_mfma_f32_16x16x32_bf16 v[52:55], v[144:147], v[176:179], v[52:55]
	v_mfma_f32_16x16x32_bf16 v[44:47], v[152:155], v[176:179], v[44:47]
	v_mfma_f32_16x16x32_bf16 v[36:39], v[144:147], v[184:187], v[36:39]
	v_mfma_f32_16x16x32_bf16 v[32:35], v[152:155], v[184:187], v[32:35]
	v_mfma_f32_16x16x32_bf16 v[20:23], v[144:147], v[192:195], v[20:23]
	v_mfma_f32_16x16x32_bf16 v[12:15], v[152:155], v[192:195], v[12:15]
	v_mfma_f32_16x16x32_bf16 v[4:7], v[144:147], v[200:203], v[4:7]
	v_mfma_f32_16x16x32_bf16 v[0:3], v[152:155], v[200:203], v[0:3]
	v_mfma_f32_16x16x32_bf16 v[52:55], v[148:151], v[180:183], v[52:55]
	v_mfma_f32_16x16x32_bf16 v[44:47], v[156:159], v[180:183], v[44:47]
	v_mfma_f32_16x16x32_bf16 v[36:39], v[148:151], v[188:191], v[36:39]
	v_mfma_f32_16x16x32_bf16 v[32:35], v[156:159], v[188:191], v[32:35]
	v_mfma_f32_16x16x32_bf16 v[20:23], v[148:151], v[196:199], v[20:23]
	v_mfma_f32_16x16x32_bf16 v[12:15], v[156:159], v[196:199], v[12:15]
	v_mfma_f32_16x16x32_bf16 v[4:7], v[148:151], v[204:207], v[4:7]
	v_mfma_f32_16x16x32_bf16 v[0:3], v[156:159], v[204:207], v[0:3]
	s_setprio 0
	s_barrier
	s_add_i32 s64, s64, 2
	s_add_u32 s62, s62, 0x100
	s_addc_u32 s63, s63, 0
	s_add_u32 s20, s20, 0x100
	s_addc_u32 s21, s21, 0
	s_cmp_gt_u32 s64, 13
	s_cbranch_scc0 .LBB0_1340
	s_cmpk_gt_i32 s8, 0xff
	s_cselect_b64 s[34:35], -1, 0
	s_mov_b64 s[20:21], 0x18000
	s_and_b64 vcc, exec, s[34:35]
	v_mbcnt_lo_u32_b32 v150, -1, 0
	v_mbcnt_hi_u32_b32 v150, -1, v150
	s_cbranch_vccnz .LBB0_1343
	s_ashr_i32 s20, s8, 31
	s_lshr_b32 s20, s20, 28
	s_add_i32 s20, s8, s20
	s_ashr_i32 s20, s20, 4
	s_mul_hi_i32 s21, s20, 0x1800
	s_mulk_i32 s20, 0x1800

; #define PG8_STAGE(bufoff, gbase, voff) do { _Pragma("unroll") for (int _i = 0; _i < 2; ++_i) \
;         __builtin_amdgcn_global_load_lds((const unsigned*)((const char*)(gbase) + (voff)[_i]), (PG8_LAS unsigned*)(lds + (bufoff) + ldsw + _i * 8192), 16, 0, 0); } while (0)
; #define PG8_LDA(dst, b, h) do { _Pragma("unroll") for (int m = 0; m < 4; ++m) _Pragma("unroll") for (int k = 0; k < 2; ++k) dst[m][k] = *(const PG8_LAS bf16x8*)(lds + PG8_SA(b, h) + aoff + m * 2048 + k * 1024); } while (0)
; #define PG8_LDB(dst, b, h) do { _Pragma("unroll") for (int n = 0; n < 2; ++n) _Pragma("unroll") for (int k = 0; k < 2; ++k) dst[n][k] = *(const PG8_LAS bf16x8*)(lds + PG8_SB(b, h) + boff + n * 2048 + k * 1024); } while (0)
; #define PG8_MMA(ai, bj, At, Bt) do { __builtin_amdgcn_s_setprio(1); _Pragma("unroll") for (int m = 0; m < 4; ++m) _Pragma("unroll") for (int n = 0; n < 2; ++n) _Pragma("unroll") for (int k = 0; k < 2; ++k) \
;         acc[ai][bj][m][n] = __builtin_amdgcn_mfma_f32_16x16x32_bf16(Bt[n][k], At[m][k], acc[ai][bj][m][n], 0, 0, 0); __builtin_amdgcn_s_setprio(0); } while (0)
; #define PG8_WAIT_V(n) asm volatile("s_waitcnt vmcnt(" #n ")" ::: "memory")
; #define PG8_BAR __builtin_amdgcn_s_barrier()
; template <class Epi, class Sched, bool ALIGN_EPI = false, bool SP2 = false>
; __device__ __forceinline__ void gemm_phase(PG8_LAS unsigned char* lds, const Gemm g, const Sched& S, const Epi& E, const int wave_s) {
;     ...
;         for (int t = 0; t < nt; t += 2) {
;             const bool last = (t == nt - 2);
;             const char* a1 = cA + (size_t)(t + 1) * kstep;
;             const char* a2 = last ? nA : cA + (size_t)(t + 2) * kstep; const char* b2 = last ? nB : cB + (size_t)(t + 2) * kstep;
;             const char* a3 = a2 + kstep; const char* b3 = b2 + kstep;
;             if (last && has_next) S.a_ready(nxt);
;             if constexpr (SP2) {
;             PG8_LDB(B0, 0, 0); PG8_LDB(B1, 0, 1); PG8_SCHED; PG8_LDA(At, 0, 0); PG8_STAGE(PG8_SA(1, 1), a1 + hstep, voffA);
;             PG8_WAIT_V(8); PG8_WAIT_L(0); PG8_BAR; PG8_MMA(0, 0, At, B0); PG8_MMA(0, 1, At, B1); PG8_BAR; PG8_SCHED;
;             PG8_LDA(At, 0, 1); PG8_STAGE(PG8_SB(0, 0), b2, voffB); PG8_STAGE(PG8_SB(0, 1), b2 + hstep, voffB); PG8_STAGE(PG8_SA(0, 0), a2, voffA);
;             PG8_WAIT_V(8); PG8_WAIT_L(0); PG8_BAR; PG8_MMA(1, 0, At, B0); PG8_MMA(1, 1, At, B1); PG8_BAR; PG8_SCHED;
.LBB0_1484:
	ds_read_b128 v[36:39], v187
	ds_read_b128 v[40:43], v187 offset:1024
	ds_read_b128 v[44:47], v187 offset:2048
	ds_read_b128 v[48:51], v187 offset:3072
	ds_read_b128 v[80:83], v188
	ds_read_b128 v[84:87], v188 offset:1024
	ds_read_b128 v[88:91], v188 offset:2048
	ds_read_b128 v[92:95], v188 offset:3072
	s_add_u32 s24, s22, 0xfffc0080
	s_addc_u32 s25, s23, -1
	s_cmp_eq_u32 s74, 12
	s_cselect_b32 s27, s21, s25
	s_cselect_b32 s26, s49, s24
	s_cselect_b32 s25, s47, s73
	s_cselect_b32 s24, s56, s57
	v_lshl_add_u64 v[184:185], s[22:23], 0, v[178:179]
	s_add_i32 m0, s41, 0xc000
	ds_read_b128 v[160:163], v189
	ds_read_b128 v[164:167], v189 offset:1024
	ds_read_b128 v[190:193], v189 offset:2048
	ds_read_b128 v[194:197], v189 offset:3072
	ds_read_b128 v[198:201], v189 offset:4096
	ds_read_b128 v[202:205], v189 offset:5120
	ds_read_b128 v[206:209], v189 offset:6144
	ds_read_b128 v[210:213], v189 offset:7168
	global_load_lds_dwordx4 v[184:185], off
	v_lshl_add_u64 v[184:185], s[22:23], 0, v[176:177]
	s_add_i32 m0, s41, 0xe000
	s_nop 0
	global_load_lds_dwordx4 v[184:185], off
	v_lshl_add_u64 v[230:231], s[24:25], 0, v[170:171]
	s_add_u32 s76, s24, 0x40000
	v_lshl_add_u64 v[232:233], s[24:25], 0, v[174:175]
	s_addc_u32 s77, s25, 0
	v_lshl_add_u64 v[234:235], s[76:77], 0, v[170:171]
	v_lshl_add_u64 v[236:237], s[26:27], 0, v[172:173]
	v_lshl_add_u64 v[238:239], s[76:77], 0, v[174:175]
	v_lshl_add_u64 v[240:241], s[26:27], 0, v[168:169]
	s_waitcnt vmcnt(8)
	s_waitcnt lgkmcnt(0)
	s_barrier
	s_setprio 1
	s_waitcnt lgkmcnt(0)
	v_mfma_f32_16x16x32_bf16 v[152:155], v[36:39], v[160:163], v[152:155]
	v_mfma_f32_16x16x32_bf16 v[120:123], v[44:47], v[160:163], v[120:123]
	v_mfma_f32_16x16x32_bf16 v[148:151], v[36:39], v[190:193], v[148:151]
	v_mfma_f32_16x16x32_bf16 v[116:119], v[44:47], v[190:193], v[116:119]
	v_mfma_f32_16x16x32_bf16 v[140:143], v[36:39], v[198:201], v[140:143]
	v_mfma_f32_16x16x32_bf16 v[108:111], v[44:47], v[198:201], v[108:111]
	v_mfma_f32_16x16x32_bf16 v[132:135], v[36:39], v[206:209], v[132:135]
	v_mfma_f32_16x16x32_bf16 v[96:99], v[44:47], v[206:209], v[96:99]
	v_mfma_f32_16x16x32_bf16 v[152:155], v[40:43], v[164:167], v[152:155]
	v_mfma_f32_16x16x32_bf16 v[120:123], v[48:51], v[164:167], v[120:123]
	v_mfma_f32_16x16x32_bf16 v[148:151], v[40:43], v[194:197], v[148:151]
	v_mfma_f32_16x16x32_bf16 v[116:119], v[48:51], v[194:197], v[116:119]
	v_mfma_f32_16x16x32_bf16 v[140:143], v[40:43], v[202:205], v[140:143]
	v_mfma_f32_16x16x32_bf16 v[108:111], v[48:51], v[202:205], v[108:111]
	v_mfma_f32_16x16x32_bf16 v[132:135], v[40:43], v[210:213], v[132:135]
	v_mfma_f32_16x16x32_bf16 v[96:99], v[48:51], v[210:213], v[96:99]
	s_setprio 0
	s_setprio 1
	v_mfma_f32_16x16x32_bf16 v[156:159], v[80:83], v[160:163], v[156:159]
	v_mfma_f32_16x16x32_bf16 v[124:127], v[88:91], v[160:163], v[124:127]
	v_mfma_f32_16x16x32_bf16 v[144:147], v[80:83], v[190:193], v[144:147]
	v_mfma_f32_16x16x32_bf16 v[112:115], v[88:91], v[190:193], v[112:115]
	v_mfma_f32_16x16x32_bf16 v[136:139], v[80:83], v[198:201], v[136:139]
	v_mfma_f32_16x16x32_bf16 v[104:107], v[88:91], v[198:201], v[104:107]
	v_mfma_f32_16x16x32_bf16 v[128:131], v[80:83], v[206:209], v[128:131]
	v_mfma_f32_16x16x32_bf16 v[100:103], v[88:91], v[206:209], v[100:103]
	v_mfma_f32_16x16x32_bf16 v[156:159], v[84:87], v[164:167], v[156:159]
	v_mfma_f32_16x16x32_bf16 v[124:127], v[92:95], v[164:167], v[124:127]
	v_mfma_f32_16x16x32_bf16 v[144:147], v[84:87], v[194:197], v[144:147]
	v_mfma_f32_16x16x32_bf16 v[112:115], v[92:95], v[194:197], v[112:115]
	v_mfma_f32_16x16x32_bf16 v[136:139], v[84:87], v[202:205], v[136:139]
	v_mfma_f32_16x16x32_bf16 v[104:107], v[92:95], v[202:205], v[104:107]
	v_mfma_f32_16x16x32_bf16 v[128:131], v[84:87], v[210:213], v[128:131]
	v_mfma_f32_16x16x32_bf16 v[100:103], v[92:95], v[210:213], v[100:103]
	s_setprio 0
	s_barrier
	s_add_i32 s75, s70, s33
	s_mov_b32 m0, s75
	ds_read_b128 v[160:163], v189 offset:16384
	ds_read_b128 v[164:167], v189 offset:17408
	ds_read_b128 v[190:193], v189 offset:18432
	ds_read_b128 v[194:197], v189 offset:19456
	ds_read_b128 v[198:201], v189 offset:20480
	ds_read_b128 v[202:205], v189 offset:21504
	ds_read_b128 v[206:209], v189 offset:22528
	ds_read_b128 v[210:213], v189 offset:23552
	global_load_lds_dwordx4 v[230:231], off
	s_add_i32 m0, s75, 0x2000
	s_add_i32 s75, s71, s33
	global_load_lds_dwordx4 v[232:233], off
	s_mov_b32 m0, s75
	s_nop 0
	global_load_lds_dwordx4 v[234:235], off
	s_add_i32 m0, s75, 0x2000
	s_nop 0
	global_load_lds_dwordx4 v[238:239], off
	s_mov_b32 m0, s41
	s_nop 0
	global_load_lds_dwordx4 v[240:241], off
	s_mov_b32 m0, s43
	s_nop 0
	global_load_lds_dwordx4 v[236:237], off
	s_waitcnt vmcnt(8)
	s_waitcnt lgkmcnt(0)
	s_barrier
; #define PG8_STAGE(bufoff, gbase, voff) do { _Pragma("unroll") for (int _i = 0; _i < 2; ++_i) \
;         __builtin_amdgcn_global_load_lds((const unsigned*)((const char*)(gbase) + (voff)[_i]), (PG8_LAS unsigned*)(lds + (bufoff) + ldsw + _i * 8192), 16, 0, 0); } while (0)
; #define PG8_LDA(dst, b, h) do { _Pragma("unroll") for (int m = 0; m < 4; ++m) _Pragma("unroll") for (int k = 0; k < 2; ++k) dst[m][k] = *(const PG8_LAS bf16x8*)(lds + PG8_SA(b, h) + aoff + m * 2048 + k * 1024); } while (0)
; #define PG8_LDB(dst, b, h) do { _Pragma("unroll") for (int n = 0; n < 2; ++n) _Pragma("unroll") for (int k = 0; k < 2; ++k) dst[n][k] = *(const PG8_LAS bf16x8*)(lds + PG8_SB(b, h) + boff + n * 2048 + k * 1024); } while (0)
; #define PG8_MMA(ai, bj, At, Bt) do { __builtin_amdgcn_s_setprio(1); _Pragma("unroll") for (int m = 0; m < 4; ++m) _Pragma("unroll") for (int n = 0; n < 2; ++n) _Pragma("unroll") for (int k = 0; k < 2; ++k) \
;         acc[ai][bj][m][n] = __builtin_amdgcn_mfma_f32_16x16x32_bf16(Bt[n][k], At[m][k], acc[ai][bj][m][n], 0, 0, 0); __builtin_amdgcn_s_setprio(0); } while (0)
; #define PG8_WAIT_V(n) asm volatile("s_waitcnt vmcnt(" #n ")" ::: "memory")
; #define PG8_WAIT_L(n) asm volatile("s_waitcnt lgkmcnt(" #n ")" ::: "memory")
; #define PG8_BAR __builtin_amdgcn_s_barrier()
; #define PG8_SCHED __builtin_amdgcn_sched_barrier(0)
; template <class Epi, class Sched, bool ALIGN_EPI = false, bool SP2 = false>
; __device__ __forceinline__ void gemm_phase(PG8_LAS unsigned char* lds, const Gemm g, const Sched& S, const Epi& E, const int wave_s) {
;     ...
;             PG8_WAIT_V(8); PG8_WAIT_L(0); PG8_BAR; PG8_MMA(1, 0, At, B0); PG8_MMA(1, 1, At, B1); PG8_BAR; PG8_SCHED;
;             PG8_LDB(B0, 1, 0); PG8_LDB(B1, 1, 1); PG8_SCHED; PG8_LDA(At, 1, 0); PG8_STAGE(PG8_SA(0, 1), a2 + hstep, voffA);
;             PG8_WAIT_V(8); PG8_WAIT_L(0); PG8_BAR; PG8_MMA(0, 0, At, B0); PG8_MMA(0, 1, At, B1); PG8_BAR; PG8_SCHED;
;             PG8_LDA(At, 1, 1); PG8_STAGE(PG8_SB(1, 0), b3, voffB); PG8_STAGE(PG8_SB(1, 1), b3 + hstep, voffB); PG8_STAGE(PG8_SA(1, 0), a3, voffA);
	s_setprio 1
	s_waitcnt lgkmcnt(0)
	v_mfma_f32_16x16x32_bf16 v[76:79], v[36:39], v[160:163], v[76:79]
	v_mfma_f32_16x16x32_bf16 v[28:31], v[44:47], v[160:163], v[28:31]
	v_mfma_f32_16x16x32_bf16 v[68:71], v[36:39], v[190:193], v[68:71]
	v_mfma_f32_16x16x32_bf16 v[20:23], v[44:47], v[190:193], v[20:23]
	v_mfma_f32_16x16x32_bf16 v[60:63], v[36:39], v[198:201], v[60:63]
	v_mfma_f32_16x16x32_bf16 v[12:15], v[44:47], v[198:201], v[12:15]
	v_mfma_f32_16x16x32_bf16 v[4:7], v[44:47], v[206:209], v[4:7]
	v_mfma_f32_16x16x32_bf16 v[76:79], v[40:43], v[164:167], v[76:79]
	v_mfma_f32_16x16x32_bf16 v[28:31], v[48:51], v[164:167], v[28:31]
	v_mfma_f32_16x16x32_bf16 v[68:71], v[40:43], v[194:197], v[68:71]
	v_mfma_f32_16x16x32_bf16 v[20:23], v[48:51], v[194:197], v[20:23]
	v_mfma_f32_16x16x32_bf16 v[60:63], v[40:43], v[202:205], v[60:63]
	v_mfma_f32_16x16x32_bf16 v[12:15], v[48:51], v[202:205], v[12:15]
	v_mfma_f32_16x16x32_bf16 v[36:39], v[36:39], v[206:209], v[52:55]
	v_mfma_f32_16x16x32_bf16 v[4:7], v[48:51], v[210:213], v[4:7]
	v_mfma_f32_16x16x32_bf16 v[36:39], v[40:43], v[210:213], v[36:39]
	s_setprio 0
	s_setprio 1
	v_mfma_f32_16x16x32_bf16 v[24:27], v[88:91], v[160:163], v[24:27]
	v_mfma_f32_16x16x32_bf16 v[16:19], v[88:91], v[190:193], v[16:19]
	v_mfma_f32_16x16x32_bf16 v[8:11], v[88:91], v[198:201], v[8:11]
	v_mfma_f32_16x16x32_bf16 v[32:35], v[80:83], v[206:209], v[32:35]
	v_mfma_f32_16x16x32_bf16 v[0:3], v[88:91], v[206:209], v[0:3]
	v_mfma_f32_16x16x32_bf16 v[40:43], v[80:83], v[160:163], v[72:75]
	v_mfma_f32_16x16x32_bf16 v[24:27], v[92:95], v[164:167], v[24:27]
	v_mfma_f32_16x16x32_bf16 v[44:47], v[80:83], v[190:193], v[64:67]
	v_mfma_f32_16x16x32_bf16 v[16:19], v[92:95], v[194:197], v[16:19]
	v_mfma_f32_16x16x32_bf16 v[48:51], v[80:83], v[198:201], v[56:59]
	v_mfma_f32_16x16x32_bf16 v[8:11], v[92:95], v[202:205], v[8:11]
	v_mfma_f32_16x16x32_bf16 v[32:35], v[84:87], v[210:213], v[32:35]
	v_mfma_f32_16x16x32_bf16 v[0:3], v[92:95], v[210:213], v[0:3]
	v_mfma_f32_16x16x32_bf16 v[40:43], v[84:87], v[164:167], v[40:43]
	v_mfma_f32_16x16x32_bf16 v[44:47], v[84:87], v[194:197], v[44:47]
	v_mfma_f32_16x16x32_bf16 v[48:51], v[84:87], v[202:205], v[48:51]
	s_setprio 0
	s_barrier
	s_add_i32 s75, 0, 0x18000
	s_add_i32 s76, 0, 0x1c000
	v_add_u32_e32 v72, s75, v186
	v_add_u32_e32 v92, s76, v186
	ds_read_b128 v[52:55], v72
	ds_read_b128 v[56:59], v72 offset:1024
	ds_read_b128 v[64:67], v72 offset:2048
	ds_read_b128 v[72:75], v72 offset:3072
	ds_read_b128 v[80:83], v92
	ds_read_b128 v[84:87], v92 offset:1024
	ds_read_b128 v[88:91], v92 offset:2048
	ds_read_b128 v[92:95], v92 offset:3072
	s_add_u32 s26, s26, 0x40000
	s_addc_u32 s27, s27, 0
	s_mov_b32 m0, s45
	v_lshl_add_u64 v[220:221], s[26:27], 0, v[168:169]
	ds_read_b128 v[160:163], v189 offset:32768
	ds_read_b128 v[164:167], v189 offset:33792
	ds_read_b128 v[190:193], v189 offset:34816
	ds_read_b128 v[194:197], v189 offset:35840
	ds_read_b128 v[198:201], v189 offset:36864
	ds_read_b128 v[202:205], v189 offset:37888
	ds_read_b128 v[206:209], v189 offset:38912
	ds_read_b128 v[210:213], v189 offset:39936
	global_load_lds_dwordx4 v[220:221], off
	v_lshl_add_u64 v[220:221], s[26:27], 0, v[172:173]
	s_mov_b32 m0, s55
	s_nop 0
	global_load_lds_dwordx4 v[220:221], off
	v_lshl_add_u64 v[242:243], v[230:231], 0, s[10:11]
	s_add_u32 s24, s24, 0x40080
	v_lshl_add_u64 v[244:245], v[232:233], 0, s[10:11]
	s_addc_u32 s25, s25, 0
	v_lshl_add_u64 v[246:247], s[24:25], 0, v[170:171]
	v_lshl_add_u64 v[248:249], s[24:25], 0, v[174:175]
	v_lshl_add_u64 v[250:251], v[240:241], 0, s[10:11]
	v_lshl_add_u64 v[252:253], v[236:237], 0, s[10:11]
	s_waitcnt vmcnt(8)
	s_waitcnt lgkmcnt(0)
	s_barrier
; #define PG8_STAGE(bufoff, gbase, voff) do { _Pragma("unroll") for (int _i = 0; _i < 2; ++_i) \
;         __builtin_amdgcn_global_load_lds((const unsigned*)((const char*)(gbase) + (voff)[_i]), (PG8_LAS unsigned*)(lds + (bufoff) + ldsw + _i * 8192), 16, 0, 0); } while (0)
; #define PG8_LDA(dst, b, h) do { _Pragma("unroll") for (int m = 0; m < 4; ++m) _Pragma("unroll") for (int k = 0; k < 2; ++k) dst[m][k] = *(const PG8_LAS bf16x8*)(lds + PG8_SA(b, h) + aoff + m * 2048 + k * 1024); } while (0)
; #define PG8_MMA(ai, bj, At, Bt) do { __builtin_amdgcn_s_setprio(1); _Pragma("unroll") for (int m = 0; m < 4; ++m) _Pragma("unroll") for (int n = 0; n < 2; ++n) _Pragma("unroll") for (int k = 0; k < 2; ++k) \
;         acc[ai][bj][m][n] = __builtin_amdgcn_mfma_f32_16x16x32_bf16(Bt[n][k], At[m][k], acc[ai][bj][m][n], 0, 0, 0); __builtin_amdgcn_s_setprio(0); } while (0)
; #define PG8_WAIT_V(n) asm volatile("s_waitcnt vmcnt(" #n ")" ::: "memory")
; #define PG8_WAIT_L(n) asm volatile("s_waitcnt lgkmcnt(" #n ")" ::: "memory")
; #define PG8_BAR __builtin_amdgcn_s_barrier()
; #define PG8_SCHED __builtin_amdgcn_sched_barrier(0)
; template <class Epi, class Sched, bool ALIGN_EPI = false, bool SP2 = false>
; __device__ __forceinline__ void gemm_phase(PG8_LAS unsigned char* lds, const Gemm g, const Sched& S, const Epi& E, const int wave_s) {
;     ...
;             PG8_LDA(At, 1, 1); PG8_STAGE(PG8_SB(1, 0), b3, voffB); PG8_STAGE(PG8_SB(1, 1), b3 + hstep, voffB); PG8_STAGE(PG8_SA(1, 0), a3, voffA);
;             PG8_WAIT_V(8); PG8_WAIT_L(0); PG8_BAR; PG8_MMA(1, 0, At, B0); PG8_MMA(1, 1, At, B1); PG8_BAR; PG8_SCHED;
;     ...
;         if constexpr (ALIGN_EPI) { if (wr == 0) PG8_BAR; }
	s_setprio 1
	s_waitcnt lgkmcnt(0)
	v_mfma_f32_16x16x32_bf16 v[152:155], v[52:55], v[160:163], v[152:155]
	v_mfma_f32_16x16x32_bf16 v[120:123], v[64:67], v[160:163], v[120:123]
	v_mfma_f32_16x16x32_bf16 v[148:151], v[52:55], v[190:193], v[148:151]
	v_mfma_f32_16x16x32_bf16 v[116:119], v[64:67], v[190:193], v[116:119]
	v_mfma_f32_16x16x32_bf16 v[140:143], v[52:55], v[198:201], v[140:143]
	v_mfma_f32_16x16x32_bf16 v[108:111], v[64:67], v[198:201], v[108:111]
	v_mfma_f32_16x16x32_bf16 v[132:135], v[52:55], v[206:209], v[132:135]
	v_mfma_f32_16x16x32_bf16 v[96:99], v[64:67], v[206:209], v[96:99]
	v_mfma_f32_16x16x32_bf16 v[152:155], v[56:59], v[164:167], v[152:155]
	v_mfma_f32_16x16x32_bf16 v[120:123], v[72:75], v[164:167], v[120:123]
	v_mfma_f32_16x16x32_bf16 v[148:151], v[56:59], v[194:197], v[148:151]
	v_mfma_f32_16x16x32_bf16 v[116:119], v[72:75], v[194:197], v[116:119]
	v_mfma_f32_16x16x32_bf16 v[140:143], v[56:59], v[202:205], v[140:143]
	v_mfma_f32_16x16x32_bf16 v[108:111], v[72:75], v[202:205], v[108:111]
	v_mfma_f32_16x16x32_bf16 v[132:135], v[56:59], v[210:213], v[132:135]
	v_mfma_f32_16x16x32_bf16 v[96:99], v[72:75], v[210:213], v[96:99]
	s_setprio 0
	s_setprio 1
	v_mfma_f32_16x16x32_bf16 v[156:159], v[80:83], v[160:163], v[156:159]
	v_mfma_f32_16x16x32_bf16 v[124:127], v[88:91], v[160:163], v[124:127]
	v_mfma_f32_16x16x32_bf16 v[144:147], v[80:83], v[190:193], v[144:147]
	v_mfma_f32_16x16x32_bf16 v[112:115], v[88:91], v[190:193], v[112:115]
	v_mfma_f32_16x16x32_bf16 v[136:139], v[80:83], v[198:201], v[136:139]
	v_mfma_f32_16x16x32_bf16 v[104:107], v[88:91], v[198:201], v[104:107]
	v_mfma_f32_16x16x32_bf16 v[128:131], v[80:83], v[206:209], v[128:131]
	v_mfma_f32_16x16x32_bf16 v[100:103], v[88:91], v[206:209], v[100:103]
	v_mfma_f32_16x16x32_bf16 v[156:159], v[84:87], v[164:167], v[156:159]
	v_mfma_f32_16x16x32_bf16 v[124:127], v[92:95], v[164:167], v[124:127]
	v_mfma_f32_16x16x32_bf16 v[144:147], v[84:87], v[194:197], v[144:147]
	v_mfma_f32_16x16x32_bf16 v[112:115], v[92:95], v[194:197], v[112:115]
	v_mfma_f32_16x16x32_bf16 v[136:139], v[84:87], v[202:205], v[136:139]
	v_mfma_f32_16x16x32_bf16 v[104:107], v[92:95], v[202:205], v[104:107]
	v_mfma_f32_16x16x32_bf16 v[128:131], v[84:87], v[210:213], v[128:131]
	v_mfma_f32_16x16x32_bf16 v[100:103], v[92:95], v[210:213], v[100:103]
	s_setprio 0
	s_barrier
	s_add_i32 s26, s75, s33
	s_mov_b32 m0, s26
	ds_read_b128 v[160:163], v189 offset:49152
	ds_read_b128 v[164:167], v189 offset:50176
	ds_read_b128 v[190:193], v189 offset:51200
	ds_read_b128 v[194:197], v189 offset:52224
	ds_read_b128 v[198:201], v189 offset:53248
	ds_read_b128 v[202:205], v189 offset:54272
	ds_read_b128 v[206:209], v189 offset:55296
	ds_read_b128 v[210:213], v189 offset:56320
	global_load_lds_dwordx4 v[242:243], off
	s_add_i32 m0, s26, 0x2000
	s_add_i32 s26, s76, s33
	global_load_lds_dwordx4 v[244:245], off
	s_mov_b32 m0, s26
	s_nop 0
	global_load_lds_dwordx4 v[246:247], off
	s_add_i32 m0, s26, 0x2000
	s_nop 0
	global_load_lds_dwordx4 v[248:249], off
	s_mov_b32 m0, s59
	s_nop 0
	global_load_lds_dwordx4 v[250:251], off
	s_mov_b32 m0, s60
	s_nop 0
	global_load_lds_dwordx4 v[252:253], off
	s_waitcnt vmcnt(8)
	s_waitcnt lgkmcnt(0)
	s_barrier
	s_setprio 1
	s_waitcnt lgkmcnt(0)
	v_mfma_f32_16x16x32_bf16 v[76:79], v[52:55], v[160:163], v[76:79]
	v_mfma_f32_16x16x32_bf16 v[28:31], v[64:67], v[160:163], v[28:31]
	v_mfma_f32_16x16x32_bf16 v[68:71], v[52:55], v[190:193], v[68:71]
	v_mfma_f32_16x16x32_bf16 v[20:23], v[64:67], v[190:193], v[20:23]
	v_mfma_f32_16x16x32_bf16 v[60:63], v[52:55], v[198:201], v[60:63]
	v_mfma_f32_16x16x32_bf16 v[12:15], v[64:67], v[198:201], v[12:15]
	v_mfma_f32_16x16x32_bf16 v[36:39], v[52:55], v[206:209], v[36:39]
	v_mfma_f32_16x16x32_bf16 v[4:7], v[64:67], v[206:209], v[4:7]
	v_mfma_f32_16x16x32_bf16 v[76:79], v[56:59], v[164:167], v[76:79]
	v_mfma_f32_16x16x32_bf16 v[28:31], v[72:75], v[164:167], v[28:31]
	v_mfma_f32_16x16x32_bf16 v[68:71], v[56:59], v[194:197], v[68:71]
	v_mfma_f32_16x16x32_bf16 v[20:23], v[72:75], v[194:197], v[20:23]
	v_mfma_f32_16x16x32_bf16 v[60:63], v[56:59], v[202:205], v[60:63]
	v_mfma_f32_16x16x32_bf16 v[12:15], v[72:75], v[202:205], v[12:15]
	v_mfma_f32_16x16x32_bf16 v[52:55], v[56:59], v[210:213], v[36:39]
	v_mfma_f32_16x16x32_bf16 v[4:7], v[72:75], v[210:213], v[4:7]
	s_setprio 0
	s_setprio 1
	v_mfma_f32_16x16x32_bf16 v[36:39], v[80:83], v[160:163], v[40:43]
	v_mfma_f32_16x16x32_bf16 v[72:75], v[84:87], v[164:167], v[36:39]
	v_mfma_f32_16x16x32_bf16 v[36:39], v[80:83], v[190:193], v[44:47]
	v_mfma_f32_16x16x32_bf16 v[24:27], v[88:91], v[160:163], v[24:27]
	v_mfma_f32_16x16x32_bf16 v[64:67], v[84:87], v[194:197], v[36:39]
	v_mfma_f32_16x16x32_bf16 v[16:19], v[88:91], v[190:193], v[16:19]
	v_mfma_f32_16x16x32_bf16 v[36:39], v[80:83], v[198:201], v[48:51]
	v_mfma_f32_16x16x32_bf16 v[8:11], v[88:91], v[198:201], v[8:11]
	v_mfma_f32_16x16x32_bf16 v[32:35], v[80:83], v[206:209], v[32:35]
	v_mfma_f32_16x16x32_bf16 v[0:3], v[88:91], v[206:209], v[0:3]
	v_mfma_f32_16x16x32_bf16 v[24:27], v[92:95], v[164:167], v[24:27]
	v_mfma_f32_16x16x32_bf16 v[16:19], v[92:95], v[194:197], v[16:19]
	v_mfma_f32_16x16x32_bf16 v[56:59], v[84:87], v[202:205], v[36:39]
	v_mfma_f32_16x16x32_bf16 v[8:11], v[92:95], v[202:205], v[8:11]
	v_mfma_f32_16x16x32_bf16 v[32:35], v[84:87], v[210:213], v[32:35]
	v_mfma_f32_16x16x32_bf16 v[0:3], v[92:95], v[210:213], v[0:3]
	s_setprio 0
	s_barrier
	s_add_i32 s74, s74, 2
	s_add_u32 s57, s57, 0x100
	s_addc_u32 s73, s73, 0
	s_add_u32 s22, s22, 0x100
	s_addc_u32 s23, s23, 0
	s_cmp_gt_u32 s74, 13
	s_cbranch_scc0 .LBB0_1484
	s_and_b64 vcc, exec, s[12:13]
	s_cbranch_vccz .LBB0_1487
	s_barrier

; #define PG8_STAGE(bufoff, gbase, voff) do { _Pragma("unroll") for (int _i = 0; _i < 2; ++_i) \
;         __builtin_amdgcn_global_load_lds((const unsigned*)((const char*)(gbase) + (voff)[_i]), (PG8_LAS unsigned*)(lds + (bufoff) + ldsw + _i * 8192), 16, 0, 0); } while (0)
; #define PG8_LDA(dst, b, h) do { _Pragma("unroll") for (int m = 0; m < 4; ++m) _Pragma("unroll") for (int k = 0; k < 2; ++k) dst[m][k] = *(const PG8_LAS bf16x8*)(lds + PG8_SA(b, h) + aoff + m * 2048 + k * 1024); } while (0)
; #define PG8_LDB(dst, b, h) do { _Pragma("unroll") for (int n = 0; n < 2; ++n) _Pragma("unroll") for (int k = 0; k < 2; ++k) dst[n][k] = *(const PG8_LAS bf16x8*)(lds + PG8_SB(b, h) + boff + n * 2048 + k * 1024); } while (0)
; #define PG8_MMA(ai, bj, At, Bt) do { __builtin_amdgcn_s_setprio(1); _Pragma("unroll") for (int m = 0; m < 4; ++m) _Pragma("unroll") for (int n = 0; n < 2; ++n) _Pragma("unroll") for (int k = 0; k < 2; ++k) \
;         acc[ai][bj][m][n] = __builtin_amdgcn_mfma_f32_16x16x32_bf16(Bt[n][k], At[m][k], acc[ai][bj][m][n], 0, 0, 0); __builtin_amdgcn_s_setprio(0); } while (0)
; #define PG8_WAIT_V(n) asm volatile("s_waitcnt vmcnt(" #n ")" ::: "memory")
; #define PG8_BAR __builtin_amdgcn_s_barrier()
; template <class Epi, class Sched, bool ALIGN_EPI = false, bool SP2 = false>
; __device__ __forceinline__ void gemm_phase(PG8_LAS unsigned char* lds, const Gemm g, const Sched& S, const Epi& E, const int wave_s) {
;     ...
;         for (int t = 0; t < nt; t += 2) {
;             const bool last = (t == nt - 2);
;             const char* a1 = cA + (size_t)(t + 1) * kstep;
;             const char* a2 = last ? nA : cA + (size_t)(t + 2) * kstep; const char* b2 = last ? nB : cB + (size_t)(t + 2) * kstep;
;             const char* a3 = a2 + kstep; const char* b3 = b2 + kstep;
;             if (last && has_next) S.a_ready(nxt);
;             if constexpr (SP2) {
;             PG8_LDB(B0, 0, 0); PG8_LDB(B1, 0, 1); PG8_SCHED; PG8_LDA(At, 0, 0); PG8_STAGE(PG8_SA(1, 1), a1 + hstep, voffA);
;             PG8_WAIT_V(8); PG8_WAIT_L(0); PG8_BAR; PG8_MMA(0, 0, At, B0); PG8_MMA(0, 1, At, B1); PG8_BAR; PG8_SCHED;
;             PG8_LDA(At, 0, 1); PG8_STAGE(PG8_SB(0, 0), b2, voffB); PG8_STAGE(PG8_SB(0, 1), b2 + hstep, voffB); PG8_STAGE(PG8_SA(0, 0), a2, voffA);
;             PG8_WAIT_V(8); PG8_WAIT_L(0); PG8_BAR; PG8_MMA(1, 0, At, B0); PG8_MMA(1, 1, At, B1); PG8_BAR; PG8_SCHED;
.LBB0_1720:
	ds_read_b128 v[144:147], v149
	ds_read_b128 v[152:155], v149 offset:1024
	ds_read_b128 v[156:159], v149 offset:2048
	ds_read_b128 v[160:163], v149 offset:3072
	ds_read_b128 v[164:167], v150
	ds_read_b128 v[168:171], v150 offset:1024
	ds_read_b128 v[172:175], v150 offset:2048
	ds_read_b128 v[176:179], v150 offset:3072
	s_add_u32 s26, s24, 0xfffc0080
	s_addc_u32 s27, s25, -1
	s_cmp_eq_u32 s54, 12
	s_cselect_b32 s29, s15, s27
	s_cselect_b32 s28, s23, s26
	s_cselect_b32 s27, s13, s53
	s_cselect_b32 s26, s51, s52
	v_lshl_add_u64 v[212:213], s[24:25], 0, v[138:139]
	s_add_i32 m0, s38, 0xc000
	ds_read_b128 v[180:183], v151
	ds_read_b128 v[184:187], v151 offset:1024
	ds_read_b128 v[188:191], v151 offset:2048
	ds_read_b128 v[192:195], v151 offset:3072
	ds_read_b128 v[196:199], v151 offset:4096
	ds_read_b128 v[200:203], v151 offset:5120
	ds_read_b128 v[204:207], v151 offset:6144
	ds_read_b128 v[208:211], v151 offset:7168
	global_load_lds_dwordx4 v[212:213], off
	v_lshl_add_u64 v[212:213], s[24:25], 0, v[136:137]
	s_add_i32 m0, s38, 0xe000
	s_nop 0
	global_load_lds_dwordx4 v[212:213], off
	v_lshl_add_u64 v[230:231], s[26:27], 0, v[132:133]
	s_add_u32 s56, s26, 0x40000
	v_lshl_add_u64 v[232:233], s[26:27], 0, v[128:129]
	s_addc_u32 s57, s27, 0
	v_lshl_add_u64 v[234:235], s[56:57], 0, v[132:133]
	v_lshl_add_u64 v[236:237], s[28:29], 0, v[130:131]
	v_lshl_add_u64 v[238:239], s[56:57], 0, v[128:129]
	v_lshl_add_u64 v[240:241], s[28:29], 0, v[134:135]
	s_waitcnt vmcnt(8)
	s_waitcnt lgkmcnt(0)
	s_barrier
	s_setprio 1
	s_waitcnt lgkmcnt(0)
	v_mfma_f32_16x16x32_bf16 v[124:127], v[144:147], v[180:183], v[124:127]
	v_mfma_f32_16x16x32_bf16 v[120:123], v[156:159], v[180:183], v[120:123]
	v_mfma_f32_16x16x32_bf16 v[112:115], v[144:147], v[188:191], v[112:115]
	v_mfma_f32_16x16x32_bf16 v[104:107], v[156:159], v[188:191], v[104:107]
	v_mfma_f32_16x16x32_bf16 v[96:99], v[144:147], v[196:199], v[96:99]
	v_mfma_f32_16x16x32_bf16 v[88:91], v[156:159], v[196:199], v[88:91]
	v_mfma_f32_16x16x32_bf16 v[80:83], v[144:147], v[204:207], v[80:83]
	v_mfma_f32_16x16x32_bf16 v[72:75], v[156:159], v[204:207], v[72:75]
	v_mfma_f32_16x16x32_bf16 v[124:127], v[152:155], v[184:187], v[124:127]
	v_mfma_f32_16x16x32_bf16 v[120:123], v[160:163], v[184:187], v[120:123]
	v_mfma_f32_16x16x32_bf16 v[112:115], v[152:155], v[192:195], v[112:115]
	v_mfma_f32_16x16x32_bf16 v[104:107], v[160:163], v[192:195], v[104:107]
	v_mfma_f32_16x16x32_bf16 v[96:99], v[152:155], v[200:203], v[96:99]
	v_mfma_f32_16x16x32_bf16 v[88:91], v[160:163], v[200:203], v[88:91]
	v_mfma_f32_16x16x32_bf16 v[80:83], v[152:155], v[208:211], v[80:83]
	v_mfma_f32_16x16x32_bf16 v[72:75], v[160:163], v[208:211], v[72:75]
	s_setprio 0
	s_setprio 1
	v_mfma_f32_16x16x32_bf16 v[116:119], v[164:167], v[180:183], v[116:119]
	v_mfma_f32_16x16x32_bf16 v[108:111], v[172:175], v[180:183], v[108:111]
	v_mfma_f32_16x16x32_bf16 v[100:103], v[164:167], v[188:191], v[100:103]
	v_mfma_f32_16x16x32_bf16 v[92:95], v[172:175], v[188:191], v[92:95]
	v_mfma_f32_16x16x32_bf16 v[84:87], v[164:167], v[196:199], v[84:87]
	v_mfma_f32_16x16x32_bf16 v[76:79], v[172:175], v[196:199], v[76:79]
	v_mfma_f32_16x16x32_bf16 v[68:71], v[164:167], v[204:207], v[68:71]
	v_mfma_f32_16x16x32_bf16 v[64:67], v[172:175], v[204:207], v[64:67]
	v_mfma_f32_16x16x32_bf16 v[116:119], v[168:171], v[184:187], v[116:119]
	v_mfma_f32_16x16x32_bf16 v[108:111], v[176:179], v[184:187], v[108:111]
	v_mfma_f32_16x16x32_bf16 v[100:103], v[168:171], v[192:195], v[100:103]
	v_mfma_f32_16x16x32_bf16 v[92:95], v[176:179], v[192:195], v[92:95]
	v_mfma_f32_16x16x32_bf16 v[84:87], v[168:171], v[200:203], v[84:87]
	v_mfma_f32_16x16x32_bf16 v[76:79], v[176:179], v[200:203], v[76:79]
	v_mfma_f32_16x16x32_bf16 v[68:71], v[168:171], v[208:211], v[68:71]
	v_mfma_f32_16x16x32_bf16 v[64:67], v[176:179], v[208:211], v[64:67]
	s_setprio 0
	s_barrier
	s_add_i32 s55, s48, s33
	s_mov_b32 m0, s55
	ds_read_b128 v[180:183], v151 offset:16384
	ds_read_b128 v[184:187], v151 offset:17408
	ds_read_b128 v[188:191], v151 offset:18432
	ds_read_b128 v[192:195], v151 offset:19456
	ds_read_b128 v[196:199], v151 offset:20480
	ds_read_b128 v[200:203], v151 offset:21504
	ds_read_b128 v[204:207], v151 offset:22528
	ds_read_b128 v[208:211], v151 offset:23552
	global_load_lds_dwordx4 v[230:231], off
	s_add_i32 m0, s55, 0x2000
	s_add_i32 s55, s49, s33
	global_load_lds_dwordx4 v[232:233], off
	s_mov_b32 m0, s55
	s_nop 0
	global_load_lds_dwordx4 v[234:235], off
	s_add_i32 m0, s55, 0x2000
	s_nop 0
	global_load_lds_dwordx4 v[238:239], off
	s_mov_b32 m0, s38
	s_nop 0
	global_load_lds_dwordx4 v[240:241], off
	s_mov_b32 m0, s39
	s_nop 0
	global_load_lds_dwordx4 v[236:237], off
	s_waitcnt vmcnt(8)
	s_waitcnt lgkmcnt(0)
	s_barrier
; #define PG8_STAGE(bufoff, gbase, voff) do { _Pragma("unroll") for (int _i = 0; _i < 2; ++_i) \
;         __builtin_amdgcn_global_load_lds((const unsigned*)((const char*)(gbase) + (voff)[_i]), (PG8_LAS unsigned*)(lds + (bufoff) + ldsw + _i * 8192), 16, 0, 0); } while (0)
; #define PG8_LDA(dst, b, h) do { _Pragma("unroll") for (int m = 0; m < 4; ++m) _Pragma("unroll") for (int k = 0; k < 2; ++k) dst[m][k] = *(const PG8_LAS bf16x8*)(lds + PG8_SA(b, h) + aoff + m * 2048 + k * 1024); } while (0)
; #define PG8_LDB(dst, b, h) do { _Pragma("unroll") for (int n = 0; n < 2; ++n) _Pragma("unroll") for (int k = 0; k < 2; ++k) dst[n][k] = *(const PG8_LAS bf16x8*)(lds + PG8_SB(b, h) + boff + n * 2048 + k * 1024); } while (0)
; #define PG8_MMA(ai, bj, At, Bt) do { __builtin_amdgcn_s_setprio(1); _Pragma("unroll") for (int m = 0; m < 4; ++m) _Pragma("unroll") for (int n = 0; n < 2; ++n) _Pragma("unroll") for (int k = 0; k < 2; ++k) \
;         acc[ai][bj][m][n] = __builtin_amdgcn_mfma_f32_16x16x32_bf16(Bt[n][k], At[m][k], acc[ai][bj][m][n], 0, 0, 0); __builtin_amdgcn_s_setprio(0); } while (0)
; #define PG8_WAIT_V(n) asm volatile("s_waitcnt vmcnt(" #n ")" ::: "memory")
; #define PG8_WAIT_L(n) asm volatile("s_waitcnt lgkmcnt(" #n ")" ::: "memory")
; #define PG8_BAR __builtin_amdgcn_s_barrier()
; #define PG8_SCHED __builtin_amdgcn_sched_barrier(0)
; template <class Epi, class Sched, bool ALIGN_EPI = false, bool SP2 = false>
; __device__ __forceinline__ void gemm_phase(PG8_LAS unsigned char* lds, const Gemm g, const Sched& S, const Epi& E, const int wave_s) {
;     ...
;             PG8_WAIT_V(8); PG8_WAIT_L(0); PG8_BAR; PG8_MMA(1, 0, At, B0); PG8_MMA(1, 1, At, B1); PG8_BAR; PG8_SCHED;
;             PG8_LDB(B0, 1, 0); PG8_LDB(B1, 1, 1); PG8_SCHED; PG8_LDA(At, 1, 0); PG8_STAGE(PG8_SA(0, 1), a2 + hstep, voffA);
;             PG8_WAIT_V(8); PG8_WAIT_L(0); PG8_BAR; PG8_MMA(0, 0, At, B0); PG8_MMA(0, 1, At, B1); PG8_BAR; PG8_SCHED;
;             PG8_LDA(At, 1, 1); PG8_STAGE(PG8_SB(1, 0), b3, voffB); PG8_STAGE(PG8_SB(1, 1), b3 + hstep, voffB); PG8_STAGE(PG8_SA(1, 0), a3, voffA);
	s_setprio 1
	s_waitcnt lgkmcnt(0)
	v_mfma_f32_16x16x32_bf16 v[60:63], v[144:147], v[180:183], v[60:63]
	v_mfma_f32_16x16x32_bf16 v[56:59], v[156:159], v[180:183], v[56:59]
	v_mfma_f32_16x16x32_bf16 v[48:51], v[144:147], v[188:191], v[48:51]
	v_mfma_f32_16x16x32_bf16 v[40:43], v[156:159], v[188:191], v[40:43]
	v_mfma_f32_16x16x32_bf16 v[32:35], v[144:147], v[196:199], v[32:35]
	v_mfma_f32_16x16x32_bf16 v[24:27], v[156:159], v[196:199], v[24:27]
	v_mfma_f32_16x16x32_bf16 v[16:19], v[144:147], v[204:207], v[16:19]
	v_mfma_f32_16x16x32_bf16 v[8:11], v[156:159], v[204:207], v[8:11]
	v_mfma_f32_16x16x32_bf16 v[60:63], v[152:155], v[184:187], v[60:63]
	v_mfma_f32_16x16x32_bf16 v[56:59], v[160:163], v[184:187], v[56:59]
	v_mfma_f32_16x16x32_bf16 v[48:51], v[152:155], v[192:195], v[48:51]
	v_mfma_f32_16x16x32_bf16 v[40:43], v[160:163], v[192:195], v[40:43]
	v_mfma_f32_16x16x32_bf16 v[32:35], v[152:155], v[200:203], v[32:35]
	v_mfma_f32_16x16x32_bf16 v[24:27], v[160:163], v[200:203], v[24:27]
	v_mfma_f32_16x16x32_bf16 v[16:19], v[152:155], v[208:211], v[16:19]
	v_mfma_f32_16x16x32_bf16 v[8:11], v[160:163], v[208:211], v[8:11]
	s_setprio 0
	s_setprio 1
	v_mfma_f32_16x16x32_bf16 v[52:55], v[164:167], v[180:183], v[52:55]
	v_mfma_f32_16x16x32_bf16 v[44:47], v[172:175], v[180:183], v[44:47]
	v_mfma_f32_16x16x32_bf16 v[36:39], v[164:167], v[188:191], v[36:39]
	v_mfma_f32_16x16x32_bf16 v[28:31], v[172:175], v[188:191], v[28:31]
	v_mfma_f32_16x16x32_bf16 v[20:23], v[164:167], v[196:199], v[20:23]
	v_mfma_f32_16x16x32_bf16 v[12:15], v[172:175], v[196:199], v[12:15]
	v_mfma_f32_16x16x32_bf16 v[4:7], v[164:167], v[204:207], v[4:7]
	v_mfma_f32_16x16x32_bf16 v[0:3], v[172:175], v[204:207], v[0:3]
	v_mfma_f32_16x16x32_bf16 v[52:55], v[168:171], v[184:187], v[52:55]
	v_mfma_f32_16x16x32_bf16 v[44:47], v[176:179], v[184:187], v[44:47]
	v_mfma_f32_16x16x32_bf16 v[36:39], v[168:171], v[192:195], v[36:39]
	v_mfma_f32_16x16x32_bf16 v[28:31], v[176:179], v[192:195], v[28:31]
	v_mfma_f32_16x16x32_bf16 v[20:23], v[168:171], v[200:203], v[20:23]
	v_mfma_f32_16x16x32_bf16 v[12:15], v[176:179], v[200:203], v[12:15]
	v_mfma_f32_16x16x32_bf16 v[4:7], v[168:171], v[208:211], v[4:7]
	v_mfma_f32_16x16x32_bf16 v[0:3], v[176:179], v[208:211], v[0:3]
	s_setprio 0
	s_barrier
	s_add_i32 s55, 0, 0x18000
	s_add_i32 s56, 0, 0x1c000
	v_add_u32_e32 v160, s55, v148
	v_add_u32_e32 v176, s56, v148
	ds_read_b128 v[144:147], v160
	ds_read_b128 v[152:155], v160 offset:1024
	ds_read_b128 v[156:159], v160 offset:2048
	ds_read_b128 v[160:163], v160 offset:3072
	ds_read_b128 v[164:167], v176
	ds_read_b128 v[168:171], v176 offset:1024
	ds_read_b128 v[172:175], v176 offset:2048
	ds_read_b128 v[176:179], v176 offset:3072
	s_add_u32 s28, s28, 0x40000
	s_addc_u32 s29, s29, 0
	s_mov_b32 m0, s40
	v_lshl_add_u64 v[220:221], s[28:29], 0, v[134:135]
	ds_read_b128 v[180:183], v151 offset:32768
	ds_read_b128 v[184:187], v151 offset:33792
	ds_read_b128 v[188:191], v151 offset:34816
	ds_read_b128 v[192:195], v151 offset:35840
	ds_read_b128 v[196:199], v151 offset:36864
	ds_read_b128 v[200:203], v151 offset:37888
	ds_read_b128 v[204:207], v151 offset:38912
	ds_read_b128 v[208:211], v151 offset:39936
	global_load_lds_dwordx4 v[220:221], off
	v_lshl_add_u64 v[220:221], s[28:29], 0, v[130:131]
	s_mov_b32 m0, s41
	s_nop 0
	global_load_lds_dwordx4 v[220:221], off
	v_lshl_add_u64 v[242:243], v[230:231], 0, s[8:9]
	s_add_u32 s26, s26, 0x40080
	v_lshl_add_u64 v[244:245], v[232:233], 0, s[8:9]
	s_addc_u32 s27, s27, 0
	v_lshl_add_u64 v[246:247], s[26:27], 0, v[132:133]
	v_lshl_add_u64 v[248:249], s[26:27], 0, v[128:129]
	v_lshl_add_u64 v[250:251], v[240:241], 0, s[8:9]
	v_lshl_add_u64 v[252:253], v[236:237], 0, s[8:9]
	s_waitcnt vmcnt(8)
	s_waitcnt lgkmcnt(0)
	s_barrier
	s_setprio 1
	s_waitcnt lgkmcnt(0)
	v_mfma_f32_16x16x32_bf16 v[124:127], v[144:147], v[180:183], v[124:127]
	v_mfma_f32_16x16x32_bf16 v[120:123], v[156:159], v[180:183], v[120:123]
	v_mfma_f32_16x16x32_bf16 v[112:115], v[144:147], v[188:191], v[112:115]
	v_mfma_f32_16x16x32_bf16 v[104:107], v[156:159], v[188:191], v[104:107]
	v_mfma_f32_16x16x32_bf16 v[96:99], v[144:147], v[196:199], v[96:99]
	v_mfma_f32_16x16x32_bf16 v[88:91], v[156:159], v[196:199], v[88:91]
	v_mfma_f32_16x16x32_bf16 v[80:83], v[144:147], v[204:207], v[80:83]
	v_mfma_f32_16x16x32_bf16 v[72:75], v[156:159], v[204:207], v[72:75]
	v_mfma_f32_16x16x32_bf16 v[124:127], v[152:155], v[184:187], v[124:127]
	v_mfma_f32_16x16x32_bf16 v[120:123], v[160:163], v[184:187], v[120:123]
	v_mfma_f32_16x16x32_bf16 v[112:115], v[152:155], v[192:195], v[112:115]
	v_mfma_f32_16x16x32_bf16 v[104:107], v[160:163], v[192:195], v[104:107]
	v_mfma_f32_16x16x32_bf16 v[96:99], v[152:155], v[200:203], v[96:99]
	v_mfma_f32_16x16x32_bf16 v[88:91], v[160:163], v[200:203], v[88:91]
	v_mfma_f32_16x16x32_bf16 v[80:83], v[152:155], v[208:211], v[80:83]
	v_mfma_f32_16x16x32_bf16 v[72:75], v[160:163], v[208:211], v[72:75]
	s_setprio 0
	s_setprio 1
	v_mfma_f32_16x16x32_bf16 v[116:119], v[164:167], v[180:183], v[116:119]
	v_mfma_f32_16x16x32_bf16 v[108:111], v[172:175], v[180:183], v[108:111]
	v_mfma_f32_16x16x32_bf16 v[100:103], v[164:167], v[188:191], v[100:103]
	v_mfma_f32_16x16x32_bf16 v[92:95], v[172:175], v[188:191], v[92:95]
	v_mfma_f32_16x16x32_bf16 v[84:87], v[164:167], v[196:199], v[84:87]
	v_mfma_f32_16x16x32_bf16 v[76:79], v[172:175], v[196:199], v[76:79]
	v_mfma_f32_16x16x32_bf16 v[68:71], v[164:167], v[204:207], v[68:71]
	v_mfma_f32_16x16x32_bf16 v[64:67], v[172:175], v[204:207], v[64:67]
	v_mfma_f32_16x16x32_bf16 v[116:119], v[168:171], v[184:187], v[116:119]
	v_mfma_f32_16x16x32_bf16 v[108:111], v[176:179], v[184:187], v[108:111]
	v_mfma_f32_16x16x32_bf16 v[100:103], v[168:171], v[192:195], v[100:103]
	v_mfma_f32_16x16x32_bf16 v[92:95], v[176:179], v[192:195], v[92:95]
	v_mfma_f32_16x16x32_bf16 v[84:87], v[168:171], v[200:203], v[84:87]
	v_mfma_f32_16x16x32_bf16 v[76:79], v[176:179], v[200:203], v[76:79]
	v_mfma_f32_16x16x32_bf16 v[68:71], v[168:171], v[208:211], v[68:71]
	v_mfma_f32_16x16x32_bf16 v[64:67], v[176:179], v[208:211], v[64:67]
	s_setprio 0
	s_barrier
; #define PG8_STAGE(bufoff, gbase, voff) do { _Pragma("unroll") for (int _i = 0; _i < 2; ++_i) \
;         __builtin_amdgcn_global_load_lds((const unsigned*)((const char*)(gbase) + (voff)[_i]), (PG8_LAS unsigned*)(lds + (bufoff) + ldsw + _i * 8192), 16, 0, 0); } while (0)
; #define PG8_LDA(dst, b, h) do { _Pragma("unroll") for (int m = 0; m < 4; ++m) _Pragma("unroll") for (int k = 0; k < 2; ++k) dst[m][k] = *(const PG8_LAS bf16x8*)(lds + PG8_SA(b, h) + aoff + m * 2048 + k * 1024); } while (0)
; template <class Epi, class Sched, bool ALIGN_EPI = false, bool SP2 = false>
; __device__ __forceinline__ void gemm_phase(PG8_LAS unsigned char* lds, const Gemm g, const Sched& S, const Epi& E, const int wave_s) {
;     ...
;             PG8_LDA(At, 1, 1); PG8_STAGE(PG8_SB(1, 0), b3, voffB); PG8_STAGE(PG8_SB(1, 1), b3 + hstep, voffB); PG8_STAGE(PG8_SA(1, 0), a3, voffA);
;             PG8_WAIT_V(8); PG8_WAIT_L(0); PG8_BAR; PG8_MMA(1, 0, At, B0); PG8_MMA(1, 1, At, B1); PG8_BAR; PG8_SCHED;
;     __device__ __forceinline__ void operator()(const af4 (&acc)[2][2][4][2], const pg8::Unit& u, int wr, int wc, int fr_, int fq_) const {
;         const int ln_ = lane_id_v(); const int fr = ln_ & 15, fq = ln_ >> 4;
;         const int row0 = u.pm * 256 + wr * 64 + fr, pn = u.pn;
;         if (pn < 8) {
;             bf16* base; int ldc, colt; float sc = 1.f;
;             if (pn < 2) { base = Q; ldc = 512; colt = pn * 256; sc = 0.08838834764831845f; }
;             else if (pn < 4) { base = K; ldc = 512; colt = (pn - 2) * 256; }
;             else { base = V; ldc = 1024; colt = (pn - 4) * 256; }
;             const int col0 = colt + wc * 32 + 8 * fq;
; #pragma unroll
;             EPI_LOOP { EPI_RR(row0) const af4 v0 = acc[ai][bj][m][0] * sc, v1 = acc[ai][bj][m][1] * sc; v4u w; w.x = cvtpk(v0[0], v0[1]); w.y = cvtpk(v0[2], v0[3]); w.z = cvtpk(v1[0], v1[1]); w.w = cvtpk(v1[2], v1[3]);
;                 *(v4u*)(base + (size_t)RR * ldc + col0 + bj * 128) = w; }
;         } else if (wc == 0) {
; #pragma unroll
;             for (int ai = 0; ai < 2; ++ai)
; #pragma unroll
;                 for (int m = 0; m < 4; ++m) { const af4 v0 = acc[ai][0][m][0], v1 = acc[ai][0][m][1]; v4u w; w.x = cvtpk(v0[0], v0[1]); w.y = cvtpk(v0[2], v0[3]); w.z = cvtpk(v1[0], v1[1]); w.w = cvtpk(v1[2], v1[3]);
;                     *(v4u*)(Z + (size_t)(row0 + ai * 128 + m * 16) * 32 + 8 * fq) = w; }
	s_add_i32 s28, s55, s33
	s_mov_b32 m0, s28
	ds_read_b128 v[180:183], v151 offset:49152
	ds_read_b128 v[184:187], v151 offset:50176
	ds_read_b128 v[188:191], v151 offset:51200
	ds_read_b128 v[192:195], v151 offset:52224
	ds_read_b128 v[196:199], v151 offset:53248
	ds_read_b128 v[200:203], v151 offset:54272
	ds_read_b128 v[204:207], v151 offset:55296
	ds_read_b128 v[208:211], v151 offset:56320
	global_load_lds_dwordx4 v[242:243], off
	s_add_i32 m0, s28, 0x2000
	s_add_i32 s28, s56, s33
	global_load_lds_dwordx4 v[244:245], off
	s_mov_b32 m0, s28
	s_nop 0
	global_load_lds_dwordx4 v[246:247], off
	s_add_i32 m0, s28, 0x2000
	s_nop 0
	global_load_lds_dwordx4 v[248:249], off
	s_mov_b32 m0, s44
	s_nop 0
	global_load_lds_dwordx4 v[250:251], off
	s_mov_b32 m0, s45
	s_nop 0
	global_load_lds_dwordx4 v[252:253], off
	s_waitcnt vmcnt(8)
	s_waitcnt lgkmcnt(0)
	s_barrier
	s_setprio 1
	s_waitcnt lgkmcnt(0)
	v_mfma_f32_16x16x32_bf16 v[60:63], v[144:147], v[180:183], v[60:63]
	v_mfma_f32_16x16x32_bf16 v[56:59], v[156:159], v[180:183], v[56:59]
	v_mfma_f32_16x16x32_bf16 v[48:51], v[144:147], v[188:191], v[48:51]
	v_mfma_f32_16x16x32_bf16 v[40:43], v[156:159], v[188:191], v[40:43]
	v_mfma_f32_16x16x32_bf16 v[32:35], v[144:147], v[196:199], v[32:35]
	v_mfma_f32_16x16x32_bf16 v[24:27], v[156:159], v[196:199], v[24:27]
	v_mfma_f32_16x16x32_bf16 v[16:19], v[144:147], v[204:207], v[16:19]
	v_mfma_f32_16x16x32_bf16 v[8:11], v[156:159], v[204:207], v[8:11]
	v_mfma_f32_16x16x32_bf16 v[60:63], v[152:155], v[184:187], v[60:63]
	v_mfma_f32_16x16x32_bf16 v[56:59], v[160:163], v[184:187], v[56:59]
	v_mfma_f32_16x16x32_bf16 v[48:51], v[152:155], v[192:195], v[48:51]
	v_mfma_f32_16x16x32_bf16 v[40:43], v[160:163], v[192:195], v[40:43]
	v_mfma_f32_16x16x32_bf16 v[32:35], v[152:155], v[200:203], v[32:35]
	v_mfma_f32_16x16x32_bf16 v[24:27], v[160:163], v[200:203], v[24:27]
	v_mfma_f32_16x16x32_bf16 v[16:19], v[152:155], v[208:211], v[16:19]
	v_mfma_f32_16x16x32_bf16 v[8:11], v[160:163], v[208:211], v[8:11]
	s_setprio 0
	s_setprio 1
	v_mfma_f32_16x16x32_bf16 v[52:55], v[164:167], v[180:183], v[52:55]
	v_mfma_f32_16x16x32_bf16 v[44:47], v[172:175], v[180:183], v[44:47]
	v_mfma_f32_16x16x32_bf16 v[36:39], v[164:167], v[188:191], v[36:39]
	v_mfma_f32_16x16x32_bf16 v[28:31], v[172:175], v[188:191], v[28:31]
	v_mfma_f32_16x16x32_bf16 v[20:23], v[164:167], v[196:199], v[20:23]
	v_mfma_f32_16x16x32_bf16 v[12:15], v[172:175], v[196:199], v[12:15]
	v_mfma_f32_16x16x32_bf16 v[4:7], v[164:167], v[204:207], v[4:7]
	v_mfma_f32_16x16x32_bf16 v[0:3], v[172:175], v[204:207], v[0:3]
	v_mfma_f32_16x16x32_bf16 v[52:55], v[168:171], v[184:187], v[52:55]
	v_mfma_f32_16x16x32_bf16 v[44:47], v[176:179], v[184:187], v[44:47]
	v_mfma_f32_16x16x32_bf16 v[36:39], v[168:171], v[192:195], v[36:39]
	v_mfma_f32_16x16x32_bf16 v[28:31], v[176:179], v[192:195], v[28:31]
	v_mfma_f32_16x16x32_bf16 v[20:23], v[168:171], v[200:203], v[20:23]
	v_mfma_f32_16x16x32_bf16 v[12:15], v[176:179], v[200:203], v[12:15]
	v_mfma_f32_16x16x32_bf16 v[4:7], v[168:171], v[208:211], v[4:7]
	v_mfma_f32_16x16x32_bf16 v[0:3], v[176:179], v[208:211], v[0:3]
	s_setprio 0
	s_barrier
	s_add_i32 s54, s54, 2
	s_add_u32 s52, s52, 0x100
	s_addc_u32 s53, s53, 0
	s_add_u32 s24, s24, 0x100
	s_addc_u32 s25, s25, 0
	s_cmp_gt_u32 s54, 13
	s_cbranch_scc0 .LBB0_1720
	s_lshl_b32 s13, s22, 8
	v_mbcnt_lo_u32_b32 v144, -1, 0
	v_mbcnt_hi_u32_b32 v144, -1, v144
	s_add_i32 s13, s13, s87
	v_ashrrev_i32_e32 v146, 4, v144
	v_and_or_b32 v144, v144, 15, s13
	s_cmp_gt_i32 s50, 7
	s_mov_b64 s[22:23], -1
	s_cbranch_scc0 .LBB0_1725
	s_andn2_b64 vcc, exec, s[10:11]
	s_cbranch_vccnz .LBB0_1724
	v_lshlrev_b32_e32 v156, 3, v146
	v_ashrrev_i32_e32 v145, 31, v144
	v_or_b32_e32 v160, 16, v144
	v_ashrrev_i32_e32 v157, 31, v156
	v_lshlrev_b64 v[158:159], 6, v[144:145]
	v_ashrrev_i32_e32 v161, 31, v160
	v_lshl_add_u64 v[158:159], s[6:7], 0, v[158:159]
	v_lshlrev_b64 v[156:157], 1, v[156:157]
	v_lshlrev_b64 v[160:161], 6, v[160:161]
	v_cvt_pk_bf16_f32 v152, v124, v125
	v_cvt_pk_bf16_f32 v153, v126, v127
	v_cvt_pk_bf16_f32 v154, v120, v121
	v_cvt_pk_bf16_f32 v155, v122, v123
	v_lshl_add_u64 v[158:159], v[158:159], 0, v[156:157]
	v_lshl_add_u64 v[160:161], s[6:7], 0, v[160:161]
	global_store_dwordx4 v[158:159], v[152:155], off
	v_lshl_add_u64 v[160:161], v[160:161], 0, v[156:157]
	s_nop 0
	v_cvt_pk_bf16_f32 v152, v112, v113
	v_cvt_pk_bf16_f32 v153, v114, v115
	v_cvt_pk_bf16_f32 v154, v104, v105
	v_cvt_pk_bf16_f32 v155, v106, v107
	global_store_dwordx4 v[160:161], v[152:155], off
	v_or_b32_e32 v160, 32, v144
	v_ashrrev_i32_e32 v161, 31, v160
	v_lshlrev_b64 v[160:161], 6, v[160:161]
	v_lshl_add_u64 v[160:161], s[6:7], 0, v[160:161]
	v_cvt_pk_bf16_f32 v152, v96, v97
	v_cvt_pk_bf16_f32 v153, v98, v99
	v_cvt_pk_bf16_f32 v154, v88, v89
	v_cvt_pk_bf16_f32 v155, v90, v91
	v_lshl_add_u64 v[160:161], v[160:161], 0, v[156:157]
	global_store_dwordx4 v[160:161], v[152:155], off
	v_or_b32_e32 v160, 48, v144
	v_ashrrev_i32_e32 v161, 31, v160
	v_lshlrev_b64 v[160:161], 6, v[160:161]
	v_lshl_add_u64 v[160:161], s[6:7], 0, v[160:161]
	v_cvt_pk_bf16_f32 v152, v80, v81
	v_cvt_pk_bf16_f32 v153, v82, v83
	v_cvt_pk_bf16_f32 v154, v72, v73
	v_cvt_pk_bf16_f32 v155, v74, v75
	v_lshl_add_u64 v[156:157], v[160:161], 0, v[156:157]
	global_store_dwordx4 v[156:157], v[152:155], off
	v_add_co_u32_e32 v156, vcc, s42, v158
	s_nop 0
	v_cvt_pk_bf16_f32 v152, v60, v61
	v_cvt_pk_bf16_f32 v153, v62, v63
	v_cvt_pk_bf16_f32 v154, v56, v57
	v_cvt_pk_bf16_f32 v155, v58, v59
	v_addc_co_u32_e32 v157, vcc, 0, v159, vcc
	global_store_dwordx4 v[156:157], v[152:155], off
	s_nop 1
	v_cvt_pk_bf16_f32 v152, v48, v49
	v_cvt_pk_bf16_f32 v153, v50, v51
	v_cvt_pk_bf16_f32 v154, v40, v41
	v_cvt_pk_bf16_f32 v155, v42, v43
	global_store_dwordx4 v[156:157], v[152:155], off offset:1024
	s_nop 1
	v_cvt_pk_bf16_f32 v152, v32, v33
	v_cvt_pk_bf16_f32 v153, v34, v35
	v_cvt_pk_bf16_f32 v154, v24, v25
	v_cvt_pk_bf16_f32 v155, v26, v27
	global_store_dwordx4 v[156:157], v[152:155], off offset:2048
	s_nop 1
	v_cvt_pk_bf16_f32 v152, v16, v17
	v_cvt_pk_bf16_f32 v153, v18, v19
	v_cvt_pk_bf16_f32 v154, v8, v9
	v_cvt_pk_bf16_f32 v155, v10, v11
	global_store_dwordx4 v[156:157], v[152:155], off offset:3072

; #define PG8_STAGE(bufoff, gbase, voff) do { _Pragma("unroll") for (int _i = 0; _i < 2; ++_i) \
;         __builtin_amdgcn_global_load_lds((const unsigned*)((const char*)(gbase) + (voff)[_i]), (PG8_LAS unsigned*)(lds + (bufoff) + ldsw + _i * 8192), 16, 0, 0); } while (0)
; #define PG8_LDA(dst, b, h) do { _Pragma("unroll") for (int m = 0; m < 4; ++m) _Pragma("unroll") for (int k = 0; k < 2; ++k) dst[m][k] = *(const PG8_LAS bf16x8*)(lds + PG8_SA(b, h) + aoff + m * 2048 + k * 1024); } while (0)
; #define PG8_LDB(dst, b, h) do { _Pragma("unroll") for (int n = 0; n < 2; ++n) _Pragma("unroll") for (int k = 0; k < 2; ++k) dst[n][k] = *(const PG8_LAS bf16x8*)(lds + PG8_SB(b, h) + boff + n * 2048 + k * 1024); } while (0)
; #define PG8_MMA(ai, bj, At, Bt) do { __builtin_amdgcn_s_setprio(1); _Pragma("unroll") for (int m = 0; m < 4; ++m) _Pragma("unroll") for (int n = 0; n < 2; ++n) _Pragma("unroll") for (int k = 0; k < 2; ++k) \
;         acc[ai][bj][m][n] = __builtin_amdgcn_mfma_f32_16x16x32_bf16(Bt[n][k], At[m][k], acc[ai][bj][m][n], 0, 0, 0); __builtin_amdgcn_s_setprio(0); } while (0)
; #define PG8_WAIT_V(n) asm volatile("s_waitcnt vmcnt(" #n ")" ::: "memory")
; #define PG8_WAIT_L(n) asm volatile("s_waitcnt lgkmcnt(" #n ")" ::: "memory")
; template <class Epi, class Sched, bool ALIGN_EPI = false, bool SP2 = false>
; __device__ __forceinline__ void gemm_phase(PG8_LAS unsigned char* lds, const Gemm g, const Sched& S, const Epi& E, const int wave_s) {
;     ...
;             const bool last = (t == nt - 2);
;             const char* a1 = cA + (size_t)(t + 1) * kstep;
;             const char* a2 = last ? nA : cA + (size_t)(t + 2) * kstep; const char* b2 = last ? nB : cB + (size_t)(t + 2) * kstep;
;             const char* a3 = a2 + kstep; const char* b3 = b2 + kstep;
;             if (last && has_next) S.a_ready(nxt);
;             if constexpr (SP2) {
;             PG8_LDB(B0, 0, 0); PG8_LDB(B1, 0, 1); PG8_SCHED; PG8_LDA(At, 0, 0); PG8_STAGE(PG8_SA(1, 1), a1 + hstep, voffA);
;             PG8_WAIT_V(8); PG8_WAIT_L(0); PG8_BAR; PG8_MMA(0, 0, At, B0); PG8_MMA(0, 1, At, B1); PG8_BAR; PG8_SCHED;
;             PG8_LDA(At, 0, 1); PG8_STAGE(PG8_SB(0, 0), b2, voffB); PG8_STAGE(PG8_SB(0, 1), b2 + hstep, voffB); PG8_STAGE(PG8_SA(0, 0), a2, voffA);
;             PG8_WAIT_V(8); PG8_WAIT_L(0); PG8_BAR; PG8_MMA(1, 0, At, B0); PG8_MMA(1, 1, At, B1); PG8_BAR; PG8_SCHED;
.LBB0_1886:
	ds_read_b128 v[128:131], v203
	ds_read_b128 v[132:135], v203 offset:1024
	ds_read_b128 v[136:139], v203 offset:2048
	ds_read_b128 v[140:143], v203 offset:3072
	ds_read_b128 v[144:147], v205
	ds_read_b128 v[148:151], v205 offset:1024
	ds_read_b128 v[152:155], v205 offset:2048
	ds_read_b128 v[156:159], v205 offset:3072
	s_add_u32 s12, s10, 0xfffc0080
	s_addc_u32 s13, s11, -1
	s_cmp_eq_u32 s68, 12
	s_cselect_b32 s17, s9, s13
	s_cselect_b32 s16, s18, s12
	s_cselect_b32 s13, s19, s67
	s_cselect_b32 s12, s29, s31
	v_lshl_add_u64 v[218:219], s[10:11], 0, v[186:187]
	s_add_i32 m0, s44, 0xc000
	ds_read_b128 v[160:163], v207
	ds_read_b128 v[164:167], v207 offset:1024
	ds_read_b128 v[168:171], v207 offset:2048
	ds_read_b128 v[172:175], v207 offset:3072
	ds_read_b128 v[192:195], v207 offset:4096
	ds_read_b128 v[196:199], v207 offset:5120
	ds_read_b128 v[208:211], v207 offset:6144
	ds_read_b128 v[214:217], v207 offset:7168
	global_load_lds_dwordx4 v[218:219], off
	v_lshl_add_u64 v[218:219], s[10:11], 0, v[184:185]
	s_add_i32 m0, s44, 0xe000
	s_nop 0
	global_load_lds_dwordx4 v[218:219], off
	v_lshl_add_u64 v[230:231], s[12:13], 0, v[180:181]
	s_add_u32 s70, s12, 0x40000
	v_lshl_add_u64 v[232:233], s[12:13], 0, v[176:177]
	s_addc_u32 s71, s13, 0
	v_lshl_add_u64 v[234:235], s[70:71], 0, v[180:181]
	v_lshl_add_u64 v[236:237], s[16:17], 0, v[178:179]
	v_lshl_add_u64 v[238:239], s[70:71], 0, v[176:177]
	v_lshl_add_u64 v[240:241], s[16:17], 0, v[182:183]
	s_waitcnt vmcnt(8)
	s_waitcnt lgkmcnt(0)
	s_barrier
	s_setprio 1
	s_waitcnt lgkmcnt(0)
	v_mfma_f32_16x16x32_bf16 v[124:127], v[128:131], v[160:163], v[124:127]
	v_mfma_f32_16x16x32_bf16 v[120:123], v[136:139], v[160:163], v[120:123]
	v_mfma_f32_16x16x32_bf16 v[116:119], v[128:131], v[168:171], v[116:119]
	v_mfma_f32_16x16x32_bf16 v[108:111], v[136:139], v[168:171], v[108:111]
	v_mfma_f32_16x16x32_bf16 v[100:103], v[128:131], v[192:195], v[100:103]
	v_mfma_f32_16x16x32_bf16 v[92:95], v[136:139], v[192:195], v[92:95]
	v_mfma_f32_16x16x32_bf16 v[84:87], v[128:131], v[208:211], v[84:87]
	v_mfma_f32_16x16x32_bf16 v[76:79], v[136:139], v[208:211], v[76:79]
	v_mfma_f32_16x16x32_bf16 v[124:127], v[132:135], v[164:167], v[124:127]
	v_mfma_f32_16x16x32_bf16 v[120:123], v[140:143], v[164:167], v[120:123]
	v_mfma_f32_16x16x32_bf16 v[116:119], v[132:135], v[172:175], v[116:119]
	v_mfma_f32_16x16x32_bf16 v[108:111], v[140:143], v[172:175], v[108:111]
	v_mfma_f32_16x16x32_bf16 v[100:103], v[132:135], v[196:199], v[100:103]
	v_mfma_f32_16x16x32_bf16 v[92:95], v[140:143], v[196:199], v[92:95]
	v_mfma_f32_16x16x32_bf16 v[84:87], v[132:135], v[214:217], v[84:87]
	v_mfma_f32_16x16x32_bf16 v[76:79], v[140:143], v[214:217], v[76:79]
	s_setprio 0
	s_setprio 1
	v_mfma_f32_16x16x32_bf16 v[112:115], v[144:147], v[160:163], v[112:115]
	v_mfma_f32_16x16x32_bf16 v[104:107], v[152:155], v[160:163], v[104:107]
	v_mfma_f32_16x16x32_bf16 v[96:99], v[144:147], v[168:171], v[96:99]
	v_mfma_f32_16x16x32_bf16 v[88:91], v[152:155], v[168:171], v[88:91]
	v_mfma_f32_16x16x32_bf16 v[80:83], v[144:147], v[192:195], v[80:83]
	v_mfma_f32_16x16x32_bf16 v[72:75], v[152:155], v[192:195], v[72:75]
	v_mfma_f32_16x16x32_bf16 v[68:71], v[144:147], v[208:211], v[68:71]
	v_mfma_f32_16x16x32_bf16 v[64:67], v[152:155], v[208:211], v[64:67]
	v_mfma_f32_16x16x32_bf16 v[112:115], v[148:151], v[164:167], v[112:115]
	v_mfma_f32_16x16x32_bf16 v[104:107], v[156:159], v[164:167], v[104:107]
	v_mfma_f32_16x16x32_bf16 v[96:99], v[148:151], v[172:175], v[96:99]
	v_mfma_f32_16x16x32_bf16 v[88:91], v[156:159], v[172:175], v[88:91]
	v_mfma_f32_16x16x32_bf16 v[80:83], v[148:151], v[196:199], v[80:83]
	v_mfma_f32_16x16x32_bf16 v[72:75], v[156:159], v[196:199], v[72:75]
	v_mfma_f32_16x16x32_bf16 v[68:71], v[148:151], v[214:217], v[68:71]
	v_mfma_f32_16x16x32_bf16 v[64:67], v[156:159], v[214:217], v[64:67]
	s_setprio 0
	s_barrier
	s_add_i32 s69, s63, s33
	s_mov_b32 m0, s69
	ds_read_b128 v[160:163], v207 offset:16384
	ds_read_b128 v[164:167], v207 offset:17408
	ds_read_b128 v[168:171], v207 offset:18432
	ds_read_b128 v[172:175], v207 offset:19456
	ds_read_b128 v[192:195], v207 offset:20480
	ds_read_b128 v[196:199], v207 offset:21504
	ds_read_b128 v[208:211], v207 offset:22528
	ds_read_b128 v[214:217], v207 offset:23552
	global_load_lds_dwordx4 v[230:231], off
	s_add_i32 m0, s69, 0x2000
	s_add_i32 s69, s64, s33
	global_load_lds_dwordx4 v[232:233], off
	s_mov_b32 m0, s69
	s_nop 0
	global_load_lds_dwordx4 v[234:235], off
	s_add_i32 m0, s69, 0x2000
	s_nop 0
	global_load_lds_dwordx4 v[238:239], off
	s_mov_b32 m0, s44
	s_nop 0
	global_load_lds_dwordx4 v[240:241], off
	s_mov_b32 m0, s45
	s_nop 0
	global_load_lds_dwordx4 v[236:237], off
	s_waitcnt vmcnt(8)
	s_waitcnt lgkmcnt(0)
	s_barrier
; #define PG8_STAGE(bufoff, gbase, voff) do { _Pragma("unroll") for (int _i = 0; _i < 2; ++_i) \
;         __builtin_amdgcn_global_load_lds((const unsigned*)((const char*)(gbase) + (voff)[_i]), (PG8_LAS unsigned*)(lds + (bufoff) + ldsw + _i * 8192), 16, 0, 0); } while (0)
; #define PG8_LDA(dst, b, h) do { _Pragma("unroll") for (int m = 0; m < 4; ++m) _Pragma("unroll") for (int k = 0; k < 2; ++k) dst[m][k] = *(const PG8_LAS bf16x8*)(lds + PG8_SA(b, h) + aoff + m * 2048 + k * 1024); } while (0)
; #define PG8_LDB(dst, b, h) do { _Pragma("unroll") for (int n = 0; n < 2; ++n) _Pragma("unroll") for (int k = 0; k < 2; ++k) dst[n][k] = *(const PG8_LAS bf16x8*)(lds + PG8_SB(b, h) + boff + n * 2048 + k * 1024); } while (0)
; #define PG8_MMA(ai, bj, At, Bt) do { __builtin_amdgcn_s_setprio(1); _Pragma("unroll") for (int m = 0; m < 4; ++m) _Pragma("unroll") for (int n = 0; n < 2; ++n) _Pragma("unroll") for (int k = 0; k < 2; ++k) \
;         acc[ai][bj][m][n] = __builtin_amdgcn_mfma_f32_16x16x32_bf16(Bt[n][k], At[m][k], acc[ai][bj][m][n], 0, 0, 0); __builtin_amdgcn_s_setprio(0); } while (0)
; #define PG8_WAIT_V(n) asm volatile("s_waitcnt vmcnt(" #n ")" ::: "memory")
; #define PG8_WAIT_L(n) asm volatile("s_waitcnt lgkmcnt(" #n ")" ::: "memory")
; #define PG8_BAR __builtin_amdgcn_s_barrier()
; #define PG8_SCHED __builtin_amdgcn_sched_barrier(0)
; template <class Epi, class Sched, bool ALIGN_EPI = false, bool SP2 = false>
; __device__ __forceinline__ void gemm_phase(PG8_LAS unsigned char* lds, const Gemm g, const Sched& S, const Epi& E, const int wave_s) {
;     ...
;             PG8_WAIT_V(8); PG8_WAIT_L(0); PG8_BAR; PG8_MMA(1, 0, At, B0); PG8_MMA(1, 1, At, B1); PG8_BAR; PG8_SCHED;
;             PG8_LDB(B0, 1, 0); PG8_LDB(B1, 1, 1); PG8_SCHED; PG8_LDA(At, 1, 0); PG8_STAGE(PG8_SA(0, 1), a2 + hstep, voffA);
;             PG8_WAIT_V(8); PG8_WAIT_L(0); PG8_BAR; PG8_MMA(0, 0, At, B0); PG8_MMA(0, 1, At, B1); PG8_BAR; PG8_SCHED;
;             PG8_LDA(At, 1, 1); PG8_STAGE(PG8_SB(1, 0), b3, voffB); PG8_STAGE(PG8_SB(1, 1), b3 + hstep, voffB); PG8_STAGE(PG8_SA(1, 0), a3, voffA);
	s_setprio 1
	s_waitcnt lgkmcnt(0)
	v_mfma_f32_16x16x32_bf16 v[60:63], v[128:131], v[160:163], v[60:63]
	v_mfma_f32_16x16x32_bf16 v[56:59], v[136:139], v[160:163], v[56:59]
	v_mfma_f32_16x16x32_bf16 v[52:55], v[128:131], v[168:171], v[52:55]
	v_mfma_f32_16x16x32_bf16 v[44:47], v[136:139], v[168:171], v[44:47]
	v_mfma_f32_16x16x32_bf16 v[36:39], v[128:131], v[192:195], v[36:39]
	v_mfma_f32_16x16x32_bf16 v[28:31], v[136:139], v[192:195], v[28:31]
	v_mfma_f32_16x16x32_bf16 v[20:23], v[128:131], v[208:211], v[20:23]
	v_mfma_f32_16x16x32_bf16 v[12:15], v[136:139], v[208:211], v[12:15]
	v_mfma_f32_16x16x32_bf16 v[60:63], v[132:135], v[164:167], v[60:63]
	v_mfma_f32_16x16x32_bf16 v[56:59], v[140:143], v[164:167], v[56:59]
	v_mfma_f32_16x16x32_bf16 v[52:55], v[132:135], v[172:175], v[52:55]
	v_mfma_f32_16x16x32_bf16 v[44:47], v[140:143], v[172:175], v[44:47]
	v_mfma_f32_16x16x32_bf16 v[36:39], v[132:135], v[196:199], v[36:39]
	v_mfma_f32_16x16x32_bf16 v[28:31], v[140:143], v[196:199], v[28:31]
	v_mfma_f32_16x16x32_bf16 v[20:23], v[132:135], v[214:217], v[20:23]
	v_mfma_f32_16x16x32_bf16 v[12:15], v[140:143], v[214:217], v[12:15]
	s_setprio 0
	s_setprio 1
	v_mfma_f32_16x16x32_bf16 v[48:51], v[144:147], v[160:163], v[48:51]
	v_mfma_f32_16x16x32_bf16 v[40:43], v[152:155], v[160:163], v[40:43]
	v_mfma_f32_16x16x32_bf16 v[32:35], v[144:147], v[168:171], v[32:35]
	v_mfma_f32_16x16x32_bf16 v[24:27], v[152:155], v[168:171], v[24:27]
	v_mfma_f32_16x16x32_bf16 v[16:19], v[144:147], v[192:195], v[16:19]
	v_mfma_f32_16x16x32_bf16 v[8:11], v[152:155], v[192:195], v[8:11]
	v_mfma_f32_16x16x32_bf16 v[4:7], v[144:147], v[208:211], v[4:7]
	v_mfma_f32_16x16x32_bf16 v[0:3], v[152:155], v[208:211], v[0:3]
	v_mfma_f32_16x16x32_bf16 v[48:51], v[148:151], v[164:167], v[48:51]
	v_mfma_f32_16x16x32_bf16 v[40:43], v[156:159], v[164:167], v[40:43]
	v_mfma_f32_16x16x32_bf16 v[32:35], v[148:151], v[172:175], v[32:35]
	v_mfma_f32_16x16x32_bf16 v[24:27], v[156:159], v[172:175], v[24:27]
	v_mfma_f32_16x16x32_bf16 v[16:19], v[148:151], v[196:199], v[16:19]
	v_mfma_f32_16x16x32_bf16 v[8:11], v[156:159], v[196:199], v[8:11]
	v_mfma_f32_16x16x32_bf16 v[4:7], v[148:151], v[214:217], v[4:7]
	v_mfma_f32_16x16x32_bf16 v[0:3], v[156:159], v[214:217], v[0:3]
	s_setprio 0
	s_barrier
	s_add_i32 s69, 0, 0x18000
	s_add_i32 s70, 0, 0x1c000
	v_add_u32_e32 v140, s69, v201
	v_add_u32_e32 v156, s70, v201
	ds_read_b128 v[128:131], v140
	ds_read_b128 v[132:135], v140 offset:1024
	ds_read_b128 v[136:139], v140 offset:2048
	ds_read_b128 v[140:143], v140 offset:3072
	ds_read_b128 v[144:147], v156
	ds_read_b128 v[148:151], v156 offset:1024
	ds_read_b128 v[152:155], v156 offset:2048
	ds_read_b128 v[156:159], v156 offset:3072
	s_add_u32 s16, s16, 0x40000
	s_addc_u32 s17, s17, 0
	s_mov_b32 m0, s46
	v_lshl_add_u64 v[226:227], s[16:17], 0, v[182:183]
	ds_read_b128 v[160:163], v207 offset:32768
	ds_read_b128 v[164:167], v207 offset:33792
	ds_read_b128 v[168:171], v207 offset:34816
	ds_read_b128 v[172:175], v207 offset:35840
	ds_read_b128 v[192:195], v207 offset:36864
	ds_read_b128 v[196:199], v207 offset:37888
	ds_read_b128 v[208:211], v207 offset:38912
	ds_read_b128 v[214:217], v207 offset:39936
	global_load_lds_dwordx4 v[226:227], off
	v_lshl_add_u64 v[226:227], s[16:17], 0, v[178:179]
	s_mov_b32 m0, s47
	s_nop 0
	global_load_lds_dwordx4 v[226:227], off
	v_lshl_add_u64 v[242:243], v[230:231], 0, s[24:25]
	s_add_u32 s12, s12, 0x40080
	v_lshl_add_u64 v[244:245], v[232:233], 0, s[24:25]
	s_addc_u32 s13, s13, 0
	v_lshl_add_u64 v[246:247], s[12:13], 0, v[180:181]
	v_lshl_add_u64 v[248:249], s[12:13], 0, v[176:177]
	v_lshl_add_u64 v[250:251], v[240:241], 0, s[24:25]
	v_lshl_add_u64 v[252:253], v[236:237], 0, s[24:25]
	s_waitcnt vmcnt(8)
	s_waitcnt lgkmcnt(0)
	s_barrier
; #define PG8_STAGE(bufoff, gbase, voff) do { _Pragma("unroll") for (int _i = 0; _i < 2; ++_i) \
;         __builtin_amdgcn_global_load_lds((const unsigned*)((const char*)(gbase) + (voff)[_i]), (PG8_LAS unsigned*)(lds + (bufoff) + ldsw + _i * 8192), 16, 0, 0); } while (0)
; #define PG8_LDA(dst, b, h) do { _Pragma("unroll") for (int m = 0; m < 4; ++m) _Pragma("unroll") for (int k = 0; k < 2; ++k) dst[m][k] = *(const PG8_LAS bf16x8*)(lds + PG8_SA(b, h) + aoff + m * 2048 + k * 1024); } while (0)
; #define PG8_MMA(ai, bj, At, Bt) do { __builtin_amdgcn_s_setprio(1); _Pragma("unroll") for (int m = 0; m < 4; ++m) _Pragma("unroll") for (int n = 0; n < 2; ++n) _Pragma("unroll") for (int k = 0; k < 2; ++k) \
;         acc[ai][bj][m][n] = __builtin_amdgcn_mfma_f32_16x16x32_bf16(Bt[n][k], At[m][k], acc[ai][bj][m][n], 0, 0, 0); __builtin_amdgcn_s_setprio(0); } while (0)
; #define PG8_WAIT_V(n) asm volatile("s_waitcnt vmcnt(" #n ")" ::: "memory")
; #define PG8_WAIT_L(n) asm volatile("s_waitcnt lgkmcnt(" #n ")" ::: "memory")
; #define PG8_BAR __builtin_amdgcn_s_barrier()
; #define PG8_SCHED __builtin_amdgcn_sched_barrier(0)
; template <class Epi, class Sched, bool ALIGN_EPI = false, bool SP2 = false>
; __device__ __forceinline__ void gemm_phase(PG8_LAS unsigned char* lds, const Gemm g, const Sched& S, const Epi& E, const int wave_s) {
;     ...
;             PG8_WAIT_V(8); PG8_WAIT_L(0); PG8_BAR; PG8_MMA(0, 0, At, B0); PG8_MMA(0, 1, At, B1); PG8_BAR; PG8_SCHED;
;             PG8_LDA(At, 1, 1); PG8_STAGE(PG8_SB(1, 0), b3, voffB); PG8_STAGE(PG8_SB(1, 1), b3 + hstep, voffB); PG8_STAGE(PG8_SA(1, 0), a3, voffA);
;             PG8_WAIT_V(8); PG8_WAIT_L(0); PG8_BAR; PG8_MMA(1, 0, At, B0); PG8_MMA(1, 1, At, B1); PG8_BAR; PG8_SCHED;
;     ...
;         if constexpr (ALIGN_EPI) { if (wr == 0) PG8_BAR; }
	s_setprio 1
	s_waitcnt lgkmcnt(0)
	v_mfma_f32_16x16x32_bf16 v[124:127], v[128:131], v[160:163], v[124:127]
	v_mfma_f32_16x16x32_bf16 v[120:123], v[136:139], v[160:163], v[120:123]
	v_mfma_f32_16x16x32_bf16 v[116:119], v[128:131], v[168:171], v[116:119]
	v_mfma_f32_16x16x32_bf16 v[108:111], v[136:139], v[168:171], v[108:111]
	v_mfma_f32_16x16x32_bf16 v[100:103], v[128:131], v[192:195], v[100:103]
	v_mfma_f32_16x16x32_bf16 v[92:95], v[136:139], v[192:195], v[92:95]
	v_mfma_f32_16x16x32_bf16 v[84:87], v[128:131], v[208:211], v[84:87]
	v_mfma_f32_16x16x32_bf16 v[76:79], v[136:139], v[208:211], v[76:79]
	v_mfma_f32_16x16x32_bf16 v[124:127], v[132:135], v[164:167], v[124:127]
	v_mfma_f32_16x16x32_bf16 v[120:123], v[140:143], v[164:167], v[120:123]
	v_mfma_f32_16x16x32_bf16 v[116:119], v[132:135], v[172:175], v[116:119]
	v_mfma_f32_16x16x32_bf16 v[108:111], v[140:143], v[172:175], v[108:111]
	v_mfma_f32_16x16x32_bf16 v[100:103], v[132:135], v[196:199], v[100:103]
	v_mfma_f32_16x16x32_bf16 v[92:95], v[140:143], v[196:199], v[92:95]
	v_mfma_f32_16x16x32_bf16 v[84:87], v[132:135], v[214:217], v[84:87]
	v_mfma_f32_16x16x32_bf16 v[76:79], v[140:143], v[214:217], v[76:79]
	s_setprio 0
	s_setprio 1
	v_mfma_f32_16x16x32_bf16 v[112:115], v[144:147], v[160:163], v[112:115]
	v_mfma_f32_16x16x32_bf16 v[104:107], v[152:155], v[160:163], v[104:107]
	v_mfma_f32_16x16x32_bf16 v[96:99], v[144:147], v[168:171], v[96:99]
	v_mfma_f32_16x16x32_bf16 v[88:91], v[152:155], v[168:171], v[88:91]
	v_mfma_f32_16x16x32_bf16 v[80:83], v[144:147], v[192:195], v[80:83]
	v_mfma_f32_16x16x32_bf16 v[72:75], v[152:155], v[192:195], v[72:75]
	v_mfma_f32_16x16x32_bf16 v[68:71], v[144:147], v[208:211], v[68:71]
	v_mfma_f32_16x16x32_bf16 v[64:67], v[152:155], v[208:211], v[64:67]
	v_mfma_f32_16x16x32_bf16 v[112:115], v[148:151], v[164:167], v[112:115]
	v_mfma_f32_16x16x32_bf16 v[104:107], v[156:159], v[164:167], v[104:107]
	v_mfma_f32_16x16x32_bf16 v[96:99], v[148:151], v[172:175], v[96:99]
	v_mfma_f32_16x16x32_bf16 v[88:91], v[156:159], v[172:175], v[88:91]
	v_mfma_f32_16x16x32_bf16 v[80:83], v[148:151], v[196:199], v[80:83]
	v_mfma_f32_16x16x32_bf16 v[72:75], v[156:159], v[196:199], v[72:75]
	v_mfma_f32_16x16x32_bf16 v[68:71], v[148:151], v[214:217], v[68:71]
	v_mfma_f32_16x16x32_bf16 v[64:67], v[156:159], v[214:217], v[64:67]
	s_setprio 0
	s_barrier
	s_add_i32 s16, s69, s33
	s_mov_b32 m0, s16
	ds_read_b128 v[160:163], v207 offset:49152
	ds_read_b128 v[164:167], v207 offset:50176
	ds_read_b128 v[168:171], v207 offset:51200
	ds_read_b128 v[172:175], v207 offset:52224
	ds_read_b128 v[192:195], v207 offset:53248
	ds_read_b128 v[196:199], v207 offset:54272
	ds_read_b128 v[208:211], v207 offset:55296
	ds_read_b128 v[214:217], v207 offset:56320
	global_load_lds_dwordx4 v[242:243], off
	s_add_i32 m0, s16, 0x2000
	s_add_i32 s16, s70, s33
	global_load_lds_dwordx4 v[244:245], off
	s_mov_b32 m0, s16
	s_nop 0
	global_load_lds_dwordx4 v[246:247], off
	s_add_i32 m0, s16, 0x2000
	s_nop 0
	global_load_lds_dwordx4 v[248:249], off
	s_mov_b32 m0, s49
	s_nop 0
	global_load_lds_dwordx4 v[250:251], off
	s_mov_b32 m0, s50
	s_nop 0
	global_load_lds_dwordx4 v[252:253], off
	s_waitcnt vmcnt(8)
	s_waitcnt lgkmcnt(0)
	s_barrier
	s_setprio 1
	s_waitcnt lgkmcnt(0)
	v_mfma_f32_16x16x32_bf16 v[60:63], v[128:131], v[160:163], v[60:63]
	v_mfma_f32_16x16x32_bf16 v[56:59], v[136:139], v[160:163], v[56:59]
	v_mfma_f32_16x16x32_bf16 v[52:55], v[128:131], v[168:171], v[52:55]
	v_mfma_f32_16x16x32_bf16 v[44:47], v[136:139], v[168:171], v[44:47]
	v_mfma_f32_16x16x32_bf16 v[36:39], v[128:131], v[192:195], v[36:39]
	v_mfma_f32_16x16x32_bf16 v[28:31], v[136:139], v[192:195], v[28:31]
	v_mfma_f32_16x16x32_bf16 v[20:23], v[128:131], v[208:211], v[20:23]
	v_mfma_f32_16x16x32_bf16 v[12:15], v[136:139], v[208:211], v[12:15]
	v_mfma_f32_16x16x32_bf16 v[60:63], v[132:135], v[164:167], v[60:63]
	v_mfma_f32_16x16x32_bf16 v[56:59], v[140:143], v[164:167], v[56:59]
	v_mfma_f32_16x16x32_bf16 v[52:55], v[132:135], v[172:175], v[52:55]
	v_mfma_f32_16x16x32_bf16 v[44:47], v[140:143], v[172:175], v[44:47]
	v_mfma_f32_16x16x32_bf16 v[36:39], v[132:135], v[196:199], v[36:39]
	v_mfma_f32_16x16x32_bf16 v[28:31], v[140:143], v[196:199], v[28:31]
	v_mfma_f32_16x16x32_bf16 v[20:23], v[132:135], v[214:217], v[20:23]
	v_mfma_f32_16x16x32_bf16 v[12:15], v[140:143], v[214:217], v[12:15]
	s_setprio 0
	s_setprio 1
	v_mfma_f32_16x16x32_bf16 v[48:51], v[144:147], v[160:163], v[48:51]
	v_mfma_f32_16x16x32_bf16 v[40:43], v[152:155], v[160:163], v[40:43]
	v_mfma_f32_16x16x32_bf16 v[32:35], v[144:147], v[168:171], v[32:35]
	v_mfma_f32_16x16x32_bf16 v[24:27], v[152:155], v[168:171], v[24:27]
	v_mfma_f32_16x16x32_bf16 v[16:19], v[144:147], v[192:195], v[16:19]
	v_mfma_f32_16x16x32_bf16 v[8:11], v[152:155], v[192:195], v[8:11]
	v_mfma_f32_16x16x32_bf16 v[4:7], v[144:147], v[208:211], v[4:7]
	v_mfma_f32_16x16x32_bf16 v[0:3], v[152:155], v[208:211], v[0:3]
	v_mfma_f32_16x16x32_bf16 v[48:51], v[148:151], v[164:167], v[48:51]
	v_mfma_f32_16x16x32_bf16 v[40:43], v[156:159], v[164:167], v[40:43]
	v_mfma_f32_16x16x32_bf16 v[32:35], v[148:151], v[172:175], v[32:35]
	v_mfma_f32_16x16x32_bf16 v[24:27], v[156:159], v[172:175], v[24:27]
	v_mfma_f32_16x16x32_bf16 v[16:19], v[148:151], v[196:199], v[16:19]
	v_mfma_f32_16x16x32_bf16 v[8:11], v[156:159], v[196:199], v[8:11]
	v_mfma_f32_16x16x32_bf16 v[4:7], v[148:151], v[214:217], v[4:7]
	v_mfma_f32_16x16x32_bf16 v[0:3], v[156:159], v[214:217], v[0:3]
	s_setprio 0
	s_barrier
	s_add_i32 s68, s68, 2
	s_add_u32 s31, s31, 0x100
	s_addc_u32 s67, s67, 0
	s_add_u32 s10, s10, 0x100
	s_addc_u32 s11, s11, 0
	s_cmp_gt_u32 s68, 13
	s_cbranch_scc0 .LBB0_1886
	s_and_b64 vcc, exec, s[26:27]
	s_cbranch_vccz .LBB0_1889
	s_barrier

; #define PG8_STAGE(bufoff, gbase, voff) do { _Pragma("unroll") for (int _i = 0; _i < 2; ++_i) \
;         __builtin_amdgcn_global_load_lds((const unsigned*)((const char*)(gbase) + (voff)[_i]), (PG8_LAS unsigned*)(lds + (bufoff) + ldsw + _i * 8192), 16, 0, 0); } while (0)
; #define PG8_LDA(dst, b, h) do { _Pragma("unroll") for (int m = 0; m < 4; ++m) _Pragma("unroll") for (int k = 0; k < 2; ++k) dst[m][k] = *(const PG8_LAS bf16x8*)(lds + PG8_SA(b, h) + aoff + m * 2048 + k * 1024); } while (0)
; #define PG8_LDB(dst, b, h) do { _Pragma("unroll") for (int n = 0; n < 2; ++n) _Pragma("unroll") for (int k = 0; k < 2; ++k) dst[n][k] = *(const PG8_LAS bf16x8*)(lds + PG8_SB(b, h) + boff + n * 2048 + k * 1024); } while (0)
; #define PG8_MMA(ai, bj, At, Bt) do { __builtin_amdgcn_s_setprio(1); _Pragma("unroll") for (int m = 0; m < 4; ++m) _Pragma("unroll") for (int n = 0; n < 2; ++n) _Pragma("unroll") for (int k = 0; k < 2; ++k) \
;         acc[ai][bj][m][n] = __builtin_amdgcn_mfma_f32_16x16x32_bf16(Bt[n][k], At[m][k], acc[ai][bj][m][n], 0, 0, 0); __builtin_amdgcn_s_setprio(0); } while (0)
; #define PG8_WAIT_V(n) asm volatile("s_waitcnt vmcnt(" #n ")" ::: "memory")
; #define PG8_WAIT_L(n) asm volatile("s_waitcnt lgkmcnt(" #n ")" ::: "memory")
; template <class Epi, class Sched, bool ALIGN_EPI = false, bool SP2 = false>
; __device__ __forceinline__ void gemm_phase(PG8_LAS unsigned char* lds, const Gemm g, const Sched& S, const Epi& E, const int wave_s) {
;     ...
;             const bool last = (t == nt - 2);
;             const char* a1 = cA + (size_t)(t + 1) * kstep;
;             const char* a2 = last ? nA : cA + (size_t)(t + 2) * kstep; const char* b2 = last ? nB : cB + (size_t)(t + 2) * kstep;
;             const char* a3 = a2 + kstep; const char* b3 = b2 + kstep;
;             if (last && has_next) S.a_ready(nxt);
;             if constexpr (SP2) {
;             PG8_LDB(B0, 0, 0); PG8_LDB(B1, 0, 1); PG8_SCHED; PG8_LDA(At, 0, 0); PG8_STAGE(PG8_SA(1, 1), a1 + hstep, voffA);
;             PG8_WAIT_V(8); PG8_WAIT_L(0); PG8_BAR; PG8_MMA(0, 0, At, B0); PG8_MMA(0, 1, At, B1); PG8_BAR; PG8_SCHED;
;             PG8_LDA(At, 0, 1); PG8_STAGE(PG8_SB(0, 0), b2, voffB); PG8_STAGE(PG8_SB(0, 1), b2 + hstep, voffB); PG8_STAGE(PG8_SA(0, 0), a2, voffA);
;             PG8_WAIT_V(8); PG8_WAIT_L(0); PG8_BAR; PG8_MMA(1, 0, At, B0); PG8_MMA(1, 1, At, B1); PG8_BAR; PG8_SCHED;
.LBB0_2021:
	ds_read_b128 v[128:131], v155
	ds_read_b128 v[132:135], v155 offset:1024
	ds_read_b128 v[158:161], v155 offset:2048
	ds_read_b128 v[162:165], v155 offset:3072
	ds_read_b128 v[166:169], v156
	ds_read_b128 v[170:173], v156 offset:1024
	ds_read_b128 v[174:177], v156 offset:2048
	ds_read_b128 v[178:181], v156 offset:3072
	s_add_u32 s18, s16, 0xfffe0080
	s_addc_u32 s19, s17, -1
	s_cmp_eq_u32 s46, 4
	s_cselect_b32 s21, s7, s19
	s_cselect_b32 s20, s42, s18
	s_cselect_b32 s19, s5, s45
	s_cselect_b32 s18, s43, s44
	v_lshl_add_u64 v[152:153], s[16:17], 0, v[146:147]
	s_add_i32 m0, s13, 0xc000
	ds_read_b128 v[182:185], v157
	ds_read_b128 v[186:189], v157 offset:1024
	ds_read_b128 v[190:193], v157 offset:2048
	ds_read_b128 v[194:197], v157 offset:3072
	ds_read_b128 v[198:201], v157 offset:4096
	ds_read_b128 v[202:205], v157 offset:5120
	ds_read_b128 v[206:209], v157 offset:6144
	ds_read_b128 v[210:213], v157 offset:7168
	global_load_lds_dwordx4 v[152:153], off
	v_lshl_add_u64 v[152:153], s[16:17], 0, v[144:145]
	s_add_i32 m0, s13, 0xe000
	s_nop 0
	global_load_lds_dwordx4 v[152:153], off
	v_lshl_add_u64 v[230:231], s[18:19], 0, v[140:141]
	s_add_u32 s48, s18, 0x20000
	v_lshl_add_u64 v[232:233], s[18:19], 0, v[136:137]
	s_addc_u32 s49, s19, 0
	v_lshl_add_u64 v[234:235], s[48:49], 0, v[140:141]
	v_lshl_add_u64 v[236:237], s[20:21], 0, v[138:139]
	v_lshl_add_u64 v[238:239], s[48:49], 0, v[136:137]
	v_lshl_add_u64 v[240:241], s[20:21], 0, v[142:143]
	s_waitcnt vmcnt(8)
	s_waitcnt lgkmcnt(0)
	s_barrier
	s_setprio 1
	s_waitcnt lgkmcnt(0)
	v_mfma_f32_16x16x32_bf16 v[124:127], v[128:131], v[182:185], v[124:127]
	v_mfma_f32_16x16x32_bf16 v[120:123], v[158:161], v[182:185], v[120:123]
	v_mfma_f32_16x16x32_bf16 v[108:111], v[128:131], v[190:193], v[108:111]
	v_mfma_f32_16x16x32_bf16 v[104:107], v[158:161], v[190:193], v[104:107]
	v_mfma_f32_16x16x32_bf16 v[92:95], v[128:131], v[198:201], v[92:95]
	v_mfma_f32_16x16x32_bf16 v[88:91], v[158:161], v[198:201], v[88:91]
	v_mfma_f32_16x16x32_bf16 v[80:83], v[128:131], v[206:209], v[80:83]
	v_mfma_f32_16x16x32_bf16 v[72:75], v[158:161], v[206:209], v[72:75]
	v_mfma_f32_16x16x32_bf16 v[124:127], v[132:135], v[186:189], v[124:127]
	v_mfma_f32_16x16x32_bf16 v[120:123], v[162:165], v[186:189], v[120:123]
	v_mfma_f32_16x16x32_bf16 v[108:111], v[132:135], v[194:197], v[108:111]
	v_mfma_f32_16x16x32_bf16 v[104:107], v[162:165], v[194:197], v[104:107]
	v_mfma_f32_16x16x32_bf16 v[92:95], v[132:135], v[202:205], v[92:95]
	v_mfma_f32_16x16x32_bf16 v[88:91], v[162:165], v[202:205], v[88:91]
	v_mfma_f32_16x16x32_bf16 v[80:83], v[132:135], v[210:213], v[80:83]
	v_mfma_f32_16x16x32_bf16 v[72:75], v[162:165], v[210:213], v[72:75]
	s_setprio 0
	s_setprio 1
	v_mfma_f32_16x16x32_bf16 v[116:119], v[166:169], v[182:185], v[116:119]
	v_mfma_f32_16x16x32_bf16 v[112:115], v[174:177], v[182:185], v[112:115]
	v_mfma_f32_16x16x32_bf16 v[100:103], v[166:169], v[190:193], v[100:103]
	v_mfma_f32_16x16x32_bf16 v[96:99], v[174:177], v[190:193], v[96:99]
	v_mfma_f32_16x16x32_bf16 v[84:87], v[166:169], v[198:201], v[84:87]
	v_mfma_f32_16x16x32_bf16 v[76:79], v[174:177], v[198:201], v[76:79]
	v_mfma_f32_16x16x32_bf16 v[68:71], v[166:169], v[206:209], v[68:71]
	v_mfma_f32_16x16x32_bf16 v[64:67], v[174:177], v[206:209], v[64:67]
	v_mfma_f32_16x16x32_bf16 v[116:119], v[170:173], v[186:189], v[116:119]
	v_mfma_f32_16x16x32_bf16 v[112:115], v[178:181], v[186:189], v[112:115]
	v_mfma_f32_16x16x32_bf16 v[100:103], v[170:173], v[194:197], v[100:103]
	v_mfma_f32_16x16x32_bf16 v[96:99], v[178:181], v[194:197], v[96:99]
	v_mfma_f32_16x16x32_bf16 v[84:87], v[170:173], v[202:205], v[84:87]
	v_mfma_f32_16x16x32_bf16 v[76:79], v[178:181], v[202:205], v[76:79]
	v_mfma_f32_16x16x32_bf16 v[68:71], v[170:173], v[210:213], v[68:71]
	v_mfma_f32_16x16x32_bf16 v[64:67], v[178:181], v[210:213], v[64:67]
	s_setprio 0
	s_barrier
	s_add_i32 s47, s39, s33
	s_mov_b32 m0, s47
	ds_read_b128 v[182:185], v157 offset:16384
	ds_read_b128 v[186:189], v157 offset:17408
	ds_read_b128 v[190:193], v157 offset:18432
	ds_read_b128 v[194:197], v157 offset:19456
	ds_read_b128 v[198:201], v157 offset:20480
	ds_read_b128 v[202:205], v157 offset:21504
	ds_read_b128 v[206:209], v157 offset:22528
	ds_read_b128 v[210:213], v157 offset:23552
	global_load_lds_dwordx4 v[230:231], off
	s_add_i32 m0, s47, 0x2000
	s_add_i32 s47, s40, s33
	global_load_lds_dwordx4 v[232:233], off
	s_mov_b32 m0, s47
	s_nop 0
	global_load_lds_dwordx4 v[234:235], off
	s_add_i32 m0, s47, 0x2000
	s_nop 0
	global_load_lds_dwordx4 v[238:239], off
	s_mov_b32 m0, s13
	s_nop 0
	global_load_lds_dwordx4 v[240:241], off
	s_mov_b32 m0, s28
	s_nop 0
	global_load_lds_dwordx4 v[236:237], off
	s_waitcnt vmcnt(8)
	s_waitcnt lgkmcnt(0)
	s_barrier
; #define PG8_STAGE(bufoff, gbase, voff) do { _Pragma("unroll") for (int _i = 0; _i < 2; ++_i) \
;         __builtin_amdgcn_global_load_lds((const unsigned*)((const char*)(gbase) + (voff)[_i]), (PG8_LAS unsigned*)(lds + (bufoff) + ldsw + _i * 8192), 16, 0, 0); } while (0)
; #define PG8_LDA(dst, b, h) do { _Pragma("unroll") for (int m = 0; m < 4; ++m) _Pragma("unroll") for (int k = 0; k < 2; ++k) dst[m][k] = *(const PG8_LAS bf16x8*)(lds + PG8_SA(b, h) + aoff + m * 2048 + k * 1024); } while (0)
; #define PG8_LDB(dst, b, h) do { _Pragma("unroll") for (int n = 0; n < 2; ++n) _Pragma("unroll") for (int k = 0; k < 2; ++k) dst[n][k] = *(const PG8_LAS bf16x8*)(lds + PG8_SB(b, h) + boff + n * 2048 + k * 1024); } while (0)
; #define PG8_MMA(ai, bj, At, Bt) do { __builtin_amdgcn_s_setprio(1); _Pragma("unroll") for (int m = 0; m < 4; ++m) _Pragma("unroll") for (int n = 0; n < 2; ++n) _Pragma("unroll") for (int k = 0; k < 2; ++k) \
;         acc[ai][bj][m][n] = __builtin_amdgcn_mfma_f32_16x16x32_bf16(Bt[n][k], At[m][k], acc[ai][bj][m][n], 0, 0, 0); __builtin_amdgcn_s_setprio(0); } while (0)
; #define PG8_WAIT_V(n) asm volatile("s_waitcnt vmcnt(" #n ")" ::: "memory")
; #define PG8_WAIT_L(n) asm volatile("s_waitcnt lgkmcnt(" #n ")" ::: "memory")
; #define PG8_BAR __builtin_amdgcn_s_barrier()
; #define PG8_SCHED __builtin_amdgcn_sched_barrier(0)
; template <class Epi, class Sched, bool ALIGN_EPI = false, bool SP2 = false>
; __device__ __forceinline__ void gemm_phase(PG8_LAS unsigned char* lds, const Gemm g, const Sched& S, const Epi& E, const int wave_s) {
;     ...
;             PG8_WAIT_V(8); PG8_WAIT_L(0); PG8_BAR; PG8_MMA(1, 0, At, B0); PG8_MMA(1, 1, At, B1); PG8_BAR; PG8_SCHED;
;             PG8_LDB(B0, 1, 0); PG8_LDB(B1, 1, 1); PG8_SCHED; PG8_LDA(At, 1, 0); PG8_STAGE(PG8_SA(0, 1), a2 + hstep, voffA);
;             PG8_WAIT_V(8); PG8_WAIT_L(0); PG8_BAR; PG8_MMA(0, 0, At, B0); PG8_MMA(0, 1, At, B1); PG8_BAR; PG8_SCHED;
;             PG8_LDA(At, 1, 1); PG8_STAGE(PG8_SB(1, 0), b3, voffB); PG8_STAGE(PG8_SB(1, 1), b3 + hstep, voffB); PG8_STAGE(PG8_SA(1, 0), a3, voffA);
	s_setprio 1
	s_waitcnt lgkmcnt(0)
	v_mfma_f32_16x16x32_bf16 v[60:63], v[128:131], v[182:185], v[60:63]
	v_mfma_f32_16x16x32_bf16 v[56:59], v[158:161], v[182:185], v[56:59]
	v_mfma_f32_16x16x32_bf16 v[48:51], v[128:131], v[190:193], v[48:51]
	v_mfma_f32_16x16x32_bf16 v[40:43], v[158:161], v[190:193], v[40:43]
	v_mfma_f32_16x16x32_bf16 v[32:35], v[128:131], v[198:201], v[32:35]
	v_mfma_f32_16x16x32_bf16 v[24:27], v[158:161], v[198:201], v[24:27]
	v_mfma_f32_16x16x32_bf16 v[16:19], v[128:131], v[206:209], v[16:19]
	v_mfma_f32_16x16x32_bf16 v[8:11], v[158:161], v[206:209], v[8:11]
	v_mfma_f32_16x16x32_bf16 v[60:63], v[132:135], v[186:189], v[60:63]
	v_mfma_f32_16x16x32_bf16 v[56:59], v[162:165], v[186:189], v[56:59]
	v_mfma_f32_16x16x32_bf16 v[48:51], v[132:135], v[194:197], v[48:51]
	v_mfma_f32_16x16x32_bf16 v[40:43], v[162:165], v[194:197], v[40:43]
	v_mfma_f32_16x16x32_bf16 v[32:35], v[132:135], v[202:205], v[32:35]
	v_mfma_f32_16x16x32_bf16 v[24:27], v[162:165], v[202:205], v[24:27]
	v_mfma_f32_16x16x32_bf16 v[16:19], v[132:135], v[210:213], v[16:19]
	v_mfma_f32_16x16x32_bf16 v[8:11], v[162:165], v[210:213], v[8:11]
	s_setprio 0
	s_setprio 1
	v_mfma_f32_16x16x32_bf16 v[52:55], v[166:169], v[182:185], v[52:55]
	v_mfma_f32_16x16x32_bf16 v[44:47], v[174:177], v[182:185], v[44:47]
	v_mfma_f32_16x16x32_bf16 v[36:39], v[166:169], v[190:193], v[36:39]
	v_mfma_f32_16x16x32_bf16 v[28:31], v[174:177], v[190:193], v[28:31]
	v_mfma_f32_16x16x32_bf16 v[20:23], v[166:169], v[198:201], v[20:23]
	v_mfma_f32_16x16x32_bf16 v[12:15], v[174:177], v[198:201], v[12:15]
	v_mfma_f32_16x16x32_bf16 v[4:7], v[166:169], v[206:209], v[4:7]
	v_mfma_f32_16x16x32_bf16 v[0:3], v[174:177], v[206:209], v[0:3]
	v_mfma_f32_16x16x32_bf16 v[52:55], v[170:173], v[186:189], v[52:55]
	v_mfma_f32_16x16x32_bf16 v[44:47], v[178:181], v[186:189], v[44:47]
	v_mfma_f32_16x16x32_bf16 v[36:39], v[170:173], v[194:197], v[36:39]
	v_mfma_f32_16x16x32_bf16 v[28:31], v[178:181], v[194:197], v[28:31]
	v_mfma_f32_16x16x32_bf16 v[20:23], v[170:173], v[202:205], v[20:23]
	v_mfma_f32_16x16x32_bf16 v[12:15], v[178:181], v[202:205], v[12:15]
	v_mfma_f32_16x16x32_bf16 v[4:7], v[170:173], v[210:213], v[4:7]
	v_mfma_f32_16x16x32_bf16 v[0:3], v[178:181], v[210:213], v[0:3]
	s_setprio 0
	s_barrier
	s_add_i32 s47, 0, 0x18000
	s_add_i32 s48, 0, 0x1c000
	v_add_u32_e32 v162, s47, v154
	v_add_u32_e32 v178, s48, v154
	ds_read_b128 v[128:131], v162
	ds_read_b128 v[132:135], v162 offset:1024
	ds_read_b128 v[158:161], v162 offset:2048
	ds_read_b128 v[162:165], v162 offset:3072
	ds_read_b128 v[166:169], v178
	ds_read_b128 v[170:173], v178 offset:1024
	ds_read_b128 v[174:177], v178 offset:2048
	ds_read_b128 v[178:181], v178 offset:3072
	s_add_u32 s20, s20, 0x20000
	s_addc_u32 s21, s21, 0
	s_mov_b32 m0, s29
	v_lshl_add_u64 v[220:221], s[20:21], 0, v[142:143]
	ds_read_b128 v[182:185], v157 offset:32768
	ds_read_b128 v[186:189], v157 offset:33792
	ds_read_b128 v[190:193], v157 offset:34816
	ds_read_b128 v[194:197], v157 offset:35840
	ds_read_b128 v[198:201], v157 offset:36864
	ds_read_b128 v[202:205], v157 offset:37888
	ds_read_b128 v[206:209], v157 offset:38912
	ds_read_b128 v[210:213], v157 offset:39936
	global_load_lds_dwordx4 v[220:221], off
	v_lshl_add_u64 v[220:221], s[20:21], 0, v[138:139]
	s_mov_b32 m0, s30
	s_nop 0
	global_load_lds_dwordx4 v[220:221], off
	v_lshl_add_u64 v[242:243], v[230:231], 0, s[2:3]
	s_add_u32 s18, s18, 0x20080
	v_lshl_add_u64 v[244:245], v[232:233], 0, s[2:3]
	s_addc_u32 s19, s19, 0
	v_lshl_add_u64 v[246:247], s[18:19], 0, v[140:141]
	v_lshl_add_u64 v[248:249], s[18:19], 0, v[136:137]
	v_lshl_add_u64 v[250:251], v[240:241], 0, s[2:3]
	v_lshl_add_u64 v[252:253], v[236:237], 0, s[2:3]
	s_waitcnt vmcnt(8)
	s_waitcnt lgkmcnt(0)
	s_barrier
	s_setprio 1
	s_waitcnt lgkmcnt(0)
	v_mfma_f32_16x16x32_bf16 v[124:127], v[128:131], v[182:185], v[124:127]
	v_mfma_f32_16x16x32_bf16 v[120:123], v[158:161], v[182:185], v[120:123]
	v_mfma_f32_16x16x32_bf16 v[108:111], v[128:131], v[190:193], v[108:111]
	v_mfma_f32_16x16x32_bf16 v[104:107], v[158:161], v[190:193], v[104:107]
	v_mfma_f32_16x16x32_bf16 v[92:95], v[128:131], v[198:201], v[92:95]
	v_mfma_f32_16x16x32_bf16 v[88:91], v[158:161], v[198:201], v[88:91]
	v_mfma_f32_16x16x32_bf16 v[80:83], v[128:131], v[206:209], v[80:83]
	v_mfma_f32_16x16x32_bf16 v[72:75], v[158:161], v[206:209], v[72:75]
	v_mfma_f32_16x16x32_bf16 v[124:127], v[132:135], v[186:189], v[124:127]
	v_mfma_f32_16x16x32_bf16 v[120:123], v[162:165], v[186:189], v[120:123]
	v_mfma_f32_16x16x32_bf16 v[108:111], v[132:135], v[194:197], v[108:111]
	v_mfma_f32_16x16x32_bf16 v[104:107], v[162:165], v[194:197], v[104:107]
	v_mfma_f32_16x16x32_bf16 v[92:95], v[132:135], v[202:205], v[92:95]
	v_mfma_f32_16x16x32_bf16 v[88:91], v[162:165], v[202:205], v[88:91]
	v_mfma_f32_16x16x32_bf16 v[80:83], v[132:135], v[210:213], v[80:83]
	v_mfma_f32_16x16x32_bf16 v[72:75], v[162:165], v[210:213], v[72:75]
	s_setprio 0
	s_setprio 1
	v_mfma_f32_16x16x32_bf16 v[116:119], v[166:169], v[182:185], v[116:119]
	v_mfma_f32_16x16x32_bf16 v[112:115], v[174:177], v[182:185], v[112:115]
	v_mfma_f32_16x16x32_bf16 v[100:103], v[166:169], v[190:193], v[100:103]
	v_mfma_f32_16x16x32_bf16 v[96:99], v[174:177], v[190:193], v[96:99]
	v_mfma_f32_16x16x32_bf16 v[84:87], v[166:169], v[198:201], v[84:87]
	v_mfma_f32_16x16x32_bf16 v[76:79], v[174:177], v[198:201], v[76:79]
	v_mfma_f32_16x16x32_bf16 v[68:71], v[166:169], v[206:209], v[68:71]
	v_mfma_f32_16x16x32_bf16 v[64:67], v[174:177], v[206:209], v[64:67]
	v_mfma_f32_16x16x32_bf16 v[116:119], v[170:173], v[186:189], v[116:119]
	v_mfma_f32_16x16x32_bf16 v[112:115], v[178:181], v[186:189], v[112:115]
	v_mfma_f32_16x16x32_bf16 v[100:103], v[170:173], v[194:197], v[100:103]
	v_mfma_f32_16x16x32_bf16 v[96:99], v[178:181], v[194:197], v[96:99]
	v_mfma_f32_16x16x32_bf16 v[84:87], v[170:173], v[202:205], v[84:87]
	v_mfma_f32_16x16x32_bf16 v[76:79], v[178:181], v[202:205], v[76:79]
	v_mfma_f32_16x16x32_bf16 v[68:71], v[170:173], v[210:213], v[68:71]
	v_mfma_f32_16x16x32_bf16 v[64:67], v[178:181], v[210:213], v[64:67]
	s_setprio 0
	s_barrier
; #define PG8_STAGE(bufoff, gbase, voff) do { _Pragma("unroll") for (int _i = 0; _i < 2; ++_i) \
;         __builtin_amdgcn_global_load_lds((const unsigned*)((const char*)(gbase) + (voff)[_i]), (PG8_LAS unsigned*)(lds + (bufoff) + ldsw + _i * 8192), 16, 0, 0); } while (0)
; #define PG8_LDA(dst, b, h) do { _Pragma("unroll") for (int m = 0; m < 4; ++m) _Pragma("unroll") for (int k = 0; k < 2; ++k) dst[m][k] = *(const PG8_LAS bf16x8*)(lds + PG8_SA(b, h) + aoff + m * 2048 + k * 1024); } while (0)
; #define PG8_MMA(ai, bj, At, Bt) do { __builtin_amdgcn_s_setprio(1); _Pragma("unroll") for (int m = 0; m < 4; ++m) _Pragma("unroll") for (int n = 0; n < 2; ++n) _Pragma("unroll") for (int k = 0; k < 2; ++k) \
;         acc[ai][bj][m][n] = __builtin_amdgcn_mfma_f32_16x16x32_bf16(Bt[n][k], At[m][k], acc[ai][bj][m][n], 0, 0, 0); __builtin_amdgcn_s_setprio(0); } while (0)
; #define PG8_WAIT_V(n) asm volatile("s_waitcnt vmcnt(" #n ")" ::: "memory")
; #define PG8_WAIT_L(n) asm volatile("s_waitcnt lgkmcnt(" #n ")" ::: "memory")
; #define PG8_BAR __builtin_amdgcn_s_barrier()
; #define PG8_SCHED __builtin_amdgcn_sched_barrier(0)
; __device__ __forceinline__ int lane_id_v() { int l; asm volatile("v_mbcnt_lo_u32_b32 %0, -1, 0\n\tv_mbcnt_hi_u32_b32 %0, -1, %0" : "=v"(l)); return l; }
; template <class Epi, class Sched, bool ALIGN_EPI = false, bool SP2 = false>
; __device__ __forceinline__ void gemm_phase(PG8_LAS unsigned char* lds, const Gemm g, const Sched& S, const Epi& E, const int wave_s) {
;     ...
;             PG8_LDA(At, 1, 1); PG8_STAGE(PG8_SB(1, 0), b3, voffB); PG8_STAGE(PG8_SB(1, 1), b3 + hstep, voffB); PG8_STAGE(PG8_SA(1, 0), a3, voffA);
;             PG8_WAIT_V(8); PG8_WAIT_L(0); PG8_BAR; PG8_MMA(1, 0, At, B0); PG8_MMA(1, 1, At, B1); PG8_BAR; PG8_SCHED;
;     __device__ __forceinline__ void operator()(const af4 (&acc)[2][2][4][2], const pg8::Unit& u, int wr, int wc, int fr_, int fq_) const {
;         const int ln_ = lane_id_v(); const int fr = ln_ & 15, fq = ln_ >> 4;
;         const int row0 = u.pm * 256 + wr * 64 + fr, col0 = u.pn * 256 + wc * 32 + 8 * fq;
;         v4u o[2][2][2];
;     ...
;         MUL_LOAD(0, 0);
; #pragma unroll
;         for (int b_ = 0; b_ < 4; ++b_) {
;             const int ai = b_ >> 1, mp = b_ & 1, cur = b_ & 1;
;             if (b_ + 1 < 4) { if (cur == 0) MUL_LOAD(1, b_ + 1); else MUL_LOAD(0, b_ + 1); }
	s_add_i32 s20, s47, s33
	s_mov_b32 m0, s20
	ds_read_b128 v[182:185], v157 offset:49152
	ds_read_b128 v[186:189], v157 offset:50176
	ds_read_b128 v[190:193], v157 offset:51200
	ds_read_b128 v[194:197], v157 offset:52224
	ds_read_b128 v[198:201], v157 offset:53248
	ds_read_b128 v[202:205], v157 offset:54272
	ds_read_b128 v[206:209], v157 offset:55296
	ds_read_b128 v[210:213], v157 offset:56320
	global_load_lds_dwordx4 v[242:243], off
	s_add_i32 m0, s20, 0x2000
	s_add_i32 s20, s48, s33
	global_load_lds_dwordx4 v[244:245], off
	s_mov_b32 m0, s20
	s_nop 0
	global_load_lds_dwordx4 v[246:247], off
	s_add_i32 m0, s20, 0x2000
	s_nop 0
	global_load_lds_dwordx4 v[248:249], off
	s_mov_b32 m0, s34
	s_nop 0
	global_load_lds_dwordx4 v[250:251], off
	s_mov_b32 m0, s35
	s_nop 0
	global_load_lds_dwordx4 v[252:253], off
	s_waitcnt vmcnt(8)
	s_waitcnt lgkmcnt(0)
	s_barrier
	s_setprio 1
	s_waitcnt lgkmcnt(0)
	v_mfma_f32_16x16x32_bf16 v[60:63], v[128:131], v[182:185], v[60:63]
	v_mfma_f32_16x16x32_bf16 v[56:59], v[158:161], v[182:185], v[56:59]
	v_mfma_f32_16x16x32_bf16 v[48:51], v[128:131], v[190:193], v[48:51]
	v_mfma_f32_16x16x32_bf16 v[40:43], v[158:161], v[190:193], v[40:43]
	v_mfma_f32_16x16x32_bf16 v[32:35], v[128:131], v[198:201], v[32:35]
	v_mfma_f32_16x16x32_bf16 v[24:27], v[158:161], v[198:201], v[24:27]
	v_mfma_f32_16x16x32_bf16 v[16:19], v[128:131], v[206:209], v[16:19]
	v_mfma_f32_16x16x32_bf16 v[8:11], v[158:161], v[206:209], v[8:11]
	v_mfma_f32_16x16x32_bf16 v[60:63], v[132:135], v[186:189], v[60:63]
	v_mfma_f32_16x16x32_bf16 v[56:59], v[162:165], v[186:189], v[56:59]
	v_mfma_f32_16x16x32_bf16 v[48:51], v[132:135], v[194:197], v[48:51]
	v_mfma_f32_16x16x32_bf16 v[40:43], v[162:165], v[194:197], v[40:43]
	v_mfma_f32_16x16x32_bf16 v[32:35], v[132:135], v[202:205], v[32:35]
	v_mfma_f32_16x16x32_bf16 v[24:27], v[162:165], v[202:205], v[24:27]
	v_mfma_f32_16x16x32_bf16 v[16:19], v[132:135], v[210:213], v[16:19]
	v_mfma_f32_16x16x32_bf16 v[8:11], v[162:165], v[210:213], v[8:11]
	s_setprio 0
	s_setprio 1
	v_mfma_f32_16x16x32_bf16 v[52:55], v[166:169], v[182:185], v[52:55]
	v_mfma_f32_16x16x32_bf16 v[44:47], v[174:177], v[182:185], v[44:47]
	v_mfma_f32_16x16x32_bf16 v[36:39], v[166:169], v[190:193], v[36:39]
	v_mfma_f32_16x16x32_bf16 v[28:31], v[174:177], v[190:193], v[28:31]
	v_mfma_f32_16x16x32_bf16 v[20:23], v[166:169], v[198:201], v[20:23]
	v_mfma_f32_16x16x32_bf16 v[12:15], v[174:177], v[198:201], v[12:15]
	v_mfma_f32_16x16x32_bf16 v[4:7], v[166:169], v[206:209], v[4:7]
	v_mfma_f32_16x16x32_bf16 v[0:3], v[174:177], v[206:209], v[0:3]
	v_mfma_f32_16x16x32_bf16 v[52:55], v[170:173], v[186:189], v[52:55]
	v_mfma_f32_16x16x32_bf16 v[44:47], v[178:181], v[186:189], v[44:47]
	v_mfma_f32_16x16x32_bf16 v[36:39], v[170:173], v[194:197], v[36:39]
	v_mfma_f32_16x16x32_bf16 v[28:31], v[178:181], v[194:197], v[28:31]
	v_mfma_f32_16x16x32_bf16 v[20:23], v[170:173], v[202:205], v[20:23]
	v_mfma_f32_16x16x32_bf16 v[12:15], v[178:181], v[202:205], v[12:15]
	v_mfma_f32_16x16x32_bf16 v[4:7], v[170:173], v[210:213], v[4:7]
	v_mfma_f32_16x16x32_bf16 v[0:3], v[178:181], v[210:213], v[0:3]
	s_setprio 0
	s_barrier
	s_add_i32 s46, s46, 2
	s_add_u32 s44, s44, 0x100
	s_addc_u32 s45, s45, 0
	s_add_u32 s16, s16, 0x100
	s_addc_u32 s17, s17, 0
	s_cmp_gt_u32 s46, 5
	s_cbranch_scc0 .LBB0_2021
	s_lshl_b32 s5, s12, 8
	v_mbcnt_lo_u32_b32 v128, -1, 0
	v_mbcnt_hi_u32_b32 v128, -1, v128
	s_add_i32 s5, s5, s87
	v_and_or_b32 v194, v128, 15, s5
	s_lshl_b32 s5, s41, 8
	v_ashrrev_i32_e32 v128, 1, v128
	s_or_b32 s5, s5, s79
	v_and_b32_e32 v128, -8, v128
	v_mov_b32_e32 v130, v194
	v_add_u32_e32 v128, s5, v128
	v_ashrrev_i32_e32 v129, 31, v128
	v_ashrrev_i32_e32 v131, 31, v130
	v_lshlrev_b64 v[130:131], 11, v[130:131]
	v_lshl_add_u64 v[130:131], s[0:1], 0, v[130:131]
	v_lshlrev_b64 v[152:153], 1, v[128:129]
	v_lshl_add_u64 v[128:129], v[130:131], 0, v[152:153]
	global_load_dwordx4 v[158:161], v[128:129], off
	global_load_dwordx4 v[162:165], v[128:129], off offset:256
	v_add_co_u32_e32 v128, vcc, s36, v128
	v_or_b32_e32 v182, 32, v194
	s_nop 0
	v_addc_co_u32_e32 v129, vcc, 0, v129, vcc
	global_load_dwordx4 v[166:169], v[128:129], off
	global_load_dwordx4 v[170:173], v[128:129], off offset:256
	v_mov_b32_e32 v128, v182
	v_mov_b32_e32 v184, v194
	v_ashrrev_i32_e32 v129, 31, v128
	v_lshlrev_b64 v[128:129], 11, v[128:129]
	v_lshl_add_u64 v[128:129], s[0:1], 0, v[128:129]
	v_lshl_add_u64 v[128:129], v[128:129], 0, v[152:153]
	global_load_dwordx4 v[174:177], v[128:129], off
	global_load_dwordx4 v[178:181], v[128:129], off offset:256
	v_add_co_u32_e32 v128, vcc, s36, v128
	s_mov_b32 s41, s4
	s_nop 0
	v_addc_co_u32_e32 v129, vcc, 0, v129, vcc
	global_load_dwordx4 v[132:135], v[128:129], off
	s_nop 0
	global_load_dwordx4 v[128:131], v[128:129], off offset:256
	s_mov_b32 s12, s6
	v_ashrrev_i32_e32 v185, 31, v184
	v_lshlrev_b64 v[184:185], 11, v[184:185]
	v_lshl_add_u64 v[184:185], s[0:1], 0, v[184:185]
	v_lshl_add_u64 v[184:185], v[184:185], 0, v[152:153]
	s_mov_b64 s[16:17], s[10:11]
	s_mov_b64 s[18:19], s[8:9]
	s_waitcnt vmcnt(0)
; __device__ __forceinline__ unsigned cvtpk(float lo, float hi) { f32x2 v = {lo, hi}; bf16x2_t b = __builtin_convertvector(v, bf16x2_t); return __builtin_bit_cast(unsigned, b); }
; __device__ __forceinline__ float bflo(unsigned u) { return __uint_as_float(u << 16); }
; __device__ __forceinline__ float bfhi(unsigned u) { return __uint_as_float(u & 0xffff0000u); }
; #define MUL_LOAD(buf, b_) do { int RRl = row0 + ((b_) >> 1) * 128 + ((b_) & 1) * 32; asm volatile("" : "+v"(RRl)); const bf16* pl = G + (size_t)RRl * 1024 + col0; \
;             _Pragma("unroll") for (int mi = 0; mi < 2; ++mi) _Pragma("unroll") for (int bj = 0; bj < 2; ++bj) o[buf][mi][bj] = *(const v4u*)(pl + mi * 16 * 1024 + bj * 128); } while (0)
;     __device__ __forceinline__ void operator()(const af4 (&acc)[2][2][4][2], const pg8::Unit& u, int wr, int wc, int fr_, int fq_) const {
;     ...
;         MUL_LOAD(0, 0);
; #pragma unroll
;         for (int b_ = 0; b_ < 4; ++b_) {
;             const int ai = b_ >> 1, mp = b_ & 1, cur = b_ & 1;
;             if (b_ + 1 < 4) { if (cur == 0) MUL_LOAD(1, b_ + 1); else MUL_LOAD(0, b_ + 1); }
;             int RRb = row0 + ai * 128 + mp * 32; asm volatile("" : "+v"(RRb));
;             bf16* pb = G + (size_t)RRb * 1024 + col0;
; #pragma unroll
;             for (int mi = 0; mi < 2; ++mi)
; #pragma unroll
;                 for (int bj = 0; bj < 2; ++bj) { const af4 v0 = acc[ai][bj][mp * 2 + mi][0], v1 = acc[ai][bj][mp * 2 + mi][1]; const v4u oo = o[cur][mi][bj];
;                     v4u w; w.x = cvtpk(v0[0] * bflo(oo.x), v0[1] * bfhi(oo.x)); w.y = cvtpk(v0[2] * bflo(oo.y), v0[3] * bfhi(oo.y)); w.z = cvtpk(v1[0] * bflo(oo.z), v1[1] * bfhi(oo.z)); w.w = cvtpk(v1[2] * bflo(oo.w), v1[3] * bfhi(oo.w));
;                     *(v4u*)(pb + mi * 16 * 1024 + bj * 128) = w; }
;             asm volatile("" ::: "memory");
;         }
	v_lshlrev_b32_e32 v188, 16, v160
	v_and_b32_e32 v189, 0xffff0000, v160
	v_lshlrev_b32_e32 v160, 16, v161
	v_and_b32_e32 v161, 0xffff0000, v161
	v_lshlrev_b32_e32 v190, 16, v162
	v_and_b32_e32 v191, 0xffff0000, v162
	v_lshlrev_b32_e32 v162, 16, v163
	v_and_b32_e32 v163, 0xffff0000, v163
	v_lshlrev_b32_e32 v192, 16, v164
	v_and_b32_e32 v193, 0xffff0000, v164
	v_lshlrev_b32_e32 v164, 16, v165
	v_and_b32_e32 v165, 0xffff0000, v165
	v_pk_mul_f32 v[122:123], v[122:123], v[160:161]
	v_pk_mul_f32 v[118:119], v[118:119], v[162:163]
	v_pk_mul_f32 v[160:161], v[114:115], v[164:165]
	v_lshlrev_b32_e32 v162, 16, v166
	v_and_b32_e32 v163, 0xffff0000, v166
	v_lshlrev_b32_e32 v164, 16, v167
	v_and_b32_e32 v165, 0xffff0000, v167
	v_lshlrev_b32_e32 v166, 16, v168
	v_and_b32_e32 v167, 0xffff0000, v168
	v_lshlrev_b32_e32 v168, 16, v169
	v_pk_mul_f32 v[108:109], v[108:109], v[162:163]
	v_pk_mul_f32 v[110:111], v[110:111], v[164:165]
	v_pk_mul_f32 v[104:105], v[104:105], v[166:167]
	v_and_b32_e32 v169, 0xffff0000, v169
	v_cvt_pk_bf16_f32 v108, v108, v109
	v_cvt_pk_bf16_f32 v109, v110, v111
	v_cvt_pk_bf16_f32 v110, v104, v105
	v_pk_mul_f32 v[104:105], v[106:107], v[168:169]
	v_lshlrev_b32_e32 v106, 16, v170
	v_and_b32_e32 v107, 0xffff0000, v170
	v_pk_mul_f32 v[100:101], v[100:101], v[106:107]
	v_lshlrev_b32_e32 v106, 16, v171
	v_and_b32_e32 v107, 0xffff0000, v171
	v_pk_mul_f32 v[102:103], v[102:103], v[106:107]
	v_cvt_pk_bf16_f32 v100, v100, v101
	v_cvt_pk_bf16_f32 v101, v102, v103
	v_lshlrev_b32_e32 v102, 16, v172
	v_and_b32_e32 v103, 0xffff0000, v172
	v_lshlrev_b32_e32 v186, 16, v158
	v_and_b32_e32 v187, 0xffff0000, v158
	v_lshlrev_b32_e32 v158, 16, v159
	v_and_b32_e32 v159, 0xffff0000, v159
	v_pk_mul_f32 v[96:97], v[96:97], v[102:103]
	v_pk_mul_f32 v[124:125], v[124:125], v[186:187]
	v_pk_mul_f32 v[126:127], v[126:127], v[158:159]
	v_pk_mul_f32 v[120:121], v[120:121], v[188:189]
	v_cvt_pk_bf16_f32 v102, v96, v97
	v_lshlrev_b32_e32 v96, 16, v173
	v_and_b32_e32 v97, 0xffff0000, v173
	v_pk_mul_f32 v[116:117], v[116:117], v[190:191]
	v_pk_mul_f32 v[158:159], v[112:113], v[192:193]
	v_cvt_pk_bf16_f32 v112, v124, v125
	v_cvt_pk_bf16_f32 v113, v126, v127
	v_cvt_pk_bf16_f32 v114, v120, v121
	v_cvt_pk_bf16_f32 v115, v122, v123
	v_cvt_pk_bf16_f32 v111, v104, v105
	v_add_co_u32_e32 v104, vcc, s36, v184
	v_pk_mul_f32 v[96:97], v[98:99], v[96:97]
	v_cvt_pk_bf16_f32 v116, v116, v117
	v_cvt_pk_bf16_f32 v117, v118, v119
	v_cvt_pk_bf16_f32 v118, v158, v159
	v_cvt_pk_bf16_f32 v119, v160, v161
	global_store_dwordx4 v[184:185], v[112:115], off
	global_store_dwordx4 v[184:185], v[116:119], off offset:256
	v_addc_co_u32_e32 v105, vcc, 0, v185, vcc
	v_cvt_pk_bf16_f32 v103, v96, v97
	v_add_u32_e32 v112, 0x80, v194
	global_store_dwordx4 v[104:105], v[108:111], off
	global_store_dwordx4 v[104:105], v[100:103], off offset:256
	v_mov_b32_e32 v96, v112
	v_lshlrev_b32_e32 v116, 16, v174
	v_ashrrev_i32_e32 v97, 31, v96
	v_lshlrev_b64 v[96:97], 11, v[96:97]
	v_lshl_add_u64 v[96:97], s[0:1], 0, v[96:97]
	v_lshl_add_u64 v[96:97], v[96:97], 0, v[152:153]
	v_and_b32_e32 v117, 0xffff0000, v174
	global_load_dwordx4 v[104:107], v[96:97], off
	global_load_dwordx4 v[108:111], v[96:97], off offset:256
	v_pk_mul_f32 v[92:93], v[92:93], v[116:117]
	v_lshlrev_b32_e32 v116, 16, v175
	v_and_b32_e32 v117, 0xffff0000, v175
	v_pk_mul_f32 v[94:95], v[94:95], v[116:117]
	v_cvt_pk_bf16_f32 v92, v92, v93
	v_cvt_pk_bf16_f32 v93, v94, v95
	v_lshlrev_b32_e32 v94, 16, v176
	v_and_b32_e32 v95, 0xffff0000, v176
	v_pk_mul_f32 v[88:89], v[88:89], v[94:95]
	v_add_co_u32_e32 v96, vcc, s36, v96
	v_cvt_pk_bf16_f32 v94, v88, v89
	v_lshlrev_b32_e32 v88, 16, v177
	v_and_b32_e32 v89, 0xffff0000, v177
	v_pk_mul_f32 v[88:89], v[90:91], v[88:89]
	v_addc_co_u32_e32 v97, vcc, 0, v97, vcc
	v_cvt_pk_bf16_f32 v95, v88, v89
	v_lshlrev_b32_e32 v88, 16, v178
	v_and_b32_e32 v89, 0xffff0000, v178
	v_pk_mul_f32 v[84:85], v[84:85], v[88:89]
	v_lshlrev_b32_e32 v88, 16, v179
	v_and_b32_e32 v89, 0xffff0000, v179
	v_pk_mul_f32 v[86:87], v[86:87], v[88:89]
	v_cvt_pk_bf16_f32 v84, v84, v85
	v_cvt_pk_bf16_f32 v85, v86, v87
	v_lshlrev_b32_e32 v86, 16, v180
	v_and_b32_e32 v87, 0xffff0000, v180
	v_pk_mul_f32 v[76:77], v[76:77], v[86:87]
	global_load_dwordx4 v[100:103], v[96:97], off
	s_nop 0
	global_load_dwordx4 v[96:99], v[96:97], off offset:256
	v_cvt_pk_bf16_f32 v86, v76, v77
	v_lshlrev_b32_e32 v76, 16, v181
	v_and_b32_e32 v77, 0xffff0000, v181
	v_pk_mul_f32 v[76:77], v[78:79], v[76:77]
	v_lshlrev_b32_e32 v78, 16, v133
	v_cvt_pk_bf16_f32 v87, v76, v77
	v_lshlrev_b32_e32 v76, 16, v132
	v_and_b32_e32 v77, 0xffff0000, v132
	v_and_b32_e32 v79, 0xffff0000, v133
	v_pk_mul_f32 v[76:77], v[80:81], v[76:77]
	v_pk_mul_f32 v[78:79], v[82:83], v[78:79]
	v_cvt_pk_bf16_f32 v76, v76, v77
	v_cvt_pk_bf16_f32 v77, v78, v79
	v_lshlrev_b32_e32 v78, 16, v134
	v_and_b32_e32 v79, 0xffff0000, v134
	v_pk_mul_f32 v[72:73], v[72:73], v[78:79]
	v_add_u32_e32 v80, 0xa0, v194
	v_cvt_pk_bf16_f32 v78, v72, v73
	v_lshlrev_b32_e32 v72, 16, v135
	v_and_b32_e32 v73, 0xffff0000, v135
	v_pk_mul_f32 v[72:73], v[74:75], v[72:73]
	v_lshlrev_b32_e32 v74, 16, v128
	v_and_b32_e32 v75, 0xffff0000, v128
	v_pk_mul_f32 v[68:69], v[68:69], v[74:75]
	v_lshlrev_b32_e32 v74, 16, v129
	v_and_b32_e32 v75, 0xffff0000, v129
	v_ashrrev_i32_e32 v183, 31, v182
	v_pk_mul_f32 v[70:71], v[70:71], v[74:75]
	v_lshlrev_b64 v[114:115], 11, v[182:183]
	v_cvt_pk_bf16_f32 v68, v68, v69
	v_cvt_pk_bf16_f32 v69, v70, v71
	v_lshlrev_b32_e32 v70, 16, v130
	v_and_b32_e32 v71, 0xffff0000, v130
	v_lshl_add_u64 v[114:115], s[0:1], 0, v[114:115]
	v_pk_mul_f32 v[64:65], v[64:65], v[70:71]
	v_lshl_add_u64 v[114:115], v[114:115], 0, v[152:153]
	v_cvt_pk_bf16_f32 v70, v64, v65
	v_lshlrev_b32_e32 v64, 16, v131
	v_and_b32_e32 v65, 0xffff0000, v131
	v_cvt_pk_bf16_f32 v79, v72, v73
	v_add_co_u32_e32 v72, vcc, s36, v114
	v_pk_mul_f32 v[64:65], v[66:67], v[64:65]
	s_nop 0
	v_addc_co_u32_e32 v73, vcc, 0, v115, vcc
	v_cvt_pk_bf16_f32 v71, v64, v65
	global_store_dwordx4 v[114:115], v[92:95], off
	global_store_dwordx4 v[114:115], v[84:87], off offset:256
	global_store_dwordx4 v[72:73], v[76:79], off
	global_store_dwordx4 v[72:73], v[68:71], off offset:256
	v_mov_b32_e32 v64, v80
	s_waitcnt vmcnt(7)
; #define PG8_WAIT_V(n) asm volatile("s_waitcnt vmcnt(" #n ")" ::: "memory")
; #define PG8_BAR __builtin_amdgcn_s_barrier()
; __device__ __forceinline__ unsigned cvtpk(float lo, float hi) { f32x2 v = {lo, hi}; bf16x2_t b = __builtin_convertvector(v, bf16x2_t); return __builtin_bit_cast(unsigned, b); }
; __device__ __forceinline__ float bflo(unsigned u) { return __uint_as_float(u << 16); }
; __device__ __forceinline__ float bfhi(unsigned u) { return __uint_as_float(u & 0xffff0000u); }
; #define MUL_LOAD(buf, b_) do { int RRl = row0 + ((b_) >> 1) * 128 + ((b_) & 1) * 32; asm volatile("" : "+v"(RRl)); const bf16* pl = G + (size_t)RRl * 1024 + col0; \
;             _Pragma("unroll") for (int mi = 0; mi < 2; ++mi) _Pragma("unroll") for (int bj = 0; bj < 2; ++bj) o[buf][mi][bj] = *(const v4u*)(pl + mi * 16 * 1024 + bj * 128); } while (0)
; template <class Epi, class Sched, bool ALIGN_EPI = false, bool SP2 = false>
; __device__ __forceinline__ void gemm_phase(PG8_LAS unsigned char* lds, const Gemm g, const Sched& S, const Epi& E, const int wave_s) {
;     ...
;         if (!has_next) break;
;     ...
;     PG8_WAIT_V(0);
;     if constexpr (!ALIGN_EPI) { if (wr == 0) PG8_BAR; }
;     PG8_BAR;
;     __device__ __forceinline__ void operator()(const af4 (&acc)[2][2][4][2], const pg8::Unit& u, int wr, int wc, int fr_, int fq_) const {
;     ...
;         for (int b_ = 0; b_ < 4; ++b_) {
;             const int ai = b_ >> 1, mp = b_ & 1, cur = b_ & 1;
;             if (b_ + 1 < 4) { if (cur == 0) MUL_LOAD(1, b_ + 1); else MUL_LOAD(0, b_ + 1); }
;             int RRb = row0 + ai * 128 + mp * 32; asm volatile("" : "+v"(RRb));
;             bf16* pb = G + (size_t)RRb * 1024 + col0;
; #pragma unroll
;             for (int mi = 0; mi < 2; ++mi)
; #pragma unroll
;                 for (int bj = 0; bj < 2; ++bj) { const af4 v0 = acc[ai][bj][mp * 2 + mi][0], v1 = acc[ai][bj][mp * 2 + mi][1]; const v4u oo = o[cur][mi][bj];
;                     v4u w; w.x = cvtpk(v0[0] * bflo(oo.x), v0[1] * bfhi(oo.x)); w.y = cvtpk(v0[2] * bflo(oo.y), v0[3] * bfhi(oo.y)); w.z = cvtpk(v1[0] * bflo(oo.z), v1[1] * bfhi(oo.z)); w.w = cvtpk(v1[2] * bflo(oo.w), v1[3] * bfhi(oo.w));
;                     *(v4u*)(pb + mi * 16 * 1024 + bj * 128) = w; }
;             asm volatile("" ::: "memory");
;         }
	v_lshlrev_b32_e32 v84, 16, v104
	v_ashrrev_i32_e32 v65, 31, v64
	v_lshlrev_b64 v[64:65], 11, v[64:65]
	v_lshl_add_u64 v[64:65], s[0:1], 0, v[64:65]
	v_lshl_add_u64 v[64:65], v[64:65], 0, v[152:153]
	global_load_dwordx4 v[68:71], v[64:65], off
	global_load_dwordx4 v[72:75], v[64:65], off offset:256
	v_add_co_u32_e32 v64, vcc, s36, v64
	v_and_b32_e32 v85, 0xffff0000, v104
	s_nop 0
	v_addc_co_u32_e32 v65, vcc, 0, v65, vcc
	global_load_dwordx4 v[76:79], v[64:65], off
	s_nop 0
	global_load_dwordx4 v[64:67], v[64:65], off offset:256
	v_pk_mul_f32 v[60:61], v[60:61], v[84:85]
	v_lshlrev_b32_e32 v84, 16, v105
	v_and_b32_e32 v85, 0xffff0000, v105
	v_pk_mul_f32 v[62:63], v[62:63], v[84:85]
	v_cvt_pk_bf16_f32 v60, v60, v61
	v_cvt_pk_bf16_f32 v61, v62, v63
	v_lshlrev_b32_e32 v62, 16, v106
	v_and_b32_e32 v63, 0xffff0000, v106
	v_pk_mul_f32 v[56:57], v[56:57], v[62:63]
	s_nop 0
	v_cvt_pk_bf16_f32 v62, v56, v57
	v_lshlrev_b32_e32 v56, 16, v107
	v_and_b32_e32 v57, 0xffff0000, v107
	v_pk_mul_f32 v[56:57], v[58:59], v[56:57]
	v_ashrrev_i32_e32 v113, 31, v112
	v_cvt_pk_bf16_f32 v63, v56, v57
	s_waitcnt vmcnt(10)
	v_lshlrev_b32_e32 v56, 16, v108
	v_and_b32_e32 v57, 0xffff0000, v108
	v_pk_mul_f32 v[52:53], v[52:53], v[56:57]
	v_lshlrev_b32_e32 v56, 16, v109
	v_and_b32_e32 v57, 0xffff0000, v109
	v_pk_mul_f32 v[54:55], v[54:55], v[56:57]
	v_cvt_pk_bf16_f32 v52, v52, v53
	v_cvt_pk_bf16_f32 v53, v54, v55
	v_lshlrev_b32_e32 v54, 16, v110
	v_and_b32_e32 v55, 0xffff0000, v110
	v_pk_mul_f32 v[44:45], v[44:45], v[54:55]
	v_lshlrev_b64 v[82:83], 11, v[112:113]
	v_cvt_pk_bf16_f32 v54, v44, v45
	v_lshlrev_b32_e32 v44, 16, v111
	v_and_b32_e32 v45, 0xffff0000, v111
	v_pk_mul_f32 v[44:45], v[46:47], v[44:45]
	s_waitcnt vmcnt(9)
	v_lshlrev_b32_e32 v46, 16, v101
	v_cvt_pk_bf16_f32 v55, v44, v45
	v_lshlrev_b32_e32 v44, 16, v100
	v_and_b32_e32 v45, 0xffff0000, v100
	v_and_b32_e32 v47, 0xffff0000, v101
	v_pk_mul_f32 v[44:45], v[48:49], v[44:45]
	v_pk_mul_f32 v[46:47], v[50:51], v[46:47]
	v_cvt_pk_bf16_f32 v44, v44, v45
	v_cvt_pk_bf16_f32 v45, v46, v47
	v_lshlrev_b32_e32 v46, 16, v102
	v_and_b32_e32 v47, 0xffff0000, v102
	v_pk_mul_f32 v[40:41], v[40:41], v[46:47]
	v_lshl_add_u64 v[82:83], s[0:1], 0, v[82:83]
	v_cvt_pk_bf16_f32 v46, v40, v41
	v_lshlrev_b32_e32 v40, 16, v103
	v_and_b32_e32 v41, 0xffff0000, v103
	v_pk_mul_f32 v[40:41], v[42:43], v[40:41]
	s_waitcnt vmcnt(8)
	v_lshlrev_b32_e32 v42, 16, v96
	v_and_b32_e32 v43, 0xffff0000, v96
	v_pk_mul_f32 v[36:37], v[36:37], v[42:43]
	v_lshlrev_b32_e32 v42, 16, v97
	v_and_b32_e32 v43, 0xffff0000, v97
	v_pk_mul_f32 v[38:39], v[38:39], v[42:43]
	v_cvt_pk_bf16_f32 v36, v36, v37
	v_cvt_pk_bf16_f32 v37, v38, v39
	v_lshlrev_b32_e32 v38, 16, v98
	v_and_b32_e32 v39, 0xffff0000, v98
	v_pk_mul_f32 v[28:29], v[28:29], v[38:39]
	v_lshl_add_u64 v[82:83], v[82:83], 0, v[152:153]
	v_cvt_pk_bf16_f32 v38, v28, v29
	v_lshlrev_b32_e32 v28, 16, v99
	v_and_b32_e32 v29, 0xffff0000, v99
	v_cvt_pk_bf16_f32 v47, v40, v41
	v_add_co_u32_e32 v40, vcc, s36, v82
	v_pk_mul_f32 v[28:29], v[30:31], v[28:29]
	s_nop 0
	v_addc_co_u32_e32 v41, vcc, 0, v83, vcc
	v_cvt_pk_bf16_f32 v39, v28, v29
	global_store_dwordx4 v[82:83], v[60:63], off
	global_store_dwordx4 v[82:83], v[52:55], off offset:256
	global_store_dwordx4 v[40:41], v[44:47], off
	global_store_dwordx4 v[40:41], v[36:39], off offset:256
	s_waitcnt vmcnt(7)
	v_lshlrev_b32_e32 v30, 16, v69
	v_ashrrev_i32_e32 v81, 31, v80
	v_lshlrev_b64 v[28:29], 11, v[80:81]
	v_lshl_add_u64 v[28:29], s[0:1], 0, v[28:29]
	v_lshl_add_u64 v[36:37], v[28:29], 0, v[152:153]
	v_lshlrev_b32_e32 v28, 16, v68
	v_and_b32_e32 v29, 0xffff0000, v68
	v_and_b32_e32 v31, 0xffff0000, v69
	v_pk_mul_f32 v[28:29], v[32:33], v[28:29]
	v_pk_mul_f32 v[30:31], v[34:35], v[30:31]
	v_cvt_pk_bf16_f32 v28, v28, v29
	v_cvt_pk_bf16_f32 v29, v30, v31
	v_lshlrev_b32_e32 v30, 16, v70
	v_and_b32_e32 v31, 0xffff0000, v70
	v_pk_mul_f32 v[24:25], v[24:25], v[30:31]
	s_nop 0
	v_cvt_pk_bf16_f32 v30, v24, v25
	v_lshlrev_b32_e32 v24, 16, v71
	v_and_b32_e32 v25, 0xffff0000, v71
	v_pk_mul_f32 v[24:25], v[26:27], v[24:25]
	s_nop 0
	v_cvt_pk_bf16_f32 v31, v24, v25
	s_waitcnt vmcnt(6)
	v_lshlrev_b32_e32 v24, 16, v72
	v_and_b32_e32 v25, 0xffff0000, v72
	v_pk_mul_f32 v[20:21], v[20:21], v[24:25]
	v_lshlrev_b32_e32 v24, 16, v73
	v_and_b32_e32 v25, 0xffff0000, v73
	v_pk_mul_f32 v[22:23], v[22:23], v[24:25]
	v_cvt_pk_bf16_f32 v20, v20, v21
	v_cvt_pk_bf16_f32 v21, v22, v23
	v_lshlrev_b32_e32 v22, 16, v74
	v_and_b32_e32 v23, 0xffff0000, v74
	v_pk_mul_f32 v[12:13], v[12:13], v[22:23]
	global_store_dwordx4 v[36:37], v[28:31], off
	v_cvt_pk_bf16_f32 v22, v12, v13
	v_lshlrev_b32_e32 v12, 16, v75
	v_and_b32_e32 v13, 0xffff0000, v75
	v_pk_mul_f32 v[12:13], v[14:15], v[12:13]
	s_waitcnt vmcnt(6)
	v_lshlrev_b32_e32 v14, 16, v77
	v_cvt_pk_bf16_f32 v23, v12, v13
	v_lshlrev_b32_e32 v12, 16, v76
	v_and_b32_e32 v13, 0xffff0000, v76
	v_and_b32_e32 v15, 0xffff0000, v77
	v_pk_mul_f32 v[12:13], v[16:17], v[12:13]
	v_pk_mul_f32 v[14:15], v[18:19], v[14:15]
	v_cvt_pk_bf16_f32 v12, v12, v13
	v_cvt_pk_bf16_f32 v13, v14, v15
	v_lshlrev_b32_e32 v14, 16, v78
	v_and_b32_e32 v15, 0xffff0000, v78
	v_pk_mul_f32 v[8:9], v[8:9], v[14:15]
	global_store_dwordx4 v[36:37], v[20:23], off offset:256
	v_cvt_pk_bf16_f32 v14, v8, v9
	v_lshlrev_b32_e32 v8, 16, v79
	v_and_b32_e32 v9, 0xffff0000, v79
	v_pk_mul_f32 v[8:9], v[10:11], v[8:9]
	s_waitcnt vmcnt(6)
	v_lshlrev_b32_e32 v10, 16, v64
	v_and_b32_e32 v11, 0xffff0000, v64
	v_pk_mul_f32 v[4:5], v[4:5], v[10:11]
	v_lshlrev_b32_e32 v10, 16, v65
	v_and_b32_e32 v11, 0xffff0000, v65
	v_pk_mul_f32 v[6:7], v[6:7], v[10:11]
	v_cvt_pk_bf16_f32 v4, v4, v5
	v_cvt_pk_bf16_f32 v5, v6, v7
	v_lshlrev_b32_e32 v6, 16, v66
	v_and_b32_e32 v7, 0xffff0000, v66
	v_pk_mul_f32 v[0:1], v[0:1], v[6:7]
	v_cvt_pk_bf16_f32 v15, v8, v9
	v_cvt_pk_bf16_f32 v6, v0, v1
	v_lshlrev_b32_e32 v0, 16, v67
	v_and_b32_e32 v1, 0xffff0000, v67
	v_add_co_u32_e32 v8, vcc, s36, v36
	v_pk_mul_f32 v[0:1], v[2:3], v[0:1]
	s_nop 0
	v_addc_co_u32_e32 v9, vcc, 0, v37, vcc
	v_cvt_pk_bf16_f32 v7, v0, v1
	global_store_dwordx4 v[8:9], v[12:15], off
	global_store_dwordx4 v[8:9], v[4:7], off offset:256
	s_and_b64 vcc, exec, s[14:15]
	s_cbranch_vccz .LBB0_2018
	s_waitcnt vmcnt(0)
	s_cmpk_gt_u32 s86, 0xff
	s_cbranch_scc1 .LBB0_2025
	s_barrier

; #define PG8_STAGE(bufoff, gbase, voff) do { _Pragma("unroll") for (int _i = 0; _i < 2; ++_i) \
;         __builtin_amdgcn_global_load_lds((const unsigned*)((const char*)(gbase) + (voff)[_i]), (PG8_LAS unsigned*)(lds + (bufoff) + ldsw + _i * 8192), 16, 0, 0); } while (0)
; #define PG8_LDA(dst, b, h) do { _Pragma("unroll") for (int m = 0; m < 4; ++m) _Pragma("unroll") for (int k = 0; k < 2; ++k) dst[m][k] = *(const PG8_LAS bf16x8*)(lds + PG8_SA(b, h) + aoff + m * 2048 + k * 1024); } while (0)
; #define PG8_LDB(dst, b, h) do { _Pragma("unroll") for (int n = 0; n < 2; ++n) _Pragma("unroll") for (int k = 0; k < 2; ++k) dst[n][k] = *(const PG8_LAS bf16x8*)(lds + PG8_SB(b, h) + boff + n * 2048 + k * 1024); } while (0)
; #define PG8_MMA(ai, bj, At, Bt) do { __builtin_amdgcn_s_setprio(1); _Pragma("unroll") for (int m = 0; m < 4; ++m) _Pragma("unroll") for (int n = 0; n < 2; ++n) _Pragma("unroll") for (int k = 0; k < 2; ++k) \
;         acc[ai][bj][m][n] = __builtin_amdgcn_mfma_f32_16x16x32_bf16(Bt[n][k], At[m][k], acc[ai][bj][m][n], 0, 0, 0); __builtin_amdgcn_s_setprio(0); } while (0)
; #define PG8_WAIT_V(n) asm volatile("s_waitcnt vmcnt(" #n ")" ::: "memory")
; #define PG8_WAIT_L(n) asm volatile("s_waitcnt lgkmcnt(" #n ")" ::: "memory")
; template <class Epi, class Sched, bool ALIGN_EPI = false, bool SP2 = false>
; __device__ __forceinline__ void gemm_phase(PG8_LAS unsigned char* lds, const Gemm g, const Sched& S, const Epi& E, const int wave_s) {
;     ...
;             const bool last = (t == nt - 2);
;             const char* a1 = cA + (size_t)(t + 1) * kstep;
;             const char* a2 = last ? nA : cA + (size_t)(t + 2) * kstep; const char* b2 = last ? nB : cB + (size_t)(t + 2) * kstep;
;             const char* a3 = a2 + kstep; const char* b3 = b2 + kstep;
;             if (last && has_next) S.a_ready(nxt);
;             if constexpr (SP2) {
;             PG8_LDB(B0, 0, 0); PG8_LDB(B1, 0, 1); PG8_SCHED; PG8_LDA(At, 0, 0); PG8_STAGE(PG8_SA(1, 1), a1 + hstep, voffA);
;             PG8_WAIT_V(8); PG8_WAIT_L(0); PG8_BAR; PG8_MMA(0, 0, At, B0); PG8_MMA(0, 1, At, B1); PG8_BAR; PG8_SCHED;
;             PG8_LDA(At, 0, 1); PG8_STAGE(PG8_SB(0, 0), b2, voffB); PG8_STAGE(PG8_SB(0, 1), b2 + hstep, voffB); PG8_STAGE(PG8_SA(0, 0), a2, voffA);
;             PG8_WAIT_V(8); PG8_WAIT_L(0); PG8_BAR; PG8_MMA(1, 0, At, B0); PG8_MMA(1, 1, At, B1); PG8_BAR; PG8_SCHED;
.LBB0_2033:
	ds_read_b128 v[128:131], v185
	ds_read_b128 v[132:135], v185 offset:1024
	ds_read_b128 v[136:139], v185 offset:2048
	ds_read_b128 v[140:143], v185 offset:3072
	ds_read_b128 v[144:147], v186
	ds_read_b128 v[148:151], v186 offset:1024
	ds_read_b128 v[152:155], v186 offset:2048
	ds_read_b128 v[156:159], v186 offset:3072
	s_add_u32 s20, s18, 0xfffc0080
	s_addc_u32 s21, s19, -1
	s_cmp_eq_u32 s48, 12
	s_cselect_b32 s23, s9, s21
	s_cselect_b32 s22, s44, s20
	s_cselect_b32 s21, s7, s47
	s_cselect_b32 s20, s45, s46
	v_lshl_add_u64 v[212:213], s[18:19], 0, v[170:171]
	s_add_i32 m0, s17, 0xc000
	ds_read_b128 v[176:179], v187
	ds_read_b128 v[180:183], v187 offset:1024
	ds_read_b128 v[188:191], v187 offset:2048
	ds_read_b128 v[192:195], v187 offset:3072
	ds_read_b128 v[196:199], v187 offset:4096
	ds_read_b128 v[200:203], v187 offset:5120
	ds_read_b128 v[204:207], v187 offset:6144
	ds_read_b128 v[208:211], v187 offset:7168
	global_load_lds_dwordx4 v[212:213], off
	v_lshl_add_u64 v[212:213], s[18:19], 0, v[168:169]
	s_add_i32 m0, s17, 0xe000
	s_nop 0
	global_load_lds_dwordx4 v[212:213], off
	v_lshl_add_u64 v[230:231], s[20:21], 0, v[164:165]
	s_add_u32 s50, s20, 0x40000
	v_lshl_add_u64 v[232:233], s[20:21], 0, v[160:161]
	s_addc_u32 s51, s21, 0
	v_lshl_add_u64 v[234:235], s[50:51], 0, v[164:165]
	v_lshl_add_u64 v[236:237], s[22:23], 0, v[162:163]
	v_lshl_add_u64 v[238:239], s[50:51], 0, v[160:161]
	v_lshl_add_u64 v[240:241], s[22:23], 0, v[166:167]
	s_waitcnt vmcnt(8)
	s_waitcnt lgkmcnt(0)
	s_barrier
	s_setprio 1
	s_waitcnt lgkmcnt(0)
	v_mfma_f32_16x16x32_bf16 v[124:127], v[128:131], v[176:179], v[124:127]
	v_mfma_f32_16x16x32_bf16 v[120:123], v[136:139], v[176:179], v[120:123]
	v_mfma_f32_16x16x32_bf16 v[112:115], v[128:131], v[188:191], v[112:115]
	v_mfma_f32_16x16x32_bf16 v[104:107], v[136:139], v[188:191], v[104:107]
	v_mfma_f32_16x16x32_bf16 v[92:95], v[128:131], v[196:199], v[92:95]
	v_mfma_f32_16x16x32_bf16 v[88:91], v[136:139], v[196:199], v[88:91]
	v_mfma_f32_16x16x32_bf16 v[80:83], v[128:131], v[204:207], v[80:83]
	v_mfma_f32_16x16x32_bf16 v[72:75], v[136:139], v[204:207], v[72:75]
	v_mfma_f32_16x16x32_bf16 v[124:127], v[132:135], v[180:183], v[124:127]
	v_mfma_f32_16x16x32_bf16 v[120:123], v[140:143], v[180:183], v[120:123]
	v_mfma_f32_16x16x32_bf16 v[112:115], v[132:135], v[192:195], v[112:115]
	v_mfma_f32_16x16x32_bf16 v[104:107], v[140:143], v[192:195], v[104:107]
	v_mfma_f32_16x16x32_bf16 v[92:95], v[132:135], v[200:203], v[92:95]
	v_mfma_f32_16x16x32_bf16 v[88:91], v[140:143], v[200:203], v[88:91]
	v_mfma_f32_16x16x32_bf16 v[80:83], v[132:135], v[208:211], v[80:83]
	v_mfma_f32_16x16x32_bf16 v[72:75], v[140:143], v[208:211], v[72:75]
	s_setprio 0
	s_setprio 1
	v_mfma_f32_16x16x32_bf16 v[116:119], v[144:147], v[176:179], v[116:119]
	v_mfma_f32_16x16x32_bf16 v[108:111], v[152:155], v[176:179], v[108:111]
	v_mfma_f32_16x16x32_bf16 v[100:103], v[144:147], v[188:191], v[100:103]
	v_mfma_f32_16x16x32_bf16 v[96:99], v[152:155], v[188:191], v[96:99]
	v_mfma_f32_16x16x32_bf16 v[84:87], v[144:147], v[196:199], v[84:87]
	v_mfma_f32_16x16x32_bf16 v[76:79], v[152:155], v[196:199], v[76:79]
	v_mfma_f32_16x16x32_bf16 v[68:71], v[144:147], v[204:207], v[68:71]
	v_mfma_f32_16x16x32_bf16 v[64:67], v[152:155], v[204:207], v[64:67]
	v_mfma_f32_16x16x32_bf16 v[116:119], v[148:151], v[180:183], v[116:119]
	v_mfma_f32_16x16x32_bf16 v[108:111], v[156:159], v[180:183], v[108:111]
	v_mfma_f32_16x16x32_bf16 v[100:103], v[148:151], v[192:195], v[100:103]
	v_mfma_f32_16x16x32_bf16 v[96:99], v[156:159], v[192:195], v[96:99]
	v_mfma_f32_16x16x32_bf16 v[84:87], v[148:151], v[200:203], v[84:87]
	v_mfma_f32_16x16x32_bf16 v[76:79], v[156:159], v[200:203], v[76:79]
	v_mfma_f32_16x16x32_bf16 v[68:71], v[148:151], v[208:211], v[68:71]
	v_mfma_f32_16x16x32_bf16 v[64:67], v[156:159], v[208:211], v[64:67]
	s_setprio 0
	s_barrier
	s_add_i32 s49, s41, s33
	s_mov_b32 m0, s49
	ds_read_b128 v[176:179], v187 offset:16384
	ds_read_b128 v[180:183], v187 offset:17408
	ds_read_b128 v[188:191], v187 offset:18432
	ds_read_b128 v[192:195], v187 offset:19456
	ds_read_b128 v[196:199], v187 offset:20480
	ds_read_b128 v[200:203], v187 offset:21504
	ds_read_b128 v[204:207], v187 offset:22528
	ds_read_b128 v[208:211], v187 offset:23552
	global_load_lds_dwordx4 v[230:231], off
	s_add_i32 m0, s49, 0x2000
	s_add_i32 s49, s42, s33
	global_load_lds_dwordx4 v[232:233], off
	s_mov_b32 m0, s49
	s_nop 0
	global_load_lds_dwordx4 v[234:235], off
	s_add_i32 m0, s49, 0x2000
	s_nop 0
	global_load_lds_dwordx4 v[238:239], off
	s_mov_b32 m0, s17
	s_nop 0
	global_load_lds_dwordx4 v[240:241], off
	s_mov_b32 m0, s30
	s_nop 0
	global_load_lds_dwordx4 v[236:237], off
	s_waitcnt vmcnt(8)
	s_waitcnt lgkmcnt(0)
	s_barrier
; #define PG8_STAGE(bufoff, gbase, voff) do { _Pragma("unroll") for (int _i = 0; _i < 2; ++_i) \
;         __builtin_amdgcn_global_load_lds((const unsigned*)((const char*)(gbase) + (voff)[_i]), (PG8_LAS unsigned*)(lds + (bufoff) + ldsw + _i * 8192), 16, 0, 0); } while (0)
; #define PG8_LDA(dst, b, h) do { _Pragma("unroll") for (int m = 0; m < 4; ++m) _Pragma("unroll") for (int k = 0; k < 2; ++k) dst[m][k] = *(const PG8_LAS bf16x8*)(lds + PG8_SA(b, h) + aoff + m * 2048 + k * 1024); } while (0)
; #define PG8_LDB(dst, b, h) do { _Pragma("unroll") for (int n = 0; n < 2; ++n) _Pragma("unroll") for (int k = 0; k < 2; ++k) dst[n][k] = *(const PG8_LAS bf16x8*)(lds + PG8_SB(b, h) + boff + n * 2048 + k * 1024); } while (0)
; #define PG8_MMA(ai, bj, At, Bt) do { __builtin_amdgcn_s_setprio(1); _Pragma("unroll") for (int m = 0; m < 4; ++m) _Pragma("unroll") for (int n = 0; n < 2; ++n) _Pragma("unroll") for (int k = 0; k < 2; ++k) \
;         acc[ai][bj][m][n] = __builtin_amdgcn_mfma_f32_16x16x32_bf16(Bt[n][k], At[m][k], acc[ai][bj][m][n], 0, 0, 0); __builtin_amdgcn_s_setprio(0); } while (0)
; #define PG8_WAIT_V(n) asm volatile("s_waitcnt vmcnt(" #n ")" ::: "memory")
; #define PG8_WAIT_L(n) asm volatile("s_waitcnt lgkmcnt(" #n ")" ::: "memory")
; #define PG8_BAR __builtin_amdgcn_s_barrier()
; #define PG8_SCHED __builtin_amdgcn_sched_barrier(0)
; template <class Epi, class Sched, bool ALIGN_EPI = false, bool SP2 = false>
; __device__ __forceinline__ void gemm_phase(PG8_LAS unsigned char* lds, const Gemm g, const Sched& S, const Epi& E, const int wave_s) {
;     ...
;             PG8_WAIT_V(8); PG8_WAIT_L(0); PG8_BAR; PG8_MMA(1, 0, At, B0); PG8_MMA(1, 1, At, B1); PG8_BAR; PG8_SCHED;
;             PG8_LDB(B0, 1, 0); PG8_LDB(B1, 1, 1); PG8_SCHED; PG8_LDA(At, 1, 0); PG8_STAGE(PG8_SA(0, 1), a2 + hstep, voffA);
;             PG8_WAIT_V(8); PG8_WAIT_L(0); PG8_BAR; PG8_MMA(0, 0, At, B0); PG8_MMA(0, 1, At, B1); PG8_BAR; PG8_SCHED;
;             PG8_LDA(At, 1, 1); PG8_STAGE(PG8_SB(1, 0), b3, voffB); PG8_STAGE(PG8_SB(1, 1), b3 + hstep, voffB); PG8_STAGE(PG8_SA(1, 0), a3, voffA);
	s_setprio 1
	s_waitcnt lgkmcnt(0)
	v_mfma_f32_16x16x32_bf16 v[60:63], v[128:131], v[176:179], v[60:63]
	v_mfma_f32_16x16x32_bf16 v[56:59], v[136:139], v[176:179], v[56:59]
	v_mfma_f32_16x16x32_bf16 v[48:51], v[128:131], v[188:191], v[48:51]
	v_mfma_f32_16x16x32_bf16 v[40:43], v[136:139], v[188:191], v[40:43]
	v_mfma_f32_16x16x32_bf16 v[28:31], v[128:131], v[196:199], v[28:31]
	v_mfma_f32_16x16x32_bf16 v[24:27], v[136:139], v[196:199], v[24:27]
	v_mfma_f32_16x16x32_bf16 v[16:19], v[128:131], v[204:207], v[16:19]
	v_mfma_f32_16x16x32_bf16 v[8:11], v[136:139], v[204:207], v[8:11]
	v_mfma_f32_16x16x32_bf16 v[60:63], v[132:135], v[180:183], v[60:63]
	v_mfma_f32_16x16x32_bf16 v[56:59], v[140:143], v[180:183], v[56:59]
	v_mfma_f32_16x16x32_bf16 v[48:51], v[132:135], v[192:195], v[48:51]
	v_mfma_f32_16x16x32_bf16 v[40:43], v[140:143], v[192:195], v[40:43]
	v_mfma_f32_16x16x32_bf16 v[28:31], v[132:135], v[200:203], v[28:31]
	v_mfma_f32_16x16x32_bf16 v[24:27], v[140:143], v[200:203], v[24:27]
	v_mfma_f32_16x16x32_bf16 v[16:19], v[132:135], v[208:211], v[16:19]
	v_mfma_f32_16x16x32_bf16 v[8:11], v[140:143], v[208:211], v[8:11]
	s_setprio 0
	s_setprio 1
	v_mfma_f32_16x16x32_bf16 v[52:55], v[144:147], v[176:179], v[52:55]
	v_mfma_f32_16x16x32_bf16 v[44:47], v[152:155], v[176:179], v[44:47]
	v_mfma_f32_16x16x32_bf16 v[36:39], v[144:147], v[188:191], v[36:39]
	v_mfma_f32_16x16x32_bf16 v[32:35], v[152:155], v[188:191], v[32:35]
	v_mfma_f32_16x16x32_bf16 v[20:23], v[144:147], v[196:199], v[20:23]
	v_mfma_f32_16x16x32_bf16 v[12:15], v[152:155], v[196:199], v[12:15]
	v_mfma_f32_16x16x32_bf16 v[4:7], v[144:147], v[204:207], v[4:7]
	v_mfma_f32_16x16x32_bf16 v[0:3], v[152:155], v[204:207], v[0:3]
	v_mfma_f32_16x16x32_bf16 v[52:55], v[148:151], v[180:183], v[52:55]
	v_mfma_f32_16x16x32_bf16 v[44:47], v[156:159], v[180:183], v[44:47]
	v_mfma_f32_16x16x32_bf16 v[36:39], v[148:151], v[192:195], v[36:39]
	v_mfma_f32_16x16x32_bf16 v[32:35], v[156:159], v[192:195], v[32:35]
	v_mfma_f32_16x16x32_bf16 v[20:23], v[148:151], v[200:203], v[20:23]
	v_mfma_f32_16x16x32_bf16 v[12:15], v[156:159], v[200:203], v[12:15]
	v_mfma_f32_16x16x32_bf16 v[4:7], v[148:151], v[208:211], v[4:7]
	v_mfma_f32_16x16x32_bf16 v[0:3], v[156:159], v[208:211], v[0:3]
	s_setprio 0
	s_barrier
	s_add_i32 s49, 0, 0x18000
	s_add_i32 s50, 0, 0x1c000
	v_add_u32_e32 v140, s49, v184
	v_add_u32_e32 v156, s50, v184
	ds_read_b128 v[128:131], v140
	ds_read_b128 v[132:135], v140 offset:1024
	ds_read_b128 v[136:139], v140 offset:2048
	ds_read_b128 v[140:143], v140 offset:3072
	ds_read_b128 v[144:147], v156
	ds_read_b128 v[148:151], v156 offset:1024
	ds_read_b128 v[152:155], v156 offset:2048
	ds_read_b128 v[156:159], v156 offset:3072
	s_add_u32 s22, s22, 0x40000
	s_addc_u32 s23, s23, 0
	s_mov_b32 m0, s31
	v_lshl_add_u64 v[220:221], s[22:23], 0, v[166:167]
	ds_read_b128 v[176:179], v187 offset:32768
	ds_read_b128 v[180:183], v187 offset:33792
	ds_read_b128 v[188:191], v187 offset:34816
	ds_read_b128 v[192:195], v187 offset:35840
	ds_read_b128 v[196:199], v187 offset:36864
	ds_read_b128 v[200:203], v187 offset:37888
	ds_read_b128 v[204:207], v187 offset:38912
	ds_read_b128 v[208:211], v187 offset:39936
	global_load_lds_dwordx4 v[220:221], off
	v_lshl_add_u64 v[220:221], s[22:23], 0, v[162:163]
	s_mov_b32 m0, s34
	s_nop 0
	global_load_lds_dwordx4 v[220:221], off
	v_lshl_add_u64 v[242:243], v[230:231], 0, s[4:5]
	s_add_u32 s20, s20, 0x40080
	v_lshl_add_u64 v[244:245], v[232:233], 0, s[4:5]
	s_addc_u32 s21, s21, 0
	v_lshl_add_u64 v[246:247], s[20:21], 0, v[164:165]
	v_lshl_add_u64 v[248:249], s[20:21], 0, v[160:161]
	v_lshl_add_u64 v[250:251], v[240:241], 0, s[4:5]
	v_lshl_add_u64 v[252:253], v[236:237], 0, s[4:5]
	s_waitcnt vmcnt(8)
	s_waitcnt lgkmcnt(0)
	s_barrier
	s_setprio 1
	s_waitcnt lgkmcnt(0)
	v_mfma_f32_16x16x32_bf16 v[124:127], v[128:131], v[176:179], v[124:127]
	v_mfma_f32_16x16x32_bf16 v[120:123], v[136:139], v[176:179], v[120:123]
	v_mfma_f32_16x16x32_bf16 v[112:115], v[128:131], v[188:191], v[112:115]
	v_mfma_f32_16x16x32_bf16 v[104:107], v[136:139], v[188:191], v[104:107]
	v_mfma_f32_16x16x32_bf16 v[92:95], v[128:131], v[196:199], v[92:95]
	v_mfma_f32_16x16x32_bf16 v[88:91], v[136:139], v[196:199], v[88:91]
	v_mfma_f32_16x16x32_bf16 v[80:83], v[128:131], v[204:207], v[80:83]
	v_mfma_f32_16x16x32_bf16 v[72:75], v[136:139], v[204:207], v[72:75]
	v_mfma_f32_16x16x32_bf16 v[124:127], v[132:135], v[180:183], v[124:127]
	v_mfma_f32_16x16x32_bf16 v[120:123], v[140:143], v[180:183], v[120:123]
	v_mfma_f32_16x16x32_bf16 v[112:115], v[132:135], v[192:195], v[112:115]
	v_mfma_f32_16x16x32_bf16 v[104:107], v[140:143], v[192:195], v[104:107]
	v_mfma_f32_16x16x32_bf16 v[92:95], v[132:135], v[200:203], v[92:95]
	v_mfma_f32_16x16x32_bf16 v[88:91], v[140:143], v[200:203], v[88:91]
	v_mfma_f32_16x16x32_bf16 v[80:83], v[132:135], v[208:211], v[80:83]
	v_mfma_f32_16x16x32_bf16 v[72:75], v[140:143], v[208:211], v[72:75]
	s_setprio 0
	s_setprio 1
	v_mfma_f32_16x16x32_bf16 v[116:119], v[144:147], v[176:179], v[116:119]
	v_mfma_f32_16x16x32_bf16 v[108:111], v[152:155], v[176:179], v[108:111]
	v_mfma_f32_16x16x32_bf16 v[100:103], v[144:147], v[188:191], v[100:103]
	v_mfma_f32_16x16x32_bf16 v[96:99], v[152:155], v[188:191], v[96:99]
	v_mfma_f32_16x16x32_bf16 v[84:87], v[144:147], v[196:199], v[84:87]
	v_mfma_f32_16x16x32_bf16 v[76:79], v[152:155], v[196:199], v[76:79]
	v_mfma_f32_16x16x32_bf16 v[68:71], v[144:147], v[204:207], v[68:71]
	v_mfma_f32_16x16x32_bf16 v[64:67], v[152:155], v[204:207], v[64:67]
	v_mfma_f32_16x16x32_bf16 v[116:119], v[148:151], v[180:183], v[116:119]
	v_mfma_f32_16x16x32_bf16 v[108:111], v[156:159], v[180:183], v[108:111]
	v_mfma_f32_16x16x32_bf16 v[100:103], v[148:151], v[192:195], v[100:103]
	v_mfma_f32_16x16x32_bf16 v[96:99], v[156:159], v[192:195], v[96:99]
	v_mfma_f32_16x16x32_bf16 v[84:87], v[148:151], v[200:203], v[84:87]
	v_mfma_f32_16x16x32_bf16 v[76:79], v[156:159], v[200:203], v[76:79]
	v_mfma_f32_16x16x32_bf16 v[68:71], v[148:151], v[208:211], v[68:71]
	v_mfma_f32_16x16x32_bf16 v[64:67], v[156:159], v[208:211], v[64:67]
	s_setprio 0
	s_barrier
; #define PG8_STAGE(bufoff, gbase, voff) do { _Pragma("unroll") for (int _i = 0; _i < 2; ++_i) \
;         __builtin_amdgcn_global_load_lds((const unsigned*)((const char*)(gbase) + (voff)[_i]), (PG8_LAS unsigned*)(lds + (bufoff) + ldsw + _i * 8192), 16, 0, 0); } while (0)
; #define PG8_LDA(dst, b, h) do { _Pragma("unroll") for (int m = 0; m < 4; ++m) _Pragma("unroll") for (int k = 0; k < 2; ++k) dst[m][k] = *(const PG8_LAS bf16x8*)(lds + PG8_SA(b, h) + aoff + m * 2048 + k * 1024); } while (0)
; #define PG8_MMA(ai, bj, At, Bt) do { __builtin_amdgcn_s_setprio(1); _Pragma("unroll") for (int m = 0; m < 4; ++m) _Pragma("unroll") for (int n = 0; n < 2; ++n) _Pragma("unroll") for (int k = 0; k < 2; ++k) \
;         acc[ai][bj][m][n] = __builtin_amdgcn_mfma_f32_16x16x32_bf16(Bt[n][k], At[m][k], acc[ai][bj][m][n], 0, 0, 0); __builtin_amdgcn_s_setprio(0); } while (0)
; #define PG8_WAIT_V(n) asm volatile("s_waitcnt vmcnt(" #n ")" ::: "memory")
; #define PG8_WAIT_L(n) asm volatile("s_waitcnt lgkmcnt(" #n ")" ::: "memory")
; #define PG8_BAR __builtin_amdgcn_s_barrier()
; #define PG8_SCHED __builtin_amdgcn_sched_barrier(0)
; template <class Epi, class Sched, bool ALIGN_EPI = false, bool SP2 = false>
; __device__ __forceinline__ void gemm_phase(PG8_LAS unsigned char* lds, const Gemm g, const Sched& S, const Epi& E, const int wave_s) {
;     ...
;             PG8_LDA(At, 1, 1); PG8_STAGE(PG8_SB(1, 0), b3, voffB); PG8_STAGE(PG8_SB(1, 1), b3 + hstep, voffB); PG8_STAGE(PG8_SA(1, 0), a3, voffA);
;             PG8_WAIT_V(8); PG8_WAIT_L(0); PG8_BAR; PG8_MMA(1, 0, At, B0); PG8_MMA(1, 1, At, B1); PG8_BAR; PG8_SCHED;
;     __device__ __forceinline__ void operator()(const af4 (&acc)[2][2][4][2], const pg8::Unit& u, int wr, int wc, int fr_, int fq_) const {
;     ...
;         const int row0 = u.pm * 256 + wr * 64 + fr, col0 = u.pn * 256 + wc * 32 + 8 * fq;
;         v4u o[2][2][2], yv[2][2][2];
;     ...
;         MA_LOAD(0, 0);
; #pragma unroll
;         for (int b_ = 0; b_ < 4; ++b_) {
;             const int ai = b_ >> 1, mp = b_ & 1, cur = b_ & 1;
;             if (b_ + 1 < 4) { if (cur == 0) MA_LOAD(1, b_ + 1); else MA_LOAD(0, b_ + 1); }
	s_add_i32 s22, s49, s33
	s_mov_b32 m0, s22
	ds_read_b128 v[176:179], v187 offset:49152
	ds_read_b128 v[180:183], v187 offset:50176
	ds_read_b128 v[188:191], v187 offset:51200
	ds_read_b128 v[192:195], v187 offset:52224
	ds_read_b128 v[196:199], v187 offset:53248
	ds_read_b128 v[200:203], v187 offset:54272
	ds_read_b128 v[204:207], v187 offset:55296
	ds_read_b128 v[208:211], v187 offset:56320
	global_load_lds_dwordx4 v[242:243], off
	s_add_i32 m0, s22, 0x2000
	s_add_i32 s22, s50, s33
	global_load_lds_dwordx4 v[244:245], off
	s_mov_b32 m0, s22
	s_nop 0
	global_load_lds_dwordx4 v[246:247], off
	s_add_i32 m0, s22, 0x2000
	s_nop 0
	global_load_lds_dwordx4 v[248:249], off
	s_mov_b32 m0, s36
	s_nop 0
	global_load_lds_dwordx4 v[250:251], off
	s_mov_b32 m0, s37
	s_nop 0
	global_load_lds_dwordx4 v[252:253], off
	s_waitcnt vmcnt(8)
	s_waitcnt lgkmcnt(0)
	s_barrier
	s_setprio 1
	s_waitcnt lgkmcnt(0)
	v_mfma_f32_16x16x32_bf16 v[60:63], v[128:131], v[176:179], v[60:63]
	v_mfma_f32_16x16x32_bf16 v[56:59], v[136:139], v[176:179], v[56:59]
	v_mfma_f32_16x16x32_bf16 v[48:51], v[128:131], v[188:191], v[48:51]
	v_mfma_f32_16x16x32_bf16 v[40:43], v[136:139], v[188:191], v[40:43]
	v_mfma_f32_16x16x32_bf16 v[28:31], v[128:131], v[196:199], v[28:31]
	v_mfma_f32_16x16x32_bf16 v[24:27], v[136:139], v[196:199], v[24:27]
	v_mfma_f32_16x16x32_bf16 v[16:19], v[128:131], v[204:207], v[16:19]
	v_mfma_f32_16x16x32_bf16 v[8:11], v[136:139], v[204:207], v[8:11]
	v_mfma_f32_16x16x32_bf16 v[60:63], v[132:135], v[180:183], v[60:63]
	v_mfma_f32_16x16x32_bf16 v[56:59], v[140:143], v[180:183], v[56:59]
	v_mfma_f32_16x16x32_bf16 v[48:51], v[132:135], v[192:195], v[48:51]
	v_mfma_f32_16x16x32_bf16 v[40:43], v[140:143], v[192:195], v[40:43]
	v_mfma_f32_16x16x32_bf16 v[28:31], v[132:135], v[200:203], v[28:31]
	v_mfma_f32_16x16x32_bf16 v[24:27], v[140:143], v[200:203], v[24:27]
	v_mfma_f32_16x16x32_bf16 v[16:19], v[132:135], v[208:211], v[16:19]
	v_mfma_f32_16x16x32_bf16 v[8:11], v[140:143], v[208:211], v[8:11]
	s_setprio 0
	s_setprio 1
	v_mfma_f32_16x16x32_bf16 v[52:55], v[144:147], v[176:179], v[52:55]
	v_mfma_f32_16x16x32_bf16 v[44:47], v[152:155], v[176:179], v[44:47]
	v_mfma_f32_16x16x32_bf16 v[36:39], v[144:147], v[188:191], v[36:39]
	v_mfma_f32_16x16x32_bf16 v[32:35], v[152:155], v[188:191], v[32:35]
	v_mfma_f32_16x16x32_bf16 v[20:23], v[144:147], v[196:199], v[20:23]
	v_mfma_f32_16x16x32_bf16 v[12:15], v[152:155], v[196:199], v[12:15]
	v_mfma_f32_16x16x32_bf16 v[4:7], v[144:147], v[204:207], v[4:7]
	v_mfma_f32_16x16x32_bf16 v[0:3], v[152:155], v[204:207], v[0:3]
	v_mfma_f32_16x16x32_bf16 v[52:55], v[148:151], v[180:183], v[52:55]
	v_mfma_f32_16x16x32_bf16 v[44:47], v[156:159], v[180:183], v[44:47]
	v_mfma_f32_16x16x32_bf16 v[36:39], v[148:151], v[192:195], v[36:39]
	v_mfma_f32_16x16x32_bf16 v[32:35], v[156:159], v[192:195], v[32:35]
	v_mfma_f32_16x16x32_bf16 v[20:23], v[148:151], v[200:203], v[20:23]
	v_mfma_f32_16x16x32_bf16 v[12:15], v[156:159], v[200:203], v[12:15]
	v_mfma_f32_16x16x32_bf16 v[4:7], v[148:151], v[208:211], v[4:7]
	v_mfma_f32_16x16x32_bf16 v[0:3], v[156:159], v[208:211], v[0:3]
	s_setprio 0
	s_barrier
	s_add_i32 s48, s48, 2
	s_add_u32 s46, s46, 0x100
	s_addc_u32 s47, s47, 0
	s_add_u32 s18, s18, 0x100
	s_addc_u32 s19, s19, 0
	s_cmp_gt_u32 s48, 13
	s_cbranch_scc0 .LBB0_2033
	s_lshl_b32 s7, s16, 8
	v_mbcnt_lo_u32_b32 v128, -1, 0
	v_mbcnt_hi_u32_b32 v128, -1, v128
	s_add_i32 s7, s7, s87
	v_and_or_b32 v183, v128, 15, s7
	s_lshl_b32 s7, s43, 8
	v_ashrrev_i32_e32 v128, 1, v128
	s_or_b32 s7, s7, s79
	v_and_b32_e32 v128, -8, v128
	v_add_u32_e32 v178, s7, v128
	v_mov_b32_e32 v128, v183
	v_ashrrev_i32_e32 v179, 31, v178
	v_ashrrev_i32_e32 v129, 31, v128
	v_lshlrev_b64 v[128:129], 10, v[128:129]
	v_lshl_add_u64 v[128:129], v[128:129], 0, v[178:179]
	v_lshlrev_b64 v[128:129], 1, v[128:129]
	v_lshl_add_u64 v[130:131], s[2:3], 0, v[128:129]
	global_load_dwordx4 v[188:191], v[130:131], off
	v_lshl_add_u64 v[128:129], s[0:1], 0, v[128:129]
	global_load_dwordx4 v[192:195], v[128:129], off
	global_load_dwordx4 v[196:199], v[130:131], off offset:256
	global_load_dwordx4 v[200:203], v[128:129], off offset:256
	v_add_co_u32_e32 v128, vcc, s38, v128
	v_or_b32_e32 v180, 32, v183
	s_nop 0
	v_addc_co_u32_e32 v129, vcc, 0, v129, vcc
	v_add_co_u32_e32 v130, vcc, s38, v130
	v_mov_b32_e32 v132, v180
	s_nop 0
	v_addc_co_u32_e32 v131, vcc, 0, v131, vcc
	global_load_dwordx4 v[204:207], v[128:129], off
	global_load_dwordx4 v[208:211], v[128:129], off offset:256
	global_load_dwordx4 v[212:215], v[130:131], off
	global_load_dwordx4 v[216:219], v[130:131], off offset:256
	v_mov_b32_e32 v220, v183
	v_ashrrev_i32_e32 v133, 31, v132
	v_lshlrev_b64 v[128:129], 10, v[132:133]
	v_lshl_add_u64 v[128:129], v[128:129], 0, v[178:179]
	v_lshlrev_b64 v[128:129], 1, v[128:129]
	v_lshl_add_u64 v[130:131], s[0:1], 0, v[128:129]
	v_lshl_add_u64 v[128:129], s[2:3], 0, v[128:129]
	global_load_dwordx4 v[152:155], v[130:131], off
	global_load_dwordx4 v[144:147], v[130:131], off offset:256
	global_load_dwordx4 v[156:159], v[128:129], off
	global_load_dwordx4 v[148:151], v[128:129], off offset:256
	v_add_co_u32_e32 v130, vcc, s38, v130
	v_lshlrev_b64 v[176:177], 1, v[178:179]
	s_nop 0
	v_addc_co_u32_e32 v131, vcc, 0, v131, vcc
	v_add_co_u32_e32 v132, vcc, s38, v128
	v_add_u32_e32 v182, 0x80, v183
	s_nop 0
	v_addc_co_u32_e32 v133, vcc, 0, v129, vcc
	global_load_dwordx4 v[136:139], v[130:131], off
	s_nop 0
	global_load_dwordx4 v[128:131], v[130:131], off offset:256
	s_nop 0
	global_load_dwordx4 v[140:143], v[132:133], off
	s_nop 0
	global_load_dwordx4 v[132:135], v[132:133], off offset:256
	s_mov_b32 s43, s6
	v_ashrrev_i32_e32 v221, 31, v220
	v_lshlrev_b64 v[220:221], 11, v[220:221]
	v_lshl_add_u64 v[220:221], s[0:1], 0, v[220:221]
	v_lshl_add_u64 v[220:221], v[220:221], 0, v[176:177]
	s_mov_b32 s16, s8
	s_mov_b64 s[18:19], s[12:13]
	s_mov_b64 s[20:21], s[10:11]
	s_waitcnt vmcnt(0)
; __device__ __forceinline__ unsigned cvtpk(float lo, float hi) { f32x2 v = {lo, hi}; bf16x2_t b = __builtin_convertvector(v, bf16x2_t); return __builtin_bit_cast(unsigned, b); }
; __device__ __forceinline__ float bflo(unsigned u) { return __uint_as_float(u << 16); }
; __device__ __forceinline__ float bfhi(unsigned u) { return __uint_as_float(u & 0xffff0000u); }
;     __device__ __forceinline__ void operator()(const af4 (&acc)[2][2][4][2], const pg8::Unit& u, int wr, int wc, int fr_, int fq_) const {
;     ...
;         MA_LOAD(0, 0);
; #pragma unroll
;         for (int b_ = 0; b_ < 4; ++b_) {
;             const int ai = b_ >> 1, mp = b_ & 1, cur = b_ & 1;
;             if (b_ + 1 < 4) { if (cur == 0) MA_LOAD(1, b_ + 1); else MA_LOAD(0, b_ + 1); }
;             int RRb = row0 + ai * 128 + mp * 32; asm volatile("" : "+v"(RRb));
;             const size_t ob = (size_t)RRb * 1024 + col0;
; #pragma unroll
;             for (int mi = 0; mi < 2; ++mi)
; #pragma unroll
;                 for (int bj = 0; bj < 2; ++bj) { const af4 v0 = acc[ai][bj][mp * 2 + mi][0], v1 = acc[ai][bj][mp * 2 + mi][1]; const v4u oo = o[cur][mi][bj], y = yv[cur][mi][bj];
;                     v4u w; w.x = cvtpk(bflo(y.x) + v0[0] * bflo(oo.x), bfhi(y.x) + v0[1] * bfhi(oo.x)); w.y = cvtpk(bflo(y.y) + v0[2] * bflo(oo.y), bfhi(y.y) + v0[3] * bfhi(oo.y));
;                     w.z = cvtpk(bflo(y.z) + v1[0] * bflo(oo.z), bfhi(y.z) + v1[1] * bfhi(oo.z)); w.w = cvtpk(bflo(y.w) + v1[2] * bflo(oo.w), bfhi(y.w) + v1[3] * bfhi(oo.w));
;                     *(v4u*)(G + ob + mi * 16 * 1024 + bj * 128) = w; }
;             asm volatile("" ::: "memory");
	v_lshlrev_b32_e32 v224, 16, v192
	v_lshlrev_b32_e32 v222, 16, v188
	v_and_b32_e32 v223, 0xffff0000, v188
	v_and_b32_e32 v225, 0xffff0000, v192
	v_lshlrev_b32_e32 v188, 16, v189
	v_and_b32_e32 v189, 0xffff0000, v189
	v_lshlrev_b32_e32 v192, 16, v193
	v_and_b32_e32 v193, 0xffff0000, v193
	v_lshlrev_b32_e32 v226, 16, v190
	v_and_b32_e32 v227, 0xffff0000, v190
	v_lshlrev_b32_e32 v228, 16, v194
	v_and_b32_e32 v229, 0xffff0000, v194
	v_lshlrev_b32_e32 v190, 16, v191
	v_and_b32_e32 v191, 0xffff0000, v191
	v_lshlrev_b32_e32 v194, 16, v195
	v_and_b32_e32 v195, 0xffff0000, v195
	v_pk_fma_f32 v[124:125], v[124:125], v[224:225], v[222:223]
	v_pk_fma_f32 v[126:127], v[126:127], v[192:193], v[188:189]
	v_pk_fma_f32 v[188:189], v[120:121], v[228:229], v[226:227]
	v_pk_fma_f32 v[190:191], v[122:123], v[194:195], v[190:191]
	v_cvt_pk_bf16_f32 v120, v124, v125
	v_cvt_pk_bf16_f32 v121, v126, v127
	v_cvt_pk_bf16_f32 v122, v188, v189
	v_cvt_pk_bf16_f32 v123, v190, v191
	v_lshlrev_b32_e32 v230, 16, v196
	v_and_b32_e32 v231, 0xffff0000, v196
	v_lshlrev_b32_e32 v232, 16, v200
	global_store_dwordx4 v[220:221], v[120:123], off
	v_and_b32_e32 v233, 0xffff0000, v200
	v_pk_fma_f32 v[116:117], v[116:117], v[232:233], v[230:231]
	v_lshlrev_b32_e32 v120, 16, v197
	v_and_b32_e32 v121, 0xffff0000, v197
	v_lshlrev_b32_e32 v122, 16, v201
	v_and_b32_e32 v123, 0xffff0000, v201
	v_pk_fma_f32 v[118:119], v[118:119], v[122:123], v[120:121]
	v_cvt_pk_bf16_f32 v116, v116, v117
	v_cvt_pk_bf16_f32 v117, v118, v119
	v_lshlrev_b32_e32 v118, 16, v198
	v_and_b32_e32 v119, 0xffff0000, v198
	v_lshlrev_b32_e32 v120, 16, v202
	v_and_b32_e32 v121, 0xffff0000, v202
	v_pk_fma_f32 v[108:109], v[108:109], v[120:121], v[118:119]
	v_lshlrev_b32_e32 v120, 16, v203
	v_cvt_pk_bf16_f32 v118, v108, v109
	v_lshlrev_b32_e32 v108, 16, v199
	v_and_b32_e32 v109, 0xffff0000, v199
	v_and_b32_e32 v121, 0xffff0000, v203
	v_pk_fma_f32 v[108:109], v[110:111], v[120:121], v[108:109]
	v_lshlrev_b32_e32 v110, 16, v204
	v_cvt_pk_bf16_f32 v119, v108, v109
	v_lshlrev_b32_e32 v108, 16, v212
	v_and_b32_e32 v109, 0xffff0000, v212
	v_and_b32_e32 v111, 0xffff0000, v204
	v_pk_fma_f32 v[108:109], v[112:113], v[110:111], v[108:109]
	v_lshlrev_b32_e32 v110, 16, v213
	v_and_b32_e32 v111, 0xffff0000, v213
	v_lshlrev_b32_e32 v112, 16, v205
	v_and_b32_e32 v113, 0xffff0000, v205
	v_pk_fma_f32 v[110:111], v[114:115], v[112:113], v[110:111]
	v_cvt_pk_bf16_f32 v108, v108, v109
	v_cvt_pk_bf16_f32 v109, v110, v111
	v_lshlrev_b32_e32 v110, 16, v214
	v_and_b32_e32 v111, 0xffff0000, v214
	v_lshlrev_b32_e32 v112, 16, v206
	v_and_b32_e32 v113, 0xffff0000, v206
	v_pk_fma_f32 v[104:105], v[104:105], v[112:113], v[110:111]
	v_lshlrev_b32_e32 v112, 16, v207
	v_cvt_pk_bf16_f32 v110, v104, v105
	v_lshlrev_b32_e32 v104, 16, v215
	v_and_b32_e32 v105, 0xffff0000, v215
	v_and_b32_e32 v113, 0xffff0000, v207
	v_pk_fma_f32 v[104:105], v[106:107], v[112:113], v[104:105]
	v_lshlrev_b32_e32 v106, 16, v216
	v_cvt_pk_bf16_f32 v111, v104, v105
	v_add_co_u32_e32 v104, vcc, s38, v220
	v_and_b32_e32 v107, 0xffff0000, v216
	s_nop 0
	v_addc_co_u32_e32 v105, vcc, 0, v221, vcc
	global_store_dwordx4 v[104:105], v[108:111], off
	global_store_dwordx4 v[220:221], v[116:119], off offset:256
	v_lshlrev_b32_e32 v188, 16, v156
	v_lshlrev_b32_e32 v108, 16, v208
	v_and_b32_e32 v109, 0xffff0000, v208
	v_pk_fma_f32 v[100:101], v[100:101], v[108:109], v[106:107]
	v_lshlrev_b32_e32 v106, 16, v217
	v_and_b32_e32 v107, 0xffff0000, v217
	v_lshlrev_b32_e32 v108, 16, v209
	v_and_b32_e32 v109, 0xffff0000, v209
	v_pk_fma_f32 v[102:103], v[102:103], v[108:109], v[106:107]
	v_cvt_pk_bf16_f32 v100, v100, v101
	v_cvt_pk_bf16_f32 v101, v102, v103
	v_lshlrev_b32_e32 v102, 16, v218
	v_and_b32_e32 v103, 0xffff0000, v218
	v_lshlrev_b32_e32 v106, 16, v210
	v_and_b32_e32 v107, 0xffff0000, v210
	v_pk_fma_f32 v[96:97], v[96:97], v[106:107], v[102:103]
	v_lshlrev_b32_e32 v106, 16, v211
	v_cvt_pk_bf16_f32 v102, v96, v97
	v_lshlrev_b32_e32 v96, 16, v219
	v_and_b32_e32 v97, 0xffff0000, v219
	v_and_b32_e32 v107, 0xffff0000, v211
	v_pk_fma_f32 v[96:97], v[98:99], v[106:107], v[96:97]
	v_and_b32_e32 v189, 0xffff0000, v156
	v_cvt_pk_bf16_f32 v103, v96, v97
	global_store_dwordx4 v[104:105], v[100:103], off offset:256
	v_mov_b32_e32 v96, v182
	v_lshlrev_b32_e32 v190, 16, v152
	v_ashrrev_i32_e32 v97, 31, v96
	v_lshlrev_b64 v[96:97], 10, v[96:97]
	v_lshl_add_u64 v[96:97], v[96:97], 0, v[178:179]
	v_lshlrev_b64 v[96:97], 1, v[96:97]
	v_lshl_add_u64 v[98:99], s[0:1], 0, v[96:97]
	v_lshl_add_u64 v[96:97], s[2:3], 0, v[96:97]
	global_load_dwordx4 v[120:123], v[98:99], off
	global_load_dwordx4 v[112:115], v[98:99], off offset:256
	global_load_dwordx4 v[124:127], v[96:97], off
	global_load_dwordx4 v[116:119], v[96:97], off offset:256
	v_add_co_u32_e32 v98, vcc, s38, v98
	v_and_b32_e32 v191, 0xffff0000, v152
	v_lshlrev_b32_e32 v156, 16, v157
	v_and_b32_e32 v157, 0xffff0000, v157
	v_lshlrev_b32_e32 v152, 16, v153
	v_and_b32_e32 v153, 0xffff0000, v153
	v_addc_co_u32_e32 v99, vcc, 0, v99, vcc
	v_pk_fma_f32 v[92:93], v[92:93], v[190:191], v[188:189]
	v_pk_fma_f32 v[94:95], v[94:95], v[152:153], v[156:157]
	v_add_co_u32_e32 v100, vcc, s38, v96
	v_cvt_pk_bf16_f32 v92, v92, v93
	v_cvt_pk_bf16_f32 v93, v94, v95
	v_lshlrev_b32_e32 v94, 16, v158
	v_and_b32_e32 v95, 0xffff0000, v158
	v_lshlrev_b32_e32 v152, 16, v154
	v_and_b32_e32 v153, 0xffff0000, v154
	v_addc_co_u32_e32 v101, vcc, 0, v97, vcc
	v_pk_fma_f32 v[88:89], v[88:89], v[152:153], v[94:95]
	global_load_dwordx4 v[104:107], v[98:99], off
	s_nop 0
	global_load_dwordx4 v[96:99], v[98:99], off offset:256
	s_nop 0
	global_load_dwordx4 v[108:111], v[100:101], off
	s_nop 0
; __device__ __forceinline__ unsigned cvtpk(float lo, float hi) { f32x2 v = {lo, hi}; bf16x2_t b = __builtin_convertvector(v, bf16x2_t); return __builtin_bit_cast(unsigned, b); }
; __device__ __forceinline__ float bflo(unsigned u) { return __uint_as_float(u << 16); }
; __device__ __forceinline__ float bfhi(unsigned u) { return __uint_as_float(u & 0xffff0000u); }
;     __device__ __forceinline__ void operator()(const af4 (&acc)[2][2][4][2], const pg8::Unit& u, int wr, int wc, int fr_, int fq_) const {
;     ...
;         MA_LOAD(0, 0);
; #pragma unroll
;         for (int b_ = 0; b_ < 4; ++b_) {
;             const int ai = b_ >> 1, mp = b_ & 1, cur = b_ & 1;
;             if (b_ + 1 < 4) { if (cur == 0) MA_LOAD(1, b_ + 1); else MA_LOAD(0, b_ + 1); }
;             int RRb = row0 + ai * 128 + mp * 32; asm volatile("" : "+v"(RRb));
;             const size_t ob = (size_t)RRb * 1024 + col0;
; #pragma unroll
;             for (int mi = 0; mi < 2; ++mi)
; #pragma unroll
;                 for (int bj = 0; bj < 2; ++bj) { const af4 v0 = acc[ai][bj][mp * 2 + mi][0], v1 = acc[ai][bj][mp * 2 + mi][1]; const v4u oo = o[cur][mi][bj], y = yv[cur][mi][bj];
;                     v4u w; w.x = cvtpk(bflo(y.x) + v0[0] * bflo(oo.x), bfhi(y.x) + v0[1] * bfhi(oo.x)); w.y = cvtpk(bflo(y.y) + v0[2] * bflo(oo.y), bfhi(y.y) + v0[3] * bfhi(oo.y));
;                     w.z = cvtpk(bflo(y.z) + v1[0] * bflo(oo.z), bfhi(y.z) + v1[1] * bfhi(oo.z)); w.w = cvtpk(bflo(y.w) + v1[2] * bflo(oo.w), bfhi(y.w) + v1[3] * bfhi(oo.w));
;                     *(v4u*)(G + ob + mi * 16 * 1024 + bj * 128) = w; }
;             asm volatile("" ::: "memory");
	global_load_dwordx4 v[100:103], v[100:101], off offset:256
	v_cvt_pk_bf16_f32 v94, v88, v89
	v_ashrrev_i32_e32 v181, 31, v180
	v_lshlrev_b32_e32 v88, 16, v159
	v_and_b32_e32 v89, 0xffff0000, v159
	v_lshlrev_b32_e32 v152, 16, v155
	v_and_b32_e32 v153, 0xffff0000, v155
	v_lshlrev_b64 v[180:181], 11, v[180:181]
	v_pk_fma_f32 v[88:89], v[90:91], v[152:153], v[88:89]
	v_lshlrev_b32_e32 v90, 16, v148
	v_cvt_pk_bf16_f32 v95, v88, v89
	v_lshl_add_u64 v[88:89], s[0:1], 0, v[180:181]
	v_lshl_add_u64 v[88:89], v[88:89], 0, v[176:177]
	global_store_dwordx4 v[88:89], v[92:95], off
	v_and_b32_e32 v91, 0xffff0000, v148
	s_nop 0
	v_lshlrev_b32_e32 v92, 16, v144
	v_and_b32_e32 v93, 0xffff0000, v144
	v_pk_fma_f32 v[84:85], v[84:85], v[92:93], v[90:91]
	v_lshlrev_b32_e32 v90, 16, v149
	v_and_b32_e32 v91, 0xffff0000, v149
	v_lshlrev_b32_e32 v92, 16, v145
	v_and_b32_e32 v93, 0xffff0000, v145
	v_pk_fma_f32 v[86:87], v[86:87], v[92:93], v[90:91]
	v_cvt_pk_bf16_f32 v84, v84, v85
	v_cvt_pk_bf16_f32 v85, v86, v87
	v_lshlrev_b32_e32 v86, 16, v150
	v_and_b32_e32 v87, 0xffff0000, v150
	v_lshlrev_b32_e32 v90, 16, v146
	v_and_b32_e32 v91, 0xffff0000, v146
	v_pk_fma_f32 v[76:77], v[76:77], v[90:91], v[86:87]
	v_lshlrev_b32_e32 v90, 16, v147
	v_cvt_pk_bf16_f32 v86, v76, v77
	v_lshlrev_b32_e32 v76, 16, v151
	v_and_b32_e32 v77, 0xffff0000, v151
	v_and_b32_e32 v91, 0xffff0000, v147
	v_pk_fma_f32 v[76:77], v[78:79], v[90:91], v[76:77]
	v_lshlrev_b32_e32 v78, 16, v136
	v_cvt_pk_bf16_f32 v87, v76, v77
	v_lshlrev_b32_e32 v76, 16, v140
	v_and_b32_e32 v77, 0xffff0000, v140
	v_and_b32_e32 v79, 0xffff0000, v136
	v_pk_fma_f32 v[76:77], v[80:81], v[78:79], v[76:77]
	v_lshlrev_b32_e32 v78, 16, v141
	v_and_b32_e32 v79, 0xffff0000, v141
	v_lshlrev_b32_e32 v80, 16, v137
	v_and_b32_e32 v81, 0xffff0000, v137
	v_pk_fma_f32 v[78:79], v[82:83], v[80:81], v[78:79]
	v_cvt_pk_bf16_f32 v76, v76, v77
	v_cvt_pk_bf16_f32 v77, v78, v79
	v_lshlrev_b32_e32 v78, 16, v142
	v_and_b32_e32 v79, 0xffff0000, v142
	v_lshlrev_b32_e32 v80, 16, v138
	v_and_b32_e32 v81, 0xffff0000, v138
	v_pk_fma_f32 v[72:73], v[72:73], v[80:81], v[78:79]
	v_lshlrev_b32_e32 v80, 16, v139
	v_cvt_pk_bf16_f32 v78, v72, v73
	v_lshlrev_b32_e32 v72, 16, v143
	v_and_b32_e32 v73, 0xffff0000, v143
	v_and_b32_e32 v81, 0xffff0000, v139
	v_pk_fma_f32 v[72:73], v[74:75], v[80:81], v[72:73]
	v_lshlrev_b32_e32 v74, 16, v132
	v_cvt_pk_bf16_f32 v79, v72, v73
	v_add_co_u32_e32 v72, vcc, s38, v88
	v_and_b32_e32 v75, 0xffff0000, v132
	s_nop 0
	v_addc_co_u32_e32 v73, vcc, 0, v89, vcc
	global_store_dwordx4 v[72:73], v[76:79], off
	global_store_dwordx4 v[88:89], v[84:87], off offset:256
	s_waitcnt vmcnt(8)
	v_lshlrev_b32_e32 v132, 16, v124
	v_lshlrev_b32_e32 v76, 16, v128
	v_and_b32_e32 v77, 0xffff0000, v128
	v_pk_fma_f32 v[68:69], v[68:69], v[76:77], v[74:75]
	v_lshlrev_b32_e32 v74, 16, v133
	v_and_b32_e32 v75, 0xffff0000, v133
	v_lshlrev_b32_e32 v76, 16, v129
	v_and_b32_e32 v77, 0xffff0000, v129
	v_pk_fma_f32 v[70:71], v[70:71], v[76:77], v[74:75]
	v_cvt_pk_bf16_f32 v68, v68, v69
	v_cvt_pk_bf16_f32 v69, v70, v71
	v_lshlrev_b32_e32 v70, 16, v134
	v_and_b32_e32 v71, 0xffff0000, v134
	v_lshlrev_b32_e32 v74, 16, v130
	v_and_b32_e32 v75, 0xffff0000, v130
	v_pk_fma_f32 v[64:65], v[64:65], v[74:75], v[70:71]
	v_lshlrev_b32_e32 v74, 16, v131
	v_cvt_pk_bf16_f32 v70, v64, v65
	v_lshlrev_b32_e32 v64, 16, v135
	v_and_b32_e32 v65, 0xffff0000, v135
	v_and_b32_e32 v75, 0xffff0000, v131
	v_pk_fma_f32 v[64:65], v[66:67], v[74:75], v[64:65]
	v_add_u32_e32 v128, 0xa0, v183
	v_cvt_pk_bf16_f32 v71, v64, v65
	global_store_dwordx4 v[72:73], v[68:71], off offset:256
	v_mov_b32_e32 v64, v128
	v_and_b32_e32 v133, 0xffff0000, v124
	v_ashrrev_i32_e32 v65, 31, v64
	v_lshlrev_b64 v[64:65], 10, v[64:65]
	v_lshl_add_u64 v[64:65], v[64:65], 0, v[178:179]
	v_lshlrev_b64 v[64:65], 1, v[64:65]
	v_lshl_add_u64 v[66:67], s[0:1], 0, v[64:65]
	v_lshl_add_u64 v[64:65], s[2:3], 0, v[64:65]
	global_load_dwordx4 v[88:91], v[66:67], off
	global_load_dwordx4 v[80:83], v[66:67], off offset:256
	global_load_dwordx4 v[92:95], v[64:65], off
	global_load_dwordx4 v[84:87], v[64:65], off offset:256
	v_add_co_u32_e32 v66, vcc, s38, v66
	v_lshlrev_b32_e32 v134, 16, v120
	s_nop 0
	v_addc_co_u32_e32 v67, vcc, 0, v67, vcc
	v_add_co_u32_e32 v68, vcc, s38, v64
	v_and_b32_e32 v135, 0xffff0000, v120
	s_nop 0
	v_addc_co_u32_e32 v69, vcc, 0, v65, vcc
	global_load_dwordx4 v[72:75], v[66:67], off
	s_nop 0
	global_load_dwordx4 v[64:67], v[66:67], off offset:256
	s_nop 0
	global_load_dwordx4 v[76:79], v[68:69], off
	s_nop 0
	global_load_dwordx4 v[68:71], v[68:69], off offset:256
	v_lshlrev_b32_e32 v124, 16, v125
	v_and_b32_e32 v125, 0xffff0000, v125
	v_lshlrev_b32_e32 v120, 16, v121
	v_and_b32_e32 v121, 0xffff0000, v121
	v_pk_fma_f32 v[60:61], v[60:61], v[134:135], v[132:133]
	v_pk_fma_f32 v[62:63], v[62:63], v[120:121], v[124:125]
	v_cvt_pk_bf16_f32 v60, v60, v61
	v_cvt_pk_bf16_f32 v61, v62, v63
	v_lshlrev_b32_e32 v62, 16, v126
	v_and_b32_e32 v63, 0xffff0000, v126
	v_lshlrev_b32_e32 v120, 16, v122
	v_and_b32_e32 v121, 0xffff0000, v122
	v_pk_fma_f32 v[56:57], v[56:57], v[120:121], v[62:63]
	v_lshlrev_b32_e32 v120, 16, v123
	v_ashrrev_i32_e32 v183, 31, v182
	v_cvt_pk_bf16_f32 v62, v56, v57
	v_lshlrev_b32_e32 v56, 16, v127
	v_and_b32_e32 v57, 0xffff0000, v127
	v_and_b32_e32 v121, 0xffff0000, v123
	v_lshlrev_b64 v[130:131], 11, v[182:183]
	v_pk_fma_f32 v[56:57], v[58:59], v[120:121], v[56:57]
	s_waitcnt vmcnt(16)
; __device__ __forceinline__ unsigned cvtpk(float lo, float hi) { f32x2 v = {lo, hi}; bf16x2_t b = __builtin_convertvector(v, bf16x2_t); return __builtin_bit_cast(unsigned, b); }
; __device__ __forceinline__ float bflo(unsigned u) { return __uint_as_float(u << 16); }
; __device__ __forceinline__ float bfhi(unsigned u) { return __uint_as_float(u & 0xffff0000u); }
;     __device__ __forceinline__ void operator()(const af4 (&acc)[2][2][4][2], const pg8::Unit& u, int wr, int wc, int fr_, int fq_) const {
;     ...
;         for (int b_ = 0; b_ < 4; ++b_) {
;             const int ai = b_ >> 1, mp = b_ & 1, cur = b_ & 1;
;             if (b_ + 1 < 4) { if (cur == 0) MA_LOAD(1, b_ + 1); else MA_LOAD(0, b_ + 1); }
;             int RRb = row0 + ai * 128 + mp * 32; asm volatile("" : "+v"(RRb));
;             const size_t ob = (size_t)RRb * 1024 + col0;
; #pragma unroll
;             for (int mi = 0; mi < 2; ++mi)
; #pragma unroll
;                 for (int bj = 0; bj < 2; ++bj) { const af4 v0 = acc[ai][bj][mp * 2 + mi][0], v1 = acc[ai][bj][mp * 2 + mi][1]; const v4u oo = o[cur][mi][bj], y = yv[cur][mi][bj];
;                     v4u w; w.x = cvtpk(bflo(y.x) + v0[0] * bflo(oo.x), bfhi(y.x) + v0[1] * bfhi(oo.x)); w.y = cvtpk(bflo(y.y) + v0[2] * bflo(oo.y), bfhi(y.y) + v0[3] * bfhi(oo.y));
;                     w.z = cvtpk(bflo(y.z) + v1[0] * bflo(oo.z), bfhi(y.z) + v1[1] * bfhi(oo.z)); w.w = cvtpk(bflo(y.w) + v1[2] * bflo(oo.w), bfhi(y.w) + v1[3] * bfhi(oo.w));
;                     *(v4u*)(G + ob + mi * 16 * 1024 + bj * 128) = w; }
;             asm volatile("" ::: "memory");
	v_lshlrev_b32_e32 v58, 16, v116
	v_cvt_pk_bf16_f32 v63, v56, v57
	v_lshl_add_u64 v[56:57], s[0:1], 0, v[130:131]
	v_lshl_add_u64 v[56:57], v[56:57], 0, v[176:177]
	global_store_dwordx4 v[56:57], v[60:63], off
	v_and_b32_e32 v59, 0xffff0000, v116
	s_nop 0
	v_lshlrev_b32_e32 v60, 16, v112
	v_and_b32_e32 v61, 0xffff0000, v112
	v_pk_fma_f32 v[52:53], v[52:53], v[60:61], v[58:59]
	v_lshlrev_b32_e32 v58, 16, v117
	v_and_b32_e32 v59, 0xffff0000, v117
	v_lshlrev_b32_e32 v60, 16, v113
	v_and_b32_e32 v61, 0xffff0000, v113
	v_pk_fma_f32 v[54:55], v[54:55], v[60:61], v[58:59]
	v_cvt_pk_bf16_f32 v52, v52, v53
	v_cvt_pk_bf16_f32 v53, v54, v55
	v_lshlrev_b32_e32 v54, 16, v118
	v_and_b32_e32 v55, 0xffff0000, v118
	v_lshlrev_b32_e32 v58, 16, v114
	v_and_b32_e32 v59, 0xffff0000, v114
	v_pk_fma_f32 v[44:45], v[44:45], v[58:59], v[54:55]
	v_lshlrev_b32_e32 v58, 16, v115
	v_cvt_pk_bf16_f32 v54, v44, v45
	v_lshlrev_b32_e32 v44, 16, v119
	v_and_b32_e32 v45, 0xffff0000, v119
	v_and_b32_e32 v59, 0xffff0000, v115
	v_pk_fma_f32 v[44:45], v[46:47], v[58:59], v[44:45]
	s_waitcnt vmcnt(16)
	v_lshlrev_b32_e32 v46, 16, v104
	v_cvt_pk_bf16_f32 v55, v44, v45
	s_waitcnt vmcnt(14)
	v_lshlrev_b32_e32 v44, 16, v108
	v_and_b32_e32 v45, 0xffff0000, v108
	v_and_b32_e32 v47, 0xffff0000, v104
	v_pk_fma_f32 v[44:45], v[48:49], v[46:47], v[44:45]
	v_lshlrev_b32_e32 v46, 16, v109
	v_and_b32_e32 v47, 0xffff0000, v109
	v_lshlrev_b32_e32 v48, 16, v105
	v_and_b32_e32 v49, 0xffff0000, v105
	v_pk_fma_f32 v[46:47], v[50:51], v[48:49], v[46:47]
	v_cvt_pk_bf16_f32 v44, v44, v45
	v_cvt_pk_bf16_f32 v45, v46, v47
	v_lshlrev_b32_e32 v46, 16, v110
	v_and_b32_e32 v47, 0xffff0000, v110
	v_lshlrev_b32_e32 v48, 16, v106
	v_and_b32_e32 v49, 0xffff0000, v106
	v_pk_fma_f32 v[40:41], v[40:41], v[48:49], v[46:47]
	v_lshlrev_b32_e32 v48, 16, v107
	v_cvt_pk_bf16_f32 v46, v40, v41
	v_lshlrev_b32_e32 v40, 16, v111
	v_and_b32_e32 v41, 0xffff0000, v111
	v_and_b32_e32 v49, 0xffff0000, v107
	v_pk_fma_f32 v[40:41], v[42:43], v[48:49], v[40:41]
	s_waitcnt vmcnt(13)
	v_lshlrev_b32_e32 v42, 16, v100
	v_cvt_pk_bf16_f32 v47, v40, v41
	v_add_co_u32_e32 v40, vcc, s38, v56
	v_and_b32_e32 v43, 0xffff0000, v100
	s_nop 0
	v_addc_co_u32_e32 v41, vcc, 0, v57, vcc
	global_store_dwordx4 v[40:41], v[44:47], off
	global_store_dwordx4 v[56:57], v[52:55], off offset:256
	s_nop 0
	v_lshlrev_b32_e32 v44, 16, v96
	v_and_b32_e32 v45, 0xffff0000, v96
	v_pk_fma_f32 v[36:37], v[36:37], v[44:45], v[42:43]
	v_lshlrev_b32_e32 v42, 16, v101
	v_and_b32_e32 v43, 0xffff0000, v101
	v_lshlrev_b32_e32 v44, 16, v97
	v_and_b32_e32 v45, 0xffff0000, v97
	v_pk_fma_f32 v[38:39], v[38:39], v[44:45], v[42:43]
	v_cvt_pk_bf16_f32 v36, v36, v37
	v_cvt_pk_bf16_f32 v37, v38, v39
	v_lshlrev_b32_e32 v38, 16, v102
	v_and_b32_e32 v39, 0xffff0000, v102
	v_lshlrev_b32_e32 v42, 16, v98
	v_and_b32_e32 v43, 0xffff0000, v98
	v_pk_fma_f32 v[32:33], v[32:33], v[42:43], v[38:39]
	v_lshlrev_b32_e32 v42, 16, v99
	v_cvt_pk_bf16_f32 v38, v32, v33
	v_lshlrev_b32_e32 v32, 16, v103
	v_and_b32_e32 v33, 0xffff0000, v103
	v_and_b32_e32 v43, 0xffff0000, v99
	v_pk_fma_f32 v[32:33], v[34:35], v[42:43], v[32:33]
	s_waitcnt vmcnt(8)
	v_lshlrev_b32_e32 v34, 16, v92
	v_cvt_pk_bf16_f32 v39, v32, v33
	global_store_dwordx4 v[40:41], v[36:39], off offset:256
	v_and_b32_e32 v35, 0xffff0000, v92
	s_nop 0
	v_lshlrev_b32_e32 v36, 16, v88
	v_and_b32_e32 v37, 0xffff0000, v88
	v_pk_fma_f32 v[28:29], v[28:29], v[36:37], v[34:35]
	v_lshlrev_b32_e32 v34, 16, v93
	v_and_b32_e32 v35, 0xffff0000, v93
	v_lshlrev_b32_e32 v36, 16, v89
	v_and_b32_e32 v37, 0xffff0000, v89
	v_pk_fma_f32 v[30:31], v[30:31], v[36:37], v[34:35]
	v_cvt_pk_bf16_f32 v28, v28, v29
	v_cvt_pk_bf16_f32 v29, v30, v31
	v_lshlrev_b32_e32 v30, 16, v94
	v_and_b32_e32 v31, 0xffff0000, v94
	v_lshlrev_b32_e32 v34, 16, v90
	v_and_b32_e32 v35, 0xffff0000, v90
	v_pk_fma_f32 v[24:25], v[24:25], v[34:35], v[30:31]
	v_ashrrev_i32_e32 v129, 31, v128
	v_cvt_pk_bf16_f32 v30, v24, v25
	v_lshlrev_b32_e32 v24, 16, v95
	v_and_b32_e32 v25, 0xffff0000, v95
	v_lshlrev_b32_e32 v34, 16, v91
	v_and_b32_e32 v35, 0xffff0000, v91
	v_lshlrev_b64 v[32:33], 11, v[128:129]
	v_pk_fma_f32 v[24:25], v[26:27], v[34:35], v[24:25]
	s_waitcnt vmcnt(8)
; #define PG8_WAIT_V(n) asm volatile("s_waitcnt vmcnt(" #n ")" ::: "memory")
; #define PG8_BAR __builtin_amdgcn_s_barrier()
; __device__ __forceinline__ unsigned cvtpk(float lo, float hi) { f32x2 v = {lo, hi}; bf16x2_t b = __builtin_convertvector(v, bf16x2_t); return __builtin_bit_cast(unsigned, b); }
; __device__ __forceinline__ float bflo(unsigned u) { return __uint_as_float(u << 16); }
; __device__ __forceinline__ float bfhi(unsigned u) { return __uint_as_float(u & 0xffff0000u); }
; template <class Epi, class Sched, bool ALIGN_EPI = false, bool SP2 = false>
; __device__ __forceinline__ void gemm_phase(PG8_LAS unsigned char* lds, const Gemm g, const Sched& S, const Epi& E, const int wave_s) {
;     ...
;         if (!has_next) break;
;     ...
;     PG8_WAIT_V(0);
;     if constexpr (!ALIGN_EPI) { if (wr == 0) PG8_BAR; }
;     PG8_BAR;
;     __device__ __forceinline__ void operator()(const af4 (&acc)[2][2][4][2], const pg8::Unit& u, int wr, int wc, int fr_, int fq_) const {
;     ...
;         for (int b_ = 0; b_ < 4; ++b_) {
;             const int ai = b_ >> 1, mp = b_ & 1, cur = b_ & 1;
;             if (b_ + 1 < 4) { if (cur == 0) MA_LOAD(1, b_ + 1); else MA_LOAD(0, b_ + 1); }
;             int RRb = row0 + ai * 128 + mp * 32; asm volatile("" : "+v"(RRb));
;             const size_t ob = (size_t)RRb * 1024 + col0;
; #pragma unroll
;             for (int mi = 0; mi < 2; ++mi)
; #pragma unroll
;                 for (int bj = 0; bj < 2; ++bj) { const af4 v0 = acc[ai][bj][mp * 2 + mi][0], v1 = acc[ai][bj][mp * 2 + mi][1]; const v4u oo = o[cur][mi][bj], y = yv[cur][mi][bj];
;                     v4u w; w.x = cvtpk(bflo(y.x) + v0[0] * bflo(oo.x), bfhi(y.x) + v0[1] * bfhi(oo.x)); w.y = cvtpk(bflo(y.y) + v0[2] * bflo(oo.y), bfhi(y.y) + v0[3] * bfhi(oo.y));
;                     w.z = cvtpk(bflo(y.z) + v1[0] * bflo(oo.z), bfhi(y.z) + v1[1] * bfhi(oo.z)); w.w = cvtpk(bflo(y.w) + v1[2] * bflo(oo.w), bfhi(y.w) + v1[3] * bfhi(oo.w));
;                     *(v4u*)(G + ob + mi * 16 * 1024 + bj * 128) = w; }
;             asm volatile("" ::: "memory");
	v_lshlrev_b32_e32 v26, 16, v84
	v_cvt_pk_bf16_f32 v31, v24, v25
	v_lshl_add_u64 v[24:25], s[0:1], 0, v[32:33]
	v_lshl_add_u64 v[24:25], v[24:25], 0, v[176:177]
	global_store_dwordx4 v[24:25], v[28:31], off
	v_and_b32_e32 v27, 0xffff0000, v84
	s_nop 0
	v_lshlrev_b32_e32 v28, 16, v80
	v_and_b32_e32 v29, 0xffff0000, v80
	v_pk_fma_f32 v[20:21], v[20:21], v[28:29], v[26:27]
	v_lshlrev_b32_e32 v26, 16, v85
	v_and_b32_e32 v27, 0xffff0000, v85
	v_lshlrev_b32_e32 v28, 16, v81
	v_and_b32_e32 v29, 0xffff0000, v81
	v_pk_fma_f32 v[22:23], v[22:23], v[28:29], v[26:27]
	v_cvt_pk_bf16_f32 v20, v20, v21
	v_cvt_pk_bf16_f32 v21, v22, v23
	v_lshlrev_b32_e32 v22, 16, v86
	v_and_b32_e32 v23, 0xffff0000, v86
	v_lshlrev_b32_e32 v26, 16, v82
	v_and_b32_e32 v27, 0xffff0000, v82
	v_pk_fma_f32 v[12:13], v[12:13], v[26:27], v[22:23]
	v_lshlrev_b32_e32 v26, 16, v83
	v_cvt_pk_bf16_f32 v22, v12, v13
	v_lshlrev_b32_e32 v12, 16, v87
	v_and_b32_e32 v13, 0xffff0000, v87
	v_and_b32_e32 v27, 0xffff0000, v83
	v_pk_fma_f32 v[12:13], v[14:15], v[26:27], v[12:13]
	s_waitcnt vmcnt(8)
	v_lshlrev_b32_e32 v14, 16, v72
	v_cvt_pk_bf16_f32 v23, v12, v13
	s_waitcnt vmcnt(6)
	v_lshlrev_b32_e32 v12, 16, v76
	v_and_b32_e32 v13, 0xffff0000, v76
	v_and_b32_e32 v15, 0xffff0000, v72
	v_pk_fma_f32 v[12:13], v[16:17], v[14:15], v[12:13]
	v_lshlrev_b32_e32 v14, 16, v77
	v_and_b32_e32 v15, 0xffff0000, v77
	v_lshlrev_b32_e32 v16, 16, v73
	v_and_b32_e32 v17, 0xffff0000, v73
	v_pk_fma_f32 v[14:15], v[18:19], v[16:17], v[14:15]
	v_cvt_pk_bf16_f32 v12, v12, v13
	v_cvt_pk_bf16_f32 v13, v14, v15
	v_lshlrev_b32_e32 v14, 16, v78
	v_and_b32_e32 v15, 0xffff0000, v78
	v_lshlrev_b32_e32 v16, 16, v74
	v_and_b32_e32 v17, 0xffff0000, v74
	v_pk_fma_f32 v[8:9], v[8:9], v[16:17], v[14:15]
	v_lshlrev_b32_e32 v16, 16, v75
	v_cvt_pk_bf16_f32 v14, v8, v9
	v_lshlrev_b32_e32 v8, 16, v79
	v_and_b32_e32 v9, 0xffff0000, v79
	v_and_b32_e32 v17, 0xffff0000, v75
	v_pk_fma_f32 v[8:9], v[10:11], v[16:17], v[8:9]
	s_waitcnt vmcnt(5)
	v_lshlrev_b32_e32 v10, 16, v68
	v_cvt_pk_bf16_f32 v15, v8, v9
	v_add_co_u32_e32 v8, vcc, s38, v24
	v_and_b32_e32 v11, 0xffff0000, v68
	s_nop 0
	v_addc_co_u32_e32 v9, vcc, 0, v25, vcc
	global_store_dwordx4 v[8:9], v[12:15], off
	global_store_dwordx4 v[24:25], v[20:23], off offset:256
	s_and_b64 vcc, exec, s[14:15]
	v_lshlrev_b32_e32 v12, 16, v64
	v_and_b32_e32 v13, 0xffff0000, v64
	v_pk_fma_f32 v[4:5], v[4:5], v[12:13], v[10:11]
	v_lshlrev_b32_e32 v10, 16, v69
	v_and_b32_e32 v11, 0xffff0000, v69
	v_lshlrev_b32_e32 v12, 16, v65
	v_and_b32_e32 v13, 0xffff0000, v65
	v_pk_fma_f32 v[6:7], v[6:7], v[12:13], v[10:11]
	v_cvt_pk_bf16_f32 v4, v4, v5
	v_cvt_pk_bf16_f32 v5, v6, v7
	v_lshlrev_b32_e32 v6, 16, v70
	v_and_b32_e32 v7, 0xffff0000, v70
	v_lshlrev_b32_e32 v10, 16, v66
	v_and_b32_e32 v11, 0xffff0000, v66
	v_pk_fma_f32 v[0:1], v[0:1], v[10:11], v[6:7]
	v_lshlrev_b32_e32 v10, 16, v67
	v_cvt_pk_bf16_f32 v6, v0, v1
	v_lshlrev_b32_e32 v0, 16, v71
	v_and_b32_e32 v1, 0xffff0000, v71
	v_and_b32_e32 v11, 0xffff0000, v67
	v_pk_fma_f32 v[0:1], v[2:3], v[10:11], v[0:1]
	s_nop 0
	v_cvt_pk_bf16_f32 v7, v0, v1
	global_store_dwordx4 v[8:9], v[4:7], off offset:256
	s_cbranch_vccz .LBB0_2030
	s_waitcnt vmcnt(0)
	s_cmpk_gt_u32 s86, 0xff
	s_cbranch_scc1 .LBB0_2037
	s_barrier

; #define PG8_STAGE(bufoff, gbase, voff) do { _Pragma("unroll") for (int _i = 0; _i < 2; ++_i) \
;         __builtin_amdgcn_global_load_lds((const unsigned*)((const char*)(gbase) + (voff)[_i]), (PG8_LAS unsigned*)(lds + (bufoff) + ldsw + _i * 8192), 16, 0, 0); } while (0)
; #define PG8_LDA(dst, b, h) do { _Pragma("unroll") for (int m = 0; m < 4; ++m) _Pragma("unroll") for (int k = 0; k < 2; ++k) dst[m][k] = *(const PG8_LAS bf16x8*)(lds + PG8_SA(b, h) + aoff + m * 2048 + k * 1024); } while (0)
; #define PG8_LDB(dst, b, h) do { _Pragma("unroll") for (int n = 0; n < 2; ++n) _Pragma("unroll") for (int k = 0; k < 2; ++k) dst[n][k] = *(const PG8_LAS bf16x8*)(lds + PG8_SB(b, h) + boff + n * 2048 + k * 1024); } while (0)
; #define PG8_MMA(ai, bj, At, Bt) do { __builtin_amdgcn_s_setprio(1); _Pragma("unroll") for (int m = 0; m < 4; ++m) _Pragma("unroll") for (int n = 0; n < 2; ++n) _Pragma("unroll") for (int k = 0; k < 2; ++k) \
;         acc[ai][bj][m][n] = __builtin_amdgcn_mfma_f32_16x16x32_bf16(Bt[n][k], At[m][k], acc[ai][bj][m][n], 0, 0, 0); __builtin_amdgcn_s_setprio(0); } while (0)
; #define PG8_WAIT_V(n) asm volatile("s_waitcnt vmcnt(" #n ")" ::: "memory")
; #define PG8_WAIT_L(n) asm volatile("s_waitcnt lgkmcnt(" #n ")" ::: "memory")
; template <class Epi, class Sched, bool ALIGN_EPI = false, bool SP2 = false>
; __device__ __forceinline__ void gemm_phase(PG8_LAS unsigned char* lds, const Gemm g, const Sched& S, const Epi& E, const int wave_s) {
;     ...
;             const bool last = (t == nt - 2);
;             const char* a1 = cA + (size_t)(t + 1) * kstep;
;             const char* a2 = last ? nA : cA + (size_t)(t + 2) * kstep; const char* b2 = last ? nB : cB + (size_t)(t + 2) * kstep;
;             const char* a3 = a2 + kstep; const char* b3 = b2 + kstep;
;             if (last && has_next) S.a_ready(nxt);
;             if constexpr (SP2) {
;             PG8_LDB(B0, 0, 0); PG8_LDB(B1, 0, 1); PG8_SCHED; PG8_LDA(At, 0, 0); PG8_STAGE(PG8_SA(1, 1), a1 + hstep, voffA);
;             PG8_WAIT_V(8); PG8_WAIT_L(0); PG8_BAR; PG8_MMA(0, 0, At, B0); PG8_MMA(0, 1, At, B1); PG8_BAR; PG8_SCHED;
;             PG8_LDA(At, 0, 1); PG8_STAGE(PG8_SB(0, 0), b2, voffB); PG8_STAGE(PG8_SB(0, 1), b2 + hstep, voffB); PG8_STAGE(PG8_SA(0, 0), a2, voffA);
;             PG8_WAIT_V(8); PG8_WAIT_L(0); PG8_BAR; PG8_MMA(1, 0, At, B0); PG8_MMA(1, 1, At, B1); PG8_BAR; PG8_SCHED;
.LBB0_2100:
	ds_read_b128 v[128:131], v195
	ds_read_b128 v[132:135], v195 offset:1024
	ds_read_b128 v[136:139], v195 offset:2048
	ds_read_b128 v[140:143], v195 offset:3072
	ds_read_b128 v[160:163], v196
	ds_read_b128 v[164:167], v196 offset:1024
	ds_read_b128 v[168:171], v196 offset:2048
	ds_read_b128 v[172:175], v196 offset:3072
	s_add_u32 s28, s26, 0xfffc0080
	s_addc_u32 s29, s27, -1
	s_cmp_eq_u32 s62, 12
	s_cselect_b32 s31, s21, s29
	s_cselect_b32 s30, s34, s28
	s_cselect_b32 s29, s19, s61
	s_cselect_b32 s28, s35, s60
	v_lshl_add_u64 v[156:157], s[26:27], 0, v[154:155]
	s_add_i32 m0, s41, 0xc000
	ds_read_b128 v[176:179], v197
	ds_read_b128 v[180:183], v197 offset:1024
	ds_read_b128 v[184:187], v197 offset:2048
	ds_read_b128 v[188:191], v197 offset:3072
	ds_read_b128 v[198:201], v197 offset:4096
	ds_read_b128 v[202:205], v197 offset:5120
	ds_read_b128 v[206:209], v197 offset:6144
	ds_read_b128 v[210:213], v197 offset:7168
	global_load_lds_dwordx4 v[156:157], off
	v_lshl_add_u64 v[156:157], s[26:27], 0, v[152:153]
	s_add_i32 m0, s41, 0xe000
	s_nop 0
	global_load_lds_dwordx4 v[156:157], off
	v_lshl_add_u64 v[230:231], s[28:29], 0, v[148:149]
	s_add_u32 s64, s28, 0x40000
	v_lshl_add_u64 v[232:233], s[28:29], 0, v[144:145]
	s_addc_u32 s65, s29, 0
	v_lshl_add_u64 v[234:235], s[64:65], 0, v[148:149]
	v_lshl_add_u64 v[236:237], s[30:31], 0, v[146:147]
	v_lshl_add_u64 v[238:239], s[64:65], 0, v[144:145]
	v_lshl_add_u64 v[240:241], s[30:31], 0, v[150:151]
	s_waitcnt vmcnt(8)
	s_waitcnt lgkmcnt(0)
	s_barrier
	s_setprio 1
	s_waitcnt lgkmcnt(0)
	v_mfma_f32_16x16x32_bf16 v[124:127], v[128:131], v[176:179], v[124:127]
	v_mfma_f32_16x16x32_bf16 v[120:123], v[136:139], v[176:179], v[120:123]
	v_mfma_f32_16x16x32_bf16 v[112:115], v[128:131], v[184:187], v[112:115]
	v_mfma_f32_16x16x32_bf16 v[104:107], v[136:139], v[184:187], v[104:107]
	v_mfma_f32_16x16x32_bf16 v[92:95], v[128:131], v[198:201], v[92:95]
	v_mfma_f32_16x16x32_bf16 v[88:91], v[136:139], v[198:201], v[88:91]
	v_mfma_f32_16x16x32_bf16 v[80:83], v[128:131], v[206:209], v[80:83]
	v_mfma_f32_16x16x32_bf16 v[72:75], v[136:139], v[206:209], v[72:75]
	v_mfma_f32_16x16x32_bf16 v[124:127], v[132:135], v[180:183], v[124:127]
	v_mfma_f32_16x16x32_bf16 v[120:123], v[140:143], v[180:183], v[120:123]
	v_mfma_f32_16x16x32_bf16 v[112:115], v[132:135], v[188:191], v[112:115]
	v_mfma_f32_16x16x32_bf16 v[104:107], v[140:143], v[188:191], v[104:107]
	v_mfma_f32_16x16x32_bf16 v[92:95], v[132:135], v[202:205], v[92:95]
	v_mfma_f32_16x16x32_bf16 v[88:91], v[140:143], v[202:205], v[88:91]
	v_mfma_f32_16x16x32_bf16 v[80:83], v[132:135], v[210:213], v[80:83]
	v_mfma_f32_16x16x32_bf16 v[72:75], v[140:143], v[210:213], v[72:75]
	s_setprio 0
	s_setprio 1
	v_mfma_f32_16x16x32_bf16 v[116:119], v[160:163], v[176:179], v[116:119]
	v_mfma_f32_16x16x32_bf16 v[108:111], v[168:171], v[176:179], v[108:111]
	v_mfma_f32_16x16x32_bf16 v[100:103], v[160:163], v[184:187], v[100:103]
	v_mfma_f32_16x16x32_bf16 v[96:99], v[168:171], v[184:187], v[96:99]
	v_mfma_f32_16x16x32_bf16 v[84:87], v[160:163], v[198:201], v[84:87]
	v_mfma_f32_16x16x32_bf16 v[76:79], v[168:171], v[198:201], v[76:79]
	v_mfma_f32_16x16x32_bf16 v[68:71], v[160:163], v[206:209], v[68:71]
	v_mfma_f32_16x16x32_bf16 v[64:67], v[168:171], v[206:209], v[64:67]
	v_mfma_f32_16x16x32_bf16 v[116:119], v[164:167], v[180:183], v[116:119]
	v_mfma_f32_16x16x32_bf16 v[108:111], v[172:175], v[180:183], v[108:111]
	v_mfma_f32_16x16x32_bf16 v[100:103], v[164:167], v[188:191], v[100:103]
	v_mfma_f32_16x16x32_bf16 v[96:99], v[172:175], v[188:191], v[96:99]
	v_mfma_f32_16x16x32_bf16 v[84:87], v[164:167], v[202:205], v[84:87]
	v_mfma_f32_16x16x32_bf16 v[76:79], v[172:175], v[202:205], v[76:79]
	v_mfma_f32_16x16x32_bf16 v[68:71], v[164:167], v[210:213], v[68:71]
	v_mfma_f32_16x16x32_bf16 v[64:67], v[172:175], v[210:213], v[64:67]
	s_setprio 0
	s_barrier
	s_add_i32 s63, s56, s33
	s_mov_b32 m0, s63
	ds_read_b128 v[176:179], v197 offset:16384
	ds_read_b128 v[180:183], v197 offset:17408
	ds_read_b128 v[184:187], v197 offset:18432
	ds_read_b128 v[188:191], v197 offset:19456
	ds_read_b128 v[198:201], v197 offset:20480
	ds_read_b128 v[202:205], v197 offset:21504
	ds_read_b128 v[206:209], v197 offset:22528
	ds_read_b128 v[210:213], v197 offset:23552
	global_load_lds_dwordx4 v[230:231], off
	s_add_i32 m0, s63, 0x2000
	s_add_i32 s63, s57, s33
	global_load_lds_dwordx4 v[232:233], off
	s_mov_b32 m0, s63
	s_nop 0
	global_load_lds_dwordx4 v[234:235], off
	s_add_i32 m0, s63, 0x2000
	s_nop 0
	global_load_lds_dwordx4 v[238:239], off
	s_mov_b32 m0, s41
	s_nop 0
	global_load_lds_dwordx4 v[240:241], off
	s_mov_b32 m0, s42
	s_nop 0
	global_load_lds_dwordx4 v[236:237], off
	s_waitcnt vmcnt(8)
	s_waitcnt lgkmcnt(0)
	s_barrier
; #define PG8_STAGE(bufoff, gbase, voff) do { _Pragma("unroll") for (int _i = 0; _i < 2; ++_i) \
;         __builtin_amdgcn_global_load_lds((const unsigned*)((const char*)(gbase) + (voff)[_i]), (PG8_LAS unsigned*)(lds + (bufoff) + ldsw + _i * 8192), 16, 0, 0); } while (0)
; #define PG8_LDA(dst, b, h) do { _Pragma("unroll") for (int m = 0; m < 4; ++m) _Pragma("unroll") for (int k = 0; k < 2; ++k) dst[m][k] = *(const PG8_LAS bf16x8*)(lds + PG8_SA(b, h) + aoff + m * 2048 + k * 1024); } while (0)
; #define PG8_LDB(dst, b, h) do { _Pragma("unroll") for (int n = 0; n < 2; ++n) _Pragma("unroll") for (int k = 0; k < 2; ++k) dst[n][k] = *(const PG8_LAS bf16x8*)(lds + PG8_SB(b, h) + boff + n * 2048 + k * 1024); } while (0)
; #define PG8_MMA(ai, bj, At, Bt) do { __builtin_amdgcn_s_setprio(1); _Pragma("unroll") for (int m = 0; m < 4; ++m) _Pragma("unroll") for (int n = 0; n < 2; ++n) _Pragma("unroll") for (int k = 0; k < 2; ++k) \
;         acc[ai][bj][m][n] = __builtin_amdgcn_mfma_f32_16x16x32_bf16(Bt[n][k], At[m][k], acc[ai][bj][m][n], 0, 0, 0); __builtin_amdgcn_s_setprio(0); } while (0)
; #define PG8_WAIT_V(n) asm volatile("s_waitcnt vmcnt(" #n ")" ::: "memory")
; #define PG8_WAIT_L(n) asm volatile("s_waitcnt lgkmcnt(" #n ")" ::: "memory")
; #define PG8_BAR __builtin_amdgcn_s_barrier()
; #define PG8_SCHED __builtin_amdgcn_sched_barrier(0)
; template <class Epi, class Sched, bool ALIGN_EPI = false, bool SP2 = false>
; __device__ __forceinline__ void gemm_phase(PG8_LAS unsigned char* lds, const Gemm g, const Sched& S, const Epi& E, const int wave_s) {
;     ...
;             PG8_WAIT_V(8); PG8_WAIT_L(0); PG8_BAR; PG8_MMA(1, 0, At, B0); PG8_MMA(1, 1, At, B1); PG8_BAR; PG8_SCHED;
;             PG8_LDB(B0, 1, 0); PG8_LDB(B1, 1, 1); PG8_SCHED; PG8_LDA(At, 1, 0); PG8_STAGE(PG8_SA(0, 1), a2 + hstep, voffA);
;             PG8_WAIT_V(8); PG8_WAIT_L(0); PG8_BAR; PG8_MMA(0, 0, At, B0); PG8_MMA(0, 1, At, B1); PG8_BAR; PG8_SCHED;
;             PG8_LDA(At, 1, 1); PG8_STAGE(PG8_SB(1, 0), b3, voffB); PG8_STAGE(PG8_SB(1, 1), b3 + hstep, voffB); PG8_STAGE(PG8_SA(1, 0), a3, voffA);
	s_setprio 1
	s_waitcnt lgkmcnt(0)
	v_mfma_f32_16x16x32_bf16 v[60:63], v[128:131], v[176:179], v[60:63]
	v_mfma_f32_16x16x32_bf16 v[56:59], v[136:139], v[176:179], v[56:59]
	v_mfma_f32_16x16x32_bf16 v[48:51], v[128:131], v[184:187], v[48:51]
	v_mfma_f32_16x16x32_bf16 v[40:43], v[136:139], v[184:187], v[40:43]
	v_mfma_f32_16x16x32_bf16 v[28:31], v[128:131], v[198:201], v[28:31]
	v_mfma_f32_16x16x32_bf16 v[24:27], v[136:139], v[198:201], v[24:27]
	v_mfma_f32_16x16x32_bf16 v[16:19], v[128:131], v[206:209], v[16:19]
	v_mfma_f32_16x16x32_bf16 v[8:11], v[136:139], v[206:209], v[8:11]
	v_mfma_f32_16x16x32_bf16 v[60:63], v[132:135], v[180:183], v[60:63]
	v_mfma_f32_16x16x32_bf16 v[56:59], v[140:143], v[180:183], v[56:59]
	v_mfma_f32_16x16x32_bf16 v[48:51], v[132:135], v[188:191], v[48:51]
	v_mfma_f32_16x16x32_bf16 v[40:43], v[140:143], v[188:191], v[40:43]
	v_mfma_f32_16x16x32_bf16 v[28:31], v[132:135], v[202:205], v[28:31]
	v_mfma_f32_16x16x32_bf16 v[24:27], v[140:143], v[202:205], v[24:27]
	v_mfma_f32_16x16x32_bf16 v[16:19], v[132:135], v[210:213], v[16:19]
	v_mfma_f32_16x16x32_bf16 v[8:11], v[140:143], v[210:213], v[8:11]
	s_setprio 0
	s_setprio 1
	v_mfma_f32_16x16x32_bf16 v[52:55], v[160:163], v[176:179], v[52:55]
	v_mfma_f32_16x16x32_bf16 v[44:47], v[168:171], v[176:179], v[44:47]
	v_mfma_f32_16x16x32_bf16 v[36:39], v[160:163], v[184:187], v[36:39]
	v_mfma_f32_16x16x32_bf16 v[32:35], v[168:171], v[184:187], v[32:35]
	v_mfma_f32_16x16x32_bf16 v[20:23], v[160:163], v[198:201], v[20:23]
	v_mfma_f32_16x16x32_bf16 v[12:15], v[168:171], v[198:201], v[12:15]
	v_mfma_f32_16x16x32_bf16 v[4:7], v[160:163], v[206:209], v[4:7]
	v_mfma_f32_16x16x32_bf16 v[0:3], v[168:171], v[206:209], v[0:3]
	v_mfma_f32_16x16x32_bf16 v[52:55], v[164:167], v[180:183], v[52:55]
	v_mfma_f32_16x16x32_bf16 v[44:47], v[172:175], v[180:183], v[44:47]
	v_mfma_f32_16x16x32_bf16 v[36:39], v[164:167], v[188:191], v[36:39]
	v_mfma_f32_16x16x32_bf16 v[32:35], v[172:175], v[188:191], v[32:35]
	v_mfma_f32_16x16x32_bf16 v[20:23], v[164:167], v[202:205], v[20:23]
	v_mfma_f32_16x16x32_bf16 v[12:15], v[172:175], v[202:205], v[12:15]
	v_mfma_f32_16x16x32_bf16 v[4:7], v[164:167], v[210:213], v[4:7]
	v_mfma_f32_16x16x32_bf16 v[0:3], v[172:175], v[210:213], v[0:3]
	s_setprio 0
	s_barrier
	s_add_i32 s63, 0, 0x18000
	s_add_i32 s64, 0, 0x1c000
	v_add_u32_e32 v140, s63, v194
	v_add_u32_e32 v172, s64, v194
	ds_read_b128 v[128:131], v140
	ds_read_b128 v[132:135], v140 offset:1024
	ds_read_b128 v[136:139], v140 offset:2048
	ds_read_b128 v[140:143], v140 offset:3072
	ds_read_b128 v[160:163], v172
	ds_read_b128 v[164:167], v172 offset:1024
	ds_read_b128 v[168:171], v172 offset:2048
	ds_read_b128 v[172:175], v172 offset:3072
	s_add_u32 s30, s30, 0x40000
	s_addc_u32 s31, s31, 0
	s_mov_b32 m0, s43
	v_lshl_add_u64 v[218:219], s[30:31], 0, v[150:151]
	ds_read_b128 v[176:179], v197 offset:32768
	ds_read_b128 v[180:183], v197 offset:33792
	ds_read_b128 v[184:187], v197 offset:34816
	ds_read_b128 v[188:191], v197 offset:35840
	ds_read_b128 v[198:201], v197 offset:36864
	ds_read_b128 v[202:205], v197 offset:37888
	ds_read_b128 v[206:209], v197 offset:38912
	ds_read_b128 v[210:213], v197 offset:39936
	global_load_lds_dwordx4 v[218:219], off
	v_lshl_add_u64 v[218:219], s[30:31], 0, v[146:147]
	s_mov_b32 m0, s44
	s_nop 0
	global_load_lds_dwordx4 v[218:219], off
	v_lshl_add_u64 v[242:243], v[230:231], 0, s[6:7]
	s_add_u32 s28, s28, 0x40080
	v_lshl_add_u64 v[244:245], v[232:233], 0, s[6:7]
	s_addc_u32 s29, s29, 0
	v_lshl_add_u64 v[246:247], s[28:29], 0, v[148:149]
	v_lshl_add_u64 v[248:249], s[28:29], 0, v[144:145]
	v_lshl_add_u64 v[250:251], v[240:241], 0, s[6:7]
	v_lshl_add_u64 v[252:253], v[236:237], 0, s[6:7]
	s_waitcnt vmcnt(8)
	s_waitcnt lgkmcnt(0)
	s_barrier
; #define PG8_STAGE(bufoff, gbase, voff) do { _Pragma("unroll") for (int _i = 0; _i < 2; ++_i) \
;         __builtin_amdgcn_global_load_lds((const unsigned*)((const char*)(gbase) + (voff)[_i]), (PG8_LAS unsigned*)(lds + (bufoff) + ldsw + _i * 8192), 16, 0, 0); } while (0)
; #define PG8_LDA(dst, b, h) do { _Pragma("unroll") for (int m = 0; m < 4; ++m) _Pragma("unroll") for (int k = 0; k < 2; ++k) dst[m][k] = *(const PG8_LAS bf16x8*)(lds + PG8_SA(b, h) + aoff + m * 2048 + k * 1024); } while (0)
; #define PG8_MMA(ai, bj, At, Bt) do { __builtin_amdgcn_s_setprio(1); _Pragma("unroll") for (int m = 0; m < 4; ++m) _Pragma("unroll") for (int n = 0; n < 2; ++n) _Pragma("unroll") for (int k = 0; k < 2; ++k) \
;         acc[ai][bj][m][n] = __builtin_amdgcn_mfma_f32_16x16x32_bf16(Bt[n][k], At[m][k], acc[ai][bj][m][n], 0, 0, 0); __builtin_amdgcn_s_setprio(0); } while (0)
; #define PG8_WAIT_V(n) asm volatile("s_waitcnt vmcnt(" #n ")" ::: "memory")
; #define PG8_WAIT_L(n) asm volatile("s_waitcnt lgkmcnt(" #n ")" ::: "memory")
; #define PG8_BAR __builtin_amdgcn_s_barrier()
; #define PG8_SCHED __builtin_amdgcn_sched_barrier(0)
; template <class Epi, class Sched, bool ALIGN_EPI = false, bool SP2 = false>
; __device__ __forceinline__ void gemm_phase(PG8_LAS unsigned char* lds, const Gemm g, const Sched& S, const Epi& E, const int wave_s) {
;     ...
;             PG8_WAIT_V(8); PG8_WAIT_L(0); PG8_BAR; PG8_MMA(0, 0, At, B0); PG8_MMA(0, 1, At, B1); PG8_BAR; PG8_SCHED;
;             PG8_LDA(At, 1, 1); PG8_STAGE(PG8_SB(1, 0), b3, voffB); PG8_STAGE(PG8_SB(1, 1), b3 + hstep, voffB); PG8_STAGE(PG8_SA(1, 0), a3, voffA);
;             PG8_WAIT_V(8); PG8_WAIT_L(0); PG8_BAR; PG8_MMA(1, 0, At, B0); PG8_MMA(1, 1, At, B1); PG8_BAR; PG8_SCHED;
;     __device__ __forceinline__ void operator()(const af4 (&acc)[2][2][4][2], const pg8::Unit& u, int wr, int wc, int fr_, int fq_) const {
;         const int ln_ = lane_id_v(); const int fr = ln_ & 15, fq = ln_ >> 4;
;         const int grow = rowbase + u.pm * 256; const int bi = grow < TL ? grow / LSEQ : NB;
;         float* xb = grow < TL ? xl + (size_t)grow * DM : xc + (size_t)(grow - TL) * DM;
;         const float* stb = stats + 2 * (size_t)grow;
;         const int col0 = u.pn * 256 + wc * 32 + 8 * fq; const float* gp = gate + (size_t)bi * 6144 + col0;
	s_setprio 1
	s_waitcnt lgkmcnt(0)
	v_mfma_f32_16x16x32_bf16 v[124:127], v[128:131], v[176:179], v[124:127]
	v_mfma_f32_16x16x32_bf16 v[120:123], v[136:139], v[176:179], v[120:123]
	v_mfma_f32_16x16x32_bf16 v[112:115], v[128:131], v[184:187], v[112:115]
	v_mfma_f32_16x16x32_bf16 v[104:107], v[136:139], v[184:187], v[104:107]
	v_mfma_f32_16x16x32_bf16 v[92:95], v[128:131], v[198:201], v[92:95]
	v_mfma_f32_16x16x32_bf16 v[88:91], v[136:139], v[198:201], v[88:91]
	v_mfma_f32_16x16x32_bf16 v[80:83], v[128:131], v[206:209], v[80:83]
	v_mfma_f32_16x16x32_bf16 v[72:75], v[136:139], v[206:209], v[72:75]
	v_mfma_f32_16x16x32_bf16 v[124:127], v[132:135], v[180:183], v[124:127]
	v_mfma_f32_16x16x32_bf16 v[120:123], v[140:143], v[180:183], v[120:123]
	v_mfma_f32_16x16x32_bf16 v[112:115], v[132:135], v[188:191], v[112:115]
	v_mfma_f32_16x16x32_bf16 v[104:107], v[140:143], v[188:191], v[104:107]
	v_mfma_f32_16x16x32_bf16 v[92:95], v[132:135], v[202:205], v[92:95]
	v_mfma_f32_16x16x32_bf16 v[88:91], v[140:143], v[202:205], v[88:91]
	v_mfma_f32_16x16x32_bf16 v[80:83], v[132:135], v[210:213], v[80:83]
	v_mfma_f32_16x16x32_bf16 v[72:75], v[140:143], v[210:213], v[72:75]
	s_setprio 0
	s_setprio 1
	v_mfma_f32_16x16x32_bf16 v[116:119], v[160:163], v[176:179], v[116:119]
	v_mfma_f32_16x16x32_bf16 v[108:111], v[168:171], v[176:179], v[108:111]
	v_mfma_f32_16x16x32_bf16 v[100:103], v[160:163], v[184:187], v[100:103]
	v_mfma_f32_16x16x32_bf16 v[96:99], v[168:171], v[184:187], v[96:99]
	v_mfma_f32_16x16x32_bf16 v[84:87], v[160:163], v[198:201], v[84:87]
	v_mfma_f32_16x16x32_bf16 v[76:79], v[168:171], v[198:201], v[76:79]
	v_mfma_f32_16x16x32_bf16 v[68:71], v[160:163], v[206:209], v[68:71]
	v_mfma_f32_16x16x32_bf16 v[64:67], v[168:171], v[206:209], v[64:67]
	v_mfma_f32_16x16x32_bf16 v[116:119], v[164:167], v[180:183], v[116:119]
	v_mfma_f32_16x16x32_bf16 v[108:111], v[172:175], v[180:183], v[108:111]
	v_mfma_f32_16x16x32_bf16 v[100:103], v[164:167], v[188:191], v[100:103]
	v_mfma_f32_16x16x32_bf16 v[96:99], v[172:175], v[188:191], v[96:99]
	v_mfma_f32_16x16x32_bf16 v[84:87], v[164:167], v[202:205], v[84:87]
	v_mfma_f32_16x16x32_bf16 v[76:79], v[172:175], v[202:205], v[76:79]
	v_mfma_f32_16x16x32_bf16 v[68:71], v[164:167], v[210:213], v[68:71]
	v_mfma_f32_16x16x32_bf16 v[64:67], v[172:175], v[210:213], v[64:67]
	s_setprio 0
	s_barrier
	s_add_i32 s30, s63, s33
	s_mov_b32 m0, s30
	ds_read_b128 v[176:179], v197 offset:49152
	ds_read_b128 v[180:183], v197 offset:50176
	ds_read_b128 v[184:187], v197 offset:51200
	ds_read_b128 v[188:191], v197 offset:52224
	ds_read_b128 v[198:201], v197 offset:53248
	ds_read_b128 v[202:205], v197 offset:54272
	ds_read_b128 v[206:209], v197 offset:55296
	ds_read_b128 v[210:213], v197 offset:56320
	global_load_lds_dwordx4 v[242:243], off
	s_add_i32 m0, s30, 0x2000
	s_add_i32 s30, s64, s33
	global_load_lds_dwordx4 v[244:245], off
	s_mov_b32 m0, s30
	s_nop 0
	global_load_lds_dwordx4 v[246:247], off
	s_add_i32 m0, s30, 0x2000
	s_nop 0
	global_load_lds_dwordx4 v[248:249], off
	s_mov_b32 m0, s52
	s_nop 0
	global_load_lds_dwordx4 v[250:251], off
	s_mov_b32 m0, s53
	s_nop 0
	global_load_lds_dwordx4 v[252:253], off
	s_waitcnt vmcnt(8)
	s_waitcnt lgkmcnt(0)
	s_barrier
	s_setprio 1
	s_waitcnt lgkmcnt(0)
	v_mfma_f32_16x16x32_bf16 v[60:63], v[128:131], v[176:179], v[60:63]
	v_mfma_f32_16x16x32_bf16 v[56:59], v[136:139], v[176:179], v[56:59]
	v_mfma_f32_16x16x32_bf16 v[48:51], v[128:131], v[184:187], v[48:51]
	v_mfma_f32_16x16x32_bf16 v[40:43], v[136:139], v[184:187], v[40:43]
	v_mfma_f32_16x16x32_bf16 v[28:31], v[128:131], v[198:201], v[28:31]
	v_mfma_f32_16x16x32_bf16 v[24:27], v[136:139], v[198:201], v[24:27]
	v_mfma_f32_16x16x32_bf16 v[16:19], v[128:131], v[206:209], v[16:19]
	v_mfma_f32_16x16x32_bf16 v[8:11], v[136:139], v[206:209], v[8:11]
	v_mfma_f32_16x16x32_bf16 v[60:63], v[132:135], v[180:183], v[60:63]
	v_mfma_f32_16x16x32_bf16 v[56:59], v[140:143], v[180:183], v[56:59]
	v_mfma_f32_16x16x32_bf16 v[48:51], v[132:135], v[188:191], v[48:51]
	v_mfma_f32_16x16x32_bf16 v[40:43], v[140:143], v[188:191], v[40:43]
	v_mfma_f32_16x16x32_bf16 v[28:31], v[132:135], v[202:205], v[28:31]
	v_mfma_f32_16x16x32_bf16 v[24:27], v[140:143], v[202:205], v[24:27]
	v_mfma_f32_16x16x32_bf16 v[16:19], v[132:135], v[210:213], v[16:19]
	v_mfma_f32_16x16x32_bf16 v[8:11], v[140:143], v[210:213], v[8:11]
	s_setprio 0
	s_setprio 1
	v_mfma_f32_16x16x32_bf16 v[52:55], v[160:163], v[176:179], v[52:55]
	v_mfma_f32_16x16x32_bf16 v[44:47], v[168:171], v[176:179], v[44:47]
	v_mfma_f32_16x16x32_bf16 v[36:39], v[160:163], v[184:187], v[36:39]
	v_mfma_f32_16x16x32_bf16 v[32:35], v[168:171], v[184:187], v[32:35]
	v_mfma_f32_16x16x32_bf16 v[20:23], v[160:163], v[198:201], v[20:23]
	v_mfma_f32_16x16x32_bf16 v[12:15], v[168:171], v[198:201], v[12:15]
	v_mfma_f32_16x16x32_bf16 v[4:7], v[160:163], v[206:209], v[4:7]
	v_mfma_f32_16x16x32_bf16 v[0:3], v[168:171], v[206:209], v[0:3]
	v_mfma_f32_16x16x32_bf16 v[52:55], v[164:167], v[180:183], v[52:55]
	v_mfma_f32_16x16x32_bf16 v[44:47], v[172:175], v[180:183], v[44:47]
	v_mfma_f32_16x16x32_bf16 v[36:39], v[164:167], v[188:191], v[36:39]
	v_mfma_f32_16x16x32_bf16 v[32:35], v[172:175], v[188:191], v[32:35]
	v_mfma_f32_16x16x32_bf16 v[20:23], v[164:167], v[202:205], v[20:23]
	v_mfma_f32_16x16x32_bf16 v[12:15], v[172:175], v[202:205], v[12:15]
	v_mfma_f32_16x16x32_bf16 v[4:7], v[164:167], v[210:213], v[4:7]
	v_mfma_f32_16x16x32_bf16 v[0:3], v[172:175], v[210:213], v[0:3]
	s_setprio 0
	s_barrier
	s_add_i32 s62, s62, 2
	s_add_u32 s60, s60, 0x100
	s_addc_u32 s61, s61, 0
	s_add_u32 s26, s26, 0x100
	s_addc_u32 s27, s27, 0
	s_cmp_gt_u32 s62, 13
	s_cbranch_scc0 .LBB0_2100
	s_cmpk_gt_i32 s8, 0xff
	s_cselect_b64 s[28:29], -1, 0
	s_mov_b64 s[30:31], 0x18000
	s_and_b64 vcc, exec, s[28:29]
	v_mbcnt_lo_u32_b32 v160, -1, 0
	v_mbcnt_hi_u32_b32 v160, -1, v160
	s_cbranch_vccnz .LBB0_2103
	s_ashr_i32 s19, s8, 31
	s_lshr_b32 s19, s19, 28
	s_add_i32 s19, s8, s19
	s_ashr_i32 s19, s19, 4
	s_mul_hi_i32 s31, s19, 0x1800
	s_mul_i32 s30, s19, 0x1800

; #define PG8_STAGE(bufoff, gbase, voff) do { _Pragma("unroll") for (int _i = 0; _i < 2; ++_i) \
;         __builtin_amdgcn_global_load_lds((const unsigned*)((const char*)(gbase) + (voff)[_i]), (PG8_LAS unsigned*)(lds + (bufoff) + ldsw + _i * 8192), 16, 0, 0); } while (0)
; #define PG8_LDA(dst, b, h) do { _Pragma("unroll") for (int m = 0; m < 4; ++m) _Pragma("unroll") for (int k = 0; k < 2; ++k) dst[m][k] = *(const PG8_LAS bf16x8*)(lds + PG8_SA(b, h) + aoff + m * 2048 + k * 1024); } while (0)
; #define PG8_LDB(dst, b, h) do { _Pragma("unroll") for (int n = 0; n < 2; ++n) _Pragma("unroll") for (int k = 0; k < 2; ++k) dst[n][k] = *(const PG8_LAS bf16x8*)(lds + PG8_SB(b, h) + boff + n * 2048 + k * 1024); } while (0)
; #define PG8_MMA(ai, bj, At, Bt) do { __builtin_amdgcn_s_setprio(1); _Pragma("unroll") for (int m = 0; m < 4; ++m) _Pragma("unroll") for (int n = 0; n < 2; ++n) _Pragma("unroll") for (int k = 0; k < 2; ++k) \
;         acc[ai][bj][m][n] = __builtin_amdgcn_mfma_f32_16x16x32_bf16(Bt[n][k], At[m][k], acc[ai][bj][m][n], 0, 0, 0); __builtin_amdgcn_s_setprio(0); } while (0)
; #define PG8_WAIT_V(n) asm volatile("s_waitcnt vmcnt(" #n ")" ::: "memory")
; #define PG8_WAIT_L(n) asm volatile("s_waitcnt lgkmcnt(" #n ")" ::: "memory")
; template <class Epi, class Sched, bool ALIGN_EPI = false, bool SP2 = false>
; __device__ __forceinline__ void gemm_phase(PG8_LAS unsigned char* lds, const Gemm g, const Sched& S, const Epi& E, const int wave_s) {
;     ...
;             const bool last = (t == nt - 2);
;             const char* a1 = cA + (size_t)(t + 1) * kstep;
;             const char* a2 = last ? nA : cA + (size_t)(t + 2) * kstep; const char* b2 = last ? nB : cB + (size_t)(t + 2) * kstep;
;             const char* a3 = a2 + kstep; const char* b3 = b2 + kstep;
;             if (last && has_next) S.a_ready(nxt);
;             if constexpr (SP2) {
;             PG8_LDB(B0, 0, 0); PG8_LDB(B1, 0, 1); PG8_SCHED; PG8_LDA(At, 0, 0); PG8_STAGE(PG8_SA(1, 1), a1 + hstep, voffA);
;             PG8_WAIT_V(8); PG8_WAIT_L(0); PG8_BAR; PG8_MMA(0, 0, At, B0); PG8_MMA(0, 1, At, B1); PG8_BAR; PG8_SCHED;
;             PG8_LDA(At, 0, 1); PG8_STAGE(PG8_SB(0, 0), b2, voffB); PG8_STAGE(PG8_SB(0, 1), b2 + hstep, voffB); PG8_STAGE(PG8_SA(0, 0), a2, voffA);
;             PG8_WAIT_V(8); PG8_WAIT_L(0); PG8_BAR; PG8_MMA(1, 0, At, B0); PG8_MMA(1, 1, At, B1); PG8_BAR; PG8_SCHED;
.LBB0_2236:
	ds_read_b128 v[56:59], v187
	ds_read_b128 v[60:63], v187 offset:1024
	ds_read_b128 v[64:67], v187 offset:2048
	ds_read_b128 v[68:71], v187 offset:3072
	ds_read_b128 v[100:103], v188
	ds_read_b128 v[104:107], v188 offset:1024
	ds_read_b128 v[108:111], v188 offset:2048
	ds_read_b128 v[112:115], v188 offset:3072
	s_add_u32 s20, s18, 0xfffc0080
	s_addc_u32 s21, s19, -1
	s_cmp_eq_u32 s74, 12
	s_cselect_b32 s55, s15, s21
	s_cselect_b32 s54, s17, s20
	s_cselect_b32 s21, s47, s57
	s_cselect_b32 s20, s49, s56
	v_lshl_add_u64 v[184:185], s[18:19], 0, v[178:179]
	s_add_i32 m0, s41, 0xc000
	ds_read_b128 v[160:163], v189
	ds_read_b128 v[164:167], v189 offset:1024
	ds_read_b128 v[190:193], v189 offset:2048
	ds_read_b128 v[194:197], v189 offset:3072
	ds_read_b128 v[198:201], v189 offset:4096
	ds_read_b128 v[202:205], v189 offset:5120
	ds_read_b128 v[206:209], v189 offset:6144
	ds_read_b128 v[210:213], v189 offset:7168
	global_load_lds_dwordx4 v[184:185], off
	v_lshl_add_u64 v[184:185], s[18:19], 0, v[176:177]
	s_add_i32 m0, s41, 0xe000
	s_nop 0
	global_load_lds_dwordx4 v[184:185], off
	v_lshl_add_u64 v[230:231], s[20:21], 0, v[170:171]
	s_add_u32 s76, s20, 0x40000
	v_lshl_add_u64 v[232:233], s[20:21], 0, v[174:175]
	s_addc_u32 s77, s21, 0
	v_lshl_add_u64 v[234:235], s[76:77], 0, v[170:171]
	v_lshl_add_u64 v[236:237], s[54:55], 0, v[172:173]
	v_lshl_add_u64 v[238:239], s[76:77], 0, v[174:175]
	v_lshl_add_u64 v[240:241], s[54:55], 0, v[168:169]
	s_waitcnt vmcnt(8)
	s_waitcnt lgkmcnt(0)
	s_barrier
	s_setprio 1
	s_waitcnt lgkmcnt(0)
	v_mfma_f32_16x16x32_bf16 v[148:151], v[56:59], v[160:163], v[148:151]
	v_mfma_f32_16x16x32_bf16 v[116:119], v[64:67], v[160:163], v[116:119]
	v_mfma_f32_16x16x32_bf16 v[152:155], v[56:59], v[190:193], v[152:155]
	v_mfma_f32_16x16x32_bf16 v[120:123], v[64:67], v[190:193], v[120:123]
	v_mfma_f32_16x16x32_bf16 v[140:143], v[56:59], v[198:201], v[140:143]
	v_mfma_f32_16x16x32_bf16 v[92:95], v[64:67], v[198:201], v[92:95]
	v_mfma_f32_16x16x32_bf16 v[128:131], v[56:59], v[206:209], v[128:131]
	v_mfma_f32_16x16x32_bf16 v[80:83], v[64:67], v[206:209], v[80:83]
	v_mfma_f32_16x16x32_bf16 v[148:151], v[60:63], v[164:167], v[148:151]
	v_mfma_f32_16x16x32_bf16 v[116:119], v[68:71], v[164:167], v[116:119]
	v_mfma_f32_16x16x32_bf16 v[152:155], v[60:63], v[194:197], v[152:155]
	v_mfma_f32_16x16x32_bf16 v[120:123], v[68:71], v[194:197], v[120:123]
	v_mfma_f32_16x16x32_bf16 v[140:143], v[60:63], v[202:205], v[140:143]
	v_mfma_f32_16x16x32_bf16 v[92:95], v[68:71], v[202:205], v[92:95]
	v_mfma_f32_16x16x32_bf16 v[128:131], v[60:63], v[210:213], v[128:131]
	v_mfma_f32_16x16x32_bf16 v[80:83], v[68:71], v[210:213], v[80:83]
	s_setprio 0
	s_setprio 1
	v_mfma_f32_16x16x32_bf16 v[156:159], v[100:103], v[160:163], v[156:159]
	v_mfma_f32_16x16x32_bf16 v[124:127], v[108:111], v[160:163], v[124:127]
	v_mfma_f32_16x16x32_bf16 v[144:147], v[100:103], v[190:193], v[144:147]
	v_mfma_f32_16x16x32_bf16 v[96:99], v[108:111], v[190:193], v[96:99]
	v_mfma_f32_16x16x32_bf16 v[136:139], v[100:103], v[198:201], v[136:139]
	v_mfma_f32_16x16x32_bf16 v[88:91], v[108:111], v[198:201], v[88:91]
	v_mfma_f32_16x16x32_bf16 v[132:135], v[100:103], v[206:209], v[132:135]
	v_mfma_f32_16x16x32_bf16 v[84:87], v[108:111], v[206:209], v[84:87]
	v_mfma_f32_16x16x32_bf16 v[156:159], v[104:107], v[164:167], v[156:159]
	v_mfma_f32_16x16x32_bf16 v[124:127], v[112:115], v[164:167], v[124:127]
	v_mfma_f32_16x16x32_bf16 v[144:147], v[104:107], v[194:197], v[144:147]
	v_mfma_f32_16x16x32_bf16 v[96:99], v[112:115], v[194:197], v[96:99]
	v_mfma_f32_16x16x32_bf16 v[136:139], v[104:107], v[202:205], v[136:139]
	v_mfma_f32_16x16x32_bf16 v[88:91], v[112:115], v[202:205], v[88:91]
	v_mfma_f32_16x16x32_bf16 v[132:135], v[104:107], v[210:213], v[132:135]
	v_mfma_f32_16x16x32_bf16 v[84:87], v[112:115], v[210:213], v[84:87]
	s_setprio 0
	s_barrier
	s_add_i32 s75, s71, s33
	s_mov_b32 m0, s75
	ds_read_b128 v[160:163], v189 offset:16384
	ds_read_b128 v[164:167], v189 offset:17408
	ds_read_b128 v[190:193], v189 offset:18432
	ds_read_b128 v[194:197], v189 offset:19456
	ds_read_b128 v[198:201], v189 offset:20480
	ds_read_b128 v[202:205], v189 offset:21504
	ds_read_b128 v[206:209], v189 offset:22528
	ds_read_b128 v[210:213], v189 offset:23552
	global_load_lds_dwordx4 v[230:231], off
	s_add_i32 m0, s75, 0x2000
	s_add_i32 s75, s72, s33
	global_load_lds_dwordx4 v[232:233], off
	s_mov_b32 m0, s75
	s_nop 0
	global_load_lds_dwordx4 v[234:235], off
	s_add_i32 m0, s75, 0x2000
	s_nop 0
	global_load_lds_dwordx4 v[238:239], off
	s_mov_b32 m0, s41
	s_nop 0
	global_load_lds_dwordx4 v[240:241], off
	s_mov_b32 m0, s43
	s_nop 0
	global_load_lds_dwordx4 v[236:237], off
	s_waitcnt vmcnt(8)
	s_waitcnt lgkmcnt(0)
	s_barrier
; #define PG8_STAGE(bufoff, gbase, voff) do { _Pragma("unroll") for (int _i = 0; _i < 2; ++_i) \
;         __builtin_amdgcn_global_load_lds((const unsigned*)((const char*)(gbase) + (voff)[_i]), (PG8_LAS unsigned*)(lds + (bufoff) + ldsw + _i * 8192), 16, 0, 0); } while (0)
; #define PG8_LDA(dst, b, h) do { _Pragma("unroll") for (int m = 0; m < 4; ++m) _Pragma("unroll") for (int k = 0; k < 2; ++k) dst[m][k] = *(const PG8_LAS bf16x8*)(lds + PG8_SA(b, h) + aoff + m * 2048 + k * 1024); } while (0)
; #define PG8_LDB(dst, b, h) do { _Pragma("unroll") for (int n = 0; n < 2; ++n) _Pragma("unroll") for (int k = 0; k < 2; ++k) dst[n][k] = *(const PG8_LAS bf16x8*)(lds + PG8_SB(b, h) + boff + n * 2048 + k * 1024); } while (0)
; #define PG8_MMA(ai, bj, At, Bt) do { __builtin_amdgcn_s_setprio(1); _Pragma("unroll") for (int m = 0; m < 4; ++m) _Pragma("unroll") for (int n = 0; n < 2; ++n) _Pragma("unroll") for (int k = 0; k < 2; ++k) \
;         acc[ai][bj][m][n] = __builtin_amdgcn_mfma_f32_16x16x32_bf16(Bt[n][k], At[m][k], acc[ai][bj][m][n], 0, 0, 0); __builtin_amdgcn_s_setprio(0); } while (0)
; #define PG8_WAIT_V(n) asm volatile("s_waitcnt vmcnt(" #n ")" ::: "memory")
; #define PG8_WAIT_L(n) asm volatile("s_waitcnt lgkmcnt(" #n ")" ::: "memory")
; #define PG8_BAR __builtin_amdgcn_s_barrier()
; #define PG8_SCHED __builtin_amdgcn_sched_barrier(0)
; template <class Epi, class Sched, bool ALIGN_EPI = false, bool SP2 = false>
; __device__ __forceinline__ void gemm_phase(PG8_LAS unsigned char* lds, const Gemm g, const Sched& S, const Epi& E, const int wave_s) {
;     ...
;             PG8_WAIT_V(8); PG8_WAIT_L(0); PG8_BAR; PG8_MMA(1, 0, At, B0); PG8_MMA(1, 1, At, B1); PG8_BAR; PG8_SCHED;
;             PG8_LDB(B0, 1, 0); PG8_LDB(B1, 1, 1); PG8_SCHED; PG8_LDA(At, 1, 0); PG8_STAGE(PG8_SA(0, 1), a2 + hstep, voffA);
;             PG8_WAIT_V(8); PG8_WAIT_L(0); PG8_BAR; PG8_MMA(0, 0, At, B0); PG8_MMA(0, 1, At, B1); PG8_BAR; PG8_SCHED;
;             PG8_LDA(At, 1, 1); PG8_STAGE(PG8_SB(1, 0), b3, voffB); PG8_STAGE(PG8_SB(1, 1), b3 + hstep, voffB); PG8_STAGE(PG8_SA(1, 0), a3, voffA);
	s_setprio 1
	s_waitcnt lgkmcnt(0)
	v_mfma_f32_16x16x32_bf16 v[76:79], v[56:59], v[160:163], v[76:79]
	v_mfma_f32_16x16x32_bf16 v[24:27], v[64:67], v[160:163], v[24:27]
	v_mfma_f32_16x16x32_bf16 v[52:55], v[56:59], v[190:193], v[52:55]
	v_mfma_f32_16x16x32_bf16 v[20:23], v[64:67], v[190:193], v[20:23]
	v_mfma_f32_16x16x32_bf16 v[44:47], v[56:59], v[198:201], v[44:47]
	v_mfma_f32_16x16x32_bf16 v[12:15], v[64:67], v[198:201], v[12:15]
	v_mfma_f32_16x16x32_bf16 v[36:39], v[56:59], v[206:209], v[36:39]
	v_mfma_f32_16x16x32_bf16 v[0:3], v[64:67], v[206:209], v[0:3]
	v_mfma_f32_16x16x32_bf16 v[76:79], v[60:63], v[164:167], v[76:79]
	v_mfma_f32_16x16x32_bf16 v[24:27], v[68:71], v[164:167], v[24:27]
	v_mfma_f32_16x16x32_bf16 v[52:55], v[60:63], v[194:197], v[52:55]
	v_mfma_f32_16x16x32_bf16 v[20:23], v[68:71], v[194:197], v[20:23]
	v_mfma_f32_16x16x32_bf16 v[44:47], v[60:63], v[202:205], v[44:47]
	v_mfma_f32_16x16x32_bf16 v[12:15], v[68:71], v[202:205], v[12:15]
	v_mfma_f32_16x16x32_bf16 v[36:39], v[60:63], v[210:213], v[36:39]
	v_mfma_f32_16x16x32_bf16 v[0:3], v[68:71], v[210:213], v[0:3]
	s_setprio 0
	s_setprio 1
	v_mfma_f32_16x16x32_bf16 v[28:31], v[108:111], v[160:163], v[28:31]
	v_mfma_f32_16x16x32_bf16 v[48:51], v[100:103], v[190:193], v[48:51]
	v_mfma_f32_16x16x32_bf16 v[16:19], v[108:111], v[190:193], v[16:19]
	v_mfma_f32_16x16x32_bf16 v[40:43], v[100:103], v[198:201], v[40:43]
	v_mfma_f32_16x16x32_bf16 v[8:11], v[108:111], v[198:201], v[8:11]
	v_mfma_f32_16x16x32_bf16 v[32:35], v[100:103], v[206:209], v[32:35]
	v_mfma_f32_16x16x32_bf16 v[4:7], v[108:111], v[206:209], v[4:7]
	v_mfma_f32_16x16x32_bf16 v[56:59], v[100:103], v[160:163], v[72:75]
	v_mfma_f32_16x16x32_bf16 v[28:31], v[112:115], v[164:167], v[28:31]
	v_mfma_f32_16x16x32_bf16 v[48:51], v[104:107], v[194:197], v[48:51]
	v_mfma_f32_16x16x32_bf16 v[16:19], v[112:115], v[194:197], v[16:19]
	v_mfma_f32_16x16x32_bf16 v[40:43], v[104:107], v[202:205], v[40:43]
	v_mfma_f32_16x16x32_bf16 v[8:11], v[112:115], v[202:205], v[8:11]
	v_mfma_f32_16x16x32_bf16 v[32:35], v[104:107], v[210:213], v[32:35]
	v_mfma_f32_16x16x32_bf16 v[4:7], v[112:115], v[210:213], v[4:7]
	v_mfma_f32_16x16x32_bf16 v[56:59], v[104:107], v[164:167], v[56:59]
	s_setprio 0
	s_barrier
	s_add_i32 s75, 0, 0x18000
	s_add_i32 s76, 0, 0x1c000
	v_add_u32_e32 v72, s75, v186
	v_add_u32_e32 v112, s76, v186
	ds_read_b128 v[60:63], v72
	ds_read_b128 v[64:67], v72 offset:1024
	ds_read_b128 v[68:71], v72 offset:2048
	ds_read_b128 v[72:75], v72 offset:3072
	ds_read_b128 v[100:103], v112
	ds_read_b128 v[104:107], v112 offset:1024
	ds_read_b128 v[108:111], v112 offset:2048
	ds_read_b128 v[112:115], v112 offset:3072
	s_add_u32 s54, s54, 0x40000
	s_addc_u32 s55, s55, 0
	s_mov_b32 m0, s45
	v_lshl_add_u64 v[220:221], s[54:55], 0, v[168:169]
	ds_read_b128 v[160:163], v189 offset:32768
	ds_read_b128 v[164:167], v189 offset:33792
	ds_read_b128 v[190:193], v189 offset:34816
	ds_read_b128 v[194:197], v189 offset:35840
	ds_read_b128 v[198:201], v189 offset:36864
	ds_read_b128 v[202:205], v189 offset:37888
	ds_read_b128 v[206:209], v189 offset:38912
	ds_read_b128 v[210:213], v189 offset:39936
	global_load_lds_dwordx4 v[220:221], off
	v_lshl_add_u64 v[220:221], s[54:55], 0, v[172:173]
	s_mov_b32 m0, s58
	s_nop 0
	global_load_lds_dwordx4 v[220:221], off
	v_lshl_add_u64 v[242:243], v[230:231], 0, s[12:13]
	s_add_u32 s20, s20, 0x40080
	v_lshl_add_u64 v[244:245], v[232:233], 0, s[12:13]
	s_addc_u32 s21, s21, 0
	v_lshl_add_u64 v[246:247], s[20:21], 0, v[170:171]
	v_lshl_add_u64 v[248:249], s[20:21], 0, v[174:175]
	v_lshl_add_u64 v[250:251], v[240:241], 0, s[12:13]
	v_lshl_add_u64 v[252:253], v[236:237], 0, s[12:13]
	s_waitcnt vmcnt(8)
	s_waitcnt lgkmcnt(0)
	s_barrier
; #define PG8_STAGE(bufoff, gbase, voff) do { _Pragma("unroll") for (int _i = 0; _i < 2; ++_i) \
;         __builtin_amdgcn_global_load_lds((const unsigned*)((const char*)(gbase) + (voff)[_i]), (PG8_LAS unsigned*)(lds + (bufoff) + ldsw + _i * 8192), 16, 0, 0); } while (0)
; #define PG8_LDA(dst, b, h) do { _Pragma("unroll") for (int m = 0; m < 4; ++m) _Pragma("unroll") for (int k = 0; k < 2; ++k) dst[m][k] = *(const PG8_LAS bf16x8*)(lds + PG8_SA(b, h) + aoff + m * 2048 + k * 1024); } while (0)
; #define PG8_MMA(ai, bj, At, Bt) do { __builtin_amdgcn_s_setprio(1); _Pragma("unroll") for (int m = 0; m < 4; ++m) _Pragma("unroll") for (int n = 0; n < 2; ++n) _Pragma("unroll") for (int k = 0; k < 2; ++k) \
;         acc[ai][bj][m][n] = __builtin_amdgcn_mfma_f32_16x16x32_bf16(Bt[n][k], At[m][k], acc[ai][bj][m][n], 0, 0, 0); __builtin_amdgcn_s_setprio(0); } while (0)
; #define PG8_WAIT_V(n) asm volatile("s_waitcnt vmcnt(" #n ")" ::: "memory")
; #define PG8_WAIT_L(n) asm volatile("s_waitcnt lgkmcnt(" #n ")" ::: "memory")
; #define PG8_BAR __builtin_amdgcn_s_barrier()
; #define PG8_SCHED __builtin_amdgcn_sched_barrier(0)
; template <class Epi, class Sched, bool ALIGN_EPI = false, bool SP2 = false>
; __device__ __forceinline__ void gemm_phase(PG8_LAS unsigned char* lds, const Gemm g, const Sched& S, const Epi& E, const int wave_s) {
;     ...
;             PG8_WAIT_V(8); PG8_WAIT_L(0); PG8_BAR; PG8_MMA(0, 0, At, B0); PG8_MMA(0, 1, At, B1); PG8_BAR; PG8_SCHED;
;             PG8_LDA(At, 1, 1); PG8_STAGE(PG8_SB(1, 0), b3, voffB); PG8_STAGE(PG8_SB(1, 1), b3 + hstep, voffB); PG8_STAGE(PG8_SA(1, 0), a3, voffA);
;             PG8_WAIT_V(8); PG8_WAIT_L(0); PG8_BAR; PG8_MMA(1, 0, At, B0); PG8_MMA(1, 1, At, B1); PG8_BAR; PG8_SCHED;
	s_setprio 1
	s_waitcnt lgkmcnt(0)
	v_mfma_f32_16x16x32_bf16 v[148:151], v[60:63], v[160:163], v[148:151]
	v_mfma_f32_16x16x32_bf16 v[116:119], v[68:71], v[160:163], v[116:119]
	v_mfma_f32_16x16x32_bf16 v[152:155], v[60:63], v[190:193], v[152:155]
	v_mfma_f32_16x16x32_bf16 v[120:123], v[68:71], v[190:193], v[120:123]
	v_mfma_f32_16x16x32_bf16 v[140:143], v[60:63], v[198:201], v[140:143]
	v_mfma_f32_16x16x32_bf16 v[92:95], v[68:71], v[198:201], v[92:95]
	v_mfma_f32_16x16x32_bf16 v[128:131], v[60:63], v[206:209], v[128:131]
	v_mfma_f32_16x16x32_bf16 v[80:83], v[68:71], v[206:209], v[80:83]
	v_mfma_f32_16x16x32_bf16 v[148:151], v[64:67], v[164:167], v[148:151]
	v_mfma_f32_16x16x32_bf16 v[116:119], v[72:75], v[164:167], v[116:119]
	v_mfma_f32_16x16x32_bf16 v[152:155], v[64:67], v[194:197], v[152:155]
	v_mfma_f32_16x16x32_bf16 v[120:123], v[72:75], v[194:197], v[120:123]
	v_mfma_f32_16x16x32_bf16 v[140:143], v[64:67], v[202:205], v[140:143]
	v_mfma_f32_16x16x32_bf16 v[92:95], v[72:75], v[202:205], v[92:95]
	v_mfma_f32_16x16x32_bf16 v[128:131], v[64:67], v[210:213], v[128:131]
	v_mfma_f32_16x16x32_bf16 v[80:83], v[72:75], v[210:213], v[80:83]
	s_setprio 0
	s_setprio 1
	v_mfma_f32_16x16x32_bf16 v[156:159], v[100:103], v[160:163], v[156:159]
	v_mfma_f32_16x16x32_bf16 v[124:127], v[108:111], v[160:163], v[124:127]
	v_mfma_f32_16x16x32_bf16 v[144:147], v[100:103], v[190:193], v[144:147]
	v_mfma_f32_16x16x32_bf16 v[96:99], v[108:111], v[190:193], v[96:99]
	v_mfma_f32_16x16x32_bf16 v[136:139], v[100:103], v[198:201], v[136:139]
	v_mfma_f32_16x16x32_bf16 v[88:91], v[108:111], v[198:201], v[88:91]
	v_mfma_f32_16x16x32_bf16 v[132:135], v[100:103], v[206:209], v[132:135]
	v_mfma_f32_16x16x32_bf16 v[84:87], v[108:111], v[206:209], v[84:87]
	v_mfma_f32_16x16x32_bf16 v[156:159], v[104:107], v[164:167], v[156:159]
	v_mfma_f32_16x16x32_bf16 v[124:127], v[112:115], v[164:167], v[124:127]
	v_mfma_f32_16x16x32_bf16 v[144:147], v[104:107], v[194:197], v[144:147]
	v_mfma_f32_16x16x32_bf16 v[96:99], v[112:115], v[194:197], v[96:99]
	v_mfma_f32_16x16x32_bf16 v[136:139], v[104:107], v[202:205], v[136:139]
	v_mfma_f32_16x16x32_bf16 v[88:91], v[112:115], v[202:205], v[88:91]
	v_mfma_f32_16x16x32_bf16 v[132:135], v[104:107], v[210:213], v[132:135]
	v_mfma_f32_16x16x32_bf16 v[84:87], v[112:115], v[210:213], v[84:87]
	s_setprio 0
	s_barrier
	s_add_i32 s54, s75, s33
	s_mov_b32 m0, s54
	ds_read_b128 v[160:163], v189 offset:49152
	ds_read_b128 v[164:167], v189 offset:50176
	ds_read_b128 v[190:193], v189 offset:51200
	ds_read_b128 v[194:197], v189 offset:52224
	ds_read_b128 v[198:201], v189 offset:53248
	ds_read_b128 v[202:205], v189 offset:54272
	ds_read_b128 v[206:209], v189 offset:55296
	ds_read_b128 v[210:213], v189 offset:56320
	global_load_lds_dwordx4 v[242:243], off
	s_add_i32 m0, s54, 0x2000
	s_add_i32 s54, s76, s33
	global_load_lds_dwordx4 v[244:245], off
	s_mov_b32 m0, s54
	s_nop 0
	global_load_lds_dwordx4 v[246:247], off
	s_add_i32 m0, s54, 0x2000
	s_nop 0
	global_load_lds_dwordx4 v[248:249], off
	s_mov_b32 m0, s60
	s_nop 0
	global_load_lds_dwordx4 v[250:251], off
	s_mov_b32 m0, s61
	s_nop 0
	global_load_lds_dwordx4 v[252:253], off
	s_waitcnt vmcnt(8)
	s_waitcnt lgkmcnt(0)
	s_barrier
	s_setprio 1
	s_waitcnt lgkmcnt(0)
	v_mfma_f32_16x16x32_bf16 v[76:79], v[60:63], v[160:163], v[76:79]
	v_mfma_f32_16x16x32_bf16 v[24:27], v[68:71], v[160:163], v[24:27]
	v_mfma_f32_16x16x32_bf16 v[52:55], v[60:63], v[190:193], v[52:55]
	v_mfma_f32_16x16x32_bf16 v[20:23], v[68:71], v[190:193], v[20:23]
	v_mfma_f32_16x16x32_bf16 v[44:47], v[60:63], v[198:201], v[44:47]
	v_mfma_f32_16x16x32_bf16 v[12:15], v[68:71], v[198:201], v[12:15]
	v_mfma_f32_16x16x32_bf16 v[36:39], v[60:63], v[206:209], v[36:39]
	v_mfma_f32_16x16x32_bf16 v[0:3], v[68:71], v[206:209], v[0:3]
	v_mfma_f32_16x16x32_bf16 v[76:79], v[64:67], v[164:167], v[76:79]
	v_mfma_f32_16x16x32_bf16 v[24:27], v[72:75], v[164:167], v[24:27]
	v_mfma_f32_16x16x32_bf16 v[52:55], v[64:67], v[194:197], v[52:55]
	v_mfma_f32_16x16x32_bf16 v[20:23], v[72:75], v[194:197], v[20:23]
	v_mfma_f32_16x16x32_bf16 v[44:47], v[64:67], v[202:205], v[44:47]
	v_mfma_f32_16x16x32_bf16 v[12:15], v[72:75], v[202:205], v[12:15]
	v_mfma_f32_16x16x32_bf16 v[36:39], v[64:67], v[210:213], v[36:39]
	v_mfma_f32_16x16x32_bf16 v[0:3], v[72:75], v[210:213], v[0:3]
	s_setprio 0
	s_setprio 1
	v_mfma_f32_16x16x32_bf16 v[56:59], v[100:103], v[160:163], v[56:59]
	v_mfma_f32_16x16x32_bf16 v[28:31], v[108:111], v[160:163], v[28:31]
	v_mfma_f32_16x16x32_bf16 v[48:51], v[100:103], v[190:193], v[48:51]
	v_mfma_f32_16x16x32_bf16 v[16:19], v[108:111], v[190:193], v[16:19]
	v_mfma_f32_16x16x32_bf16 v[40:43], v[100:103], v[198:201], v[40:43]
	v_mfma_f32_16x16x32_bf16 v[8:11], v[108:111], v[198:201], v[8:11]
	v_mfma_f32_16x16x32_bf16 v[32:35], v[100:103], v[206:209], v[32:35]
	v_mfma_f32_16x16x32_bf16 v[4:7], v[108:111], v[206:209], v[4:7]
	v_mfma_f32_16x16x32_bf16 v[72:75], v[104:107], v[164:167], v[56:59]
	v_mfma_f32_16x16x32_bf16 v[28:31], v[112:115], v[164:167], v[28:31]
	v_mfma_f32_16x16x32_bf16 v[48:51], v[104:107], v[194:197], v[48:51]
	v_mfma_f32_16x16x32_bf16 v[16:19], v[112:115], v[194:197], v[16:19]
	v_mfma_f32_16x16x32_bf16 v[40:43], v[104:107], v[202:205], v[40:43]
	v_mfma_f32_16x16x32_bf16 v[8:11], v[112:115], v[202:205], v[8:11]
	v_mfma_f32_16x16x32_bf16 v[32:35], v[104:107], v[210:213], v[32:35]
	v_mfma_f32_16x16x32_bf16 v[4:7], v[112:115], v[210:213], v[4:7]
	s_setprio 0
	s_barrier
	s_add_i32 s74, s74, 2
	s_add_u32 s56, s56, 0x100
	s_addc_u32 s57, s57, 0
	s_add_u32 s18, s18, 0x100
	s_addc_u32 s19, s19, 0
	s_cmp_gt_u32 s74, 13
	s_cbranch_scc0 .LBB0_2236
	s_and_b64 vcc, exec, s[22:23]
	s_cbranch_vccz .LBB0_2239
	s_barrier

; #define PG8_STAGE(bufoff, gbase, voff) do { _Pragma("unroll") for (int _i = 0; _i < 2; ++_i) \
;         __builtin_amdgcn_global_load_lds((const unsigned*)((const char*)(gbase) + (voff)[_i]), (PG8_LAS unsigned*)(lds + (bufoff) + ldsw + _i * 8192), 16, 0, 0); } while (0)
; #define PG8_LDA(dst, b, h) do { _Pragma("unroll") for (int m = 0; m < 4; ++m) _Pragma("unroll") for (int k = 0; k < 2; ++k) dst[m][k] = *(const PG8_LAS bf16x8*)(lds + PG8_SA(b, h) + aoff + m * 2048 + k * 1024); } while (0)
; #define PG8_LDB(dst, b, h) do { _Pragma("unroll") for (int n = 0; n < 2; ++n) _Pragma("unroll") for (int k = 0; k < 2; ++k) dst[n][k] = *(const PG8_LAS bf16x8*)(lds + PG8_SB(b, h) + boff + n * 2048 + k * 1024); } while (0)
; #define PG8_MMA(ai, bj, At, Bt) do { __builtin_amdgcn_s_setprio(1); _Pragma("unroll") for (int m = 0; m < 4; ++m) _Pragma("unroll") for (int n = 0; n < 2; ++n) _Pragma("unroll") for (int k = 0; k < 2; ++k) \
;         acc[ai][bj][m][n] = __builtin_amdgcn_mfma_f32_16x16x32_bf16(Bt[n][k], At[m][k], acc[ai][bj][m][n], 0, 0, 0); __builtin_amdgcn_s_setprio(0); } while (0)
; #define PG8_WAIT_V(n) asm volatile("s_waitcnt vmcnt(" #n ")" ::: "memory")
; #define PG8_WAIT_L(n) asm volatile("s_waitcnt lgkmcnt(" #n ")" ::: "memory")
; #define PG8_BAR __builtin_amdgcn_s_barrier()
; #define PG8_SCHED __builtin_amdgcn_sched_barrier(0)
; template <class Epi, class Sched, bool ALIGN_EPI = false, bool SP2 = false>
; __device__ __forceinline__ void gemm_phase(PG8_LAS unsigned char* lds, const Gemm g, const Sched& S, const Epi& E, const int wave_s) {
;     ...
;             const bool last = (t == nt - 2);
;             const char* a1 = cA + (size_t)(t + 1) * kstep;
;             const char* a2 = last ? nA : cA + (size_t)(t + 2) * kstep; const char* b2 = last ? nB : cB + (size_t)(t + 2) * kstep;
;             const char* a3 = a2 + kstep; const char* b3 = b2 + kstep;
;             if (last && has_next) S.a_ready(nxt);
;             if constexpr (SP2) {
;             PG8_LDB(B0, 0, 0); PG8_LDB(B1, 0, 1); PG8_SCHED; PG8_LDA(At, 0, 0); PG8_STAGE(PG8_SA(1, 1), a1 + hstep, voffA);
;             PG8_WAIT_V(8); PG8_WAIT_L(0); PG8_BAR; PG8_MMA(0, 0, At, B0); PG8_MMA(0, 1, At, B1); PG8_BAR; PG8_SCHED;
;             PG8_LDA(At, 0, 1); PG8_STAGE(PG8_SB(0, 0), b2, voffB); PG8_STAGE(PG8_SB(0, 1), b2 + hstep, voffB); PG8_STAGE(PG8_SA(0, 0), a2, voffA);
.LBB0_2472:
	ds_read_b128 v[144:147], v149
	ds_read_b128 v[152:155], v149 offset:1024
	ds_read_b128 v[156:159], v149 offset:2048
	ds_read_b128 v[160:163], v149 offset:3072
	ds_read_b128 v[164:167], v150
	ds_read_b128 v[168:171], v150 offset:1024
	ds_read_b128 v[172:175], v150 offset:2048
	ds_read_b128 v[176:179], v150 offset:3072
	s_add_u32 s26, s24, 0xfffc0080
	s_addc_u32 s27, s25, -1
	s_cmp_eq_u32 s54, 12
	s_cselect_b32 s29, s17, s27
	s_cselect_b32 s28, s23, s26
	s_cselect_b32 s27, s15, s53
	s_cselect_b32 s26, s51, s52
	v_lshl_add_u64 v[212:213], s[24:25], 0, v[138:139]
	s_add_i32 m0, s38, 0xc000
	ds_read_b128 v[180:183], v151
	ds_read_b128 v[184:187], v151 offset:1024
	ds_read_b128 v[188:191], v151 offset:2048
	ds_read_b128 v[192:195], v151 offset:3072
	ds_read_b128 v[196:199], v151 offset:4096
	ds_read_b128 v[200:203], v151 offset:5120
	ds_read_b128 v[204:207], v151 offset:6144
	ds_read_b128 v[208:211], v151 offset:7168
	global_load_lds_dwordx4 v[212:213], off
	v_lshl_add_u64 v[212:213], s[24:25], 0, v[136:137]
	s_add_i32 m0, s38, 0xe000
	s_nop 0
	global_load_lds_dwordx4 v[212:213], off
	v_lshl_add_u64 v[230:231], s[26:27], 0, v[132:133]
	s_add_u32 s56, s26, 0x40000
	v_lshl_add_u64 v[232:233], s[26:27], 0, v[128:129]
	s_addc_u32 s57, s27, 0
	v_lshl_add_u64 v[234:235], s[56:57], 0, v[132:133]
	v_lshl_add_u64 v[236:237], s[28:29], 0, v[130:131]
	v_lshl_add_u64 v[238:239], s[56:57], 0, v[128:129]
	v_lshl_add_u64 v[240:241], s[28:29], 0, v[134:135]
	s_waitcnt vmcnt(8)
	s_waitcnt lgkmcnt(0)
	s_barrier
	s_setprio 1
	s_waitcnt lgkmcnt(0)
	v_mfma_f32_16x16x32_bf16 v[124:127], v[144:147], v[180:183], v[124:127]
	v_mfma_f32_16x16x32_bf16 v[120:123], v[156:159], v[180:183], v[120:123]
	v_mfma_f32_16x16x32_bf16 v[112:115], v[144:147], v[188:191], v[112:115]
	v_mfma_f32_16x16x32_bf16 v[104:107], v[156:159], v[188:191], v[104:107]
	v_mfma_f32_16x16x32_bf16 v[96:99], v[144:147], v[196:199], v[96:99]
	v_mfma_f32_16x16x32_bf16 v[88:91], v[156:159], v[196:199], v[88:91]
	v_mfma_f32_16x16x32_bf16 v[80:83], v[144:147], v[204:207], v[80:83]
	v_mfma_f32_16x16x32_bf16 v[72:75], v[156:159], v[204:207], v[72:75]
	v_mfma_f32_16x16x32_bf16 v[124:127], v[152:155], v[184:187], v[124:127]
	v_mfma_f32_16x16x32_bf16 v[120:123], v[160:163], v[184:187], v[120:123]
	v_mfma_f32_16x16x32_bf16 v[112:115], v[152:155], v[192:195], v[112:115]
	v_mfma_f32_16x16x32_bf16 v[104:107], v[160:163], v[192:195], v[104:107]
	v_mfma_f32_16x16x32_bf16 v[96:99], v[152:155], v[200:203], v[96:99]
	v_mfma_f32_16x16x32_bf16 v[88:91], v[160:163], v[200:203], v[88:91]
	v_mfma_f32_16x16x32_bf16 v[80:83], v[152:155], v[208:211], v[80:83]
	v_mfma_f32_16x16x32_bf16 v[72:75], v[160:163], v[208:211], v[72:75]
	s_setprio 0
	s_setprio 1
	v_mfma_f32_16x16x32_bf16 v[116:119], v[164:167], v[180:183], v[116:119]
	v_mfma_f32_16x16x32_bf16 v[108:111], v[172:175], v[180:183], v[108:111]
	v_mfma_f32_16x16x32_bf16 v[100:103], v[164:167], v[188:191], v[100:103]
	v_mfma_f32_16x16x32_bf16 v[92:95], v[172:175], v[188:191], v[92:95]
	v_mfma_f32_16x16x32_bf16 v[84:87], v[164:167], v[196:199], v[84:87]
	v_mfma_f32_16x16x32_bf16 v[76:79], v[172:175], v[196:199], v[76:79]
	v_mfma_f32_16x16x32_bf16 v[68:71], v[164:167], v[204:207], v[68:71]
	v_mfma_f32_16x16x32_bf16 v[64:67], v[172:175], v[204:207], v[64:67]
	v_mfma_f32_16x16x32_bf16 v[116:119], v[168:171], v[184:187], v[116:119]
	v_mfma_f32_16x16x32_bf16 v[108:111], v[176:179], v[184:187], v[108:111]
	v_mfma_f32_16x16x32_bf16 v[100:103], v[168:171], v[192:195], v[100:103]
	v_mfma_f32_16x16x32_bf16 v[92:95], v[176:179], v[192:195], v[92:95]
	v_mfma_f32_16x16x32_bf16 v[84:87], v[168:171], v[200:203], v[84:87]
	v_mfma_f32_16x16x32_bf16 v[76:79], v[176:179], v[200:203], v[76:79]
	v_mfma_f32_16x16x32_bf16 v[68:71], v[168:171], v[208:211], v[68:71]
	v_mfma_f32_16x16x32_bf16 v[64:67], v[176:179], v[208:211], v[64:67]
	s_setprio 0
	s_barrier
	s_add_i32 s55, s48, s33
	s_mov_b32 m0, s55
	ds_read_b128 v[180:183], v151 offset:16384
	ds_read_b128 v[184:187], v151 offset:17408
	ds_read_b128 v[188:191], v151 offset:18432
	ds_read_b128 v[192:195], v151 offset:19456
	ds_read_b128 v[196:199], v151 offset:20480
	ds_read_b128 v[200:203], v151 offset:21504
	ds_read_b128 v[204:207], v151 offset:22528
	ds_read_b128 v[208:211], v151 offset:23552
	global_load_lds_dwordx4 v[230:231], off
	s_add_i32 m0, s55, 0x2000
	s_add_i32 s55, s49, s33
	global_load_lds_dwordx4 v[232:233], off
	s_mov_b32 m0, s55
	s_nop 0
	global_load_lds_dwordx4 v[234:235], off
	s_add_i32 m0, s55, 0x2000
	s_nop 0
	global_load_lds_dwordx4 v[238:239], off
	s_mov_b32 m0, s38
	s_nop 0
	global_load_lds_dwordx4 v[240:241], off
	s_mov_b32 m0, s39
	s_nop 0
	global_load_lds_dwordx4 v[236:237], off
	s_waitcnt vmcnt(8)
	s_waitcnt lgkmcnt(0)
	s_barrier
; #define PG8_STAGE(bufoff, gbase, voff) do { _Pragma("unroll") for (int _i = 0; _i < 2; ++_i) \
;         __builtin_amdgcn_global_load_lds((const unsigned*)((const char*)(gbase) + (voff)[_i]), (PG8_LAS unsigned*)(lds + (bufoff) + ldsw + _i * 8192), 16, 0, 0); } while (0)
; #define PG8_LDA(dst, b, h) do { _Pragma("unroll") for (int m = 0; m < 4; ++m) _Pragma("unroll") for (int k = 0; k < 2; ++k) dst[m][k] = *(const PG8_LAS bf16x8*)(lds + PG8_SA(b, h) + aoff + m * 2048 + k * 1024); } while (0)
; #define PG8_LDB(dst, b, h) do { _Pragma("unroll") for (int n = 0; n < 2; ++n) _Pragma("unroll") for (int k = 0; k < 2; ++k) dst[n][k] = *(const PG8_LAS bf16x8*)(lds + PG8_SB(b, h) + boff + n * 2048 + k * 1024); } while (0)
; #define PG8_MMA(ai, bj, At, Bt) do { __builtin_amdgcn_s_setprio(1); _Pragma("unroll") for (int m = 0; m < 4; ++m) _Pragma("unroll") for (int n = 0; n < 2; ++n) _Pragma("unroll") for (int k = 0; k < 2; ++k) \
;         acc[ai][bj][m][n] = __builtin_amdgcn_mfma_f32_16x16x32_bf16(Bt[n][k], At[m][k], acc[ai][bj][m][n], 0, 0, 0); __builtin_amdgcn_s_setprio(0); } while (0)
; #define PG8_WAIT_V(n) asm volatile("s_waitcnt vmcnt(" #n ")" ::: "memory")
; #define PG8_WAIT_L(n) asm volatile("s_waitcnt lgkmcnt(" #n ")" ::: "memory")
; #define PG8_BAR __builtin_amdgcn_s_barrier()
; #define PG8_SCHED __builtin_amdgcn_sched_barrier(0)
; template <class Epi, class Sched, bool ALIGN_EPI = false, bool SP2 = false>
; __device__ __forceinline__ void gemm_phase(PG8_LAS unsigned char* lds, const Gemm g, const Sched& S, const Epi& E, const int wave_s) {
;     ...
;             PG8_WAIT_V(8); PG8_WAIT_L(0); PG8_BAR; PG8_MMA(1, 0, At, B0); PG8_MMA(1, 1, At, B1); PG8_BAR; PG8_SCHED;
;             PG8_LDB(B0, 1, 0); PG8_LDB(B1, 1, 1); PG8_SCHED; PG8_LDA(At, 1, 0); PG8_STAGE(PG8_SA(0, 1), a2 + hstep, voffA);
;             PG8_WAIT_V(8); PG8_WAIT_L(0); PG8_BAR; PG8_MMA(0, 0, At, B0); PG8_MMA(0, 1, At, B1); PG8_BAR; PG8_SCHED;
	s_setprio 1
	s_waitcnt lgkmcnt(0)
	v_mfma_f32_16x16x32_bf16 v[60:63], v[144:147], v[180:183], v[60:63]
	v_mfma_f32_16x16x32_bf16 v[56:59], v[156:159], v[180:183], v[56:59]
	v_mfma_f32_16x16x32_bf16 v[48:51], v[144:147], v[188:191], v[48:51]
	v_mfma_f32_16x16x32_bf16 v[40:43], v[156:159], v[188:191], v[40:43]
	v_mfma_f32_16x16x32_bf16 v[32:35], v[144:147], v[196:199], v[32:35]
	v_mfma_f32_16x16x32_bf16 v[24:27], v[156:159], v[196:199], v[24:27]
	v_mfma_f32_16x16x32_bf16 v[16:19], v[144:147], v[204:207], v[16:19]
	v_mfma_f32_16x16x32_bf16 v[8:11], v[156:159], v[204:207], v[8:11]
	v_mfma_f32_16x16x32_bf16 v[60:63], v[152:155], v[184:187], v[60:63]
	v_mfma_f32_16x16x32_bf16 v[56:59], v[160:163], v[184:187], v[56:59]
	v_mfma_f32_16x16x32_bf16 v[48:51], v[152:155], v[192:195], v[48:51]
	v_mfma_f32_16x16x32_bf16 v[40:43], v[160:163], v[192:195], v[40:43]
	v_mfma_f32_16x16x32_bf16 v[32:35], v[152:155], v[200:203], v[32:35]
	v_mfma_f32_16x16x32_bf16 v[24:27], v[160:163], v[200:203], v[24:27]
	v_mfma_f32_16x16x32_bf16 v[16:19], v[152:155], v[208:211], v[16:19]
	v_mfma_f32_16x16x32_bf16 v[8:11], v[160:163], v[208:211], v[8:11]
	s_setprio 0
	s_setprio 1
	v_mfma_f32_16x16x32_bf16 v[52:55], v[164:167], v[180:183], v[52:55]
	v_mfma_f32_16x16x32_bf16 v[44:47], v[172:175], v[180:183], v[44:47]
	v_mfma_f32_16x16x32_bf16 v[36:39], v[164:167], v[188:191], v[36:39]
	v_mfma_f32_16x16x32_bf16 v[28:31], v[172:175], v[188:191], v[28:31]
	v_mfma_f32_16x16x32_bf16 v[20:23], v[164:167], v[196:199], v[20:23]
	v_mfma_f32_16x16x32_bf16 v[12:15], v[172:175], v[196:199], v[12:15]
	v_mfma_f32_16x16x32_bf16 v[4:7], v[164:167], v[204:207], v[4:7]
	v_mfma_f32_16x16x32_bf16 v[0:3], v[172:175], v[204:207], v[0:3]
	v_mfma_f32_16x16x32_bf16 v[52:55], v[168:171], v[184:187], v[52:55]
	v_mfma_f32_16x16x32_bf16 v[44:47], v[176:179], v[184:187], v[44:47]
	v_mfma_f32_16x16x32_bf16 v[36:39], v[168:171], v[192:195], v[36:39]
	v_mfma_f32_16x16x32_bf16 v[28:31], v[176:179], v[192:195], v[28:31]
	v_mfma_f32_16x16x32_bf16 v[20:23], v[168:171], v[200:203], v[20:23]
	v_mfma_f32_16x16x32_bf16 v[12:15], v[176:179], v[200:203], v[12:15]
	v_mfma_f32_16x16x32_bf16 v[4:7], v[168:171], v[208:211], v[4:7]
	v_mfma_f32_16x16x32_bf16 v[0:3], v[176:179], v[208:211], v[0:3]
	s_setprio 0
	s_barrier
	s_add_i32 s55, 0, 0x18000
	s_add_i32 s56, 0, 0x1c000
	v_add_u32_e32 v160, s55, v148
	v_add_u32_e32 v176, s56, v148
	ds_read_b128 v[144:147], v160
	ds_read_b128 v[152:155], v160 offset:1024
	ds_read_b128 v[156:159], v160 offset:2048
	ds_read_b128 v[160:163], v160 offset:3072
	ds_read_b128 v[164:167], v176
	ds_read_b128 v[168:171], v176 offset:1024
	ds_read_b128 v[172:175], v176 offset:2048
	ds_read_b128 v[176:179], v176 offset:3072
	s_add_u32 s28, s28, 0x40000
	s_addc_u32 s29, s29, 0
	s_mov_b32 m0, s40
	v_lshl_add_u64 v[220:221], s[28:29], 0, v[134:135]
	ds_read_b128 v[180:183], v151 offset:32768
	ds_read_b128 v[184:187], v151 offset:33792
	ds_read_b128 v[188:191], v151 offset:34816
	ds_read_b128 v[192:195], v151 offset:35840
	ds_read_b128 v[196:199], v151 offset:36864
	ds_read_b128 v[200:203], v151 offset:37888
	ds_read_b128 v[204:207], v151 offset:38912
	ds_read_b128 v[208:211], v151 offset:39936
	global_load_lds_dwordx4 v[220:221], off
	v_lshl_add_u64 v[220:221], s[28:29], 0, v[130:131]
	s_mov_b32 m0, s41
	s_nop 0
	global_load_lds_dwordx4 v[220:221], off
	v_lshl_add_u64 v[242:243], v[230:231], 0, s[10:11]
	s_add_u32 s26, s26, 0x40080
	v_lshl_add_u64 v[244:245], v[232:233], 0, s[10:11]
	s_addc_u32 s27, s27, 0
	v_lshl_add_u64 v[246:247], s[26:27], 0, v[132:133]
	v_lshl_add_u64 v[248:249], s[26:27], 0, v[128:129]
	v_lshl_add_u64 v[250:251], v[240:241], 0, s[10:11]
	v_lshl_add_u64 v[252:253], v[236:237], 0, s[10:11]
	s_waitcnt vmcnt(8)
	s_waitcnt lgkmcnt(0)
	s_barrier
	s_setprio 1
	s_waitcnt lgkmcnt(0)
	v_mfma_f32_16x16x32_bf16 v[124:127], v[144:147], v[180:183], v[124:127]
	v_mfma_f32_16x16x32_bf16 v[120:123], v[156:159], v[180:183], v[120:123]
	v_mfma_f32_16x16x32_bf16 v[112:115], v[144:147], v[188:191], v[112:115]
	v_mfma_f32_16x16x32_bf16 v[104:107], v[156:159], v[188:191], v[104:107]
	v_mfma_f32_16x16x32_bf16 v[96:99], v[144:147], v[196:199], v[96:99]
	v_mfma_f32_16x16x32_bf16 v[88:91], v[156:159], v[196:199], v[88:91]
	v_mfma_f32_16x16x32_bf16 v[80:83], v[144:147], v[204:207], v[80:83]
	v_mfma_f32_16x16x32_bf16 v[72:75], v[156:159], v[204:207], v[72:75]
	v_mfma_f32_16x16x32_bf16 v[124:127], v[152:155], v[184:187], v[124:127]
	v_mfma_f32_16x16x32_bf16 v[120:123], v[160:163], v[184:187], v[120:123]
	v_mfma_f32_16x16x32_bf16 v[112:115], v[152:155], v[192:195], v[112:115]
	v_mfma_f32_16x16x32_bf16 v[104:107], v[160:163], v[192:195], v[104:107]
	v_mfma_f32_16x16x32_bf16 v[96:99], v[152:155], v[200:203], v[96:99]
	v_mfma_f32_16x16x32_bf16 v[88:91], v[160:163], v[200:203], v[88:91]
	v_mfma_f32_16x16x32_bf16 v[80:83], v[152:155], v[208:211], v[80:83]
	v_mfma_f32_16x16x32_bf16 v[72:75], v[160:163], v[208:211], v[72:75]
	s_setprio 0
	s_setprio 1
	v_mfma_f32_16x16x32_bf16 v[116:119], v[164:167], v[180:183], v[116:119]
	v_mfma_f32_16x16x32_bf16 v[108:111], v[172:175], v[180:183], v[108:111]
	v_mfma_f32_16x16x32_bf16 v[100:103], v[164:167], v[188:191], v[100:103]
	v_mfma_f32_16x16x32_bf16 v[92:95], v[172:175], v[188:191], v[92:95]
	v_mfma_f32_16x16x32_bf16 v[84:87], v[164:167], v[196:199], v[84:87]
	v_mfma_f32_16x16x32_bf16 v[76:79], v[172:175], v[196:199], v[76:79]
	v_mfma_f32_16x16x32_bf16 v[68:71], v[164:167], v[204:207], v[68:71]
	v_mfma_f32_16x16x32_bf16 v[64:67], v[172:175], v[204:207], v[64:67]
	v_mfma_f32_16x16x32_bf16 v[116:119], v[168:171], v[184:187], v[116:119]
	v_mfma_f32_16x16x32_bf16 v[108:111], v[176:179], v[184:187], v[108:111]
	v_mfma_f32_16x16x32_bf16 v[100:103], v[168:171], v[192:195], v[100:103]
	v_mfma_f32_16x16x32_bf16 v[92:95], v[176:179], v[192:195], v[92:95]
	v_mfma_f32_16x16x32_bf16 v[84:87], v[168:171], v[200:203], v[84:87]
	v_mfma_f32_16x16x32_bf16 v[76:79], v[176:179], v[200:203], v[76:79]
	v_mfma_f32_16x16x32_bf16 v[68:71], v[168:171], v[208:211], v[68:71]
	v_mfma_f32_16x16x32_bf16 v[64:67], v[176:179], v[208:211], v[64:67]
	s_setprio 0
	s_barrier
; #define PG8_STAGE(bufoff, gbase, voff) do { _Pragma("unroll") for (int _i = 0; _i < 2; ++_i) \
;         __builtin_amdgcn_global_load_lds((const unsigned*)((const char*)(gbase) + (voff)[_i]), (PG8_LAS unsigned*)(lds + (bufoff) + ldsw + _i * 8192), 16, 0, 0); } while (0)
; #define PG8_LDA(dst, b, h) do { _Pragma("unroll") for (int m = 0; m < 4; ++m) _Pragma("unroll") for (int k = 0; k < 2; ++k) dst[m][k] = *(const PG8_LAS bf16x8*)(lds + PG8_SA(b, h) + aoff + m * 2048 + k * 1024); } while (0)
; #define PG8_MMA(ai, bj, At, Bt) do { __builtin_amdgcn_s_setprio(1); _Pragma("unroll") for (int m = 0; m < 4; ++m) _Pragma("unroll") for (int n = 0; n < 2; ++n) _Pragma("unroll") for (int k = 0; k < 2; ++k) \
;         acc[ai][bj][m][n] = __builtin_amdgcn_mfma_f32_16x16x32_bf16(Bt[n][k], At[m][k], acc[ai][bj][m][n], 0, 0, 0); __builtin_amdgcn_s_setprio(0); } while (0)
; #define PG8_WAIT_V(n) asm volatile("s_waitcnt vmcnt(" #n ")" ::: "memory")
; #define PG8_WAIT_L(n) asm volatile("s_waitcnt lgkmcnt(" #n ")" ::: "memory")
; #define PG8_BAR __builtin_amdgcn_s_barrier()
; #define PG8_SCHED __builtin_amdgcn_sched_barrier(0)
; __device__ __forceinline__ unsigned cvtpk(float lo, float hi) { f32x2 v = {lo, hi}; bf16x2_t b = __builtin_convertvector(v, bf16x2_t); return __builtin_bit_cast(unsigned, b); }
; template <class Epi, class Sched, bool ALIGN_EPI = false, bool SP2 = false>
; __device__ __forceinline__ void gemm_phase(PG8_LAS unsigned char* lds, const Gemm g, const Sched& S, const Epi& E, const int wave_s) {
;     ...
;             PG8_LDA(At, 1, 1); PG8_STAGE(PG8_SB(1, 0), b3, voffB); PG8_STAGE(PG8_SB(1, 1), b3 + hstep, voffB); PG8_STAGE(PG8_SA(1, 0), a3, voffA);
;             PG8_WAIT_V(8); PG8_WAIT_L(0); PG8_BAR; PG8_MMA(1, 0, At, B0); PG8_MMA(1, 1, At, B1); PG8_BAR; PG8_SCHED;
;     __device__ __forceinline__ void operator()(const af4 (&acc)[2][2][4][2], const pg8::Unit& u, int wr, int wc, int fr_, int fq_) const {
;     ...
;         } else if (wc == 0) {
; #pragma unroll
;             for (int ai = 0; ai < 2; ++ai)
; #pragma unroll
;                 for (int m = 0; m < 4; ++m) { const af4 v0 = acc[ai][0][m][0], v1 = acc[ai][0][m][1]; v4u w; w.x = cvtpk(v0[0], v0[1]); w.y = cvtpk(v0[2], v0[3]); w.z = cvtpk(v1[0], v1[1]); w.w = cvtpk(v1[2], v1[3]);
;                     *(v4u*)(Z + (size_t)(row0 + ai * 128 + m * 16) * 32 + 8 * fq) = w; }
	s_add_i32 s28, s55, s33
	s_mov_b32 m0, s28
	ds_read_b128 v[180:183], v151 offset:49152
	ds_read_b128 v[184:187], v151 offset:50176
	ds_read_b128 v[188:191], v151 offset:51200
	ds_read_b128 v[192:195], v151 offset:52224
	ds_read_b128 v[196:199], v151 offset:53248
	ds_read_b128 v[200:203], v151 offset:54272
	ds_read_b128 v[204:207], v151 offset:55296
	ds_read_b128 v[208:211], v151 offset:56320
	global_load_lds_dwordx4 v[242:243], off
	s_add_i32 m0, s28, 0x2000
	s_add_i32 s28, s56, s33
	global_load_lds_dwordx4 v[244:245], off
	s_mov_b32 m0, s28
	s_nop 0
	global_load_lds_dwordx4 v[246:247], off
	s_add_i32 m0, s28, 0x2000
	s_nop 0
	global_load_lds_dwordx4 v[248:249], off
	s_mov_b32 m0, s44
	s_nop 0
	global_load_lds_dwordx4 v[250:251], off
	s_mov_b32 m0, s45
	s_nop 0
	global_load_lds_dwordx4 v[252:253], off
	s_waitcnt vmcnt(8)
	s_waitcnt lgkmcnt(0)
	s_barrier
	s_setprio 1
	s_waitcnt lgkmcnt(0)
	v_mfma_f32_16x16x32_bf16 v[60:63], v[144:147], v[180:183], v[60:63]
	v_mfma_f32_16x16x32_bf16 v[56:59], v[156:159], v[180:183], v[56:59]
	v_mfma_f32_16x16x32_bf16 v[48:51], v[144:147], v[188:191], v[48:51]
	v_mfma_f32_16x16x32_bf16 v[40:43], v[156:159], v[188:191], v[40:43]
	v_mfma_f32_16x16x32_bf16 v[32:35], v[144:147], v[196:199], v[32:35]
	v_mfma_f32_16x16x32_bf16 v[24:27], v[156:159], v[196:199], v[24:27]
	v_mfma_f32_16x16x32_bf16 v[16:19], v[144:147], v[204:207], v[16:19]
	v_mfma_f32_16x16x32_bf16 v[8:11], v[156:159], v[204:207], v[8:11]
	v_mfma_f32_16x16x32_bf16 v[60:63], v[152:155], v[184:187], v[60:63]
	v_mfma_f32_16x16x32_bf16 v[56:59], v[160:163], v[184:187], v[56:59]
	v_mfma_f32_16x16x32_bf16 v[48:51], v[152:155], v[192:195], v[48:51]
	v_mfma_f32_16x16x32_bf16 v[40:43], v[160:163], v[192:195], v[40:43]
	v_mfma_f32_16x16x32_bf16 v[32:35], v[152:155], v[200:203], v[32:35]
	v_mfma_f32_16x16x32_bf16 v[24:27], v[160:163], v[200:203], v[24:27]
	v_mfma_f32_16x16x32_bf16 v[16:19], v[152:155], v[208:211], v[16:19]
	v_mfma_f32_16x16x32_bf16 v[8:11], v[160:163], v[208:211], v[8:11]
	s_setprio 0
	s_setprio 1
	v_mfma_f32_16x16x32_bf16 v[52:55], v[164:167], v[180:183], v[52:55]
	v_mfma_f32_16x16x32_bf16 v[44:47], v[172:175], v[180:183], v[44:47]
	v_mfma_f32_16x16x32_bf16 v[36:39], v[164:167], v[188:191], v[36:39]
	v_mfma_f32_16x16x32_bf16 v[28:31], v[172:175], v[188:191], v[28:31]
	v_mfma_f32_16x16x32_bf16 v[20:23], v[164:167], v[196:199], v[20:23]
	v_mfma_f32_16x16x32_bf16 v[12:15], v[172:175], v[196:199], v[12:15]
	v_mfma_f32_16x16x32_bf16 v[4:7], v[164:167], v[204:207], v[4:7]
	v_mfma_f32_16x16x32_bf16 v[0:3], v[172:175], v[204:207], v[0:3]
	v_mfma_f32_16x16x32_bf16 v[52:55], v[168:171], v[184:187], v[52:55]
	v_mfma_f32_16x16x32_bf16 v[44:47], v[176:179], v[184:187], v[44:47]
	v_mfma_f32_16x16x32_bf16 v[36:39], v[168:171], v[192:195], v[36:39]
	v_mfma_f32_16x16x32_bf16 v[28:31], v[176:179], v[192:195], v[28:31]
	v_mfma_f32_16x16x32_bf16 v[20:23], v[168:171], v[200:203], v[20:23]
	v_mfma_f32_16x16x32_bf16 v[12:15], v[176:179], v[200:203], v[12:15]
	v_mfma_f32_16x16x32_bf16 v[4:7], v[168:171], v[208:211], v[4:7]
	v_mfma_f32_16x16x32_bf16 v[0:3], v[176:179], v[208:211], v[0:3]
	s_setprio 0
	s_barrier
	s_add_i32 s54, s54, 2
	s_add_u32 s52, s52, 0x100
	s_addc_u32 s53, s53, 0
	s_add_u32 s24, s24, 0x100
	s_addc_u32 s25, s25, 0
	s_cmp_gt_u32 s54, 13
	s_cbranch_scc0 .LBB0_2472
	s_lshl_b32 s15, s22, 8
	v_mbcnt_lo_u32_b32 v144, -1, 0
	v_mbcnt_hi_u32_b32 v144, -1, v144
	s_add_i32 s15, s15, s87
	v_ashrrev_i32_e32 v146, 4, v144
	v_and_or_b32 v144, v144, 15, s15
	s_cmp_gt_i32 s50, 7
	s_mov_b64 s[22:23], -1
	s_cbranch_scc0 .LBB0_2477
	s_andn2_b64 vcc, exec, s[12:13]
	s_cbranch_vccnz .LBB0_2476
	v_lshlrev_b32_e32 v156, 3, v146
	v_ashrrev_i32_e32 v145, 31, v144
	v_or_b32_e32 v160, 16, v144
	v_ashrrev_i32_e32 v157, 31, v156
	v_lshlrev_b64 v[158:159], 6, v[144:145]
	v_ashrrev_i32_e32 v161, 31, v160
	v_lshl_add_u64 v[158:159], s[8:9], 0, v[158:159]
	v_lshlrev_b64 v[156:157], 1, v[156:157]
	v_lshlrev_b64 v[160:161], 6, v[160:161]
	v_cvt_pk_bf16_f32 v152, v124, v125
	v_cvt_pk_bf16_f32 v153, v126, v127
	v_cvt_pk_bf16_f32 v154, v120, v121
	v_cvt_pk_bf16_f32 v155, v122, v123
	v_lshl_add_u64 v[158:159], v[158:159], 0, v[156:157]
	v_lshl_add_u64 v[160:161], s[8:9], 0, v[160:161]
	global_store_dwordx4 v[158:159], v[152:155], off
	v_lshl_add_u64 v[160:161], v[160:161], 0, v[156:157]
	s_nop 0
	v_cvt_pk_bf16_f32 v152, v112, v113
	v_cvt_pk_bf16_f32 v153, v114, v115
	v_cvt_pk_bf16_f32 v154, v104, v105
	v_cvt_pk_bf16_f32 v155, v106, v107
	global_store_dwordx4 v[160:161], v[152:155], off
	v_or_b32_e32 v160, 32, v144
	v_ashrrev_i32_e32 v161, 31, v160
	v_lshlrev_b64 v[160:161], 6, v[160:161]
	v_lshl_add_u64 v[160:161], s[8:9], 0, v[160:161]
	v_cvt_pk_bf16_f32 v152, v96, v97
	v_cvt_pk_bf16_f32 v153, v98, v99
	v_cvt_pk_bf16_f32 v154, v88, v89
	v_cvt_pk_bf16_f32 v155, v90, v91
	v_lshl_add_u64 v[160:161], v[160:161], 0, v[156:157]
	global_store_dwordx4 v[160:161], v[152:155], off
	v_or_b32_e32 v160, 48, v144
	v_ashrrev_i32_e32 v161, 31, v160
	v_lshlrev_b64 v[160:161], 6, v[160:161]
	v_lshl_add_u64 v[160:161], s[8:9], 0, v[160:161]
	v_cvt_pk_bf16_f32 v152, v80, v81
	v_cvt_pk_bf16_f32 v153, v82, v83
	v_cvt_pk_bf16_f32 v154, v72, v73
	v_cvt_pk_bf16_f32 v155, v74, v75
	v_lshl_add_u64 v[156:157], v[160:161], 0, v[156:157]
	global_store_dwordx4 v[156:157], v[152:155], off
	v_add_co_u32_e32 v156, vcc, s42, v158
	s_nop 0
	v_cvt_pk_bf16_f32 v152, v60, v61
	v_cvt_pk_bf16_f32 v153, v62, v63
	v_cvt_pk_bf16_f32 v154, v56, v57
	v_cvt_pk_bf16_f32 v155, v58, v59
	v_addc_co_u32_e32 v157, vcc, 0, v159, vcc
	global_store_dwordx4 v[156:157], v[152:155], off
	s_nop 1
	v_cvt_pk_bf16_f32 v152, v48, v49
	v_cvt_pk_bf16_f32 v153, v50, v51
	v_cvt_pk_bf16_f32 v154, v40, v41
	v_cvt_pk_bf16_f32 v155, v42, v43
	global_store_dwordx4 v[156:157], v[152:155], off offset:1024
	s_nop 1
	v_cvt_pk_bf16_f32 v152, v32, v33
	v_cvt_pk_bf16_f32 v153, v34, v35
	v_cvt_pk_bf16_f32 v154, v24, v25
	v_cvt_pk_bf16_f32 v155, v26, v27
	global_store_dwordx4 v[156:157], v[152:155], off offset:2048
	s_nop 1
	v_cvt_pk_bf16_f32 v152, v16, v17
	v_cvt_pk_bf16_f32 v153, v18, v19
	v_cvt_pk_bf16_f32 v154, v8, v9
	v_cvt_pk_bf16_f32 v155, v10, v11
	global_store_dwordx4 v[156:157], v[152:155], off offset:3072
